# batched hand-written weight conversion now also for layer 0 (G0) and software-pipelined (next iteration loads issued before LDS transpose/pack/store); compiler conv_T loops for w_in,w_br,w_o,w_f1,w_f2
# speedup vs baseline: 1.0231x; 1.0019x over previous
; DI int ltid() { int t = threadIdx.x; asm volatile("" : "+v"(t)); return t; }
; DI int lbid() { int b = blockIdx.x; asm volatile("" : "+s"(b)); return b; }
; template <class Map>
; DI void conv_T(bf16_t* __restrict__ dst, const float* __restrict__ src, int K, int ldsrc, int nphys, Map map, const float* __restrict__ kscale, float* tile) {
;   const int tid = ltid(), ntn = nphys >> 6, ntiles = (K >> 6) * ntn;
;   for (int tl = lbid(); tl < ntiles; tl += gridDim.x) {
;     const int k0 = (tl / ntn) << 6, n0 = (tl % ntn) << 6;
;     const int nn = tid & 63, sc = map(n0 + nn);
; #pragma unroll
;     for (int i = 0; i < 8; ++i) { const int kk = i * 8 + (tid >> 6);
;       float v = sc >= 0 ? __builtin_nontemporal_load(&src[(size_t)(k0 + kk) * ldsrc + sc]) : 0.f;
;       if (kscale) v *= kscale[k0 + kk];
;       tile[kk * 65 + nn] = v; }
; DI void convert_layer(const Params& p, int l, float* tile) {
;     ...
;   conv_T((bf16_t*)(ws + O_WIN), p.w_in + (size_t)l * 2048 * NIN, 2048, NIN, NPHYS, MapIn{}, nullptr, tile);
.LBB0_41:
	s_or_b64 exec, exec, s[0:1]
	v_mov_b32_e32 v2, v248
	s_mov_b32 s6, s85
	s_barrier
	s_mov_b64 s[18:19], s[54:55]
	s_mov_b32 s20, s85
	s_mov_b32 s21, s56
	v_lshrrev_b32_e32 v36, 6, v248
	v_and_b32_e32 v37, 63, v248
	v_mul_u32_u24_e32 v30, 0x104, v36
	v_lshl_add_u32 v30, v37, 2, v30
	v_add_u32_e32 v31, 0x10400, v30
	v_and_b32_e32 v36, 7, v248
	v_lshrrev_b32_e32 v37, 3, v248
	v_mul_u32_u24_e32 v32, 0x820, v36
	v_lshl_add_u32 v32, v37, 2, v32
	v_add_u32_e32 v33, 0x10400, v32
	v_readlane_b32 s22, v249, 16
	v_readlane_b32 s23, v249, 17
	s_sub_u32 s22, s22, 0xa0
	s_subb_u32 s23, s23, 0
	s_load_dwordx2 s[24:25], s[22:23], 0x20
	s_waitcnt lgkmcnt(0)
	s_add_u32 s26, s18, 0x0
	s_addc_u32 s27, s19, 0
	v_lshrrev_b32_e32 v36, 6, v248
	v_and_b32_e32 v37, 63, v248
	v_mov_b32_e32 v38, 0xe1a0
	v_mul_u32_u24_e32 v34, v36, v38
	v_lshl_add_u32 v34, v37, 2, v34
	v_lshrrev_b32_e32 v36, 3, v248
	v_and_b32_e32 v37, 7, v248
	v_mov_b32_e32 v38, 0x1000
	v_mul_u32_u24_e32 v35, v36, v38
	v_lshl_add_u32 v35, v37, 4, v35
	s_mov_b32 s28, s20
	s_cmp_ge_u32 s28, 0x1c00
	s_cbranch_scc1 .Lcv_win_l0_end
	s_mov_b32 s12, s28
	s_mul_i32 s13, s12, 0x4925
	s_lshr_b32 s13, s13, 22
	s_mul_i32 s14, s13, 224
	s_sub_u32 s14, s12, s14
	s_mul_i32 s15, s13, 0x386800
	s_lshl_b32 s16, s14, 8
	s_cmp_ge_u32 s14, 40
	s_cselect_b32 s12, 0x140, 0
	s_cmp_ge_u32 s14, 80
	s_cselect_b32 s12, 0x1a0, s12
	s_add_u32 s16, s16, s12
	s_add_u32 s15, s15, s16
	s_add_u32 s30, s24, s15
	s_addc_u32 s31, s25, 0
	global_load_dword v40, v34, s[30:31] nt
	s_add_u32 s30, s30, 0x70d00
	s_addc_u32 s31, s31, 0
	global_load_dword v41, v34, s[30:31] nt
	s_add_u32 s30, s30, 0x70d00
	s_addc_u32 s31, s31, 0
	global_load_dword v42, v34, s[30:31] nt
	s_add_u32 s30, s30, 0x70d00
	s_addc_u32 s31, s31, 0
	global_load_dword v43, v34, s[30:31] nt
	s_add_u32 s30, s30, 0x70d00
	s_addc_u32 s31, s31, 0
	global_load_dword v44, v34, s[30:31] nt
	s_add_u32 s30, s30, 0x70d00
	s_addc_u32 s31, s31, 0
	global_load_dword v45, v34, s[30:31] nt
	s_add_u32 s30, s30, 0x70d00
	s_addc_u32 s31, s31, 0
	global_load_dword v46, v34, s[30:31] nt
	s_add_u32 s30, s30, 0x70d00
	s_addc_u32 s31, s31, 0
	global_load_dword v47, v34, s[30:31] nt
	s_mul_i32 s12, s21, 1
	s_add_u32 s12, s12, s28
	s_cmp_ge_u32 s12, 0x1c00
	s_cbranch_scc1 .Lcv_win_l0_pro_done
	s_mul_i32 s12, s21, 1
	s_add_u32 s12, s12, s28
	s_mul_i32 s13, s12, 0x4925
	s_lshr_b32 s13, s13, 22
	s_mul_i32 s14, s13, 224
	s_sub_u32 s14, s12, s14
	s_mul_i32 s15, s13, 0x386800
	s_lshl_b32 s16, s14, 8
	s_cmp_ge_u32 s14, 40
	s_cselect_b32 s12, 0x140, 0
	s_cmp_ge_u32 s14, 80
	s_cselect_b32 s12, 0x1a0, s12
	s_add_u32 s16, s16, s12
	s_add_u32 s15, s15, s16
	s_add_u32 s30, s24, s15
	s_addc_u32 s31, s25, 0
	global_load_dword v48, v34, s[30:31] nt
	s_add_u32 s30, s30, 0x70d00
	s_addc_u32 s31, s31, 0
	global_load_dword v49, v34, s[30:31] nt
	s_add_u32 s30, s30, 0x70d00
	s_addc_u32 s31, s31, 0
	global_load_dword v50, v34, s[30:31] nt
	s_add_u32 s30, s30, 0x70d00
	s_addc_u32 s31, s31, 0
	global_load_dword v51, v34, s[30:31] nt
	s_add_u32 s30, s30, 0x70d00
	s_addc_u32 s31, s31, 0
	global_load_dword v52, v34, s[30:31] nt
	s_add_u32 s30, s30, 0x70d00
	s_addc_u32 s31, s31, 0
	global_load_dword v53, v34, s[30:31] nt
	s_add_u32 s30, s30, 0x70d00
	s_addc_u32 s31, s31, 0
	global_load_dword v54, v34, s[30:31] nt
	s_add_u32 s30, s30, 0x70d00
	s_addc_u32 s31, s31, 0
	global_load_dword v55, v34, s[30:31] nt
	s_mul_i32 s12, s21, 2
	s_add_u32 s12, s12, s28
	s_cmp_ge_u32 s12, 0x1c00
	s_cbranch_scc1 .Lcv_win_l0_pro_done
	s_mul_i32 s12, s21, 2
	s_add_u32 s12, s12, s28
	s_mul_i32 s13, s12, 0x4925
	s_lshr_b32 s13, s13, 22
	s_mul_i32 s14, s13, 224
	s_sub_u32 s14, s12, s14
	s_mul_i32 s15, s13, 0x386800
	s_lshl_b32 s16, s14, 8
	s_cmp_ge_u32 s14, 40
	s_cselect_b32 s12, 0x140, 0
	s_cmp_ge_u32 s14, 80
	s_cselect_b32 s12, 0x1a0, s12
	s_add_u32 s16, s16, s12
	s_add_u32 s15, s15, s16
	s_add_u32 s30, s24, s15
	s_addc_u32 s31, s25, 0
	global_load_dword v56, v34, s[30:31] nt
	s_add_u32 s30, s30, 0x70d00
	s_addc_u32 s31, s31, 0
	global_load_dword v57, v34, s[30:31] nt
	s_add_u32 s30, s30, 0x70d00
	s_addc_u32 s31, s31, 0
	global_load_dword v58, v34, s[30:31] nt
	s_add_u32 s30, s30, 0x70d00
	s_addc_u32 s31, s31, 0
	global_load_dword v59, v34, s[30:31] nt
	s_add_u32 s30, s30, 0x70d00
	s_addc_u32 s31, s31, 0
	global_load_dword v60, v34, s[30:31] nt
	s_add_u32 s30, s30, 0x70d00
	s_addc_u32 s31, s31, 0
	global_load_dword v61, v34, s[30:31] nt
	s_add_u32 s30, s30, 0x70d00
	s_addc_u32 s31, s31, 0
	global_load_dword v62, v34, s[30:31] nt
	s_add_u32 s30, s30, 0x70d00
	s_addc_u32 s31, s31, 0
	global_load_dword v63, v34, s[30:31] nt
	s_mul_i32 s12, s21, 3
	s_add_u32 s12, s12, s28
	s_cmp_ge_u32 s12, 0x1c00
	s_cbranch_scc1 .Lcv_win_l0_pro_done
	s_mul_i32 s12, s21, 3
	s_add_u32 s12, s12, s28
	s_mul_i32 s13, s12, 0x4925
	s_lshr_b32 s13, s13, 22
	s_mul_i32 s14, s13, 224
	s_sub_u32 s14, s12, s14
	s_mul_i32 s15, s13, 0x386800
	s_lshl_b32 s16, s14, 8
	s_cmp_ge_u32 s14, 40
	s_cselect_b32 s12, 0x140, 0
	s_cmp_ge_u32 s14, 80
	s_cselect_b32 s12, 0x1a0, s12
	s_add_u32 s16, s16, s12
	s_add_u32 s15, s15, s16
	s_add_u32 s30, s24, s15
	s_addc_u32 s31, s25, 0
	global_load_dword v64, v34, s[30:31] nt
	s_add_u32 s30, s30, 0x70d00
	s_addc_u32 s31, s31, 0
	global_load_dword v65, v34, s[30:31] nt
	s_add_u32 s30, s30, 0x70d00
	s_addc_u32 s31, s31, 0
	global_load_dword v66, v34, s[30:31] nt
	s_add_u32 s30, s30, 0x70d00
	s_addc_u32 s31, s31, 0
	global_load_dword v67, v34, s[30:31] nt
	s_add_u32 s30, s30, 0x70d00
	s_addc_u32 s31, s31, 0
	global_load_dword v68, v34, s[30:31] nt
	s_add_u32 s30, s30, 0x70d00
	s_addc_u32 s31, s31, 0
	global_load_dword v69, v34, s[30:31] nt
	s_add_u32 s30, s30, 0x70d00
	s_addc_u32 s31, s31, 0
	global_load_dword v70, v34, s[30:31] nt
	s_add_u32 s30, s30, 0x70d00
	s_addc_u32 s31, s31, 0
	global_load_dword v71, v34, s[30:31] nt
; DI int ltid() { int t = threadIdx.x; asm volatile("" : "+v"(t)); return t; }
; DI int lbid() { int b = blockIdx.x; asm volatile("" : "+s"(b)); return b; }
; template <class Map>
; DI void conv_T(bf16_t* __restrict__ dst, const float* __restrict__ src, int K, int ldsrc, int nphys, Map map, const float* __restrict__ kscale, float* tile) {
;   const int tid = ltid(), ntn = nphys >> 6, ntiles = (K >> 6) * ntn;
;   for (int tl = lbid(); tl < ntiles; tl += gridDim.x) {
;     const int k0 = (tl / ntn) << 6, n0 = (tl % ntn) << 6;
;     const int nn = tid & 63, sc = map(n0 + nn);
; #pragma unroll
;     for (int i = 0; i < 8; ++i) { const int kk = i * 8 + (tid >> 6);
;       float v = sc >= 0 ? __builtin_nontemporal_load(&src[(size_t)(k0 + kk) * ldsrc + sc]) : 0.f;
;       if (kscale) v *= kscale[k0 + kk];
;       tile[kk * 65 + nn] = v; }
; DI void convert_layer(const Params& p, int l, float* tile) {
;     ...
;   conv_T((bf16_t*)(ws + O_WIN), p.w_in + (size_t)l * 2048 * NIN, 2048, NIN, NPHYS, MapIn{}, nullptr, tile);
.Lcv_win_l0_pro_done:
	s_waitcnt vmcnt(0)
	s_branch .Lcv_win_l0_p0_after
.Lcv_win_l0_loop:
	s_waitcnt vmcnt(4)
.Lcv_win_l0_p0_after:
	ds_write_b32 v30, v40
	ds_write_b32 v30, v41 offset:2080
	ds_write_b32 v30, v42 offset:4160
	ds_write_b32 v30, v43 offset:6240
	ds_write_b32 v30, v44 offset:8320
	ds_write_b32 v30, v45 offset:10400
	ds_write_b32 v30, v46 offset:12480
	ds_write_b32 v30, v47 offset:14560
	s_mul_i32 s12, s21, 1
	s_add_u32 s12, s12, s28
	s_cmp_ge_u32 s12, 0x1c00
	s_cbranch_scc1 .Lcv_win_l0_p0_wr_done
	ds_write_b32 v30, v48 offset:16640
	ds_write_b32 v30, v49 offset:18720
	ds_write_b32 v30, v50 offset:20800
	ds_write_b32 v30, v51 offset:22880
	ds_write_b32 v30, v52 offset:24960
	ds_write_b32 v30, v53 offset:27040
	ds_write_b32 v30, v54 offset:29120
	ds_write_b32 v30, v55 offset:31200
	s_mul_i32 s12, s21, 2
	s_add_u32 s12, s12, s28
	s_cmp_ge_u32 s12, 0x1c00
	s_cbranch_scc1 .Lcv_win_l0_p0_wr_done
	ds_write_b32 v30, v56 offset:33280
	ds_write_b32 v30, v57 offset:35360
	ds_write_b32 v30, v58 offset:37440
	ds_write_b32 v30, v59 offset:39520
	ds_write_b32 v30, v60 offset:41600
	ds_write_b32 v30, v61 offset:43680
	ds_write_b32 v30, v62 offset:45760
	ds_write_b32 v30, v63 offset:47840
	s_mul_i32 s12, s21, 3
	s_add_u32 s12, s12, s28
	s_cmp_ge_u32 s12, 0x1c00
	s_cbranch_scc1 .Lcv_win_l0_p0_wr_done
	ds_write_b32 v30, v64 offset:49920
	ds_write_b32 v30, v65 offset:52000
	ds_write_b32 v30, v66 offset:54080
	ds_write_b32 v30, v67 offset:56160
	ds_write_b32 v30, v68 offset:58240
	ds_write_b32 v30, v69 offset:60320
	ds_write_b32 v30, v70 offset:62400
	ds_write_b32 v30, v71 offset:64480
.Lcv_win_l0_p0_wr_done:
	s_mul_i32 s12, s21, 4
	s_add_u32 s12, s12, s28
	s_cmp_ge_u32 s12, 0x1c00
	s_cbranch_scc1 .Lcv_win_l0_p0_pf_done
	s_mul_i32 s12, s21, 4
	s_add_u32 s12, s12, s28
	s_mul_i32 s13, s12, 0x4925
	s_lshr_b32 s13, s13, 22
	s_mul_i32 s14, s13, 224
	s_sub_u32 s14, s12, s14
	s_mul_i32 s15, s13, 0x386800
	s_lshl_b32 s16, s14, 8
	s_cmp_ge_u32 s14, 40
	s_cselect_b32 s12, 0x140, 0
	s_cmp_ge_u32 s14, 80
	s_cselect_b32 s12, 0x1a0, s12
	s_add_u32 s16, s16, s12
	s_add_u32 s15, s15, s16
	s_add_u32 s30, s24, s15
	s_addc_u32 s31, s25, 0
	global_load_dword v88, v34, s[30:31] nt
	s_add_u32 s30, s30, 0x70d00
	s_addc_u32 s31, s31, 0
	global_load_dword v89, v34, s[30:31] nt
	s_add_u32 s30, s30, 0x70d00
	s_addc_u32 s31, s31, 0
	global_load_dword v90, v34, s[30:31] nt
	s_add_u32 s30, s30, 0x70d00
	s_addc_u32 s31, s31, 0
	global_load_dword v91, v34, s[30:31] nt
	s_add_u32 s30, s30, 0x70d00
	s_addc_u32 s31, s31, 0
	global_load_dword v92, v34, s[30:31] nt
	s_add_u32 s30, s30, 0x70d00
	s_addc_u32 s31, s31, 0
	global_load_dword v93, v34, s[30:31] nt
	s_add_u32 s30, s30, 0x70d00
	s_addc_u32 s31, s31, 0
	global_load_dword v94, v34, s[30:31] nt
	s_add_u32 s30, s30, 0x70d00
	s_addc_u32 s31, s31, 0
	global_load_dword v95, v34, s[30:31] nt
	s_mul_i32 s12, s21, 5
	s_add_u32 s12, s12, s28
	s_cmp_ge_u32 s12, 0x1c00
	s_cbranch_scc1 .Lcv_win_l0_p0_pf_done
	s_mul_i32 s12, s21, 5
	s_add_u32 s12, s12, s28
	s_mul_i32 s13, s12, 0x4925
	s_lshr_b32 s13, s13, 22
	s_mul_i32 s14, s13, 224
	s_sub_u32 s14, s12, s14
	s_mul_i32 s15, s13, 0x386800
	s_lshl_b32 s16, s14, 8
	s_cmp_ge_u32 s14, 40
	s_cselect_b32 s12, 0x140, 0
	s_cmp_ge_u32 s14, 80
	s_cselect_b32 s12, 0x1a0, s12
	s_add_u32 s16, s16, s12
	s_add_u32 s15, s15, s16
	s_add_u32 s30, s24, s15
	s_addc_u32 s31, s25, 0
	global_load_dword v96, v34, s[30:31] nt
	s_add_u32 s30, s30, 0x70d00
	s_addc_u32 s31, s31, 0
	global_load_dword v97, v34, s[30:31] nt
	s_add_u32 s30, s30, 0x70d00
	s_addc_u32 s31, s31, 0
	global_load_dword v98, v34, s[30:31] nt
	s_add_u32 s30, s30, 0x70d00
	s_addc_u32 s31, s31, 0
	global_load_dword v99, v34, s[30:31] nt
	s_add_u32 s30, s30, 0x70d00
	s_addc_u32 s31, s31, 0
	global_load_dword v100, v34, s[30:31] nt
	s_add_u32 s30, s30, 0x70d00
	s_addc_u32 s31, s31, 0
	global_load_dword v101, v34, s[30:31] nt
	s_add_u32 s30, s30, 0x70d00
	s_addc_u32 s31, s31, 0
	global_load_dword v102, v34, s[30:31] nt
	s_add_u32 s30, s30, 0x70d00
	s_addc_u32 s31, s31, 0
	global_load_dword v103, v34, s[30:31] nt
	s_mul_i32 s12, s21, 6
	s_add_u32 s12, s12, s28
	s_cmp_ge_u32 s12, 0x1c00
	s_cbranch_scc1 .Lcv_win_l0_p0_pf_done
	s_mul_i32 s12, s21, 6
	s_add_u32 s12, s12, s28
	s_mul_i32 s13, s12, 0x4925
	s_lshr_b32 s13, s13, 22
	s_mul_i32 s14, s13, 224
	s_sub_u32 s14, s12, s14
	s_mul_i32 s15, s13, 0x386800
	s_lshl_b32 s16, s14, 8
	s_cmp_ge_u32 s14, 40
	s_cselect_b32 s12, 0x140, 0
	s_cmp_ge_u32 s14, 80
	s_cselect_b32 s12, 0x1a0, s12
	s_add_u32 s16, s16, s12
	s_add_u32 s15, s15, s16
	s_add_u32 s30, s24, s15
	s_addc_u32 s31, s25, 0
	global_load_dword v104, v34, s[30:31] nt
	s_add_u32 s30, s30, 0x70d00
	s_addc_u32 s31, s31, 0
	global_load_dword v105, v34, s[30:31] nt
	s_add_u32 s30, s30, 0x70d00
	s_addc_u32 s31, s31, 0
	global_load_dword v106, v34, s[30:31] nt
	s_add_u32 s30, s30, 0x70d00
	s_addc_u32 s31, s31, 0
	global_load_dword v107, v34, s[30:31] nt
	s_add_u32 s30, s30, 0x70d00
	s_addc_u32 s31, s31, 0
	global_load_dword v108, v34, s[30:31] nt
	s_add_u32 s30, s30, 0x70d00
	s_addc_u32 s31, s31, 0
	global_load_dword v109, v34, s[30:31] nt
	s_add_u32 s30, s30, 0x70d00
	s_addc_u32 s31, s31, 0
	global_load_dword v110, v34, s[30:31] nt
	s_add_u32 s30, s30, 0x70d00
	s_addc_u32 s31, s31, 0
	global_load_dword v111, v34, s[30:31] nt
	s_mul_i32 s12, s21, 7
	s_add_u32 s12, s12, s28
	s_cmp_ge_u32 s12, 0x1c00
	s_cbranch_scc1 .Lcv_win_l0_p0_pf_done
	s_mul_i32 s12, s21, 7
	s_add_u32 s12, s12, s28
	s_mul_i32 s13, s12, 0x4925
	s_lshr_b32 s13, s13, 22
	s_mul_i32 s14, s13, 224
	s_sub_u32 s14, s12, s14
	s_mul_i32 s15, s13, 0x386800
	s_lshl_b32 s16, s14, 8
	s_cmp_ge_u32 s14, 40
	s_cselect_b32 s12, 0x140, 0
	s_cmp_ge_u32 s14, 80
	s_cselect_b32 s12, 0x1a0, s12
	s_add_u32 s16, s16, s12
	s_add_u32 s15, s15, s16
	s_add_u32 s30, s24, s15
	s_addc_u32 s31, s25, 0
	global_load_dword v112, v34, s[30:31] nt
	s_add_u32 s30, s30, 0x70d00
	s_addc_u32 s31, s31, 0
	global_load_dword v113, v34, s[30:31] nt
	s_add_u32 s30, s30, 0x70d00
	s_addc_u32 s31, s31, 0
	global_load_dword v114, v34, s[30:31] nt
	s_add_u32 s30, s30, 0x70d00
	s_addc_u32 s31, s31, 0
	global_load_dword v115, v34, s[30:31] nt
	s_add_u32 s30, s30, 0x70d00
	s_addc_u32 s31, s31, 0
	global_load_dword v116, v34, s[30:31] nt
	s_add_u32 s30, s30, 0x70d00
	s_addc_u32 s31, s31, 0
	global_load_dword v117, v34, s[30:31] nt
	s_add_u32 s30, s30, 0x70d00
	s_addc_u32 s31, s31, 0
	global_load_dword v118, v34, s[30:31] nt
	s_add_u32 s30, s30, 0x70d00
	s_addc_u32 s31, s31, 0
	global_load_dword v119, v34, s[30:31] nt
; DI unsigned cvtpk(float lo, float hi) { unsigned r; asm volatile("v_cvt_pk_bf16_f32 %0, %1, %2" : "=v"(r) : "v"(lo), "v"(hi)); return r; }
; template <class Map>
; DI void conv_T(bf16_t* __restrict__ dst, const float* __restrict__ src, int K, int ldsrc, int nphys, Map map, const float* __restrict__ kscale, float* tile) {
;     ...
;     __syncthreads();
;     const int np = tid >> 3, ks = tid & 7;
;     float v[8];
; #pragma unroll
;     for (int j = 0; j < 8; ++j) v[j] = tile[(ks * 8 + j) * 65 + np];
;     u32x4 w = {cvtpk(v[0], v[1]), cvtpk(v[2], v[3]), cvtpk(v[4], v[5]), cvtpk(v[6], v[7])};
;     *(u32x4*)(dst + (size_t)(n0 + np) * K + k0 + ks * 8) = w;
;     __syncthreads();
;   }
; DI void convert_layer(const Params& p, int l, float* tile) {
;     ...
;   conv_T((bf16_t*)(ws + O_WIN), p.w_in + (size_t)l * 2048 * NIN, 2048, NIN, NPHYS, MapIn{}, nullptr, tile);
.Lcv_win_l0_p0_pf_done:
	s_waitcnt lgkmcnt(0)
	s_barrier
	ds_read_b32 v40, v32
	ds_read_b32 v41, v32 offset:260
	ds_read_b32 v42, v32 offset:520
	ds_read_b32 v43, v32 offset:780
	ds_read_b32 v44, v32 offset:1040
	ds_read_b32 v45, v32 offset:1300
	ds_read_b32 v46, v32 offset:1560
	ds_read_b32 v47, v32 offset:1820
	s_mul_i32 s12, s21, 1
	s_add_u32 s12, s12, s28
	s_cmp_ge_u32 s12, 0x1c00
	s_cbranch_scc1 .Lcv_win_l0_p0_rd_done
	ds_read_b32 v48, v32 offset:16640
	ds_read_b32 v49, v32 offset:16900
	ds_read_b32 v50, v32 offset:17160
	ds_read_b32 v51, v32 offset:17420
	ds_read_b32 v52, v32 offset:17680
	ds_read_b32 v53, v32 offset:17940
	ds_read_b32 v54, v32 offset:18200
	ds_read_b32 v55, v32 offset:18460
	s_mul_i32 s12, s21, 2
	s_add_u32 s12, s12, s28
	s_cmp_ge_u32 s12, 0x1c00
	s_cbranch_scc1 .Lcv_win_l0_p0_rd_done
	ds_read_b32 v56, v32 offset:33280
	ds_read_b32 v57, v32 offset:33540
	ds_read_b32 v58, v32 offset:33800
	ds_read_b32 v59, v32 offset:34060
	ds_read_b32 v60, v32 offset:34320
	ds_read_b32 v61, v32 offset:34580
	ds_read_b32 v62, v32 offset:34840
	ds_read_b32 v63, v32 offset:35100
	s_mul_i32 s12, s21, 3
	s_add_u32 s12, s12, s28
	s_cmp_ge_u32 s12, 0x1c00
	s_cbranch_scc1 .Lcv_win_l0_p0_rd_done
	ds_read_b32 v64, v32 offset:49920
	ds_read_b32 v65, v32 offset:50180
	ds_read_b32 v66, v32 offset:50440
	ds_read_b32 v67, v32 offset:50700
	ds_read_b32 v68, v32 offset:50960
	ds_read_b32 v69, v32 offset:51220
	ds_read_b32 v70, v32 offset:51480
	ds_read_b32 v71, v32 offset:51740
.Lcv_win_l0_p0_rd_done:
	s_waitcnt lgkmcnt(0)
	s_mov_b32 s12, s28
	s_mul_i32 s13, s12, 0x4925
	s_lshr_b32 s13, s13, 22
	s_mul_i32 s14, s13, 224
	s_sub_u32 s14, s12, s14
	s_mul_i32 s15, s14, 0x40000
	s_lshl_b32 s16, s13, 7
	s_add_u32 s15, s15, s16
	s_add_u32 s30, s26, s15
	s_addc_u32 s31, s27, 0
	v_cvt_pk_bf16_f32 v72, v40, v41
	v_cvt_pk_bf16_f32 v73, v42, v43
	v_cvt_pk_bf16_f32 v74, v44, v45
	v_cvt_pk_bf16_f32 v75, v46, v47
	global_store_dwordx4 v35, v[72:75], s[30:31]
	s_mul_i32 s12, s21, 1
	s_add_u32 s12, s12, s28
	s_cmp_ge_u32 s12, 0x1c00
	s_cbranch_scc1 .Lcv_win_l0_p0_st_done
	s_mul_i32 s12, s21, 1
	s_add_u32 s12, s12, s28
	s_mul_i32 s13, s12, 0x4925
	s_lshr_b32 s13, s13, 22
	s_mul_i32 s14, s13, 224
	s_sub_u32 s14, s12, s14
	s_mul_i32 s15, s14, 0x40000
	s_lshl_b32 s16, s13, 7
	s_add_u32 s15, s15, s16
	s_add_u32 s30, s26, s15
	s_addc_u32 s31, s27, 0
	v_cvt_pk_bf16_f32 v76, v48, v49
	v_cvt_pk_bf16_f32 v77, v50, v51
	v_cvt_pk_bf16_f32 v78, v52, v53
	v_cvt_pk_bf16_f32 v79, v54, v55
	global_store_dwordx4 v35, v[76:79], s[30:31]
	s_mul_i32 s12, s21, 2
	s_add_u32 s12, s12, s28
	s_cmp_ge_u32 s12, 0x1c00
	s_cbranch_scc1 .Lcv_win_l0_p0_st_done
	s_mul_i32 s12, s21, 2
	s_add_u32 s12, s12, s28
	s_mul_i32 s13, s12, 0x4925
	s_lshr_b32 s13, s13, 22
	s_mul_i32 s14, s13, 224
	s_sub_u32 s14, s12, s14
	s_mul_i32 s15, s14, 0x40000
	s_lshl_b32 s16, s13, 7
	s_add_u32 s15, s15, s16
	s_add_u32 s30, s26, s15
	s_addc_u32 s31, s27, 0
	v_cvt_pk_bf16_f32 v80, v56, v57
	v_cvt_pk_bf16_f32 v81, v58, v59
	v_cvt_pk_bf16_f32 v82, v60, v61
	v_cvt_pk_bf16_f32 v83, v62, v63
	global_store_dwordx4 v35, v[80:83], s[30:31]
	s_mul_i32 s12, s21, 3
	s_add_u32 s12, s12, s28
	s_cmp_ge_u32 s12, 0x1c00
	s_cbranch_scc1 .Lcv_win_l0_p0_st_done
	s_mul_i32 s12, s21, 3
	s_add_u32 s12, s12, s28
	s_mul_i32 s13, s12, 0x4925
	s_lshr_b32 s13, s13, 22
	s_mul_i32 s14, s13, 224
	s_sub_u32 s14, s12, s14
	s_mul_i32 s15, s14, 0x40000
	s_lshl_b32 s16, s13, 7
	s_add_u32 s15, s15, s16
	s_add_u32 s30, s26, s15
	s_addc_u32 s31, s27, 0
	v_cvt_pk_bf16_f32 v84, v64, v65
	v_cvt_pk_bf16_f32 v85, v66, v67
	v_cvt_pk_bf16_f32 v86, v68, v69
	v_cvt_pk_bf16_f32 v87, v70, v71
	global_store_dwordx4 v35, v[84:87], s[30:31]
.Lcv_win_l0_p0_st_done:
	s_lshl_b32 s12, s21, 2
	s_add_u32 s28, s28, s12
	s_cmp_ge_u32 s28, 0x1c00
	s_cbranch_scc1 .Lcv_win_l0_end
	s_waitcnt vmcnt(4)
.Lcv_win_l0_p1_after:
	ds_write_b32 v31, v88
	ds_write_b32 v31, v89 offset:2080
	ds_write_b32 v31, v90 offset:4160
	ds_write_b32 v31, v91 offset:6240
	ds_write_b32 v31, v92 offset:8320
	ds_write_b32 v31, v93 offset:10400
	ds_write_b32 v31, v94 offset:12480
	ds_write_b32 v31, v95 offset:14560
	s_mul_i32 s12, s21, 1
	s_add_u32 s12, s12, s28
	s_cmp_ge_u32 s12, 0x1c00
	s_cbranch_scc1 .Lcv_win_l0_p1_wr_done
	ds_write_b32 v31, v96 offset:16640
	ds_write_b32 v31, v97 offset:18720
	ds_write_b32 v31, v98 offset:20800
	ds_write_b32 v31, v99 offset:22880
	ds_write_b32 v31, v100 offset:24960
	ds_write_b32 v31, v101 offset:27040
	ds_write_b32 v31, v102 offset:29120
	ds_write_b32 v31, v103 offset:31200
	s_mul_i32 s12, s21, 2
	s_add_u32 s12, s12, s28
	s_cmp_ge_u32 s12, 0x1c00
	s_cbranch_scc1 .Lcv_win_l0_p1_wr_done
	ds_write_b32 v31, v104 offset:33280
	ds_write_b32 v31, v105 offset:35360
	ds_write_b32 v31, v106 offset:37440
	ds_write_b32 v31, v107 offset:39520
	ds_write_b32 v31, v108 offset:41600
	ds_write_b32 v31, v109 offset:43680
	ds_write_b32 v31, v110 offset:45760
	ds_write_b32 v31, v111 offset:47840
	s_mul_i32 s12, s21, 3
	s_add_u32 s12, s12, s28
	s_cmp_ge_u32 s12, 0x1c00
	s_cbranch_scc1 .Lcv_win_l0_p1_wr_done
	ds_write_b32 v31, v112 offset:49920
	ds_write_b32 v31, v113 offset:52000
	ds_write_b32 v31, v114 offset:54080
	ds_write_b32 v31, v115 offset:56160
	ds_write_b32 v31, v116 offset:58240
	ds_write_b32 v31, v117 offset:60320
	ds_write_b32 v31, v118 offset:62400
	ds_write_b32 v31, v119 offset:64480
; DI int lbid() { int b = blockIdx.x; asm volatile("" : "+s"(b)); return b; }
; template <class Map>
; DI void conv_T(bf16_t* __restrict__ dst, const float* __restrict__ src, int K, int ldsrc, int nphys, Map map, const float* __restrict__ kscale, float* tile) {
;     ...
;   for (int tl = lbid(); tl < ntiles; tl += gridDim.x) {
;     const int k0 = (tl / ntn) << 6, n0 = (tl % ntn) << 6;
;     const int nn = tid & 63, sc = map(n0 + nn);
; #pragma unroll
;     for (int i = 0; i < 8; ++i) { const int kk = i * 8 + (tid >> 6);
;       float v = sc >= 0 ? __builtin_nontemporal_load(&src[(size_t)(k0 + kk) * ldsrc + sc]) : 0.f;
; DI void convert_layer(const Params& p, int l, float* tile) {
;     ...
;   conv_T((bf16_t*)(ws + O_WIN), p.w_in + (size_t)l * 2048 * NIN, 2048, NIN, NPHYS, MapIn{}, nullptr, tile);
.Lcv_win_l0_p1_wr_done:
	s_mul_i32 s12, s21, 4
	s_add_u32 s12, s12, s28
	s_cmp_ge_u32 s12, 0x1c00
	s_cbranch_scc1 .Lcv_win_l0_p1_pf_done
	s_mul_i32 s12, s21, 4
	s_add_u32 s12, s12, s28
	s_mul_i32 s13, s12, 0x4925
	s_lshr_b32 s13, s13, 22
	s_mul_i32 s14, s13, 224
	s_sub_u32 s14, s12, s14
	s_mul_i32 s15, s13, 0x386800
	s_lshl_b32 s16, s14, 8
	s_cmp_ge_u32 s14, 40
	s_cselect_b32 s12, 0x140, 0
	s_cmp_ge_u32 s14, 80
	s_cselect_b32 s12, 0x1a0, s12
	s_add_u32 s16, s16, s12
	s_add_u32 s15, s15, s16
	s_add_u32 s30, s24, s15
	s_addc_u32 s31, s25, 0
	global_load_dword v40, v34, s[30:31] nt
	s_add_u32 s30, s30, 0x70d00
	s_addc_u32 s31, s31, 0
	global_load_dword v41, v34, s[30:31] nt
	s_add_u32 s30, s30, 0x70d00
	s_addc_u32 s31, s31, 0
	global_load_dword v42, v34, s[30:31] nt
	s_add_u32 s30, s30, 0x70d00
	s_addc_u32 s31, s31, 0
	global_load_dword v43, v34, s[30:31] nt
	s_add_u32 s30, s30, 0x70d00
	s_addc_u32 s31, s31, 0
	global_load_dword v44, v34, s[30:31] nt
	s_add_u32 s30, s30, 0x70d00
	s_addc_u32 s31, s31, 0
	global_load_dword v45, v34, s[30:31] nt
	s_add_u32 s30, s30, 0x70d00
	s_addc_u32 s31, s31, 0
	global_load_dword v46, v34, s[30:31] nt
	s_add_u32 s30, s30, 0x70d00
	s_addc_u32 s31, s31, 0
	global_load_dword v47, v34, s[30:31] nt
	s_mul_i32 s12, s21, 5
	s_add_u32 s12, s12, s28
	s_cmp_ge_u32 s12, 0x1c00
	s_cbranch_scc1 .Lcv_win_l0_p1_pf_done
	s_mul_i32 s12, s21, 5
	s_add_u32 s12, s12, s28
	s_mul_i32 s13, s12, 0x4925
	s_lshr_b32 s13, s13, 22
	s_mul_i32 s14, s13, 224
	s_sub_u32 s14, s12, s14
	s_mul_i32 s15, s13, 0x386800
	s_lshl_b32 s16, s14, 8
	s_cmp_ge_u32 s14, 40
	s_cselect_b32 s12, 0x140, 0
	s_cmp_ge_u32 s14, 80
	s_cselect_b32 s12, 0x1a0, s12
	s_add_u32 s16, s16, s12
	s_add_u32 s15, s15, s16
	s_add_u32 s30, s24, s15
	s_addc_u32 s31, s25, 0
	global_load_dword v48, v34, s[30:31] nt
	s_add_u32 s30, s30, 0x70d00
	s_addc_u32 s31, s31, 0
	global_load_dword v49, v34, s[30:31] nt
	s_add_u32 s30, s30, 0x70d00
	s_addc_u32 s31, s31, 0
	global_load_dword v50, v34, s[30:31] nt
	s_add_u32 s30, s30, 0x70d00
	s_addc_u32 s31, s31, 0
	global_load_dword v51, v34, s[30:31] nt
	s_add_u32 s30, s30, 0x70d00
	s_addc_u32 s31, s31, 0
	global_load_dword v52, v34, s[30:31] nt
	s_add_u32 s30, s30, 0x70d00
	s_addc_u32 s31, s31, 0
	global_load_dword v53, v34, s[30:31] nt
	s_add_u32 s30, s30, 0x70d00
	s_addc_u32 s31, s31, 0
	global_load_dword v54, v34, s[30:31] nt
	s_add_u32 s30, s30, 0x70d00
	s_addc_u32 s31, s31, 0
	global_load_dword v55, v34, s[30:31] nt
	s_mul_i32 s12, s21, 6
	s_add_u32 s12, s12, s28
	s_cmp_ge_u32 s12, 0x1c00
	s_cbranch_scc1 .Lcv_win_l0_p1_pf_done
	s_mul_i32 s12, s21, 6
	s_add_u32 s12, s12, s28
	s_mul_i32 s13, s12, 0x4925
	s_lshr_b32 s13, s13, 22
	s_mul_i32 s14, s13, 224
	s_sub_u32 s14, s12, s14
	s_mul_i32 s15, s13, 0x386800
	s_lshl_b32 s16, s14, 8
	s_cmp_ge_u32 s14, 40
	s_cselect_b32 s12, 0x140, 0
	s_cmp_ge_u32 s14, 80
	s_cselect_b32 s12, 0x1a0, s12
	s_add_u32 s16, s16, s12
	s_add_u32 s15, s15, s16
	s_add_u32 s30, s24, s15
	s_addc_u32 s31, s25, 0
	global_load_dword v56, v34, s[30:31] nt
	s_add_u32 s30, s30, 0x70d00
	s_addc_u32 s31, s31, 0
	global_load_dword v57, v34, s[30:31] nt
	s_add_u32 s30, s30, 0x70d00
	s_addc_u32 s31, s31, 0
	global_load_dword v58, v34, s[30:31] nt
	s_add_u32 s30, s30, 0x70d00
	s_addc_u32 s31, s31, 0
	global_load_dword v59, v34, s[30:31] nt
	s_add_u32 s30, s30, 0x70d00
	s_addc_u32 s31, s31, 0
	global_load_dword v60, v34, s[30:31] nt
	s_add_u32 s30, s30, 0x70d00
	s_addc_u32 s31, s31, 0
	global_load_dword v61, v34, s[30:31] nt
	s_add_u32 s30, s30, 0x70d00
	s_addc_u32 s31, s31, 0
	global_load_dword v62, v34, s[30:31] nt
	s_add_u32 s30, s30, 0x70d00
	s_addc_u32 s31, s31, 0
	global_load_dword v63, v34, s[30:31] nt
	s_mul_i32 s12, s21, 7
	s_add_u32 s12, s12, s28
	s_cmp_ge_u32 s12, 0x1c00
	s_cbranch_scc1 .Lcv_win_l0_p1_pf_done
	s_mul_i32 s12, s21, 7
	s_add_u32 s12, s12, s28
	s_mul_i32 s13, s12, 0x4925
	s_lshr_b32 s13, s13, 22
	s_mul_i32 s14, s13, 224
	s_sub_u32 s14, s12, s14
	s_mul_i32 s15, s13, 0x386800
	s_lshl_b32 s16, s14, 8
	s_cmp_ge_u32 s14, 40
	s_cselect_b32 s12, 0x140, 0
	s_cmp_ge_u32 s14, 80
	s_cselect_b32 s12, 0x1a0, s12
	s_add_u32 s16, s16, s12
	s_add_u32 s15, s15, s16
	s_add_u32 s30, s24, s15
	s_addc_u32 s31, s25, 0
	global_load_dword v64, v34, s[30:31] nt
	s_add_u32 s30, s30, 0x70d00
	s_addc_u32 s31, s31, 0
	global_load_dword v65, v34, s[30:31] nt
	s_add_u32 s30, s30, 0x70d00
	s_addc_u32 s31, s31, 0
	global_load_dword v66, v34, s[30:31] nt
	s_add_u32 s30, s30, 0x70d00
	s_addc_u32 s31, s31, 0
	global_load_dword v67, v34, s[30:31] nt
	s_add_u32 s30, s30, 0x70d00
	s_addc_u32 s31, s31, 0
	global_load_dword v68, v34, s[30:31] nt
	s_add_u32 s30, s30, 0x70d00
	s_addc_u32 s31, s31, 0
	global_load_dword v69, v34, s[30:31] nt
	s_add_u32 s30, s30, 0x70d00
	s_addc_u32 s31, s31, 0
	global_load_dword v70, v34, s[30:31] nt
	s_add_u32 s30, s30, 0x70d00
	s_addc_u32 s31, s31, 0
	global_load_dword v71, v34, s[30:31] nt
; DI unsigned cvtpk(float lo, float hi) { unsigned r; asm volatile("v_cvt_pk_bf16_f32 %0, %1, %2" : "=v"(r) : "v"(lo), "v"(hi)); return r; }
; template <class Map>
; DI void conv_T(bf16_t* __restrict__ dst, const float* __restrict__ src, int K, int ldsrc, int nphys, Map map, const float* __restrict__ kscale, float* tile) {
;     ...
;     __syncthreads();
;     const int np = tid >> 3, ks = tid & 7;
;     float v[8];
; #pragma unroll
;     for (int j = 0; j < 8; ++j) v[j] = tile[(ks * 8 + j) * 65 + np];
;     u32x4 w = {cvtpk(v[0], v[1]), cvtpk(v[2], v[3]), cvtpk(v[4], v[5]), cvtpk(v[6], v[7])};
;     *(u32x4*)(dst + (size_t)(n0 + np) * K + k0 + ks * 8) = w;
;     __syncthreads();
;   }
; DI void convert_layer(const Params& p, int l, float* tile) {
;     ...
;   conv_T((bf16_t*)(ws + O_WIN), p.w_in + (size_t)l * 2048 * NIN, 2048, NIN, NPHYS, MapIn{}, nullptr, tile);
.Lcv_win_l0_p1_pf_done:
	s_waitcnt lgkmcnt(0)
	s_barrier
	ds_read_b32 v88, v33
	ds_read_b32 v89, v33 offset:260
	ds_read_b32 v90, v33 offset:520
	ds_read_b32 v91, v33 offset:780
	ds_read_b32 v92, v33 offset:1040
	ds_read_b32 v93, v33 offset:1300
	ds_read_b32 v94, v33 offset:1560
	ds_read_b32 v95, v33 offset:1820
	s_mul_i32 s12, s21, 1
	s_add_u32 s12, s12, s28
	s_cmp_ge_u32 s12, 0x1c00
	s_cbranch_scc1 .Lcv_win_l0_p1_rd_done
	ds_read_b32 v96, v33 offset:16640
	ds_read_b32 v97, v33 offset:16900
	ds_read_b32 v98, v33 offset:17160
	ds_read_b32 v99, v33 offset:17420
	ds_read_b32 v100, v33 offset:17680
	ds_read_b32 v101, v33 offset:17940
	ds_read_b32 v102, v33 offset:18200
	ds_read_b32 v103, v33 offset:18460
	s_mul_i32 s12, s21, 2
	s_add_u32 s12, s12, s28
	s_cmp_ge_u32 s12, 0x1c00
	s_cbranch_scc1 .Lcv_win_l0_p1_rd_done
	ds_read_b32 v104, v33 offset:33280
	ds_read_b32 v105, v33 offset:33540
	ds_read_b32 v106, v33 offset:33800
	ds_read_b32 v107, v33 offset:34060
	ds_read_b32 v108, v33 offset:34320
	ds_read_b32 v109, v33 offset:34580
	ds_read_b32 v110, v33 offset:34840
	ds_read_b32 v111, v33 offset:35100
	s_mul_i32 s12, s21, 3
	s_add_u32 s12, s12, s28
	s_cmp_ge_u32 s12, 0x1c00
	s_cbranch_scc1 .Lcv_win_l0_p1_rd_done
	ds_read_b32 v112, v33 offset:49920
	ds_read_b32 v113, v33 offset:50180
	ds_read_b32 v114, v33 offset:50440
	ds_read_b32 v115, v33 offset:50700
	ds_read_b32 v116, v33 offset:50960
	ds_read_b32 v117, v33 offset:51220
	ds_read_b32 v118, v33 offset:51480
	ds_read_b32 v119, v33 offset:51740
.Lcv_win_l0_p1_rd_done:
	s_waitcnt lgkmcnt(0)
	s_mov_b32 s12, s28
	s_mul_i32 s13, s12, 0x4925
	s_lshr_b32 s13, s13, 22
	s_mul_i32 s14, s13, 224
	s_sub_u32 s14, s12, s14
	s_mul_i32 s15, s14, 0x40000
	s_lshl_b32 s16, s13, 7
	s_add_u32 s15, s15, s16
	s_add_u32 s30, s26, s15
	s_addc_u32 s31, s27, 0
	v_cvt_pk_bf16_f32 v72, v88, v89
	v_cvt_pk_bf16_f32 v73, v90, v91
	v_cvt_pk_bf16_f32 v74, v92, v93
	v_cvt_pk_bf16_f32 v75, v94, v95
	global_store_dwordx4 v35, v[72:75], s[30:31]
	s_mul_i32 s12, s21, 1
	s_add_u32 s12, s12, s28
	s_cmp_ge_u32 s12, 0x1c00
	s_cbranch_scc1 .Lcv_win_l0_p1_st_done
	s_mul_i32 s12, s21, 1
	s_add_u32 s12, s12, s28
	s_mul_i32 s13, s12, 0x4925
	s_lshr_b32 s13, s13, 22
	s_mul_i32 s14, s13, 224
	s_sub_u32 s14, s12, s14
	s_mul_i32 s15, s14, 0x40000
	s_lshl_b32 s16, s13, 7
	s_add_u32 s15, s15, s16
	s_add_u32 s30, s26, s15
	s_addc_u32 s31, s27, 0
	v_cvt_pk_bf16_f32 v76, v96, v97
	v_cvt_pk_bf16_f32 v77, v98, v99
	v_cvt_pk_bf16_f32 v78, v100, v101
	v_cvt_pk_bf16_f32 v79, v102, v103
	global_store_dwordx4 v35, v[76:79], s[30:31]
	s_mul_i32 s12, s21, 2
	s_add_u32 s12, s12, s28
	s_cmp_ge_u32 s12, 0x1c00
	s_cbranch_scc1 .Lcv_win_l0_p1_st_done
	s_mul_i32 s12, s21, 2
	s_add_u32 s12, s12, s28
	s_mul_i32 s13, s12, 0x4925
	s_lshr_b32 s13, s13, 22
	s_mul_i32 s14, s13, 224
	s_sub_u32 s14, s12, s14
	s_mul_i32 s15, s14, 0x40000
	s_lshl_b32 s16, s13, 7
	s_add_u32 s15, s15, s16
	s_add_u32 s30, s26, s15
	s_addc_u32 s31, s27, 0
	v_cvt_pk_bf16_f32 v80, v104, v105
	v_cvt_pk_bf16_f32 v81, v106, v107
	v_cvt_pk_bf16_f32 v82, v108, v109
	v_cvt_pk_bf16_f32 v83, v110, v111
	global_store_dwordx4 v35, v[80:83], s[30:31]
	s_mul_i32 s12, s21, 3
	s_add_u32 s12, s12, s28
	s_cmp_ge_u32 s12, 0x1c00
	s_cbranch_scc1 .Lcv_win_l0_p1_st_done
	s_mul_i32 s12, s21, 3
	s_add_u32 s12, s12, s28
	s_mul_i32 s13, s12, 0x4925
	s_lshr_b32 s13, s13, 22
	s_mul_i32 s14, s13, 224
	s_sub_u32 s14, s12, s14
	s_mul_i32 s15, s14, 0x40000
	s_lshl_b32 s16, s13, 7
	s_add_u32 s15, s15, s16
	s_add_u32 s30, s26, s15
	s_addc_u32 s31, s27, 0
	v_cvt_pk_bf16_f32 v84, v112, v113
	v_cvt_pk_bf16_f32 v85, v114, v115
	v_cvt_pk_bf16_f32 v86, v116, v117
	v_cvt_pk_bf16_f32 v87, v118, v119
	global_store_dwordx4 v35, v[84:87], s[30:31]
.Lcv_win_l0_p1_st_done:
	s_lshl_b32 s12, s21, 2
	s_add_u32 s28, s28, s12
	s_cmp_ge_u32 s28, 0x1c00
	s_cbranch_scc0 .Lcv_win_l0_loop
; DI int ltid() { int t = threadIdx.x; asm volatile("" : "+v"(t)); return t; }
; DI int lbid() { int b = blockIdx.x; asm volatile("" : "+s"(b)); return b; }
; template <class Map>
; DI void conv_T(bf16_t* __restrict__ dst, const float* __restrict__ src, int K, int ldsrc, int nphys, Map map, const float* __restrict__ kscale, float* tile) {
;   const int tid = ltid(), ntn = nphys >> 6, ntiles = (K >> 6) * ntn;
;   for (int tl = lbid(); tl < ntiles; tl += gridDim.x) {
;     const int k0 = (tl / ntn) << 6, n0 = (tl % ntn) << 6;
;     const int nn = tid & 63, sc = map(n0 + nn);
; #pragma unroll
;     for (int i = 0; i < 8; ++i) { const int kk = i * 8 + (tid >> 6);
;       float v = sc >= 0 ? __builtin_nontemporal_load(&src[(size_t)(k0 + kk) * ldsrc + sc]) : 0.f;
; DI void convert_layer(const Params& p, int l, float* tile) {
;     ...
;   for (int r = 0; r < 3; ++r)
;     conv_T((bf16_t*)(ws + O_WBR) + (size_t)r * 2048 * 1024, p.w_br + (size_t)(l * 3 + r) * 1024 * 2048, 1024, 2048, 2048, MapId{0}, nullptr, tile);
.Lcv_win_l0_end:
	s_barrier
	v_readlane_b32 s24, v249, 8
	v_readlane_b32 s25, v249, 9
	s_add_u32 s26, s18, 0x3c00000
	s_addc_u32 s27, s19, 0
	v_lshrrev_b32_e32 v36, 6, v248
	v_and_b32_e32 v37, 63, v248
	v_mov_b32_e32 v38, 0x2000
	v_mul_u32_u24_e32 v34, v36, v38
	v_lshl_add_u32 v34, v37, 2, v34
	v_lshrrev_b32_e32 v36, 3, v248
	v_and_b32_e32 v37, 7, v248
	v_mov_b32_e32 v38, 0x800
	v_mul_u32_u24_e32 v35, v36, v38
	v_lshl_add_u32 v35, v37, 4, v35
	s_mov_b32 s28, s20
	s_cmp_ge_u32 s28, 0x200
	s_cbranch_scc1 .Lcv_wbr0_l0_end
	s_mov_b32 s12, s28
	s_lshr_b32 s13, s12, 5
	s_and_b32 s14, s12, 31
	s_mul_i32 s15, s13, 0x80000
	s_lshl_b32 s16, s14, 8
	s_add_u32 s15, s15, s16
	s_add_u32 s30, s24, s15
	s_addc_u32 s31, s25, 0
	global_load_dword v40, v34, s[30:31] nt
	s_add_u32 s30, s30, 0x10000
	s_addc_u32 s31, s31, 0
	global_load_dword v41, v34, s[30:31] nt
	s_add_u32 s30, s30, 0x10000
	s_addc_u32 s31, s31, 0
	global_load_dword v42, v34, s[30:31] nt
	s_add_u32 s30, s30, 0x10000
	s_addc_u32 s31, s31, 0
	global_load_dword v43, v34, s[30:31] nt
	s_add_u32 s30, s30, 0x10000
	s_addc_u32 s31, s31, 0
	global_load_dword v44, v34, s[30:31] nt
	s_add_u32 s30, s30, 0x10000
	s_addc_u32 s31, s31, 0
	global_load_dword v45, v34, s[30:31] nt
	s_add_u32 s30, s30, 0x10000
	s_addc_u32 s31, s31, 0
	global_load_dword v46, v34, s[30:31] nt
	s_add_u32 s30, s30, 0x10000
	s_addc_u32 s31, s31, 0
	global_load_dword v47, v34, s[30:31] nt
	s_mul_i32 s12, s21, 1
	s_add_u32 s12, s12, s28
	s_cmp_ge_u32 s12, 0x200
	s_cbranch_scc1 .Lcv_wbr0_l0_pro_done
	s_mul_i32 s12, s21, 1
	s_add_u32 s12, s12, s28
	s_lshr_b32 s13, s12, 5
	s_and_b32 s14, s12, 31
	s_mul_i32 s15, s13, 0x80000
	s_lshl_b32 s16, s14, 8
	s_add_u32 s15, s15, s16
	s_add_u32 s30, s24, s15
	s_addc_u32 s31, s25, 0
	global_load_dword v48, v34, s[30:31] nt
	s_add_u32 s30, s30, 0x10000
	s_addc_u32 s31, s31, 0
	global_load_dword v49, v34, s[30:31] nt
	s_add_u32 s30, s30, 0x10000
	s_addc_u32 s31, s31, 0
	global_load_dword v50, v34, s[30:31] nt
	s_add_u32 s30, s30, 0x10000
	s_addc_u32 s31, s31, 0
	global_load_dword v51, v34, s[30:31] nt
	s_add_u32 s30, s30, 0x10000
	s_addc_u32 s31, s31, 0
	global_load_dword v52, v34, s[30:31] nt
	s_add_u32 s30, s30, 0x10000
	s_addc_u32 s31, s31, 0
	global_load_dword v53, v34, s[30:31] nt
	s_add_u32 s30, s30, 0x10000
	s_addc_u32 s31, s31, 0
	global_load_dword v54, v34, s[30:31] nt
	s_add_u32 s30, s30, 0x10000
	s_addc_u32 s31, s31, 0
	global_load_dword v55, v34, s[30:31] nt
	s_mul_i32 s12, s21, 2
	s_add_u32 s12, s12, s28
	s_cmp_ge_u32 s12, 0x200
	s_cbranch_scc1 .Lcv_wbr0_l0_pro_done
	s_mul_i32 s12, s21, 2
	s_add_u32 s12, s12, s28
	s_lshr_b32 s13, s12, 5
	s_and_b32 s14, s12, 31
	s_mul_i32 s15, s13, 0x80000
	s_lshl_b32 s16, s14, 8
	s_add_u32 s15, s15, s16
	s_add_u32 s30, s24, s15
	s_addc_u32 s31, s25, 0
	global_load_dword v56, v34, s[30:31] nt
	s_add_u32 s30, s30, 0x10000
	s_addc_u32 s31, s31, 0
	global_load_dword v57, v34, s[30:31] nt
	s_add_u32 s30, s30, 0x10000
	s_addc_u32 s31, s31, 0
	global_load_dword v58, v34, s[30:31] nt
	s_add_u32 s30, s30, 0x10000
	s_addc_u32 s31, s31, 0
	global_load_dword v59, v34, s[30:31] nt
	s_add_u32 s30, s30, 0x10000
	s_addc_u32 s31, s31, 0
	global_load_dword v60, v34, s[30:31] nt
	s_add_u32 s30, s30, 0x10000
	s_addc_u32 s31, s31, 0
	global_load_dword v61, v34, s[30:31] nt
	s_add_u32 s30, s30, 0x10000
	s_addc_u32 s31, s31, 0
	global_load_dword v62, v34, s[30:31] nt
	s_add_u32 s30, s30, 0x10000
	s_addc_u32 s31, s31, 0
	global_load_dword v63, v34, s[30:31] nt
	s_mul_i32 s12, s21, 3
	s_add_u32 s12, s12, s28
	s_cmp_ge_u32 s12, 0x200
	s_cbranch_scc1 .Lcv_wbr0_l0_pro_done
	s_mul_i32 s12, s21, 3
	s_add_u32 s12, s12, s28
	s_lshr_b32 s13, s12, 5
	s_and_b32 s14, s12, 31
	s_mul_i32 s15, s13, 0x80000
	s_lshl_b32 s16, s14, 8
	s_add_u32 s15, s15, s16
	s_add_u32 s30, s24, s15
	s_addc_u32 s31, s25, 0
	global_load_dword v64, v34, s[30:31] nt
	s_add_u32 s30, s30, 0x10000
	s_addc_u32 s31, s31, 0
	global_load_dword v65, v34, s[30:31] nt
	s_add_u32 s30, s30, 0x10000
	s_addc_u32 s31, s31, 0
	global_load_dword v66, v34, s[30:31] nt
	s_add_u32 s30, s30, 0x10000
	s_addc_u32 s31, s31, 0
	global_load_dword v67, v34, s[30:31] nt
	s_add_u32 s30, s30, 0x10000
	s_addc_u32 s31, s31, 0
	global_load_dword v68, v34, s[30:31] nt
	s_add_u32 s30, s30, 0x10000
	s_addc_u32 s31, s31, 0
	global_load_dword v69, v34, s[30:31] nt
	s_add_u32 s30, s30, 0x10000
	s_addc_u32 s31, s31, 0
	global_load_dword v70, v34, s[30:31] nt
	s_add_u32 s30, s30, 0x10000
	s_addc_u32 s31, s31, 0
	global_load_dword v71, v34, s[30:31] nt

; DI int lbid() { int b = blockIdx.x; asm volatile("" : "+s"(b)); return b; }
; template <class Map>
; DI void conv_T(bf16_t* __restrict__ dst, const float* __restrict__ src, int K, int ldsrc, int nphys, Map map, const float* __restrict__ kscale, float* tile) {
;     ...
;   for (int tl = lbid(); tl < ntiles; tl += gridDim.x) {
;     const int k0 = (tl / ntn) << 6, n0 = (tl % ntn) << 6;
;     const int nn = tid & 63, sc = map(n0 + nn);
; #pragma unroll
;     for (int i = 0; i < 8; ++i) { const int kk = i * 8 + (tid >> 6);
;       float v = sc >= 0 ? __builtin_nontemporal_load(&src[(size_t)(k0 + kk) * ldsrc + sc]) : 0.f;
;       if (kscale) v *= kscale[k0 + kk];
;       tile[kk * 65 + nn] = v; }
; DI void convert_layer(const Params& p, int l, float* tile) {
;     ...
;     conv_T((bf16_t*)(ws + O_WBR) + (size_t)r * 2048 * 1024, p.w_br + (size_t)(l * 3 + r) * 1024 * 2048, 1024, 2048, 2048, MapId{0}, nullptr, tile);
.Lcv_wbr0_l0_p0_after:
	ds_write_b32 v30, v40
	ds_write_b32 v30, v41 offset:2080
	ds_write_b32 v30, v42 offset:4160
	ds_write_b32 v30, v43 offset:6240
	ds_write_b32 v30, v44 offset:8320
	ds_write_b32 v30, v45 offset:10400
	ds_write_b32 v30, v46 offset:12480
	ds_write_b32 v30, v47 offset:14560
	s_mul_i32 s12, s21, 1
	s_add_u32 s12, s12, s28
	s_cmp_ge_u32 s12, 0x200
	s_cbranch_scc1 .Lcv_wbr0_l0_p0_wr_done
	ds_write_b32 v30, v48 offset:16640
	ds_write_b32 v30, v49 offset:18720
	ds_write_b32 v30, v50 offset:20800
	ds_write_b32 v30, v51 offset:22880
	ds_write_b32 v30, v52 offset:24960
	ds_write_b32 v30, v53 offset:27040
	ds_write_b32 v30, v54 offset:29120
	ds_write_b32 v30, v55 offset:31200
	s_mul_i32 s12, s21, 2
	s_add_u32 s12, s12, s28
	s_cmp_ge_u32 s12, 0x200
	s_cbranch_scc1 .Lcv_wbr0_l0_p0_wr_done
	ds_write_b32 v30, v56 offset:33280
	ds_write_b32 v30, v57 offset:35360
	ds_write_b32 v30, v58 offset:37440
	ds_write_b32 v30, v59 offset:39520
	ds_write_b32 v30, v60 offset:41600
	ds_write_b32 v30, v61 offset:43680
	ds_write_b32 v30, v62 offset:45760
	ds_write_b32 v30, v63 offset:47840
	s_mul_i32 s12, s21, 3
	s_add_u32 s12, s12, s28
	s_cmp_ge_u32 s12, 0x200
	s_cbranch_scc1 .Lcv_wbr0_l0_p0_wr_done
	ds_write_b32 v30, v64 offset:49920
	ds_write_b32 v30, v65 offset:52000
	ds_write_b32 v30, v66 offset:54080
	ds_write_b32 v30, v67 offset:56160
	ds_write_b32 v30, v68 offset:58240
	ds_write_b32 v30, v69 offset:60320
	ds_write_b32 v30, v70 offset:62400
	ds_write_b32 v30, v71 offset:64480
.Lcv_wbr0_l0_p0_wr_done:
	s_mul_i32 s12, s21, 4
	s_add_u32 s12, s12, s28
	s_cmp_ge_u32 s12, 0x200
	s_cbranch_scc1 .Lcv_wbr0_l0_p0_pf_done
	s_mul_i32 s12, s21, 4
	s_add_u32 s12, s12, s28
	s_lshr_b32 s13, s12, 5
	s_and_b32 s14, s12, 31
	s_mul_i32 s15, s13, 0x80000
	s_lshl_b32 s16, s14, 8
	s_add_u32 s15, s15, s16
	s_add_u32 s30, s24, s15
	s_addc_u32 s31, s25, 0
	global_load_dword v88, v34, s[30:31] nt
	s_add_u32 s30, s30, 0x10000
	s_addc_u32 s31, s31, 0
	global_load_dword v89, v34, s[30:31] nt
	s_add_u32 s30, s30, 0x10000
	s_addc_u32 s31, s31, 0
	global_load_dword v90, v34, s[30:31] nt
	s_add_u32 s30, s30, 0x10000
	s_addc_u32 s31, s31, 0
	global_load_dword v91, v34, s[30:31] nt
	s_add_u32 s30, s30, 0x10000
	s_addc_u32 s31, s31, 0
	global_load_dword v92, v34, s[30:31] nt
	s_add_u32 s30, s30, 0x10000
	s_addc_u32 s31, s31, 0
	global_load_dword v93, v34, s[30:31] nt
	s_add_u32 s30, s30, 0x10000
	s_addc_u32 s31, s31, 0
	global_load_dword v94, v34, s[30:31] nt
	s_add_u32 s30, s30, 0x10000
	s_addc_u32 s31, s31, 0
	global_load_dword v95, v34, s[30:31] nt
	s_mul_i32 s12, s21, 5
	s_add_u32 s12, s12, s28
	s_cmp_ge_u32 s12, 0x200
	s_cbranch_scc1 .Lcv_wbr0_l0_p0_pf_done
	s_mul_i32 s12, s21, 5
	s_add_u32 s12, s12, s28
	s_lshr_b32 s13, s12, 5
	s_and_b32 s14, s12, 31
	s_mul_i32 s15, s13, 0x80000
	s_lshl_b32 s16, s14, 8
	s_add_u32 s15, s15, s16
	s_add_u32 s30, s24, s15
	s_addc_u32 s31, s25, 0
	global_load_dword v96, v34, s[30:31] nt
	s_add_u32 s30, s30, 0x10000
	s_addc_u32 s31, s31, 0
	global_load_dword v97, v34, s[30:31] nt
	s_add_u32 s30, s30, 0x10000
	s_addc_u32 s31, s31, 0
	global_load_dword v98, v34, s[30:31] nt
	s_add_u32 s30, s30, 0x10000
	s_addc_u32 s31, s31, 0
	global_load_dword v99, v34, s[30:31] nt
	s_add_u32 s30, s30, 0x10000
	s_addc_u32 s31, s31, 0
	global_load_dword v100, v34, s[30:31] nt
	s_add_u32 s30, s30, 0x10000
	s_addc_u32 s31, s31, 0
	global_load_dword v101, v34, s[30:31] nt
	s_add_u32 s30, s30, 0x10000
	s_addc_u32 s31, s31, 0
	global_load_dword v102, v34, s[30:31] nt
	s_add_u32 s30, s30, 0x10000
	s_addc_u32 s31, s31, 0
	global_load_dword v103, v34, s[30:31] nt
	s_mul_i32 s12, s21, 6
	s_add_u32 s12, s12, s28
	s_cmp_ge_u32 s12, 0x200
	s_cbranch_scc1 .Lcv_wbr0_l0_p0_pf_done
	s_mul_i32 s12, s21, 6
	s_add_u32 s12, s12, s28
	s_lshr_b32 s13, s12, 5
	s_and_b32 s14, s12, 31
	s_mul_i32 s15, s13, 0x80000
	s_lshl_b32 s16, s14, 8
	s_add_u32 s15, s15, s16
	s_add_u32 s30, s24, s15
	s_addc_u32 s31, s25, 0
	global_load_dword v104, v34, s[30:31] nt
	s_add_u32 s30, s30, 0x10000
	s_addc_u32 s31, s31, 0
	global_load_dword v105, v34, s[30:31] nt
	s_add_u32 s30, s30, 0x10000
	s_addc_u32 s31, s31, 0
	global_load_dword v106, v34, s[30:31] nt
	s_add_u32 s30, s30, 0x10000
	s_addc_u32 s31, s31, 0
	global_load_dword v107, v34, s[30:31] nt
	s_add_u32 s30, s30, 0x10000
	s_addc_u32 s31, s31, 0
	global_load_dword v108, v34, s[30:31] nt
	s_add_u32 s30, s30, 0x10000
	s_addc_u32 s31, s31, 0
	global_load_dword v109, v34, s[30:31] nt
	s_add_u32 s30, s30, 0x10000
	s_addc_u32 s31, s31, 0
	global_load_dword v110, v34, s[30:31] nt
	s_add_u32 s30, s30, 0x10000
	s_addc_u32 s31, s31, 0
	global_load_dword v111, v34, s[30:31] nt
	s_mul_i32 s12, s21, 7
	s_add_u32 s12, s12, s28
	s_cmp_ge_u32 s12, 0x200
	s_cbranch_scc1 .Lcv_wbr0_l0_p0_pf_done
	s_mul_i32 s12, s21, 7
	s_add_u32 s12, s12, s28
	s_lshr_b32 s13, s12, 5
	s_and_b32 s14, s12, 31
	s_mul_i32 s15, s13, 0x80000
	s_lshl_b32 s16, s14, 8
	s_add_u32 s15, s15, s16
	s_add_u32 s30, s24, s15
	s_addc_u32 s31, s25, 0
	global_load_dword v112, v34, s[30:31] nt
	s_add_u32 s30, s30, 0x10000
	s_addc_u32 s31, s31, 0
	global_load_dword v113, v34, s[30:31] nt
	s_add_u32 s30, s30, 0x10000
	s_addc_u32 s31, s31, 0
	global_load_dword v114, v34, s[30:31] nt
	s_add_u32 s30, s30, 0x10000
	s_addc_u32 s31, s31, 0
	global_load_dword v115, v34, s[30:31] nt
	s_add_u32 s30, s30, 0x10000
	s_addc_u32 s31, s31, 0
	global_load_dword v116, v34, s[30:31] nt
	s_add_u32 s30, s30, 0x10000
	s_addc_u32 s31, s31, 0
	global_load_dword v117, v34, s[30:31] nt
	s_add_u32 s30, s30, 0x10000
	s_addc_u32 s31, s31, 0
	global_load_dword v118, v34, s[30:31] nt
	s_add_u32 s30, s30, 0x10000
	s_addc_u32 s31, s31, 0
	global_load_dword v119, v34, s[30:31] nt
; DI unsigned cvtpk(float lo, float hi) { unsigned r; asm volatile("v_cvt_pk_bf16_f32 %0, %1, %2" : "=v"(r) : "v"(lo), "v"(hi)); return r; }
; template <class Map>
; DI void conv_T(bf16_t* __restrict__ dst, const float* __restrict__ src, int K, int ldsrc, int nphys, Map map, const float* __restrict__ kscale, float* tile) {
;     ...
;     __syncthreads();
;     const int np = tid >> 3, ks = tid & 7;
;     float v[8];
; #pragma unroll
;     for (int j = 0; j < 8; ++j) v[j] = tile[(ks * 8 + j) * 65 + np];
;     u32x4 w = {cvtpk(v[0], v[1]), cvtpk(v[2], v[3]), cvtpk(v[4], v[5]), cvtpk(v[6], v[7])};
;     *(u32x4*)(dst + (size_t)(n0 + np) * K + k0 + ks * 8) = w;
;     __syncthreads();
;   }
; DI void convert_layer(const Params& p, int l, float* tile) {
;     ...
;     conv_T((bf16_t*)(ws + O_WBR) + (size_t)r * 2048 * 1024, p.w_br + (size_t)(l * 3 + r) * 1024 * 2048, 1024, 2048, 2048, MapId{0}, nullptr, tile);
.Lcv_wbr0_l0_p0_pf_done:
	s_waitcnt lgkmcnt(0)
	s_barrier
	ds_read_b32 v40, v32
	ds_read_b32 v41, v32 offset:260
	ds_read_b32 v42, v32 offset:520
	ds_read_b32 v43, v32 offset:780
	ds_read_b32 v44, v32 offset:1040
	ds_read_b32 v45, v32 offset:1300
	ds_read_b32 v46, v32 offset:1560
	ds_read_b32 v47, v32 offset:1820
	s_mul_i32 s12, s21, 1
	s_add_u32 s12, s12, s28
	s_cmp_ge_u32 s12, 0x200
	s_cbranch_scc1 .Lcv_wbr0_l0_p0_rd_done
	ds_read_b32 v48, v32 offset:16640
	ds_read_b32 v49, v32 offset:16900
	ds_read_b32 v50, v32 offset:17160
	ds_read_b32 v51, v32 offset:17420
	ds_read_b32 v52, v32 offset:17680
	ds_read_b32 v53, v32 offset:17940
	ds_read_b32 v54, v32 offset:18200
	ds_read_b32 v55, v32 offset:18460
	s_mul_i32 s12, s21, 2
	s_add_u32 s12, s12, s28
	s_cmp_ge_u32 s12, 0x200
	s_cbranch_scc1 .Lcv_wbr0_l0_p0_rd_done
	ds_read_b32 v56, v32 offset:33280
	ds_read_b32 v57, v32 offset:33540
	ds_read_b32 v58, v32 offset:33800
	ds_read_b32 v59, v32 offset:34060
	ds_read_b32 v60, v32 offset:34320
	ds_read_b32 v61, v32 offset:34580
	ds_read_b32 v62, v32 offset:34840
	ds_read_b32 v63, v32 offset:35100
	s_mul_i32 s12, s21, 3
	s_add_u32 s12, s12, s28
	s_cmp_ge_u32 s12, 0x200
	s_cbranch_scc1 .Lcv_wbr0_l0_p0_rd_done
	ds_read_b32 v64, v32 offset:49920
	ds_read_b32 v65, v32 offset:50180
	ds_read_b32 v66, v32 offset:50440
	ds_read_b32 v67, v32 offset:50700
	ds_read_b32 v68, v32 offset:50960
	ds_read_b32 v69, v32 offset:51220
	ds_read_b32 v70, v32 offset:51480
	ds_read_b32 v71, v32 offset:51740
.Lcv_wbr0_l0_p0_rd_done:
	s_waitcnt lgkmcnt(0)
	s_mov_b32 s12, s28
	s_lshr_b32 s13, s12, 5
	s_and_b32 s14, s12, 31
	s_mul_i32 s15, s14, 0x20000
	s_lshl_b32 s16, s13, 7
	s_add_u32 s15, s15, s16
	s_add_u32 s30, s26, s15
	s_addc_u32 s31, s27, 0
	v_cvt_pk_bf16_f32 v72, v40, v41
	v_cvt_pk_bf16_f32 v73, v42, v43
	v_cvt_pk_bf16_f32 v74, v44, v45
	v_cvt_pk_bf16_f32 v75, v46, v47
	global_store_dwordx4 v35, v[72:75], s[30:31]
	s_mul_i32 s12, s21, 1
	s_add_u32 s12, s12, s28
	s_cmp_ge_u32 s12, 0x200
	s_cbranch_scc1 .Lcv_wbr0_l0_p0_st_done
	s_mul_i32 s12, s21, 1
	s_add_u32 s12, s12, s28
	s_lshr_b32 s13, s12, 5
	s_and_b32 s14, s12, 31
	s_mul_i32 s15, s14, 0x20000
	s_lshl_b32 s16, s13, 7
	s_add_u32 s15, s15, s16
	s_add_u32 s30, s26, s15
	s_addc_u32 s31, s27, 0
	v_cvt_pk_bf16_f32 v76, v48, v49
	v_cvt_pk_bf16_f32 v77, v50, v51
	v_cvt_pk_bf16_f32 v78, v52, v53
	v_cvt_pk_bf16_f32 v79, v54, v55
	global_store_dwordx4 v35, v[76:79], s[30:31]
	s_mul_i32 s12, s21, 2
	s_add_u32 s12, s12, s28
	s_cmp_ge_u32 s12, 0x200
	s_cbranch_scc1 .Lcv_wbr0_l0_p0_st_done
	s_mul_i32 s12, s21, 2
	s_add_u32 s12, s12, s28
	s_lshr_b32 s13, s12, 5
	s_and_b32 s14, s12, 31
	s_mul_i32 s15, s14, 0x20000
	s_lshl_b32 s16, s13, 7
	s_add_u32 s15, s15, s16
	s_add_u32 s30, s26, s15
	s_addc_u32 s31, s27, 0
	v_cvt_pk_bf16_f32 v80, v56, v57
	v_cvt_pk_bf16_f32 v81, v58, v59
	v_cvt_pk_bf16_f32 v82, v60, v61
	v_cvt_pk_bf16_f32 v83, v62, v63
	global_store_dwordx4 v35, v[80:83], s[30:31]
	s_mul_i32 s12, s21, 3
	s_add_u32 s12, s12, s28
	s_cmp_ge_u32 s12, 0x200
	s_cbranch_scc1 .Lcv_wbr0_l0_p0_st_done
	s_mul_i32 s12, s21, 3
	s_add_u32 s12, s12, s28
	s_lshr_b32 s13, s12, 5
	s_and_b32 s14, s12, 31
	s_mul_i32 s15, s14, 0x20000
	s_lshl_b32 s16, s13, 7
	s_add_u32 s15, s15, s16
	s_add_u32 s30, s26, s15
	s_addc_u32 s31, s27, 0
	v_cvt_pk_bf16_f32 v84, v64, v65
	v_cvt_pk_bf16_f32 v85, v66, v67
	v_cvt_pk_bf16_f32 v86, v68, v69
	v_cvt_pk_bf16_f32 v87, v70, v71
	global_store_dwordx4 v35, v[84:87], s[30:31]
.Lcv_wbr0_l0_p0_st_done:
	s_lshl_b32 s12, s21, 2
	s_add_u32 s28, s28, s12
	s_cmp_ge_u32 s28, 0x200
	s_cbranch_scc1 .Lcv_wbr0_l0_end
	s_waitcnt vmcnt(4)
.Lcv_wbr0_l0_p1_after:
	ds_write_b32 v31, v88
	ds_write_b32 v31, v89 offset:2080
	ds_write_b32 v31, v90 offset:4160
	ds_write_b32 v31, v91 offset:6240
	ds_write_b32 v31, v92 offset:8320
	ds_write_b32 v31, v93 offset:10400
	ds_write_b32 v31, v94 offset:12480
	ds_write_b32 v31, v95 offset:14560
	s_mul_i32 s12, s21, 1
	s_add_u32 s12, s12, s28
	s_cmp_ge_u32 s12, 0x200
	s_cbranch_scc1 .Lcv_wbr0_l0_p1_wr_done
	ds_write_b32 v31, v96 offset:16640
	ds_write_b32 v31, v97 offset:18720
	ds_write_b32 v31, v98 offset:20800
	ds_write_b32 v31, v99 offset:22880
	ds_write_b32 v31, v100 offset:24960
	ds_write_b32 v31, v101 offset:27040
	ds_write_b32 v31, v102 offset:29120
	ds_write_b32 v31, v103 offset:31200
	s_mul_i32 s12, s21, 2
	s_add_u32 s12, s12, s28
	s_cmp_ge_u32 s12, 0x200
	s_cbranch_scc1 .Lcv_wbr0_l0_p1_wr_done
	ds_write_b32 v31, v104 offset:33280
	ds_write_b32 v31, v105 offset:35360
	ds_write_b32 v31, v106 offset:37440
	ds_write_b32 v31, v107 offset:39520
	ds_write_b32 v31, v108 offset:41600
	ds_write_b32 v31, v109 offset:43680
	ds_write_b32 v31, v110 offset:45760
	ds_write_b32 v31, v111 offset:47840
	s_mul_i32 s12, s21, 3
	s_add_u32 s12, s12, s28
	s_cmp_ge_u32 s12, 0x200
	s_cbranch_scc1 .Lcv_wbr0_l0_p1_wr_done
	ds_write_b32 v31, v112 offset:49920
	ds_write_b32 v31, v113 offset:52000
	ds_write_b32 v31, v114 offset:54080
	ds_write_b32 v31, v115 offset:56160
	ds_write_b32 v31, v116 offset:58240
	ds_write_b32 v31, v117 offset:60320
	ds_write_b32 v31, v118 offset:62400
	ds_write_b32 v31, v119 offset:64480
; DI unsigned cvtpk(float lo, float hi) { unsigned r; asm volatile("v_cvt_pk_bf16_f32 %0, %1, %2" : "=v"(r) : "v"(lo), "v"(hi)); return r; }
; DI int lbid() { int b = blockIdx.x; asm volatile("" : "+s"(b)); return b; }
; template <class Map>
; DI void conv_T(bf16_t* __restrict__ dst, const float* __restrict__ src, int K, int ldsrc, int nphys, Map map, const float* __restrict__ kscale, float* tile) {
;     ...
;   for (int tl = lbid(); tl < ntiles; tl += gridDim.x) {
;     const int k0 = (tl / ntn) << 6, n0 = (tl % ntn) << 6;
;     const int nn = tid & 63, sc = map(n0 + nn);
; #pragma unroll
;     for (int i = 0; i < 8; ++i) { const int kk = i * 8 + (tid >> 6);
;       float v = sc >= 0 ? __builtin_nontemporal_load(&src[(size_t)(k0 + kk) * ldsrc + sc]) : 0.f;
;       if (kscale) v *= kscale[k0 + kk];
;       tile[kk * 65 + nn] = v; }
;     __syncthreads();
;     const int np = tid >> 3, ks = tid & 7;
;     float v[8];
; #pragma unroll
;     for (int j = 0; j < 8; ++j) v[j] = tile[(ks * 8 + j) * 65 + np];
;     u32x4 w = {cvtpk(v[0], v[1]), cvtpk(v[2], v[3]), cvtpk(v[4], v[5]), cvtpk(v[6], v[7])};
;     *(u32x4*)(dst + (size_t)(n0 + np) * K + k0 + ks * 8) = w;
;     __syncthreads();
;   }
; DI void convert_layer(const Params& p, int l, float* tile) {
;     ...
;     conv_T((bf16_t*)(ws + O_WBR) + (size_t)r * 2048 * 1024, p.w_br + (size_t)(l * 3 + r) * 1024 * 2048, 1024, 2048, 2048, MapId{0}, nullptr, tile);
.Lcv_wbr0_l0_p1_wr_done:
	s_mul_i32 s12, s21, 4
	s_add_u32 s12, s12, s28
	s_cmp_ge_u32 s12, 0x200
	s_cbranch_scc1 .Lcv_wbr0_l0_p1_pf_done
	s_mul_i32 s12, s21, 4
	s_add_u32 s12, s12, s28
	s_lshr_b32 s13, s12, 5
	s_and_b32 s14, s12, 31
	s_mul_i32 s15, s13, 0x80000
	s_lshl_b32 s16, s14, 8
	s_add_u32 s15, s15, s16
	s_add_u32 s30, s24, s15
	s_addc_u32 s31, s25, 0
	global_load_dword v40, v34, s[30:31] nt
	s_add_u32 s30, s30, 0x10000
	s_addc_u32 s31, s31, 0
	global_load_dword v41, v34, s[30:31] nt
	s_add_u32 s30, s30, 0x10000
	s_addc_u32 s31, s31, 0
	global_load_dword v42, v34, s[30:31] nt
	s_add_u32 s30, s30, 0x10000
	s_addc_u32 s31, s31, 0
	global_load_dword v43, v34, s[30:31] nt
	s_add_u32 s30, s30, 0x10000
	s_addc_u32 s31, s31, 0
	global_load_dword v44, v34, s[30:31] nt
	s_add_u32 s30, s30, 0x10000
	s_addc_u32 s31, s31, 0
	global_load_dword v45, v34, s[30:31] nt
	s_add_u32 s30, s30, 0x10000
	s_addc_u32 s31, s31, 0
	global_load_dword v46, v34, s[30:31] nt
	s_add_u32 s30, s30, 0x10000
	s_addc_u32 s31, s31, 0
	global_load_dword v47, v34, s[30:31] nt
	s_mul_i32 s12, s21, 5
	s_add_u32 s12, s12, s28
	s_cmp_ge_u32 s12, 0x200
	s_cbranch_scc1 .Lcv_wbr0_l0_p1_pf_done
	s_mul_i32 s12, s21, 5
	s_add_u32 s12, s12, s28
	s_lshr_b32 s13, s12, 5
	s_and_b32 s14, s12, 31
	s_mul_i32 s15, s13, 0x80000
	s_lshl_b32 s16, s14, 8
	s_add_u32 s15, s15, s16
	s_add_u32 s30, s24, s15
	s_addc_u32 s31, s25, 0
	global_load_dword v48, v34, s[30:31] nt
	s_add_u32 s30, s30, 0x10000
	s_addc_u32 s31, s31, 0
	global_load_dword v49, v34, s[30:31] nt
	s_add_u32 s30, s30, 0x10000
	s_addc_u32 s31, s31, 0
	global_load_dword v50, v34, s[30:31] nt
	s_add_u32 s30, s30, 0x10000
	s_addc_u32 s31, s31, 0
	global_load_dword v51, v34, s[30:31] nt
	s_add_u32 s30, s30, 0x10000
	s_addc_u32 s31, s31, 0
	global_load_dword v52, v34, s[30:31] nt
	s_add_u32 s30, s30, 0x10000
	s_addc_u32 s31, s31, 0
	global_load_dword v53, v34, s[30:31] nt
	s_add_u32 s30, s30, 0x10000
	s_addc_u32 s31, s31, 0
	global_load_dword v54, v34, s[30:31] nt
	s_add_u32 s30, s30, 0x10000
	s_addc_u32 s31, s31, 0
	global_load_dword v55, v34, s[30:31] nt
	s_mul_i32 s12, s21, 6
	s_add_u32 s12, s12, s28
	s_cmp_ge_u32 s12, 0x200
	s_cbranch_scc1 .Lcv_wbr0_l0_p1_pf_done
	s_mul_i32 s12, s21, 6
	s_add_u32 s12, s12, s28
	s_lshr_b32 s13, s12, 5
	s_and_b32 s14, s12, 31
	s_mul_i32 s15, s13, 0x80000
	s_lshl_b32 s16, s14, 8
	s_add_u32 s15, s15, s16
	s_add_u32 s30, s24, s15
	s_addc_u32 s31, s25, 0
	global_load_dword v56, v34, s[30:31] nt
	s_add_u32 s30, s30, 0x10000
	s_addc_u32 s31, s31, 0
	global_load_dword v57, v34, s[30:31] nt
	s_add_u32 s30, s30, 0x10000
	s_addc_u32 s31, s31, 0
	global_load_dword v58, v34, s[30:31] nt
	s_add_u32 s30, s30, 0x10000
	s_addc_u32 s31, s31, 0
	global_load_dword v59, v34, s[30:31] nt
	s_add_u32 s30, s30, 0x10000
	s_addc_u32 s31, s31, 0
	global_load_dword v60, v34, s[30:31] nt
	s_add_u32 s30, s30, 0x10000
	s_addc_u32 s31, s31, 0
	global_load_dword v61, v34, s[30:31] nt
	s_add_u32 s30, s30, 0x10000
	s_addc_u32 s31, s31, 0
	global_load_dword v62, v34, s[30:31] nt
	s_add_u32 s30, s30, 0x10000
	s_addc_u32 s31, s31, 0
	global_load_dword v63, v34, s[30:31] nt
	s_mul_i32 s12, s21, 7
	s_add_u32 s12, s12, s28
	s_cmp_ge_u32 s12, 0x200
	s_cbranch_scc1 .Lcv_wbr0_l0_p1_pf_done
	s_mul_i32 s12, s21, 7
	s_add_u32 s12, s12, s28
	s_lshr_b32 s13, s12, 5
	s_and_b32 s14, s12, 31
	s_mul_i32 s15, s13, 0x80000
	s_lshl_b32 s16, s14, 8
	s_add_u32 s15, s15, s16
	s_add_u32 s30, s24, s15
	s_addc_u32 s31, s25, 0
	global_load_dword v64, v34, s[30:31] nt
	s_add_u32 s30, s30, 0x10000
	s_addc_u32 s31, s31, 0
	global_load_dword v65, v34, s[30:31] nt
	s_add_u32 s30, s30, 0x10000
	s_addc_u32 s31, s31, 0
	global_load_dword v66, v34, s[30:31] nt
	s_add_u32 s30, s30, 0x10000
	s_addc_u32 s31, s31, 0
	global_load_dword v67, v34, s[30:31] nt
	s_add_u32 s30, s30, 0x10000
	s_addc_u32 s31, s31, 0
	global_load_dword v68, v34, s[30:31] nt
	s_add_u32 s30, s30, 0x10000
	s_addc_u32 s31, s31, 0
	global_load_dword v69, v34, s[30:31] nt
	s_add_u32 s30, s30, 0x10000
	s_addc_u32 s31, s31, 0
	global_load_dword v70, v34, s[30:31] nt
	s_add_u32 s30, s30, 0x10000
	s_addc_u32 s31, s31, 0
	global_load_dword v71, v34, s[30:31] nt
.Lcv_wbr0_l0_p1_pf_done:
	s_waitcnt lgkmcnt(0)
	s_barrier
	ds_read_b32 v88, v33
	ds_read_b32 v89, v33 offset:260
	ds_read_b32 v90, v33 offset:520
	ds_read_b32 v91, v33 offset:780
	ds_read_b32 v92, v33 offset:1040
	ds_read_b32 v93, v33 offset:1300
	ds_read_b32 v94, v33 offset:1560
	ds_read_b32 v95, v33 offset:1820
	s_mul_i32 s12, s21, 1
	s_add_u32 s12, s12, s28
	s_cmp_ge_u32 s12, 0x200
	s_cbranch_scc1 .Lcv_wbr0_l0_p1_rd_done
	ds_read_b32 v96, v33 offset:16640
	ds_read_b32 v97, v33 offset:16900
	ds_read_b32 v98, v33 offset:17160
	ds_read_b32 v99, v33 offset:17420
	ds_read_b32 v100, v33 offset:17680
	ds_read_b32 v101, v33 offset:17940
	ds_read_b32 v102, v33 offset:18200
	ds_read_b32 v103, v33 offset:18460
	s_mul_i32 s12, s21, 2
	s_add_u32 s12, s12, s28
	s_cmp_ge_u32 s12, 0x200
	s_cbranch_scc1 .Lcv_wbr0_l0_p1_rd_done
	ds_read_b32 v104, v33 offset:33280
	ds_read_b32 v105, v33 offset:33540
	ds_read_b32 v106, v33 offset:33800
	ds_read_b32 v107, v33 offset:34060
	ds_read_b32 v108, v33 offset:34320
	ds_read_b32 v109, v33 offset:34580
	ds_read_b32 v110, v33 offset:34840
	ds_read_b32 v111, v33 offset:35100
	s_mul_i32 s12, s21, 3
	s_add_u32 s12, s12, s28
	s_cmp_ge_u32 s12, 0x200
	s_cbranch_scc1 .Lcv_wbr0_l0_p1_rd_done
	ds_read_b32 v112, v33 offset:49920
	ds_read_b32 v113, v33 offset:50180
	ds_read_b32 v114, v33 offset:50440
	ds_read_b32 v115, v33 offset:50700
	ds_read_b32 v116, v33 offset:50960
	ds_read_b32 v117, v33 offset:51220
	ds_read_b32 v118, v33 offset:51480
	ds_read_b32 v119, v33 offset:51740
; DI unsigned cvtpk(float lo, float hi) { unsigned r; asm volatile("v_cvt_pk_bf16_f32 %0, %1, %2" : "=v"(r) : "v"(lo), "v"(hi)); return r; }
; template <class Map>
; DI void conv_T(bf16_t* __restrict__ dst, const float* __restrict__ src, int K, int ldsrc, int nphys, Map map, const float* __restrict__ kscale, float* tile) {
;     ...
;     __syncthreads();
;     const int np = tid >> 3, ks = tid & 7;
;     float v[8];
; #pragma unroll
;     for (int j = 0; j < 8; ++j) v[j] = tile[(ks * 8 + j) * 65 + np];
;     u32x4 w = {cvtpk(v[0], v[1]), cvtpk(v[2], v[3]), cvtpk(v[4], v[5]), cvtpk(v[6], v[7])};
;     *(u32x4*)(dst + (size_t)(n0 + np) * K + k0 + ks * 8) = w;
;     __syncthreads();
;   }
; DI void convert_layer(const Params& p, int l, float* tile) {
;     ...
;     conv_T((bf16_t*)(ws + O_WBR) + (size_t)r * 2048 * 1024, p.w_br + (size_t)(l * 3 + r) * 1024 * 2048, 1024, 2048, 2048, MapId{0}, nullptr, tile);
.Lcv_wbr0_l0_p1_rd_done:
	s_waitcnt lgkmcnt(0)
	s_mov_b32 s12, s28
	s_lshr_b32 s13, s12, 5
	s_and_b32 s14, s12, 31
	s_mul_i32 s15, s14, 0x20000
	s_lshl_b32 s16, s13, 7
	s_add_u32 s15, s15, s16
	s_add_u32 s30, s26, s15
	s_addc_u32 s31, s27, 0
	v_cvt_pk_bf16_f32 v72, v88, v89
	v_cvt_pk_bf16_f32 v73, v90, v91
	v_cvt_pk_bf16_f32 v74, v92, v93
	v_cvt_pk_bf16_f32 v75, v94, v95
	global_store_dwordx4 v35, v[72:75], s[30:31]
	s_mul_i32 s12, s21, 1
	s_add_u32 s12, s12, s28
	s_cmp_ge_u32 s12, 0x200
	s_cbranch_scc1 .Lcv_wbr0_l0_p1_st_done
	s_mul_i32 s12, s21, 1
	s_add_u32 s12, s12, s28
	s_lshr_b32 s13, s12, 5
	s_and_b32 s14, s12, 31
	s_mul_i32 s15, s14, 0x20000
	s_lshl_b32 s16, s13, 7
	s_add_u32 s15, s15, s16
	s_add_u32 s30, s26, s15
	s_addc_u32 s31, s27, 0
	v_cvt_pk_bf16_f32 v76, v96, v97
	v_cvt_pk_bf16_f32 v77, v98, v99
	v_cvt_pk_bf16_f32 v78, v100, v101
	v_cvt_pk_bf16_f32 v79, v102, v103
	global_store_dwordx4 v35, v[76:79], s[30:31]
	s_mul_i32 s12, s21, 2
	s_add_u32 s12, s12, s28
	s_cmp_ge_u32 s12, 0x200
	s_cbranch_scc1 .Lcv_wbr0_l0_p1_st_done
	s_mul_i32 s12, s21, 2
	s_add_u32 s12, s12, s28
	s_lshr_b32 s13, s12, 5
	s_and_b32 s14, s12, 31
	s_mul_i32 s15, s14, 0x20000
	s_lshl_b32 s16, s13, 7
	s_add_u32 s15, s15, s16
	s_add_u32 s30, s26, s15
	s_addc_u32 s31, s27, 0
	v_cvt_pk_bf16_f32 v80, v104, v105
	v_cvt_pk_bf16_f32 v81, v106, v107
	v_cvt_pk_bf16_f32 v82, v108, v109
	v_cvt_pk_bf16_f32 v83, v110, v111
	global_store_dwordx4 v35, v[80:83], s[30:31]
	s_mul_i32 s12, s21, 3
	s_add_u32 s12, s12, s28
	s_cmp_ge_u32 s12, 0x200
	s_cbranch_scc1 .Lcv_wbr0_l0_p1_st_done
	s_mul_i32 s12, s21, 3
	s_add_u32 s12, s12, s28
	s_lshr_b32 s13, s12, 5
	s_and_b32 s14, s12, 31
	s_mul_i32 s15, s14, 0x20000
	s_lshl_b32 s16, s13, 7
	s_add_u32 s15, s15, s16
	s_add_u32 s30, s26, s15
	s_addc_u32 s31, s27, 0
	v_cvt_pk_bf16_f32 v84, v112, v113
	v_cvt_pk_bf16_f32 v85, v114, v115
	v_cvt_pk_bf16_f32 v86, v116, v117
	v_cvt_pk_bf16_f32 v87, v118, v119
	global_store_dwordx4 v35, v[84:87], s[30:31]
.Lcv_wbr0_l0_p1_st_done:
	s_lshl_b32 s12, s21, 2
	s_add_u32 s28, s28, s12
	s_cmp_ge_u32 s28, 0x200
	s_cbranch_scc0 .Lcv_wbr0_l0_loop
.Lcv_wbr0_l0_end:
	s_barrier
	v_readlane_b32 s24, v249, 8
	v_readlane_b32 s25, v249, 9
	s_add_u32 s24, s24, 0x800000
	s_addc_u32 s25, s25, 0
	s_add_u32 s26, s18, 0x4000000
	s_addc_u32 s27, s19, 0
	v_lshrrev_b32_e32 v36, 6, v248
	v_and_b32_e32 v37, 63, v248
	v_mov_b32_e32 v38, 0x2000
	v_mul_u32_u24_e32 v34, v36, v38
	v_lshl_add_u32 v34, v37, 2, v34
	v_lshrrev_b32_e32 v36, 3, v248
	v_and_b32_e32 v37, 7, v248
	v_mov_b32_e32 v38, 0x800
	v_mul_u32_u24_e32 v35, v36, v38
	v_lshl_add_u32 v35, v37, 4, v35
	s_mov_b32 s28, s20
	s_cmp_ge_u32 s28, 0x200
	s_cbranch_scc1 .Lcv_wbr1_l0_end
	s_mov_b32 s12, s28
	s_lshr_b32 s13, s12, 5
	s_and_b32 s14, s12, 31
	s_mul_i32 s15, s13, 0x80000
	s_lshl_b32 s16, s14, 8
	s_add_u32 s15, s15, s16
	s_add_u32 s30, s24, s15
	s_addc_u32 s31, s25, 0
	global_load_dword v40, v34, s[30:31] nt
	s_add_u32 s30, s30, 0x10000
	s_addc_u32 s31, s31, 0
	global_load_dword v41, v34, s[30:31] nt
	s_add_u32 s30, s30, 0x10000
	s_addc_u32 s31, s31, 0
	global_load_dword v42, v34, s[30:31] nt
	s_add_u32 s30, s30, 0x10000
	s_addc_u32 s31, s31, 0
	global_load_dword v43, v34, s[30:31] nt
	s_add_u32 s30, s30, 0x10000
	s_addc_u32 s31, s31, 0
	global_load_dword v44, v34, s[30:31] nt
	s_add_u32 s30, s30, 0x10000
	s_addc_u32 s31, s31, 0
	global_load_dword v45, v34, s[30:31] nt
	s_add_u32 s30, s30, 0x10000
	s_addc_u32 s31, s31, 0
	global_load_dword v46, v34, s[30:31] nt
	s_add_u32 s30, s30, 0x10000
	s_addc_u32 s31, s31, 0
	global_load_dword v47, v34, s[30:31] nt
	s_mul_i32 s12, s21, 1
	s_add_u32 s12, s12, s28
	s_cmp_ge_u32 s12, 0x200
	s_cbranch_scc1 .Lcv_wbr1_l0_pro_done
	s_mul_i32 s12, s21, 1
	s_add_u32 s12, s12, s28
	s_lshr_b32 s13, s12, 5
	s_and_b32 s14, s12, 31
	s_mul_i32 s15, s13, 0x80000
	s_lshl_b32 s16, s14, 8
	s_add_u32 s15, s15, s16
	s_add_u32 s30, s24, s15
	s_addc_u32 s31, s25, 0
	global_load_dword v48, v34, s[30:31] nt
	s_add_u32 s30, s30, 0x10000
	s_addc_u32 s31, s31, 0
	global_load_dword v49, v34, s[30:31] nt
	s_add_u32 s30, s30, 0x10000
	s_addc_u32 s31, s31, 0
	global_load_dword v50, v34, s[30:31] nt
	s_add_u32 s30, s30, 0x10000
	s_addc_u32 s31, s31, 0
	global_load_dword v51, v34, s[30:31] nt
	s_add_u32 s30, s30, 0x10000
	s_addc_u32 s31, s31, 0
	global_load_dword v52, v34, s[30:31] nt
	s_add_u32 s30, s30, 0x10000
	s_addc_u32 s31, s31, 0
	global_load_dword v53, v34, s[30:31] nt
	s_add_u32 s30, s30, 0x10000
	s_addc_u32 s31, s31, 0
	global_load_dword v54, v34, s[30:31] nt
	s_add_u32 s30, s30, 0x10000
	s_addc_u32 s31, s31, 0
	global_load_dword v55, v34, s[30:31] nt
	s_mul_i32 s12, s21, 2
	s_add_u32 s12, s12, s28
	s_cmp_ge_u32 s12, 0x200
	s_cbranch_scc1 .Lcv_wbr1_l0_pro_done
	s_mul_i32 s12, s21, 2
	s_add_u32 s12, s12, s28
	s_lshr_b32 s13, s12, 5
	s_and_b32 s14, s12, 31
	s_mul_i32 s15, s13, 0x80000
	s_lshl_b32 s16, s14, 8
	s_add_u32 s15, s15, s16
	s_add_u32 s30, s24, s15
	s_addc_u32 s31, s25, 0
	global_load_dword v56, v34, s[30:31] nt
	s_add_u32 s30, s30, 0x10000
	s_addc_u32 s31, s31, 0
	global_load_dword v57, v34, s[30:31] nt
	s_add_u32 s30, s30, 0x10000
	s_addc_u32 s31, s31, 0
	global_load_dword v58, v34, s[30:31] nt
	s_add_u32 s30, s30, 0x10000
	s_addc_u32 s31, s31, 0
	global_load_dword v59, v34, s[30:31] nt
	s_add_u32 s30, s30, 0x10000
	s_addc_u32 s31, s31, 0
	global_load_dword v60, v34, s[30:31] nt
	s_add_u32 s30, s30, 0x10000
	s_addc_u32 s31, s31, 0
	global_load_dword v61, v34, s[30:31] nt
	s_add_u32 s30, s30, 0x10000
	s_addc_u32 s31, s31, 0
	global_load_dword v62, v34, s[30:31] nt
	s_add_u32 s30, s30, 0x10000
	s_addc_u32 s31, s31, 0
	global_load_dword v63, v34, s[30:31] nt
	s_mul_i32 s12, s21, 3
	s_add_u32 s12, s12, s28
	s_cmp_ge_u32 s12, 0x200
	s_cbranch_scc1 .Lcv_wbr1_l0_pro_done
	s_mul_i32 s12, s21, 3
	s_add_u32 s12, s12, s28
	s_lshr_b32 s13, s12, 5
	s_and_b32 s14, s12, 31
	s_mul_i32 s15, s13, 0x80000
	s_lshl_b32 s16, s14, 8
	s_add_u32 s15, s15, s16
	s_add_u32 s30, s24, s15
	s_addc_u32 s31, s25, 0
	global_load_dword v64, v34, s[30:31] nt
	s_add_u32 s30, s30, 0x10000
	s_addc_u32 s31, s31, 0
	global_load_dword v65, v34, s[30:31] nt
	s_add_u32 s30, s30, 0x10000
	s_addc_u32 s31, s31, 0
	global_load_dword v66, v34, s[30:31] nt
	s_add_u32 s30, s30, 0x10000
	s_addc_u32 s31, s31, 0
	global_load_dword v67, v34, s[30:31] nt
	s_add_u32 s30, s30, 0x10000
	s_addc_u32 s31, s31, 0
	global_load_dword v68, v34, s[30:31] nt
	s_add_u32 s30, s30, 0x10000
	s_addc_u32 s31, s31, 0
	global_load_dword v69, v34, s[30:31] nt
	s_add_u32 s30, s30, 0x10000
	s_addc_u32 s31, s31, 0
	global_load_dword v70, v34, s[30:31] nt
	s_add_u32 s30, s30, 0x10000
	s_addc_u32 s31, s31, 0
	global_load_dword v71, v34, s[30:31] nt

; DI int ltid() { int t = threadIdx.x; asm volatile("" : "+v"(t)); return t; }
; DI int lbid() { int b = blockIdx.x; asm volatile("" : "+s"(b)); return b; }
; template <class Map>
; DI void conv_T(bf16_t* __restrict__ dst, const float* __restrict__ src, int K, int ldsrc, int nphys, Map map, const float* __restrict__ kscale, float* tile) {
;   const int tid = ltid(), ntn = nphys >> 6, ntiles = (K >> 6) * ntn;
;   for (int tl = lbid(); tl < ntiles; tl += gridDim.x) {
;     const int k0 = (tl / ntn) << 6, n0 = (tl % ntn) << 6;
;     const int nn = tid & 63, sc = map(n0 + nn);
; #pragma unroll
;     for (int i = 0; i < 8; ++i) { const int kk = i * 8 + (tid >> 6);
;       float v = sc >= 0 ? __builtin_nontemporal_load(&src[(size_t)(k0 + kk) * ldsrc + sc]) : 0.f;
; DI void convert_layer(const Params& p, int l, float* tile) {
;     ...
;   for (int r = 0; r < 3; ++r)
;     conv_T((bf16_t*)(ws + O_WBR) + (size_t)r * 2048 * 1024, p.w_br + (size_t)(l * 3 + r) * 1024 * 2048, 1024, 2048, 2048, MapId{0}, nullptr, tile);
.Lcv_wbr1_l0_end:
	s_barrier
	v_readlane_b32 s24, v249, 8
	v_readlane_b32 s25, v249, 9
	s_add_u32 s24, s24, 0x1000000
	s_addc_u32 s25, s25, 0
	s_add_u32 s26, s18, 0x4400000
	s_addc_u32 s27, s19, 0
	v_lshrrev_b32_e32 v36, 6, v248
	v_and_b32_e32 v37, 63, v248
	v_mov_b32_e32 v38, 0x2000
	v_mul_u32_u24_e32 v34, v36, v38
	v_lshl_add_u32 v34, v37, 2, v34
	v_lshrrev_b32_e32 v36, 3, v248
	v_and_b32_e32 v37, 7, v248
	v_mov_b32_e32 v38, 0x800
	v_mul_u32_u24_e32 v35, v36, v38
	v_lshl_add_u32 v35, v37, 4, v35
	s_mov_b32 s28, s20
	s_cmp_ge_u32 s28, 0x200
	s_cbranch_scc1 .Lcv_wbr2_l0_end
	s_mov_b32 s12, s28
	s_lshr_b32 s13, s12, 5
	s_and_b32 s14, s12, 31
	s_mul_i32 s15, s13, 0x80000
	s_lshl_b32 s16, s14, 8
	s_add_u32 s15, s15, s16
	s_add_u32 s30, s24, s15
	s_addc_u32 s31, s25, 0
	global_load_dword v40, v34, s[30:31] nt
	s_add_u32 s30, s30, 0x10000
	s_addc_u32 s31, s31, 0
	global_load_dword v41, v34, s[30:31] nt
	s_add_u32 s30, s30, 0x10000
	s_addc_u32 s31, s31, 0
	global_load_dword v42, v34, s[30:31] nt
	s_add_u32 s30, s30, 0x10000
	s_addc_u32 s31, s31, 0
	global_load_dword v43, v34, s[30:31] nt
	s_add_u32 s30, s30, 0x10000
	s_addc_u32 s31, s31, 0
	global_load_dword v44, v34, s[30:31] nt
	s_add_u32 s30, s30, 0x10000
	s_addc_u32 s31, s31, 0
	global_load_dword v45, v34, s[30:31] nt
	s_add_u32 s30, s30, 0x10000
	s_addc_u32 s31, s31, 0
	global_load_dword v46, v34, s[30:31] nt
	s_add_u32 s30, s30, 0x10000
	s_addc_u32 s31, s31, 0
	global_load_dword v47, v34, s[30:31] nt
	s_mul_i32 s12, s21, 1
	s_add_u32 s12, s12, s28
	s_cmp_ge_u32 s12, 0x200
	s_cbranch_scc1 .Lcv_wbr2_l0_pro_done
	s_mul_i32 s12, s21, 1
	s_add_u32 s12, s12, s28
	s_lshr_b32 s13, s12, 5
	s_and_b32 s14, s12, 31
	s_mul_i32 s15, s13, 0x80000
	s_lshl_b32 s16, s14, 8
	s_add_u32 s15, s15, s16
	s_add_u32 s30, s24, s15
	s_addc_u32 s31, s25, 0
	global_load_dword v48, v34, s[30:31] nt
	s_add_u32 s30, s30, 0x10000
	s_addc_u32 s31, s31, 0
	global_load_dword v49, v34, s[30:31] nt
	s_add_u32 s30, s30, 0x10000
	s_addc_u32 s31, s31, 0
	global_load_dword v50, v34, s[30:31] nt
	s_add_u32 s30, s30, 0x10000
	s_addc_u32 s31, s31, 0
	global_load_dword v51, v34, s[30:31] nt
	s_add_u32 s30, s30, 0x10000
	s_addc_u32 s31, s31, 0
	global_load_dword v52, v34, s[30:31] nt
	s_add_u32 s30, s30, 0x10000
	s_addc_u32 s31, s31, 0
	global_load_dword v53, v34, s[30:31] nt
	s_add_u32 s30, s30, 0x10000
	s_addc_u32 s31, s31, 0
	global_load_dword v54, v34, s[30:31] nt
	s_add_u32 s30, s30, 0x10000
	s_addc_u32 s31, s31, 0
	global_load_dword v55, v34, s[30:31] nt
	s_mul_i32 s12, s21, 2
	s_add_u32 s12, s12, s28
	s_cmp_ge_u32 s12, 0x200
	s_cbranch_scc1 .Lcv_wbr2_l0_pro_done
	s_mul_i32 s12, s21, 2
	s_add_u32 s12, s12, s28
	s_lshr_b32 s13, s12, 5
	s_and_b32 s14, s12, 31
	s_mul_i32 s15, s13, 0x80000
	s_lshl_b32 s16, s14, 8
	s_add_u32 s15, s15, s16
	s_add_u32 s30, s24, s15
	s_addc_u32 s31, s25, 0
	global_load_dword v56, v34, s[30:31] nt
	s_add_u32 s30, s30, 0x10000
	s_addc_u32 s31, s31, 0
	global_load_dword v57, v34, s[30:31] nt
	s_add_u32 s30, s30, 0x10000
	s_addc_u32 s31, s31, 0
	global_load_dword v58, v34, s[30:31] nt
	s_add_u32 s30, s30, 0x10000
	s_addc_u32 s31, s31, 0
	global_load_dword v59, v34, s[30:31] nt
	s_add_u32 s30, s30, 0x10000
	s_addc_u32 s31, s31, 0
	global_load_dword v60, v34, s[30:31] nt
	s_add_u32 s30, s30, 0x10000
	s_addc_u32 s31, s31, 0
	global_load_dword v61, v34, s[30:31] nt
	s_add_u32 s30, s30, 0x10000
	s_addc_u32 s31, s31, 0
	global_load_dword v62, v34, s[30:31] nt
	s_add_u32 s30, s30, 0x10000
	s_addc_u32 s31, s31, 0
	global_load_dword v63, v34, s[30:31] nt
	s_mul_i32 s12, s21, 3
	s_add_u32 s12, s12, s28
	s_cmp_ge_u32 s12, 0x200
	s_cbranch_scc1 .Lcv_wbr2_l0_pro_done
	s_mul_i32 s12, s21, 3
	s_add_u32 s12, s12, s28
	s_lshr_b32 s13, s12, 5
	s_and_b32 s14, s12, 31
	s_mul_i32 s15, s13, 0x80000
	s_lshl_b32 s16, s14, 8
	s_add_u32 s15, s15, s16
	s_add_u32 s30, s24, s15
	s_addc_u32 s31, s25, 0
	global_load_dword v64, v34, s[30:31] nt
	s_add_u32 s30, s30, 0x10000
	s_addc_u32 s31, s31, 0
	global_load_dword v65, v34, s[30:31] nt
	s_add_u32 s30, s30, 0x10000
	s_addc_u32 s31, s31, 0
	global_load_dword v66, v34, s[30:31] nt
	s_add_u32 s30, s30, 0x10000
	s_addc_u32 s31, s31, 0
	global_load_dword v67, v34, s[30:31] nt
	s_add_u32 s30, s30, 0x10000
	s_addc_u32 s31, s31, 0
	global_load_dword v68, v34, s[30:31] nt
	s_add_u32 s30, s30, 0x10000
	s_addc_u32 s31, s31, 0
	global_load_dword v69, v34, s[30:31] nt
	s_add_u32 s30, s30, 0x10000
	s_addc_u32 s31, s31, 0
	global_load_dword v70, v34, s[30:31] nt
	s_add_u32 s30, s30, 0x10000
	s_addc_u32 s31, s31, 0
	global_load_dword v71, v34, s[30:31] nt

; DI int ltid() { int t = threadIdx.x; asm volatile("" : "+v"(t)); return t; }
; DI int lbid() { int b = blockIdx.x; asm volatile("" : "+s"(b)); return b; }
; template <class Map>
; DI void conv_T(bf16_t* __restrict__ dst, const float* __restrict__ src, int K, int ldsrc, int nphys, Map map, const float* __restrict__ kscale, float* tile) {
;   const int tid = ltid(), ntn = nphys >> 6, ntiles = (K >> 6) * ntn;
;   for (int tl = lbid(); tl < ntiles; tl += gridDim.x) {
;     const int k0 = (tl / ntn) << 6, n0 = (tl % ntn) << 6;
;     const int nn = tid & 63, sc = map(n0 + nn);
; #pragma unroll
;     for (int i = 0; i < 8; ++i) { const int kk = i * 8 + (tid >> 6);
;       float v = sc >= 0 ? __builtin_nontemporal_load(&src[(size_t)(k0 + kk) * ldsrc + sc]) : 0.f;
; DI void convert_layer(const Params& p, int l, float* tile) {
;     ...
;   conv_T((bf16_t*)(ws + O_WO), p.w_o + (size_t)l * 2048 * 2048, 2048, 2048, 2048, MapId{0}, nullptr, tile);
.Lcv_wbr2_l0_end:
	s_barrier
	v_readlane_b32 s24, v249, 10
	v_readlane_b32 s25, v249, 11
	s_add_u32 s26, s18, 0x4800000
	s_addc_u32 s27, s19, 0
	v_lshrrev_b32_e32 v36, 6, v248
	v_and_b32_e32 v37, 63, v248
	v_mov_b32_e32 v38, 0x2000
	v_mul_u32_u24_e32 v34, v36, v38
	v_lshl_add_u32 v34, v37, 2, v34
	v_lshrrev_b32_e32 v36, 3, v248
	v_and_b32_e32 v37, 7, v248
	v_mov_b32_e32 v38, 0x1000
	v_mul_u32_u24_e32 v35, v36, v38
	v_lshl_add_u32 v35, v37, 4, v35
	s_mov_b32 s28, s20
	s_cmp_ge_u32 s28, 0x400
	s_cbranch_scc1 .Lcv_wo_l0_end
	s_mov_b32 s12, s28
	s_lshr_b32 s13, s12, 5
	s_and_b32 s14, s12, 31
	s_mul_i32 s15, s13, 0x80000
	s_lshl_b32 s16, s14, 8
	s_add_u32 s15, s15, s16
	s_add_u32 s30, s24, s15
	s_addc_u32 s31, s25, 0
	global_load_dword v40, v34, s[30:31] nt
	s_add_u32 s30, s30, 0x10000
	s_addc_u32 s31, s31, 0
	global_load_dword v41, v34, s[30:31] nt
	s_add_u32 s30, s30, 0x10000
	s_addc_u32 s31, s31, 0
	global_load_dword v42, v34, s[30:31] nt
	s_add_u32 s30, s30, 0x10000
	s_addc_u32 s31, s31, 0
	global_load_dword v43, v34, s[30:31] nt
	s_add_u32 s30, s30, 0x10000
	s_addc_u32 s31, s31, 0
	global_load_dword v44, v34, s[30:31] nt
	s_add_u32 s30, s30, 0x10000
	s_addc_u32 s31, s31, 0
	global_load_dword v45, v34, s[30:31] nt
	s_add_u32 s30, s30, 0x10000
	s_addc_u32 s31, s31, 0
	global_load_dword v46, v34, s[30:31] nt
	s_add_u32 s30, s30, 0x10000
	s_addc_u32 s31, s31, 0
	global_load_dword v47, v34, s[30:31] nt
	s_mul_i32 s12, s21, 1
	s_add_u32 s12, s12, s28
	s_cmp_ge_u32 s12, 0x400
	s_cbranch_scc1 .Lcv_wo_l0_pro_done
	s_mul_i32 s12, s21, 1
	s_add_u32 s12, s12, s28
	s_lshr_b32 s13, s12, 5
	s_and_b32 s14, s12, 31
	s_mul_i32 s15, s13, 0x80000
	s_lshl_b32 s16, s14, 8
	s_add_u32 s15, s15, s16
	s_add_u32 s30, s24, s15
	s_addc_u32 s31, s25, 0
	global_load_dword v48, v34, s[30:31] nt
	s_add_u32 s30, s30, 0x10000
	s_addc_u32 s31, s31, 0
	global_load_dword v49, v34, s[30:31] nt
	s_add_u32 s30, s30, 0x10000
	s_addc_u32 s31, s31, 0
	global_load_dword v50, v34, s[30:31] nt
	s_add_u32 s30, s30, 0x10000
	s_addc_u32 s31, s31, 0
	global_load_dword v51, v34, s[30:31] nt
	s_add_u32 s30, s30, 0x10000
	s_addc_u32 s31, s31, 0
	global_load_dword v52, v34, s[30:31] nt
	s_add_u32 s30, s30, 0x10000
	s_addc_u32 s31, s31, 0
	global_load_dword v53, v34, s[30:31] nt
	s_add_u32 s30, s30, 0x10000
	s_addc_u32 s31, s31, 0
	global_load_dword v54, v34, s[30:31] nt
	s_add_u32 s30, s30, 0x10000
	s_addc_u32 s31, s31, 0
	global_load_dword v55, v34, s[30:31] nt
	s_mul_i32 s12, s21, 2
	s_add_u32 s12, s12, s28
	s_cmp_ge_u32 s12, 0x400
	s_cbranch_scc1 .Lcv_wo_l0_pro_done
	s_mul_i32 s12, s21, 2
	s_add_u32 s12, s12, s28
	s_lshr_b32 s13, s12, 5
	s_and_b32 s14, s12, 31
	s_mul_i32 s15, s13, 0x80000
	s_lshl_b32 s16, s14, 8
	s_add_u32 s15, s15, s16
	s_add_u32 s30, s24, s15
	s_addc_u32 s31, s25, 0
	global_load_dword v56, v34, s[30:31] nt
	s_add_u32 s30, s30, 0x10000
	s_addc_u32 s31, s31, 0
	global_load_dword v57, v34, s[30:31] nt
	s_add_u32 s30, s30, 0x10000
	s_addc_u32 s31, s31, 0
	global_load_dword v58, v34, s[30:31] nt
	s_add_u32 s30, s30, 0x10000
	s_addc_u32 s31, s31, 0
	global_load_dword v59, v34, s[30:31] nt
	s_add_u32 s30, s30, 0x10000
	s_addc_u32 s31, s31, 0
	global_load_dword v60, v34, s[30:31] nt
	s_add_u32 s30, s30, 0x10000
	s_addc_u32 s31, s31, 0
	global_load_dword v61, v34, s[30:31] nt
	s_add_u32 s30, s30, 0x10000
	s_addc_u32 s31, s31, 0
	global_load_dword v62, v34, s[30:31] nt
	s_add_u32 s30, s30, 0x10000
	s_addc_u32 s31, s31, 0
	global_load_dword v63, v34, s[30:31] nt
	s_mul_i32 s12, s21, 3
	s_add_u32 s12, s12, s28
	s_cmp_ge_u32 s12, 0x400
	s_cbranch_scc1 .Lcv_wo_l0_pro_done
	s_mul_i32 s12, s21, 3
	s_add_u32 s12, s12, s28
	s_lshr_b32 s13, s12, 5
	s_and_b32 s14, s12, 31
	s_mul_i32 s15, s13, 0x80000
	s_lshl_b32 s16, s14, 8
	s_add_u32 s15, s15, s16
	s_add_u32 s30, s24, s15
	s_addc_u32 s31, s25, 0
	global_load_dword v64, v34, s[30:31] nt
	s_add_u32 s30, s30, 0x10000
	s_addc_u32 s31, s31, 0
	global_load_dword v65, v34, s[30:31] nt
	s_add_u32 s30, s30, 0x10000
	s_addc_u32 s31, s31, 0
	global_load_dword v66, v34, s[30:31] nt
	s_add_u32 s30, s30, 0x10000
	s_addc_u32 s31, s31, 0
	global_load_dword v67, v34, s[30:31] nt
	s_add_u32 s30, s30, 0x10000
	s_addc_u32 s31, s31, 0
	global_load_dword v68, v34, s[30:31] nt
	s_add_u32 s30, s30, 0x10000
	s_addc_u32 s31, s31, 0
	global_load_dword v69, v34, s[30:31] nt
	s_add_u32 s30, s30, 0x10000
	s_addc_u32 s31, s31, 0
	global_load_dword v70, v34, s[30:31] nt
	s_add_u32 s30, s30, 0x10000
	s_addc_u32 s31, s31, 0
	global_load_dword v71, v34, s[30:31] nt

; DI int lbid() { int b = blockIdx.x; asm volatile("" : "+s"(b)); return b; }
; template <class Map>
; DI void conv_T(bf16_t* __restrict__ dst, const float* __restrict__ src, int K, int ldsrc, int nphys, Map map, const float* __restrict__ kscale, float* tile) {
;     ...
;   for (int tl = lbid(); tl < ntiles; tl += gridDim.x) {
;     const int k0 = (tl / ntn) << 6, n0 = (tl % ntn) << 6;
;     const int nn = tid & 63, sc = map(n0 + nn);
; #pragma unroll
;     for (int i = 0; i < 8; ++i) { const int kk = i * 8 + (tid >> 6);
;       float v = sc >= 0 ? __builtin_nontemporal_load(&src[(size_t)(k0 + kk) * ldsrc + sc]) : 0.f;
;       if (kscale) v *= kscale[k0 + kk];
;       tile[kk * 65 + nn] = v; }
; DI void convert_layer(const Params& p, int l, float* tile) {
;     ...
;   conv_T((bf16_t*)(ws + O_WO), p.w_o + (size_t)l * 2048 * 2048, 2048, 2048, 2048, MapId{0}, nullptr, tile);
.Lcv_wo_l0_p0_after:
	ds_write_b32 v30, v40
	ds_write_b32 v30, v41 offset:2080
	ds_write_b32 v30, v42 offset:4160
	ds_write_b32 v30, v43 offset:6240
	ds_write_b32 v30, v44 offset:8320
	ds_write_b32 v30, v45 offset:10400
	ds_write_b32 v30, v46 offset:12480
	ds_write_b32 v30, v47 offset:14560
	s_mul_i32 s12, s21, 1
	s_add_u32 s12, s12, s28
	s_cmp_ge_u32 s12, 0x400
	s_cbranch_scc1 .Lcv_wo_l0_p0_wr_done
	ds_write_b32 v30, v48 offset:16640
	ds_write_b32 v30, v49 offset:18720
	ds_write_b32 v30, v50 offset:20800
	ds_write_b32 v30, v51 offset:22880
	ds_write_b32 v30, v52 offset:24960
	ds_write_b32 v30, v53 offset:27040
	ds_write_b32 v30, v54 offset:29120
	ds_write_b32 v30, v55 offset:31200
	s_mul_i32 s12, s21, 2
	s_add_u32 s12, s12, s28
	s_cmp_ge_u32 s12, 0x400
	s_cbranch_scc1 .Lcv_wo_l0_p0_wr_done
	ds_write_b32 v30, v56 offset:33280
	ds_write_b32 v30, v57 offset:35360
	ds_write_b32 v30, v58 offset:37440
	ds_write_b32 v30, v59 offset:39520
	ds_write_b32 v30, v60 offset:41600
	ds_write_b32 v30, v61 offset:43680
	ds_write_b32 v30, v62 offset:45760
	ds_write_b32 v30, v63 offset:47840
	s_mul_i32 s12, s21, 3
	s_add_u32 s12, s12, s28
	s_cmp_ge_u32 s12, 0x400
	s_cbranch_scc1 .Lcv_wo_l0_p0_wr_done
	ds_write_b32 v30, v64 offset:49920
	ds_write_b32 v30, v65 offset:52000
	ds_write_b32 v30, v66 offset:54080
	ds_write_b32 v30, v67 offset:56160
	ds_write_b32 v30, v68 offset:58240
	ds_write_b32 v30, v69 offset:60320
	ds_write_b32 v30, v70 offset:62400
	ds_write_b32 v30, v71 offset:64480
.Lcv_wo_l0_p0_wr_done:
	s_mul_i32 s12, s21, 4
	s_add_u32 s12, s12, s28
	s_cmp_ge_u32 s12, 0x400
	s_cbranch_scc1 .Lcv_wo_l0_p0_pf_done
	s_mul_i32 s12, s21, 4
	s_add_u32 s12, s12, s28
	s_lshr_b32 s13, s12, 5
	s_and_b32 s14, s12, 31
	s_mul_i32 s15, s13, 0x80000
	s_lshl_b32 s16, s14, 8
	s_add_u32 s15, s15, s16
	s_add_u32 s30, s24, s15
	s_addc_u32 s31, s25, 0
	global_load_dword v88, v34, s[30:31] nt
	s_add_u32 s30, s30, 0x10000
	s_addc_u32 s31, s31, 0
	global_load_dword v89, v34, s[30:31] nt
	s_add_u32 s30, s30, 0x10000
	s_addc_u32 s31, s31, 0
	global_load_dword v90, v34, s[30:31] nt
	s_add_u32 s30, s30, 0x10000
	s_addc_u32 s31, s31, 0
	global_load_dword v91, v34, s[30:31] nt
	s_add_u32 s30, s30, 0x10000
	s_addc_u32 s31, s31, 0
	global_load_dword v92, v34, s[30:31] nt
	s_add_u32 s30, s30, 0x10000
	s_addc_u32 s31, s31, 0
	global_load_dword v93, v34, s[30:31] nt
	s_add_u32 s30, s30, 0x10000
	s_addc_u32 s31, s31, 0
	global_load_dword v94, v34, s[30:31] nt
	s_add_u32 s30, s30, 0x10000
	s_addc_u32 s31, s31, 0
	global_load_dword v95, v34, s[30:31] nt
	s_mul_i32 s12, s21, 5
	s_add_u32 s12, s12, s28
	s_cmp_ge_u32 s12, 0x400
	s_cbranch_scc1 .Lcv_wo_l0_p0_pf_done
	s_mul_i32 s12, s21, 5
	s_add_u32 s12, s12, s28
	s_lshr_b32 s13, s12, 5
	s_and_b32 s14, s12, 31
	s_mul_i32 s15, s13, 0x80000
	s_lshl_b32 s16, s14, 8
	s_add_u32 s15, s15, s16
	s_add_u32 s30, s24, s15
	s_addc_u32 s31, s25, 0
	global_load_dword v96, v34, s[30:31] nt
	s_add_u32 s30, s30, 0x10000
	s_addc_u32 s31, s31, 0
	global_load_dword v97, v34, s[30:31] nt
	s_add_u32 s30, s30, 0x10000
	s_addc_u32 s31, s31, 0
	global_load_dword v98, v34, s[30:31] nt
	s_add_u32 s30, s30, 0x10000
	s_addc_u32 s31, s31, 0
	global_load_dword v99, v34, s[30:31] nt
	s_add_u32 s30, s30, 0x10000
	s_addc_u32 s31, s31, 0
	global_load_dword v100, v34, s[30:31] nt
	s_add_u32 s30, s30, 0x10000
	s_addc_u32 s31, s31, 0
	global_load_dword v101, v34, s[30:31] nt
	s_add_u32 s30, s30, 0x10000
	s_addc_u32 s31, s31, 0
	global_load_dword v102, v34, s[30:31] nt
	s_add_u32 s30, s30, 0x10000
	s_addc_u32 s31, s31, 0
	global_load_dword v103, v34, s[30:31] nt
	s_mul_i32 s12, s21, 6
	s_add_u32 s12, s12, s28
	s_cmp_ge_u32 s12, 0x400
	s_cbranch_scc1 .Lcv_wo_l0_p0_pf_done
	s_mul_i32 s12, s21, 6
	s_add_u32 s12, s12, s28
	s_lshr_b32 s13, s12, 5
	s_and_b32 s14, s12, 31
	s_mul_i32 s15, s13, 0x80000
	s_lshl_b32 s16, s14, 8
	s_add_u32 s15, s15, s16
	s_add_u32 s30, s24, s15
	s_addc_u32 s31, s25, 0
	global_load_dword v104, v34, s[30:31] nt
	s_add_u32 s30, s30, 0x10000
	s_addc_u32 s31, s31, 0
	global_load_dword v105, v34, s[30:31] nt
	s_add_u32 s30, s30, 0x10000
	s_addc_u32 s31, s31, 0
	global_load_dword v106, v34, s[30:31] nt
	s_add_u32 s30, s30, 0x10000
	s_addc_u32 s31, s31, 0
	global_load_dword v107, v34, s[30:31] nt
	s_add_u32 s30, s30, 0x10000
	s_addc_u32 s31, s31, 0
	global_load_dword v108, v34, s[30:31] nt
	s_add_u32 s30, s30, 0x10000
	s_addc_u32 s31, s31, 0
	global_load_dword v109, v34, s[30:31] nt
	s_add_u32 s30, s30, 0x10000
	s_addc_u32 s31, s31, 0
	global_load_dword v110, v34, s[30:31] nt
	s_add_u32 s30, s30, 0x10000
	s_addc_u32 s31, s31, 0
	global_load_dword v111, v34, s[30:31] nt
	s_mul_i32 s12, s21, 7
	s_add_u32 s12, s12, s28
	s_cmp_ge_u32 s12, 0x400
	s_cbranch_scc1 .Lcv_wo_l0_p0_pf_done
	s_mul_i32 s12, s21, 7
	s_add_u32 s12, s12, s28
	s_lshr_b32 s13, s12, 5
	s_and_b32 s14, s12, 31
	s_mul_i32 s15, s13, 0x80000
	s_lshl_b32 s16, s14, 8
	s_add_u32 s15, s15, s16
	s_add_u32 s30, s24, s15
	s_addc_u32 s31, s25, 0
	global_load_dword v112, v34, s[30:31] nt
	s_add_u32 s30, s30, 0x10000
	s_addc_u32 s31, s31, 0
	global_load_dword v113, v34, s[30:31] nt
	s_add_u32 s30, s30, 0x10000
	s_addc_u32 s31, s31, 0
	global_load_dword v114, v34, s[30:31] nt
	s_add_u32 s30, s30, 0x10000
	s_addc_u32 s31, s31, 0
	global_load_dword v115, v34, s[30:31] nt
	s_add_u32 s30, s30, 0x10000
	s_addc_u32 s31, s31, 0
	global_load_dword v116, v34, s[30:31] nt
	s_add_u32 s30, s30, 0x10000
	s_addc_u32 s31, s31, 0
	global_load_dword v117, v34, s[30:31] nt
	s_add_u32 s30, s30, 0x10000
	s_addc_u32 s31, s31, 0
	global_load_dword v118, v34, s[30:31] nt
	s_add_u32 s30, s30, 0x10000
	s_addc_u32 s31, s31, 0
	global_load_dword v119, v34, s[30:31] nt
; DI unsigned cvtpk(float lo, float hi) { unsigned r; asm volatile("v_cvt_pk_bf16_f32 %0, %1, %2" : "=v"(r) : "v"(lo), "v"(hi)); return r; }
; template <class Map>
; DI void conv_T(bf16_t* __restrict__ dst, const float* __restrict__ src, int K, int ldsrc, int nphys, Map map, const float* __restrict__ kscale, float* tile) {
;     ...
;     __syncthreads();
;     const int np = tid >> 3, ks = tid & 7;
;     float v[8];
; #pragma unroll
;     for (int j = 0; j < 8; ++j) v[j] = tile[(ks * 8 + j) * 65 + np];
;     u32x4 w = {cvtpk(v[0], v[1]), cvtpk(v[2], v[3]), cvtpk(v[4], v[5]), cvtpk(v[6], v[7])};
;     *(u32x4*)(dst + (size_t)(n0 + np) * K + k0 + ks * 8) = w;
;     __syncthreads();
;   }
; DI void convert_layer(const Params& p, int l, float* tile) {
;     ...
;   conv_T((bf16_t*)(ws + O_WO), p.w_o + (size_t)l * 2048 * 2048, 2048, 2048, 2048, MapId{0}, nullptr, tile);
.Lcv_wo_l0_p0_pf_done:
	s_waitcnt lgkmcnt(0)
	s_barrier
	ds_read_b32 v40, v32
	ds_read_b32 v41, v32 offset:260
	ds_read_b32 v42, v32 offset:520
	ds_read_b32 v43, v32 offset:780
	ds_read_b32 v44, v32 offset:1040
	ds_read_b32 v45, v32 offset:1300
	ds_read_b32 v46, v32 offset:1560
	ds_read_b32 v47, v32 offset:1820
	s_mul_i32 s12, s21, 1
	s_add_u32 s12, s12, s28
	s_cmp_ge_u32 s12, 0x400
	s_cbranch_scc1 .Lcv_wo_l0_p0_rd_done
	ds_read_b32 v48, v32 offset:16640
	ds_read_b32 v49, v32 offset:16900
	ds_read_b32 v50, v32 offset:17160
	ds_read_b32 v51, v32 offset:17420
	ds_read_b32 v52, v32 offset:17680
	ds_read_b32 v53, v32 offset:17940
	ds_read_b32 v54, v32 offset:18200
	ds_read_b32 v55, v32 offset:18460
	s_mul_i32 s12, s21, 2
	s_add_u32 s12, s12, s28
	s_cmp_ge_u32 s12, 0x400
	s_cbranch_scc1 .Lcv_wo_l0_p0_rd_done
	ds_read_b32 v56, v32 offset:33280
	ds_read_b32 v57, v32 offset:33540
	ds_read_b32 v58, v32 offset:33800
	ds_read_b32 v59, v32 offset:34060
	ds_read_b32 v60, v32 offset:34320
	ds_read_b32 v61, v32 offset:34580
	ds_read_b32 v62, v32 offset:34840
	ds_read_b32 v63, v32 offset:35100
	s_mul_i32 s12, s21, 3
	s_add_u32 s12, s12, s28
	s_cmp_ge_u32 s12, 0x400
	s_cbranch_scc1 .Lcv_wo_l0_p0_rd_done
	ds_read_b32 v64, v32 offset:49920
	ds_read_b32 v65, v32 offset:50180
	ds_read_b32 v66, v32 offset:50440
	ds_read_b32 v67, v32 offset:50700
	ds_read_b32 v68, v32 offset:50960
	ds_read_b32 v69, v32 offset:51220
	ds_read_b32 v70, v32 offset:51480
	ds_read_b32 v71, v32 offset:51740
.Lcv_wo_l0_p0_rd_done:
	s_waitcnt lgkmcnt(0)
	s_mov_b32 s12, s28
	s_lshr_b32 s13, s12, 5
	s_and_b32 s14, s12, 31
	s_mul_i32 s15, s14, 0x40000
	s_lshl_b32 s16, s13, 7
	s_add_u32 s15, s15, s16
	s_add_u32 s30, s26, s15
	s_addc_u32 s31, s27, 0
	v_cvt_pk_bf16_f32 v72, v40, v41
	v_cvt_pk_bf16_f32 v73, v42, v43
	v_cvt_pk_bf16_f32 v74, v44, v45
	v_cvt_pk_bf16_f32 v75, v46, v47
	global_store_dwordx4 v35, v[72:75], s[30:31]
	s_mul_i32 s12, s21, 1
	s_add_u32 s12, s12, s28
	s_cmp_ge_u32 s12, 0x400
	s_cbranch_scc1 .Lcv_wo_l0_p0_st_done
	s_mul_i32 s12, s21, 1
	s_add_u32 s12, s12, s28
	s_lshr_b32 s13, s12, 5
	s_and_b32 s14, s12, 31
	s_mul_i32 s15, s14, 0x40000
	s_lshl_b32 s16, s13, 7
	s_add_u32 s15, s15, s16
	s_add_u32 s30, s26, s15
	s_addc_u32 s31, s27, 0
	v_cvt_pk_bf16_f32 v76, v48, v49
	v_cvt_pk_bf16_f32 v77, v50, v51
	v_cvt_pk_bf16_f32 v78, v52, v53
	v_cvt_pk_bf16_f32 v79, v54, v55
	global_store_dwordx4 v35, v[76:79], s[30:31]
	s_mul_i32 s12, s21, 2
	s_add_u32 s12, s12, s28
	s_cmp_ge_u32 s12, 0x400
	s_cbranch_scc1 .Lcv_wo_l0_p0_st_done
	s_mul_i32 s12, s21, 2
	s_add_u32 s12, s12, s28
	s_lshr_b32 s13, s12, 5
	s_and_b32 s14, s12, 31
	s_mul_i32 s15, s14, 0x40000
	s_lshl_b32 s16, s13, 7
	s_add_u32 s15, s15, s16
	s_add_u32 s30, s26, s15
	s_addc_u32 s31, s27, 0
	v_cvt_pk_bf16_f32 v80, v56, v57
	v_cvt_pk_bf16_f32 v81, v58, v59
	v_cvt_pk_bf16_f32 v82, v60, v61
	v_cvt_pk_bf16_f32 v83, v62, v63
	global_store_dwordx4 v35, v[80:83], s[30:31]
	s_mul_i32 s12, s21, 3
	s_add_u32 s12, s12, s28
	s_cmp_ge_u32 s12, 0x400
	s_cbranch_scc1 .Lcv_wo_l0_p0_st_done
	s_mul_i32 s12, s21, 3
	s_add_u32 s12, s12, s28
	s_lshr_b32 s13, s12, 5
	s_and_b32 s14, s12, 31
	s_mul_i32 s15, s14, 0x40000
	s_lshl_b32 s16, s13, 7
	s_add_u32 s15, s15, s16
	s_add_u32 s30, s26, s15
	s_addc_u32 s31, s27, 0
	v_cvt_pk_bf16_f32 v84, v64, v65
	v_cvt_pk_bf16_f32 v85, v66, v67
	v_cvt_pk_bf16_f32 v86, v68, v69
	v_cvt_pk_bf16_f32 v87, v70, v71
	global_store_dwordx4 v35, v[84:87], s[30:31]
.Lcv_wo_l0_p0_st_done:
	s_lshl_b32 s12, s21, 2
	s_add_u32 s28, s28, s12
	s_cmp_ge_u32 s28, 0x400
	s_cbranch_scc1 .Lcv_wo_l0_end
	s_waitcnt vmcnt(4)
.Lcv_wo_l0_p1_after:
	ds_write_b32 v31, v88
	ds_write_b32 v31, v89 offset:2080
	ds_write_b32 v31, v90 offset:4160
	ds_write_b32 v31, v91 offset:6240
	ds_write_b32 v31, v92 offset:8320
	ds_write_b32 v31, v93 offset:10400
	ds_write_b32 v31, v94 offset:12480
	ds_write_b32 v31, v95 offset:14560
	s_mul_i32 s12, s21, 1
	s_add_u32 s12, s12, s28
	s_cmp_ge_u32 s12, 0x400
	s_cbranch_scc1 .Lcv_wo_l0_p1_wr_done
	ds_write_b32 v31, v96 offset:16640
	ds_write_b32 v31, v97 offset:18720
	ds_write_b32 v31, v98 offset:20800
	ds_write_b32 v31, v99 offset:22880
	ds_write_b32 v31, v100 offset:24960
	ds_write_b32 v31, v101 offset:27040
	ds_write_b32 v31, v102 offset:29120
	ds_write_b32 v31, v103 offset:31200
	s_mul_i32 s12, s21, 2
	s_add_u32 s12, s12, s28
	s_cmp_ge_u32 s12, 0x400
	s_cbranch_scc1 .Lcv_wo_l0_p1_wr_done
	ds_write_b32 v31, v104 offset:33280
	ds_write_b32 v31, v105 offset:35360
	ds_write_b32 v31, v106 offset:37440
	ds_write_b32 v31, v107 offset:39520
	ds_write_b32 v31, v108 offset:41600
	ds_write_b32 v31, v109 offset:43680
	ds_write_b32 v31, v110 offset:45760
	ds_write_b32 v31, v111 offset:47840
	s_mul_i32 s12, s21, 3
	s_add_u32 s12, s12, s28
	s_cmp_ge_u32 s12, 0x400
	s_cbranch_scc1 .Lcv_wo_l0_p1_wr_done
	ds_write_b32 v31, v112 offset:49920
	ds_write_b32 v31, v113 offset:52000
	ds_write_b32 v31, v114 offset:54080
	ds_write_b32 v31, v115 offset:56160
	ds_write_b32 v31, v116 offset:58240
	ds_write_b32 v31, v117 offset:60320
	ds_write_b32 v31, v118 offset:62400
	ds_write_b32 v31, v119 offset:64480
; DI unsigned cvtpk(float lo, float hi) { unsigned r; asm volatile("v_cvt_pk_bf16_f32 %0, %1, %2" : "=v"(r) : "v"(lo), "v"(hi)); return r; }
; DI int lbid() { int b = blockIdx.x; asm volatile("" : "+s"(b)); return b; }
; template <class Map>
; DI void conv_T(bf16_t* __restrict__ dst, const float* __restrict__ src, int K, int ldsrc, int nphys, Map map, const float* __restrict__ kscale, float* tile) {
;     ...
;   for (int tl = lbid(); tl < ntiles; tl += gridDim.x) {
;     const int k0 = (tl / ntn) << 6, n0 = (tl % ntn) << 6;
;     const int nn = tid & 63, sc = map(n0 + nn);
; #pragma unroll
;     for (int i = 0; i < 8; ++i) { const int kk = i * 8 + (tid >> 6);
;       float v = sc >= 0 ? __builtin_nontemporal_load(&src[(size_t)(k0 + kk) * ldsrc + sc]) : 0.f;
;       if (kscale) v *= kscale[k0 + kk];
;       tile[kk * 65 + nn] = v; }
;     __syncthreads();
;     const int np = tid >> 3, ks = tid & 7;
;     float v[8];
; #pragma unroll
;     for (int j = 0; j < 8; ++j) v[j] = tile[(ks * 8 + j) * 65 + np];
;     u32x4 w = {cvtpk(v[0], v[1]), cvtpk(v[2], v[3]), cvtpk(v[4], v[5]), cvtpk(v[6], v[7])};
;     *(u32x4*)(dst + (size_t)(n0 + np) * K + k0 + ks * 8) = w;
;     __syncthreads();
;   }
; DI void convert_layer(const Params& p, int l, float* tile) {
;     ...
;   conv_T((bf16_t*)(ws + O_WO), p.w_o + (size_t)l * 2048 * 2048, 2048, 2048, 2048, MapId{0}, nullptr, tile);
.Lcv_wo_l0_p1_wr_done:
	s_mul_i32 s12, s21, 4
	s_add_u32 s12, s12, s28
	s_cmp_ge_u32 s12, 0x400
	s_cbranch_scc1 .Lcv_wo_l0_p1_pf_done
	s_mul_i32 s12, s21, 4
	s_add_u32 s12, s12, s28
	s_lshr_b32 s13, s12, 5
	s_and_b32 s14, s12, 31
	s_mul_i32 s15, s13, 0x80000
	s_lshl_b32 s16, s14, 8
	s_add_u32 s15, s15, s16
	s_add_u32 s30, s24, s15
	s_addc_u32 s31, s25, 0
	global_load_dword v40, v34, s[30:31] nt
	s_add_u32 s30, s30, 0x10000
	s_addc_u32 s31, s31, 0
	global_load_dword v41, v34, s[30:31] nt
	s_add_u32 s30, s30, 0x10000
	s_addc_u32 s31, s31, 0
	global_load_dword v42, v34, s[30:31] nt
	s_add_u32 s30, s30, 0x10000
	s_addc_u32 s31, s31, 0
	global_load_dword v43, v34, s[30:31] nt
	s_add_u32 s30, s30, 0x10000
	s_addc_u32 s31, s31, 0
	global_load_dword v44, v34, s[30:31] nt
	s_add_u32 s30, s30, 0x10000
	s_addc_u32 s31, s31, 0
	global_load_dword v45, v34, s[30:31] nt
	s_add_u32 s30, s30, 0x10000
	s_addc_u32 s31, s31, 0
	global_load_dword v46, v34, s[30:31] nt
	s_add_u32 s30, s30, 0x10000
	s_addc_u32 s31, s31, 0
	global_load_dword v47, v34, s[30:31] nt
	s_mul_i32 s12, s21, 5
	s_add_u32 s12, s12, s28
	s_cmp_ge_u32 s12, 0x400
	s_cbranch_scc1 .Lcv_wo_l0_p1_pf_done
	s_mul_i32 s12, s21, 5
	s_add_u32 s12, s12, s28
	s_lshr_b32 s13, s12, 5
	s_and_b32 s14, s12, 31
	s_mul_i32 s15, s13, 0x80000
	s_lshl_b32 s16, s14, 8
	s_add_u32 s15, s15, s16
	s_add_u32 s30, s24, s15
	s_addc_u32 s31, s25, 0
	global_load_dword v48, v34, s[30:31] nt
	s_add_u32 s30, s30, 0x10000
	s_addc_u32 s31, s31, 0
	global_load_dword v49, v34, s[30:31] nt
	s_add_u32 s30, s30, 0x10000
	s_addc_u32 s31, s31, 0
	global_load_dword v50, v34, s[30:31] nt
	s_add_u32 s30, s30, 0x10000
	s_addc_u32 s31, s31, 0
	global_load_dword v51, v34, s[30:31] nt
	s_add_u32 s30, s30, 0x10000
	s_addc_u32 s31, s31, 0
	global_load_dword v52, v34, s[30:31] nt
	s_add_u32 s30, s30, 0x10000
	s_addc_u32 s31, s31, 0
	global_load_dword v53, v34, s[30:31] nt
	s_add_u32 s30, s30, 0x10000
	s_addc_u32 s31, s31, 0
	global_load_dword v54, v34, s[30:31] nt
	s_add_u32 s30, s30, 0x10000
	s_addc_u32 s31, s31, 0
	global_load_dword v55, v34, s[30:31] nt
	s_mul_i32 s12, s21, 6
	s_add_u32 s12, s12, s28
	s_cmp_ge_u32 s12, 0x400
	s_cbranch_scc1 .Lcv_wo_l0_p1_pf_done
	s_mul_i32 s12, s21, 6
	s_add_u32 s12, s12, s28
	s_lshr_b32 s13, s12, 5
	s_and_b32 s14, s12, 31
	s_mul_i32 s15, s13, 0x80000
	s_lshl_b32 s16, s14, 8
	s_add_u32 s15, s15, s16
	s_add_u32 s30, s24, s15
	s_addc_u32 s31, s25, 0
	global_load_dword v56, v34, s[30:31] nt
	s_add_u32 s30, s30, 0x10000
	s_addc_u32 s31, s31, 0
	global_load_dword v57, v34, s[30:31] nt
	s_add_u32 s30, s30, 0x10000
	s_addc_u32 s31, s31, 0
	global_load_dword v58, v34, s[30:31] nt
	s_add_u32 s30, s30, 0x10000
	s_addc_u32 s31, s31, 0
	global_load_dword v59, v34, s[30:31] nt
	s_add_u32 s30, s30, 0x10000
	s_addc_u32 s31, s31, 0
	global_load_dword v60, v34, s[30:31] nt
	s_add_u32 s30, s30, 0x10000
	s_addc_u32 s31, s31, 0
	global_load_dword v61, v34, s[30:31] nt
	s_add_u32 s30, s30, 0x10000
	s_addc_u32 s31, s31, 0
	global_load_dword v62, v34, s[30:31] nt
	s_add_u32 s30, s30, 0x10000
	s_addc_u32 s31, s31, 0
	global_load_dword v63, v34, s[30:31] nt
	s_mul_i32 s12, s21, 7
	s_add_u32 s12, s12, s28
	s_cmp_ge_u32 s12, 0x400
	s_cbranch_scc1 .Lcv_wo_l0_p1_pf_done
	s_mul_i32 s12, s21, 7
	s_add_u32 s12, s12, s28
	s_lshr_b32 s13, s12, 5
	s_and_b32 s14, s12, 31
	s_mul_i32 s15, s13, 0x80000
	s_lshl_b32 s16, s14, 8
	s_add_u32 s15, s15, s16
	s_add_u32 s30, s24, s15
	s_addc_u32 s31, s25, 0
	global_load_dword v64, v34, s[30:31] nt
	s_add_u32 s30, s30, 0x10000
	s_addc_u32 s31, s31, 0
	global_load_dword v65, v34, s[30:31] nt
	s_add_u32 s30, s30, 0x10000
	s_addc_u32 s31, s31, 0
	global_load_dword v66, v34, s[30:31] nt
	s_add_u32 s30, s30, 0x10000
	s_addc_u32 s31, s31, 0
	global_load_dword v67, v34, s[30:31] nt
	s_add_u32 s30, s30, 0x10000
	s_addc_u32 s31, s31, 0
	global_load_dword v68, v34, s[30:31] nt
	s_add_u32 s30, s30, 0x10000
	s_addc_u32 s31, s31, 0
	global_load_dword v69, v34, s[30:31] nt
	s_add_u32 s30, s30, 0x10000
	s_addc_u32 s31, s31, 0
	global_load_dword v70, v34, s[30:31] nt
	s_add_u32 s30, s30, 0x10000
	s_addc_u32 s31, s31, 0
	global_load_dword v71, v34, s[30:31] nt
.Lcv_wo_l0_p1_pf_done:
	s_waitcnt lgkmcnt(0)
	s_barrier
	ds_read_b32 v88, v33
	ds_read_b32 v89, v33 offset:260
	ds_read_b32 v90, v33 offset:520
	ds_read_b32 v91, v33 offset:780
	ds_read_b32 v92, v33 offset:1040
	ds_read_b32 v93, v33 offset:1300
	ds_read_b32 v94, v33 offset:1560
	ds_read_b32 v95, v33 offset:1820
	s_mul_i32 s12, s21, 1
	s_add_u32 s12, s12, s28
	s_cmp_ge_u32 s12, 0x400
	s_cbranch_scc1 .Lcv_wo_l0_p1_rd_done
	ds_read_b32 v96, v33 offset:16640
	ds_read_b32 v97, v33 offset:16900
	ds_read_b32 v98, v33 offset:17160
	ds_read_b32 v99, v33 offset:17420
	ds_read_b32 v100, v33 offset:17680
	ds_read_b32 v101, v33 offset:17940
	ds_read_b32 v102, v33 offset:18200
	ds_read_b32 v103, v33 offset:18460
	s_mul_i32 s12, s21, 2
	s_add_u32 s12, s12, s28
	s_cmp_ge_u32 s12, 0x400
	s_cbranch_scc1 .Lcv_wo_l0_p1_rd_done
	ds_read_b32 v104, v33 offset:33280
	ds_read_b32 v105, v33 offset:33540
	ds_read_b32 v106, v33 offset:33800
	ds_read_b32 v107, v33 offset:34060
	ds_read_b32 v108, v33 offset:34320
	ds_read_b32 v109, v33 offset:34580
	ds_read_b32 v110, v33 offset:34840
	ds_read_b32 v111, v33 offset:35100
	s_mul_i32 s12, s21, 3
	s_add_u32 s12, s12, s28
	s_cmp_ge_u32 s12, 0x400
	s_cbranch_scc1 .Lcv_wo_l0_p1_rd_done
	ds_read_b32 v112, v33 offset:49920
	ds_read_b32 v113, v33 offset:50180
	ds_read_b32 v114, v33 offset:50440
	ds_read_b32 v115, v33 offset:50700
	ds_read_b32 v116, v33 offset:50960
	ds_read_b32 v117, v33 offset:51220
	ds_read_b32 v118, v33 offset:51480
	ds_read_b32 v119, v33 offset:51740
; DI unsigned cvtpk(float lo, float hi) { unsigned r; asm volatile("v_cvt_pk_bf16_f32 %0, %1, %2" : "=v"(r) : "v"(lo), "v"(hi)); return r; }
; template <class Map>
; DI void conv_T(bf16_t* __restrict__ dst, const float* __restrict__ src, int K, int ldsrc, int nphys, Map map, const float* __restrict__ kscale, float* tile) {
;     ...
;     __syncthreads();
;     const int np = tid >> 3, ks = tid & 7;
;     float v[8];
; #pragma unroll
;     for (int j = 0; j < 8; ++j) v[j] = tile[(ks * 8 + j) * 65 + np];
;     u32x4 w = {cvtpk(v[0], v[1]), cvtpk(v[2], v[3]), cvtpk(v[4], v[5]), cvtpk(v[6], v[7])};
;     *(u32x4*)(dst + (size_t)(n0 + np) * K + k0 + ks * 8) = w;
;     __syncthreads();
;   }
; DI void convert_layer(const Params& p, int l, float* tile) {
;     ...
;   conv_T((bf16_t*)(ws + O_WF1), p.w_f1 + (size_t)l * 2048 * 2 * DFF, 2048, 2 * DFF, 2 * DFF, MapF1{}, nullptr, tile);
.Lcv_wo_l0_p1_rd_done:
	s_waitcnt lgkmcnt(0)
	s_mov_b32 s12, s28
	s_lshr_b32 s13, s12, 5
	s_and_b32 s14, s12, 31
	s_mul_i32 s15, s14, 0x40000
	s_lshl_b32 s16, s13, 7
	s_add_u32 s15, s15, s16
	s_add_u32 s30, s26, s15
	s_addc_u32 s31, s27, 0
	v_cvt_pk_bf16_f32 v72, v88, v89
	v_cvt_pk_bf16_f32 v73, v90, v91
	v_cvt_pk_bf16_f32 v74, v92, v93
	v_cvt_pk_bf16_f32 v75, v94, v95
	global_store_dwordx4 v35, v[72:75], s[30:31]
	s_mul_i32 s12, s21, 1
	s_add_u32 s12, s12, s28
	s_cmp_ge_u32 s12, 0x400
	s_cbranch_scc1 .Lcv_wo_l0_p1_st_done
	s_mul_i32 s12, s21, 1
	s_add_u32 s12, s12, s28
	s_lshr_b32 s13, s12, 5
	s_and_b32 s14, s12, 31
	s_mul_i32 s15, s14, 0x40000
	s_lshl_b32 s16, s13, 7
	s_add_u32 s15, s15, s16
	s_add_u32 s30, s26, s15
	s_addc_u32 s31, s27, 0
	v_cvt_pk_bf16_f32 v76, v96, v97
	v_cvt_pk_bf16_f32 v77, v98, v99
	v_cvt_pk_bf16_f32 v78, v100, v101
	v_cvt_pk_bf16_f32 v79, v102, v103
	global_store_dwordx4 v35, v[76:79], s[30:31]
	s_mul_i32 s12, s21, 2
	s_add_u32 s12, s12, s28
	s_cmp_ge_u32 s12, 0x400
	s_cbranch_scc1 .Lcv_wo_l0_p1_st_done
	s_mul_i32 s12, s21, 2
	s_add_u32 s12, s12, s28
	s_lshr_b32 s13, s12, 5
	s_and_b32 s14, s12, 31
	s_mul_i32 s15, s14, 0x40000
	s_lshl_b32 s16, s13, 7
	s_add_u32 s15, s15, s16
	s_add_u32 s30, s26, s15
	s_addc_u32 s31, s27, 0
	v_cvt_pk_bf16_f32 v80, v104, v105
	v_cvt_pk_bf16_f32 v81, v106, v107
	v_cvt_pk_bf16_f32 v82, v108, v109
	v_cvt_pk_bf16_f32 v83, v110, v111
	global_store_dwordx4 v35, v[80:83], s[30:31]
	s_mul_i32 s12, s21, 3
	s_add_u32 s12, s12, s28
	s_cmp_ge_u32 s12, 0x400
	s_cbranch_scc1 .Lcv_wo_l0_p1_st_done
	s_mul_i32 s12, s21, 3
	s_add_u32 s12, s12, s28
	s_lshr_b32 s13, s12, 5
	s_and_b32 s14, s12, 31
	s_mul_i32 s15, s14, 0x40000
	s_lshl_b32 s16, s13, 7
	s_add_u32 s15, s15, s16
	s_add_u32 s30, s26, s15
	s_addc_u32 s31, s27, 0
	v_cvt_pk_bf16_f32 v84, v112, v113
	v_cvt_pk_bf16_f32 v85, v114, v115
	v_cvt_pk_bf16_f32 v86, v116, v117
	v_cvt_pk_bf16_f32 v87, v118, v119
	global_store_dwordx4 v35, v[84:87], s[30:31]
.Lcv_wo_l0_p1_st_done:
	s_lshl_b32 s12, s21, 2
	s_add_u32 s28, s28, s12
	s_cmp_ge_u32 s28, 0x400
	s_cbranch_scc0 .Lcv_wo_l0_loop
.Lcv_wo_l0_end:
	s_barrier
	v_readlane_b32 s24, v249, 12
	v_readlane_b32 s25, v249, 13
	s_add_u32 s26, s18, 0x5000000
	s_addc_u32 s27, s19, 0
	v_lshrrev_b32_e32 v36, 6, v248
	v_and_b32_e32 v37, 63, v248
	v_mov_b32_e32 v38, 0xb000
	v_mul_u32_u24_e32 v34, v36, v38
	v_lshrrev_b32_e32 v36, 5, v37
	v_and_b32_e32 v38, 31, v37
	v_lshl_add_u32 v36, v36, 4, v38
	v_and_b32_e32 v38, 16, v37
	v_mul_u32_u24_e32 v38, 0x15f, v38
	v_add_u32_e32 v37, v36, v38
	v_lshl_add_u32 v34, v37, 2, v34
	v_lshrrev_b32_e32 v36, 3, v248
	v_and_b32_e32 v37, 7, v248
	v_mov_b32_e32 v38, 0x1000
	v_mul_u32_u24_e32 v35, v36, v38
	v_lshl_add_u32 v35, v37, 4, v35
	s_mov_b32 s28, s20
	s_cmp_ge_u32 s28, 0x1600
	s_cbranch_scc1 .Lcv_wf1_l0_end
	s_mov_b32 s12, s28
	s_mul_i32 s13, s12, 0xba3
	s_lshr_b32 s13, s13, 19
	s_mul_i32 s14, s13, 176
	s_sub_u32 s14, s12, s14
	s_mul_i32 s15, s13, 0x2c0000
	s_lshl_b32 s16, s14, 7
	s_add_u32 s15, s15, s16
	s_add_u32 s30, s24, s15
	s_addc_u32 s31, s25, 0
	global_load_dword v40, v34, s[30:31] nt
	s_add_u32 s30, s30, 0x58000
	s_addc_u32 s31, s31, 0
	global_load_dword v41, v34, s[30:31] nt
	s_add_u32 s30, s30, 0x58000
	s_addc_u32 s31, s31, 0
	global_load_dword v42, v34, s[30:31] nt
	s_add_u32 s30, s30, 0x58000
	s_addc_u32 s31, s31, 0
	global_load_dword v43, v34, s[30:31] nt
	s_add_u32 s30, s30, 0x58000
	s_addc_u32 s31, s31, 0
	global_load_dword v44, v34, s[30:31] nt
	s_add_u32 s30, s30, 0x58000
	s_addc_u32 s31, s31, 0
	global_load_dword v45, v34, s[30:31] nt
	s_add_u32 s30, s30, 0x58000
	s_addc_u32 s31, s31, 0
	global_load_dword v46, v34, s[30:31] nt
	s_add_u32 s30, s30, 0x58000
	s_addc_u32 s31, s31, 0
	global_load_dword v47, v34, s[30:31] nt
	s_mul_i32 s12, s21, 1
	s_add_u32 s12, s12, s28
	s_cmp_ge_u32 s12, 0x1600
	s_cbranch_scc1 .Lcv_wf1_l0_pro_done
	s_mul_i32 s12, s21, 1
	s_add_u32 s12, s12, s28
	s_mul_i32 s13, s12, 0xba3
	s_lshr_b32 s13, s13, 19
	s_mul_i32 s14, s13, 176
	s_sub_u32 s14, s12, s14
	s_mul_i32 s15, s13, 0x2c0000
	s_lshl_b32 s16, s14, 7
	s_add_u32 s15, s15, s16
	s_add_u32 s30, s24, s15
	s_addc_u32 s31, s25, 0
	global_load_dword v48, v34, s[30:31] nt
	s_add_u32 s30, s30, 0x58000
	s_addc_u32 s31, s31, 0
	global_load_dword v49, v34, s[30:31] nt
	s_add_u32 s30, s30, 0x58000
	s_addc_u32 s31, s31, 0
	global_load_dword v50, v34, s[30:31] nt
	s_add_u32 s30, s30, 0x58000
	s_addc_u32 s31, s31, 0
	global_load_dword v51, v34, s[30:31] nt
	s_add_u32 s30, s30, 0x58000
	s_addc_u32 s31, s31, 0
	global_load_dword v52, v34, s[30:31] nt
	s_add_u32 s30, s30, 0x58000
	s_addc_u32 s31, s31, 0
	global_load_dword v53, v34, s[30:31] nt
	s_add_u32 s30, s30, 0x58000
	s_addc_u32 s31, s31, 0
	global_load_dword v54, v34, s[30:31] nt
	s_add_u32 s30, s30, 0x58000
	s_addc_u32 s31, s31, 0
	global_load_dword v55, v34, s[30:31] nt
	s_mul_i32 s12, s21, 2
	s_add_u32 s12, s12, s28
	s_cmp_ge_u32 s12, 0x1600
	s_cbranch_scc1 .Lcv_wf1_l0_pro_done
	s_mul_i32 s12, s21, 2
	s_add_u32 s12, s12, s28
	s_mul_i32 s13, s12, 0xba3
	s_lshr_b32 s13, s13, 19
	s_mul_i32 s14, s13, 176
	s_sub_u32 s14, s12, s14
	s_mul_i32 s15, s13, 0x2c0000
	s_lshl_b32 s16, s14, 7
	s_add_u32 s15, s15, s16
	s_add_u32 s30, s24, s15
	s_addc_u32 s31, s25, 0
	global_load_dword v56, v34, s[30:31] nt
	s_add_u32 s30, s30, 0x58000
	s_addc_u32 s31, s31, 0
	global_load_dword v57, v34, s[30:31] nt
	s_add_u32 s30, s30, 0x58000
	s_addc_u32 s31, s31, 0
	global_load_dword v58, v34, s[30:31] nt
	s_add_u32 s30, s30, 0x58000
	s_addc_u32 s31, s31, 0
	global_load_dword v59, v34, s[30:31] nt
	s_add_u32 s30, s30, 0x58000
	s_addc_u32 s31, s31, 0
	global_load_dword v60, v34, s[30:31] nt
	s_add_u32 s30, s30, 0x58000
	s_addc_u32 s31, s31, 0
	global_load_dword v61, v34, s[30:31] nt
	s_add_u32 s30, s30, 0x58000
	s_addc_u32 s31, s31, 0
	global_load_dword v62, v34, s[30:31] nt
	s_add_u32 s30, s30, 0x58000
	s_addc_u32 s31, s31, 0
	global_load_dword v63, v34, s[30:31] nt
	s_mul_i32 s12, s21, 3
	s_add_u32 s12, s12, s28
	s_cmp_ge_u32 s12, 0x1600
	s_cbranch_scc1 .Lcv_wf1_l0_pro_done
	s_mul_i32 s12, s21, 3
	s_add_u32 s12, s12, s28
	s_mul_i32 s13, s12, 0xba3
	s_lshr_b32 s13, s13, 19
	s_mul_i32 s14, s13, 176
	s_sub_u32 s14, s12, s14
	s_mul_i32 s15, s13, 0x2c0000
	s_lshl_b32 s16, s14, 7
	s_add_u32 s15, s15, s16
	s_add_u32 s30, s24, s15
	s_addc_u32 s31, s25, 0
	global_load_dword v64, v34, s[30:31] nt
	s_add_u32 s30, s30, 0x58000
	s_addc_u32 s31, s31, 0
	global_load_dword v65, v34, s[30:31] nt
	s_add_u32 s30, s30, 0x58000
	s_addc_u32 s31, s31, 0
	global_load_dword v66, v34, s[30:31] nt
	s_add_u32 s30, s30, 0x58000
	s_addc_u32 s31, s31, 0
	global_load_dword v67, v34, s[30:31] nt
	s_add_u32 s30, s30, 0x58000
	s_addc_u32 s31, s31, 0
	global_load_dword v68, v34, s[30:31] nt
	s_add_u32 s30, s30, 0x58000
	s_addc_u32 s31, s31, 0
	global_load_dword v69, v34, s[30:31] nt
	s_add_u32 s30, s30, 0x58000
	s_addc_u32 s31, s31, 0
	global_load_dword v70, v34, s[30:31] nt
	s_add_u32 s30, s30, 0x58000
	s_addc_u32 s31, s31, 0
	global_load_dword v71, v34, s[30:31] nt

; DI int lbid() { int b = blockIdx.x; asm volatile("" : "+s"(b)); return b; }
; template <class Map>
; DI void conv_T(bf16_t* __restrict__ dst, const float* __restrict__ src, int K, int ldsrc, int nphys, Map map, const float* __restrict__ kscale, float* tile) {
;     ...
;   for (int tl = lbid(); tl < ntiles; tl += gridDim.x) {
;     const int k0 = (tl / ntn) << 6, n0 = (tl % ntn) << 6;
;     const int nn = tid & 63, sc = map(n0 + nn);
; #pragma unroll
;     for (int i = 0; i < 8; ++i) { const int kk = i * 8 + (tid >> 6);
;       float v = sc >= 0 ? __builtin_nontemporal_load(&src[(size_t)(k0 + kk) * ldsrc + sc]) : 0.f;
;       if (kscale) v *= kscale[k0 + kk];
;       tile[kk * 65 + nn] = v; }
; DI void convert_layer(const Params& p, int l, float* tile) {
;     ...
;   conv_T((bf16_t*)(ws + O_WF1), p.w_f1 + (size_t)l * 2048 * 2 * DFF, 2048, 2 * DFF, 2 * DFF, MapF1{}, nullptr, tile);
.Lcv_wf1_l0_p0_after:
	ds_write_b32 v30, v40
	ds_write_b32 v30, v41 offset:2080
	ds_write_b32 v30, v42 offset:4160
	ds_write_b32 v30, v43 offset:6240
	ds_write_b32 v30, v44 offset:8320
	ds_write_b32 v30, v45 offset:10400
	ds_write_b32 v30, v46 offset:12480
	ds_write_b32 v30, v47 offset:14560
	s_mul_i32 s12, s21, 1
	s_add_u32 s12, s12, s28
	s_cmp_ge_u32 s12, 0x1600
	s_cbranch_scc1 .Lcv_wf1_l0_p0_wr_done
	ds_write_b32 v30, v48 offset:16640
	ds_write_b32 v30, v49 offset:18720
	ds_write_b32 v30, v50 offset:20800
	ds_write_b32 v30, v51 offset:22880
	ds_write_b32 v30, v52 offset:24960
	ds_write_b32 v30, v53 offset:27040
	ds_write_b32 v30, v54 offset:29120
	ds_write_b32 v30, v55 offset:31200
	s_mul_i32 s12, s21, 2
	s_add_u32 s12, s12, s28
	s_cmp_ge_u32 s12, 0x1600
	s_cbranch_scc1 .Lcv_wf1_l0_p0_wr_done
	ds_write_b32 v30, v56 offset:33280
	ds_write_b32 v30, v57 offset:35360
	ds_write_b32 v30, v58 offset:37440
	ds_write_b32 v30, v59 offset:39520
	ds_write_b32 v30, v60 offset:41600
	ds_write_b32 v30, v61 offset:43680
	ds_write_b32 v30, v62 offset:45760
	ds_write_b32 v30, v63 offset:47840
	s_mul_i32 s12, s21, 3
	s_add_u32 s12, s12, s28
	s_cmp_ge_u32 s12, 0x1600
	s_cbranch_scc1 .Lcv_wf1_l0_p0_wr_done
	ds_write_b32 v30, v64 offset:49920
	ds_write_b32 v30, v65 offset:52000
	ds_write_b32 v30, v66 offset:54080
	ds_write_b32 v30, v67 offset:56160
	ds_write_b32 v30, v68 offset:58240
	ds_write_b32 v30, v69 offset:60320
	ds_write_b32 v30, v70 offset:62400
	ds_write_b32 v30, v71 offset:64480
.Lcv_wf1_l0_p0_wr_done:
	s_mul_i32 s12, s21, 4
	s_add_u32 s12, s12, s28
	s_cmp_ge_u32 s12, 0x1600
	s_cbranch_scc1 .Lcv_wf1_l0_p0_pf_done
	s_mul_i32 s12, s21, 4
	s_add_u32 s12, s12, s28
	s_mul_i32 s13, s12, 0xba3
	s_lshr_b32 s13, s13, 19
	s_mul_i32 s14, s13, 176
	s_sub_u32 s14, s12, s14
	s_mul_i32 s15, s13, 0x2c0000
	s_lshl_b32 s16, s14, 7
	s_add_u32 s15, s15, s16
	s_add_u32 s30, s24, s15
	s_addc_u32 s31, s25, 0
	global_load_dword v88, v34, s[30:31] nt
	s_add_u32 s30, s30, 0x58000
	s_addc_u32 s31, s31, 0
	global_load_dword v89, v34, s[30:31] nt
	s_add_u32 s30, s30, 0x58000
	s_addc_u32 s31, s31, 0
	global_load_dword v90, v34, s[30:31] nt
	s_add_u32 s30, s30, 0x58000
	s_addc_u32 s31, s31, 0
	global_load_dword v91, v34, s[30:31] nt
	s_add_u32 s30, s30, 0x58000
	s_addc_u32 s31, s31, 0
	global_load_dword v92, v34, s[30:31] nt
	s_add_u32 s30, s30, 0x58000
	s_addc_u32 s31, s31, 0
	global_load_dword v93, v34, s[30:31] nt
	s_add_u32 s30, s30, 0x58000
	s_addc_u32 s31, s31, 0
	global_load_dword v94, v34, s[30:31] nt
	s_add_u32 s30, s30, 0x58000
	s_addc_u32 s31, s31, 0
	global_load_dword v95, v34, s[30:31] nt
	s_mul_i32 s12, s21, 5
	s_add_u32 s12, s12, s28
	s_cmp_ge_u32 s12, 0x1600
	s_cbranch_scc1 .Lcv_wf1_l0_p0_pf_done
	s_mul_i32 s12, s21, 5
	s_add_u32 s12, s12, s28
	s_mul_i32 s13, s12, 0xba3
	s_lshr_b32 s13, s13, 19
	s_mul_i32 s14, s13, 176
	s_sub_u32 s14, s12, s14
	s_mul_i32 s15, s13, 0x2c0000
	s_lshl_b32 s16, s14, 7
	s_add_u32 s15, s15, s16
	s_add_u32 s30, s24, s15
	s_addc_u32 s31, s25, 0
	global_load_dword v96, v34, s[30:31] nt
	s_add_u32 s30, s30, 0x58000
	s_addc_u32 s31, s31, 0
	global_load_dword v97, v34, s[30:31] nt
	s_add_u32 s30, s30, 0x58000
	s_addc_u32 s31, s31, 0
	global_load_dword v98, v34, s[30:31] nt
	s_add_u32 s30, s30, 0x58000
	s_addc_u32 s31, s31, 0
	global_load_dword v99, v34, s[30:31] nt
	s_add_u32 s30, s30, 0x58000
	s_addc_u32 s31, s31, 0
	global_load_dword v100, v34, s[30:31] nt
	s_add_u32 s30, s30, 0x58000
	s_addc_u32 s31, s31, 0
	global_load_dword v101, v34, s[30:31] nt
	s_add_u32 s30, s30, 0x58000
	s_addc_u32 s31, s31, 0
	global_load_dword v102, v34, s[30:31] nt
	s_add_u32 s30, s30, 0x58000
	s_addc_u32 s31, s31, 0
	global_load_dword v103, v34, s[30:31] nt
	s_mul_i32 s12, s21, 6
	s_add_u32 s12, s12, s28
	s_cmp_ge_u32 s12, 0x1600
	s_cbranch_scc1 .Lcv_wf1_l0_p0_pf_done
	s_mul_i32 s12, s21, 6
	s_add_u32 s12, s12, s28
	s_mul_i32 s13, s12, 0xba3
	s_lshr_b32 s13, s13, 19
	s_mul_i32 s14, s13, 176
	s_sub_u32 s14, s12, s14
	s_mul_i32 s15, s13, 0x2c0000
	s_lshl_b32 s16, s14, 7
	s_add_u32 s15, s15, s16
	s_add_u32 s30, s24, s15
	s_addc_u32 s31, s25, 0
	global_load_dword v104, v34, s[30:31] nt
	s_add_u32 s30, s30, 0x58000
	s_addc_u32 s31, s31, 0
	global_load_dword v105, v34, s[30:31] nt
	s_add_u32 s30, s30, 0x58000
	s_addc_u32 s31, s31, 0
	global_load_dword v106, v34, s[30:31] nt
	s_add_u32 s30, s30, 0x58000
	s_addc_u32 s31, s31, 0
	global_load_dword v107, v34, s[30:31] nt
	s_add_u32 s30, s30, 0x58000
	s_addc_u32 s31, s31, 0
	global_load_dword v108, v34, s[30:31] nt
	s_add_u32 s30, s30, 0x58000
	s_addc_u32 s31, s31, 0
	global_load_dword v109, v34, s[30:31] nt
	s_add_u32 s30, s30, 0x58000
	s_addc_u32 s31, s31, 0
	global_load_dword v110, v34, s[30:31] nt
	s_add_u32 s30, s30, 0x58000
	s_addc_u32 s31, s31, 0
	global_load_dword v111, v34, s[30:31] nt
	s_mul_i32 s12, s21, 7
	s_add_u32 s12, s12, s28
	s_cmp_ge_u32 s12, 0x1600
	s_cbranch_scc1 .Lcv_wf1_l0_p0_pf_done
	s_mul_i32 s12, s21, 7
	s_add_u32 s12, s12, s28
	s_mul_i32 s13, s12, 0xba3
	s_lshr_b32 s13, s13, 19
	s_mul_i32 s14, s13, 176
	s_sub_u32 s14, s12, s14
	s_mul_i32 s15, s13, 0x2c0000
	s_lshl_b32 s16, s14, 7
	s_add_u32 s15, s15, s16
	s_add_u32 s30, s24, s15
	s_addc_u32 s31, s25, 0
	global_load_dword v112, v34, s[30:31] nt
	s_add_u32 s30, s30, 0x58000
	s_addc_u32 s31, s31, 0
	global_load_dword v113, v34, s[30:31] nt
	s_add_u32 s30, s30, 0x58000
	s_addc_u32 s31, s31, 0
	global_load_dword v114, v34, s[30:31] nt
	s_add_u32 s30, s30, 0x58000
	s_addc_u32 s31, s31, 0
	global_load_dword v115, v34, s[30:31] nt
	s_add_u32 s30, s30, 0x58000
	s_addc_u32 s31, s31, 0
	global_load_dword v116, v34, s[30:31] nt
	s_add_u32 s30, s30, 0x58000
	s_addc_u32 s31, s31, 0
	global_load_dword v117, v34, s[30:31] nt
	s_add_u32 s30, s30, 0x58000
	s_addc_u32 s31, s31, 0
	global_load_dword v118, v34, s[30:31] nt
	s_add_u32 s30, s30, 0x58000
	s_addc_u32 s31, s31, 0
	global_load_dword v119, v34, s[30:31] nt
; DI unsigned cvtpk(float lo, float hi) { unsigned r; asm volatile("v_cvt_pk_bf16_f32 %0, %1, %2" : "=v"(r) : "v"(lo), "v"(hi)); return r; }
; template <class Map>
; DI void conv_T(bf16_t* __restrict__ dst, const float* __restrict__ src, int K, int ldsrc, int nphys, Map map, const float* __restrict__ kscale, float* tile) {
;     ...
;     __syncthreads();
;     const int np = tid >> 3, ks = tid & 7;
;     float v[8];
; #pragma unroll
;     for (int j = 0; j < 8; ++j) v[j] = tile[(ks * 8 + j) * 65 + np];
;     u32x4 w = {cvtpk(v[0], v[1]), cvtpk(v[2], v[3]), cvtpk(v[4], v[5]), cvtpk(v[6], v[7])};
;     *(u32x4*)(dst + (size_t)(n0 + np) * K + k0 + ks * 8) = w;
;     __syncthreads();
;   }
; DI void convert_layer(const Params& p, int l, float* tile) {
;     ...
;   conv_T((bf16_t*)(ws + O_WF1), p.w_f1 + (size_t)l * 2048 * 2 * DFF, 2048, 2 * DFF, 2 * DFF, MapF1{}, nullptr, tile);
.Lcv_wf1_l0_p0_pf_done:
	s_waitcnt lgkmcnt(0)
	s_barrier
	ds_read_b32 v40, v32
	ds_read_b32 v41, v32 offset:260
	ds_read_b32 v42, v32 offset:520
	ds_read_b32 v43, v32 offset:780
	ds_read_b32 v44, v32 offset:1040
	ds_read_b32 v45, v32 offset:1300
	ds_read_b32 v46, v32 offset:1560
	ds_read_b32 v47, v32 offset:1820
	s_mul_i32 s12, s21, 1
	s_add_u32 s12, s12, s28
	s_cmp_ge_u32 s12, 0x1600
	s_cbranch_scc1 .Lcv_wf1_l0_p0_rd_done
	ds_read_b32 v48, v32 offset:16640
	ds_read_b32 v49, v32 offset:16900
	ds_read_b32 v50, v32 offset:17160
	ds_read_b32 v51, v32 offset:17420
	ds_read_b32 v52, v32 offset:17680
	ds_read_b32 v53, v32 offset:17940
	ds_read_b32 v54, v32 offset:18200
	ds_read_b32 v55, v32 offset:18460
	s_mul_i32 s12, s21, 2
	s_add_u32 s12, s12, s28
	s_cmp_ge_u32 s12, 0x1600
	s_cbranch_scc1 .Lcv_wf1_l0_p0_rd_done
	ds_read_b32 v56, v32 offset:33280
	ds_read_b32 v57, v32 offset:33540
	ds_read_b32 v58, v32 offset:33800
	ds_read_b32 v59, v32 offset:34060
	ds_read_b32 v60, v32 offset:34320
	ds_read_b32 v61, v32 offset:34580
	ds_read_b32 v62, v32 offset:34840
	ds_read_b32 v63, v32 offset:35100
	s_mul_i32 s12, s21, 3
	s_add_u32 s12, s12, s28
	s_cmp_ge_u32 s12, 0x1600
	s_cbranch_scc1 .Lcv_wf1_l0_p0_rd_done
	ds_read_b32 v64, v32 offset:49920
	ds_read_b32 v65, v32 offset:50180
	ds_read_b32 v66, v32 offset:50440
	ds_read_b32 v67, v32 offset:50700
	ds_read_b32 v68, v32 offset:50960
	ds_read_b32 v69, v32 offset:51220
	ds_read_b32 v70, v32 offset:51480
	ds_read_b32 v71, v32 offset:51740
.Lcv_wf1_l0_p0_rd_done:
	s_waitcnt lgkmcnt(0)
	s_mov_b32 s12, s28
	s_mul_i32 s13, s12, 0xba3
	s_lshr_b32 s13, s13, 19
	s_mul_i32 s14, s13, 176
	s_sub_u32 s14, s12, s14
	s_mul_i32 s15, s14, 0x40000
	s_lshl_b32 s16, s13, 7
	s_add_u32 s15, s15, s16
	s_add_u32 s30, s26, s15
	s_addc_u32 s31, s27, 0
	v_cvt_pk_bf16_f32 v72, v40, v41
	v_cvt_pk_bf16_f32 v73, v42, v43
	v_cvt_pk_bf16_f32 v74, v44, v45
	v_cvt_pk_bf16_f32 v75, v46, v47
	global_store_dwordx4 v35, v[72:75], s[30:31]
	s_mul_i32 s12, s21, 1
	s_add_u32 s12, s12, s28
	s_cmp_ge_u32 s12, 0x1600
	s_cbranch_scc1 .Lcv_wf1_l0_p0_st_done
	s_mul_i32 s12, s21, 1
	s_add_u32 s12, s12, s28
	s_mul_i32 s13, s12, 0xba3
	s_lshr_b32 s13, s13, 19
	s_mul_i32 s14, s13, 176
	s_sub_u32 s14, s12, s14
	s_mul_i32 s15, s14, 0x40000
	s_lshl_b32 s16, s13, 7
	s_add_u32 s15, s15, s16
	s_add_u32 s30, s26, s15
	s_addc_u32 s31, s27, 0
	v_cvt_pk_bf16_f32 v76, v48, v49
	v_cvt_pk_bf16_f32 v77, v50, v51
	v_cvt_pk_bf16_f32 v78, v52, v53
	v_cvt_pk_bf16_f32 v79, v54, v55
	global_store_dwordx4 v35, v[76:79], s[30:31]
	s_mul_i32 s12, s21, 2
	s_add_u32 s12, s12, s28
	s_cmp_ge_u32 s12, 0x1600
	s_cbranch_scc1 .Lcv_wf1_l0_p0_st_done
	s_mul_i32 s12, s21, 2
	s_add_u32 s12, s12, s28
	s_mul_i32 s13, s12, 0xba3
	s_lshr_b32 s13, s13, 19
	s_mul_i32 s14, s13, 176
	s_sub_u32 s14, s12, s14
	s_mul_i32 s15, s14, 0x40000
	s_lshl_b32 s16, s13, 7
	s_add_u32 s15, s15, s16
	s_add_u32 s30, s26, s15
	s_addc_u32 s31, s27, 0
	v_cvt_pk_bf16_f32 v80, v56, v57
	v_cvt_pk_bf16_f32 v81, v58, v59
	v_cvt_pk_bf16_f32 v82, v60, v61
	v_cvt_pk_bf16_f32 v83, v62, v63
	global_store_dwordx4 v35, v[80:83], s[30:31]
	s_mul_i32 s12, s21, 3
	s_add_u32 s12, s12, s28
	s_cmp_ge_u32 s12, 0x1600
	s_cbranch_scc1 .Lcv_wf1_l0_p0_st_done
	s_mul_i32 s12, s21, 3
	s_add_u32 s12, s12, s28
	s_mul_i32 s13, s12, 0xba3
	s_lshr_b32 s13, s13, 19
	s_mul_i32 s14, s13, 176
	s_sub_u32 s14, s12, s14
	s_mul_i32 s15, s14, 0x40000
	s_lshl_b32 s16, s13, 7
	s_add_u32 s15, s15, s16
	s_add_u32 s30, s26, s15
	s_addc_u32 s31, s27, 0
	v_cvt_pk_bf16_f32 v84, v64, v65
	v_cvt_pk_bf16_f32 v85, v66, v67
	v_cvt_pk_bf16_f32 v86, v68, v69
	v_cvt_pk_bf16_f32 v87, v70, v71
	global_store_dwordx4 v35, v[84:87], s[30:31]
.Lcv_wf1_l0_p0_st_done:
	s_lshl_b32 s12, s21, 2
	s_add_u32 s28, s28, s12
	s_cmp_ge_u32 s28, 0x1600
	s_cbranch_scc1 .Lcv_wf1_l0_end
	s_waitcnt vmcnt(4)
.Lcv_wf1_l0_p1_after:
	ds_write_b32 v31, v88
	ds_write_b32 v31, v89 offset:2080
	ds_write_b32 v31, v90 offset:4160
	ds_write_b32 v31, v91 offset:6240
	ds_write_b32 v31, v92 offset:8320
	ds_write_b32 v31, v93 offset:10400
	ds_write_b32 v31, v94 offset:12480
	ds_write_b32 v31, v95 offset:14560
	s_mul_i32 s12, s21, 1
	s_add_u32 s12, s12, s28
	s_cmp_ge_u32 s12, 0x1600
	s_cbranch_scc1 .Lcv_wf1_l0_p1_wr_done
	ds_write_b32 v31, v96 offset:16640
	ds_write_b32 v31, v97 offset:18720
	ds_write_b32 v31, v98 offset:20800
	ds_write_b32 v31, v99 offset:22880
	ds_write_b32 v31, v100 offset:24960
	ds_write_b32 v31, v101 offset:27040
	ds_write_b32 v31, v102 offset:29120
	ds_write_b32 v31, v103 offset:31200
	s_mul_i32 s12, s21, 2
	s_add_u32 s12, s12, s28
	s_cmp_ge_u32 s12, 0x1600
	s_cbranch_scc1 .Lcv_wf1_l0_p1_wr_done
	ds_write_b32 v31, v104 offset:33280
	ds_write_b32 v31, v105 offset:35360
	ds_write_b32 v31, v106 offset:37440
	ds_write_b32 v31, v107 offset:39520
	ds_write_b32 v31, v108 offset:41600
	ds_write_b32 v31, v109 offset:43680
	ds_write_b32 v31, v110 offset:45760
	ds_write_b32 v31, v111 offset:47840
	s_mul_i32 s12, s21, 3
	s_add_u32 s12, s12, s28
	s_cmp_ge_u32 s12, 0x1600
	s_cbranch_scc1 .Lcv_wf1_l0_p1_wr_done
	ds_write_b32 v31, v112 offset:49920
	ds_write_b32 v31, v113 offset:52000
	ds_write_b32 v31, v114 offset:54080
	ds_write_b32 v31, v115 offset:56160
	ds_write_b32 v31, v116 offset:58240
	ds_write_b32 v31, v117 offset:60320
	ds_write_b32 v31, v118 offset:62400
	ds_write_b32 v31, v119 offset:64480
; DI unsigned cvtpk(float lo, float hi) { unsigned r; asm volatile("v_cvt_pk_bf16_f32 %0, %1, %2" : "=v"(r) : "v"(lo), "v"(hi)); return r; }
; DI int lbid() { int b = blockIdx.x; asm volatile("" : "+s"(b)); return b; }
; template <class Map>
; DI void conv_T(bf16_t* __restrict__ dst, const float* __restrict__ src, int K, int ldsrc, int nphys, Map map, const float* __restrict__ kscale, float* tile) {
;     ...
;   for (int tl = lbid(); tl < ntiles; tl += gridDim.x) {
;     const int k0 = (tl / ntn) << 6, n0 = (tl % ntn) << 6;
;     const int nn = tid & 63, sc = map(n0 + nn);
; #pragma unroll
;     for (int i = 0; i < 8; ++i) { const int kk = i * 8 + (tid >> 6);
;       float v = sc >= 0 ? __builtin_nontemporal_load(&src[(size_t)(k0 + kk) * ldsrc + sc]) : 0.f;
;       if (kscale) v *= kscale[k0 + kk];
;       tile[kk * 65 + nn] = v; }
;     __syncthreads();
;     const int np = tid >> 3, ks = tid & 7;
;     float v[8];
; #pragma unroll
;     for (int j = 0; j < 8; ++j) v[j] = tile[(ks * 8 + j) * 65 + np];
;     u32x4 w = {cvtpk(v[0], v[1]), cvtpk(v[2], v[3]), cvtpk(v[4], v[5]), cvtpk(v[6], v[7])};
;     *(u32x4*)(dst + (size_t)(n0 + np) * K + k0 + ks * 8) = w;
;     __syncthreads();
;   }
; DI void convert_layer(const Params& p, int l, float* tile) {
;     ...
;   conv_T((bf16_t*)(ws + O_WF1), p.w_f1 + (size_t)l * 2048 * 2 * DFF, 2048, 2 * DFF, 2 * DFF, MapF1{}, nullptr, tile);
.Lcv_wf1_l0_p1_wr_done:
	s_mul_i32 s12, s21, 4
	s_add_u32 s12, s12, s28
	s_cmp_ge_u32 s12, 0x1600
	s_cbranch_scc1 .Lcv_wf1_l0_p1_pf_done
	s_mul_i32 s12, s21, 4
	s_add_u32 s12, s12, s28
	s_mul_i32 s13, s12, 0xba3
	s_lshr_b32 s13, s13, 19
	s_mul_i32 s14, s13, 176
	s_sub_u32 s14, s12, s14
	s_mul_i32 s15, s13, 0x2c0000
	s_lshl_b32 s16, s14, 7
	s_add_u32 s15, s15, s16
	s_add_u32 s30, s24, s15
	s_addc_u32 s31, s25, 0
	global_load_dword v40, v34, s[30:31] nt
	s_add_u32 s30, s30, 0x58000
	s_addc_u32 s31, s31, 0
	global_load_dword v41, v34, s[30:31] nt
	s_add_u32 s30, s30, 0x58000
	s_addc_u32 s31, s31, 0
	global_load_dword v42, v34, s[30:31] nt
	s_add_u32 s30, s30, 0x58000
	s_addc_u32 s31, s31, 0
	global_load_dword v43, v34, s[30:31] nt
	s_add_u32 s30, s30, 0x58000
	s_addc_u32 s31, s31, 0
	global_load_dword v44, v34, s[30:31] nt
	s_add_u32 s30, s30, 0x58000
	s_addc_u32 s31, s31, 0
	global_load_dword v45, v34, s[30:31] nt
	s_add_u32 s30, s30, 0x58000
	s_addc_u32 s31, s31, 0
	global_load_dword v46, v34, s[30:31] nt
	s_add_u32 s30, s30, 0x58000
	s_addc_u32 s31, s31, 0
	global_load_dword v47, v34, s[30:31] nt
	s_mul_i32 s12, s21, 5
	s_add_u32 s12, s12, s28
	s_cmp_ge_u32 s12, 0x1600
	s_cbranch_scc1 .Lcv_wf1_l0_p1_pf_done
	s_mul_i32 s12, s21, 5
	s_add_u32 s12, s12, s28
	s_mul_i32 s13, s12, 0xba3
	s_lshr_b32 s13, s13, 19
	s_mul_i32 s14, s13, 176
	s_sub_u32 s14, s12, s14
	s_mul_i32 s15, s13, 0x2c0000
	s_lshl_b32 s16, s14, 7
	s_add_u32 s15, s15, s16
	s_add_u32 s30, s24, s15
	s_addc_u32 s31, s25, 0
	global_load_dword v48, v34, s[30:31] nt
	s_add_u32 s30, s30, 0x58000
	s_addc_u32 s31, s31, 0
	global_load_dword v49, v34, s[30:31] nt
	s_add_u32 s30, s30, 0x58000
	s_addc_u32 s31, s31, 0
	global_load_dword v50, v34, s[30:31] nt
	s_add_u32 s30, s30, 0x58000
	s_addc_u32 s31, s31, 0
	global_load_dword v51, v34, s[30:31] nt
	s_add_u32 s30, s30, 0x58000
	s_addc_u32 s31, s31, 0
	global_load_dword v52, v34, s[30:31] nt
	s_add_u32 s30, s30, 0x58000
	s_addc_u32 s31, s31, 0
	global_load_dword v53, v34, s[30:31] nt
	s_add_u32 s30, s30, 0x58000
	s_addc_u32 s31, s31, 0
	global_load_dword v54, v34, s[30:31] nt
	s_add_u32 s30, s30, 0x58000
	s_addc_u32 s31, s31, 0
	global_load_dword v55, v34, s[30:31] nt
	s_mul_i32 s12, s21, 6
	s_add_u32 s12, s12, s28
	s_cmp_ge_u32 s12, 0x1600
	s_cbranch_scc1 .Lcv_wf1_l0_p1_pf_done
	s_mul_i32 s12, s21, 6
	s_add_u32 s12, s12, s28
	s_mul_i32 s13, s12, 0xba3
	s_lshr_b32 s13, s13, 19
	s_mul_i32 s14, s13, 176
	s_sub_u32 s14, s12, s14
	s_mul_i32 s15, s13, 0x2c0000
	s_lshl_b32 s16, s14, 7
	s_add_u32 s15, s15, s16
	s_add_u32 s30, s24, s15
	s_addc_u32 s31, s25, 0
	global_load_dword v56, v34, s[30:31] nt
	s_add_u32 s30, s30, 0x58000
	s_addc_u32 s31, s31, 0
	global_load_dword v57, v34, s[30:31] nt
	s_add_u32 s30, s30, 0x58000
	s_addc_u32 s31, s31, 0
	global_load_dword v58, v34, s[30:31] nt
	s_add_u32 s30, s30, 0x58000
	s_addc_u32 s31, s31, 0
	global_load_dword v59, v34, s[30:31] nt
	s_add_u32 s30, s30, 0x58000
	s_addc_u32 s31, s31, 0
	global_load_dword v60, v34, s[30:31] nt
	s_add_u32 s30, s30, 0x58000
	s_addc_u32 s31, s31, 0
	global_load_dword v61, v34, s[30:31] nt
	s_add_u32 s30, s30, 0x58000
	s_addc_u32 s31, s31, 0
	global_load_dword v62, v34, s[30:31] nt
	s_add_u32 s30, s30, 0x58000
	s_addc_u32 s31, s31, 0
	global_load_dword v63, v34, s[30:31] nt
	s_mul_i32 s12, s21, 7
	s_add_u32 s12, s12, s28
	s_cmp_ge_u32 s12, 0x1600
	s_cbranch_scc1 .Lcv_wf1_l0_p1_pf_done
	s_mul_i32 s12, s21, 7
	s_add_u32 s12, s12, s28
	s_mul_i32 s13, s12, 0xba3
	s_lshr_b32 s13, s13, 19
	s_mul_i32 s14, s13, 176
	s_sub_u32 s14, s12, s14
	s_mul_i32 s15, s13, 0x2c0000
	s_lshl_b32 s16, s14, 7
	s_add_u32 s15, s15, s16
	s_add_u32 s30, s24, s15
	s_addc_u32 s31, s25, 0
	global_load_dword v64, v34, s[30:31] nt
	s_add_u32 s30, s30, 0x58000
	s_addc_u32 s31, s31, 0
	global_load_dword v65, v34, s[30:31] nt
	s_add_u32 s30, s30, 0x58000
	s_addc_u32 s31, s31, 0
	global_load_dword v66, v34, s[30:31] nt
	s_add_u32 s30, s30, 0x58000
	s_addc_u32 s31, s31, 0
	global_load_dword v67, v34, s[30:31] nt
	s_add_u32 s30, s30, 0x58000
	s_addc_u32 s31, s31, 0
	global_load_dword v68, v34, s[30:31] nt
	s_add_u32 s30, s30, 0x58000
	s_addc_u32 s31, s31, 0
	global_load_dword v69, v34, s[30:31] nt
	s_add_u32 s30, s30, 0x58000
	s_addc_u32 s31, s31, 0
	global_load_dword v70, v34, s[30:31] nt
	s_add_u32 s30, s30, 0x58000
	s_addc_u32 s31, s31, 0
	global_load_dword v71, v34, s[30:31] nt
.Lcv_wf1_l0_p1_pf_done:
	s_waitcnt lgkmcnt(0)
	s_barrier
	ds_read_b32 v88, v33
	ds_read_b32 v89, v33 offset:260
	ds_read_b32 v90, v33 offset:520
	ds_read_b32 v91, v33 offset:780
	ds_read_b32 v92, v33 offset:1040
	ds_read_b32 v93, v33 offset:1300
	ds_read_b32 v94, v33 offset:1560
	ds_read_b32 v95, v33 offset:1820
	s_mul_i32 s12, s21, 1
	s_add_u32 s12, s12, s28
	s_cmp_ge_u32 s12, 0x1600
	s_cbranch_scc1 .Lcv_wf1_l0_p1_rd_done
	ds_read_b32 v96, v33 offset:16640
	ds_read_b32 v97, v33 offset:16900
	ds_read_b32 v98, v33 offset:17160
	ds_read_b32 v99, v33 offset:17420
	ds_read_b32 v100, v33 offset:17680
	ds_read_b32 v101, v33 offset:17940
	ds_read_b32 v102, v33 offset:18200
	ds_read_b32 v103, v33 offset:18460
	s_mul_i32 s12, s21, 2
	s_add_u32 s12, s12, s28
	s_cmp_ge_u32 s12, 0x1600
	s_cbranch_scc1 .Lcv_wf1_l0_p1_rd_done
	ds_read_b32 v104, v33 offset:33280
	ds_read_b32 v105, v33 offset:33540
	ds_read_b32 v106, v33 offset:33800
	ds_read_b32 v107, v33 offset:34060
	ds_read_b32 v108, v33 offset:34320
	ds_read_b32 v109, v33 offset:34580
	ds_read_b32 v110, v33 offset:34840
	ds_read_b32 v111, v33 offset:35100
	s_mul_i32 s12, s21, 3
	s_add_u32 s12, s12, s28
	s_cmp_ge_u32 s12, 0x1600
	s_cbranch_scc1 .Lcv_wf1_l0_p1_rd_done
	ds_read_b32 v112, v33 offset:49920
	ds_read_b32 v113, v33 offset:50180
	ds_read_b32 v114, v33 offset:50440
	ds_read_b32 v115, v33 offset:50700
	ds_read_b32 v116, v33 offset:50960
	ds_read_b32 v117, v33 offset:51220
	ds_read_b32 v118, v33 offset:51480
	ds_read_b32 v119, v33 offset:51740
; DI unsigned cvtpk(float lo, float hi) { unsigned r; asm volatile("v_cvt_pk_bf16_f32 %0, %1, %2" : "=v"(r) : "v"(lo), "v"(hi)); return r; }
; template <class Map>
; DI void conv_T(bf16_t* __restrict__ dst, const float* __restrict__ src, int K, int ldsrc, int nphys, Map map, const float* __restrict__ kscale, float* tile) {
;     ...
;     __syncthreads();
;     const int np = tid >> 3, ks = tid & 7;
;     float v[8];
; #pragma unroll
;     for (int j = 0; j < 8; ++j) v[j] = tile[(ks * 8 + j) * 65 + np];
;     u32x4 w = {cvtpk(v[0], v[1]), cvtpk(v[2], v[3]), cvtpk(v[4], v[5]), cvtpk(v[6], v[7])};
;     *(u32x4*)(dst + (size_t)(n0 + np) * K + k0 + ks * 8) = w;
;     __syncthreads();
;   }
; DI void convert_layer(const Params& p, int l, float* tile) {
;     ...
;   conv_T((bf16_t*)(ws + O_WF2), p.w_f2 + (size_t)l * DFF * 2048, DFF, 2048, 2048, MapId{0}, nullptr, tile);
.Lcv_wf1_l0_p1_rd_done:
	s_waitcnt lgkmcnt(0)
	s_mov_b32 s12, s28
	s_mul_i32 s13, s12, 0xba3
	s_lshr_b32 s13, s13, 19
	s_mul_i32 s14, s13, 176
	s_sub_u32 s14, s12, s14
	s_mul_i32 s15, s14, 0x40000
	s_lshl_b32 s16, s13, 7
	s_add_u32 s15, s15, s16
	s_add_u32 s30, s26, s15
	s_addc_u32 s31, s27, 0
	v_cvt_pk_bf16_f32 v72, v88, v89
	v_cvt_pk_bf16_f32 v73, v90, v91
	v_cvt_pk_bf16_f32 v74, v92, v93
	v_cvt_pk_bf16_f32 v75, v94, v95
	global_store_dwordx4 v35, v[72:75], s[30:31]
	s_mul_i32 s12, s21, 1
	s_add_u32 s12, s12, s28
	s_cmp_ge_u32 s12, 0x1600
	s_cbranch_scc1 .Lcv_wf1_l0_p1_st_done
	s_mul_i32 s12, s21, 1
	s_add_u32 s12, s12, s28
	s_mul_i32 s13, s12, 0xba3
	s_lshr_b32 s13, s13, 19
	s_mul_i32 s14, s13, 176
	s_sub_u32 s14, s12, s14
	s_mul_i32 s15, s14, 0x40000
	s_lshl_b32 s16, s13, 7
	s_add_u32 s15, s15, s16
	s_add_u32 s30, s26, s15
	s_addc_u32 s31, s27, 0
	v_cvt_pk_bf16_f32 v76, v96, v97
	v_cvt_pk_bf16_f32 v77, v98, v99
	v_cvt_pk_bf16_f32 v78, v100, v101
	v_cvt_pk_bf16_f32 v79, v102, v103
	global_store_dwordx4 v35, v[76:79], s[30:31]
	s_mul_i32 s12, s21, 2
	s_add_u32 s12, s12, s28
	s_cmp_ge_u32 s12, 0x1600
	s_cbranch_scc1 .Lcv_wf1_l0_p1_st_done
	s_mul_i32 s12, s21, 2
	s_add_u32 s12, s12, s28
	s_mul_i32 s13, s12, 0xba3
	s_lshr_b32 s13, s13, 19
	s_mul_i32 s14, s13, 176
	s_sub_u32 s14, s12, s14
	s_mul_i32 s15, s14, 0x40000
	s_lshl_b32 s16, s13, 7
	s_add_u32 s15, s15, s16
	s_add_u32 s30, s26, s15
	s_addc_u32 s31, s27, 0
	v_cvt_pk_bf16_f32 v80, v104, v105
	v_cvt_pk_bf16_f32 v81, v106, v107
	v_cvt_pk_bf16_f32 v82, v108, v109
	v_cvt_pk_bf16_f32 v83, v110, v111
	global_store_dwordx4 v35, v[80:83], s[30:31]
	s_mul_i32 s12, s21, 3
	s_add_u32 s12, s12, s28
	s_cmp_ge_u32 s12, 0x1600
	s_cbranch_scc1 .Lcv_wf1_l0_p1_st_done
	s_mul_i32 s12, s21, 3
	s_add_u32 s12, s12, s28
	s_mul_i32 s13, s12, 0xba3
	s_lshr_b32 s13, s13, 19
	s_mul_i32 s14, s13, 176
	s_sub_u32 s14, s12, s14
	s_mul_i32 s15, s14, 0x40000
	s_lshl_b32 s16, s13, 7
	s_add_u32 s15, s15, s16
	s_add_u32 s30, s26, s15
	s_addc_u32 s31, s27, 0
	v_cvt_pk_bf16_f32 v84, v112, v113
	v_cvt_pk_bf16_f32 v85, v114, v115
	v_cvt_pk_bf16_f32 v86, v116, v117
	v_cvt_pk_bf16_f32 v87, v118, v119
	global_store_dwordx4 v35, v[84:87], s[30:31]
.Lcv_wf1_l0_p1_st_done:
	s_lshl_b32 s12, s21, 2
	s_add_u32 s28, s28, s12
	s_cmp_ge_u32 s28, 0x1600
	s_cbranch_scc0 .Lcv_wf1_l0_loop
.Lcv_wf1_l0_end:
	s_barrier
	v_readlane_b32 s24, v249, 14
	v_readlane_b32 s25, v249, 15
	s_add_u32 s26, s18, 0x7c00000
	s_addc_u32 s27, s19, 0
	v_lshrrev_b32_e32 v36, 6, v248
	v_and_b32_e32 v37, 63, v248
	v_mov_b32_e32 v38, 0x2000
	v_mul_u32_u24_e32 v34, v36, v38
	v_lshl_add_u32 v34, v37, 2, v34
	v_lshrrev_b32_e32 v36, 3, v248
	v_and_b32_e32 v37, 7, v248
	v_mov_b32_e32 v38, 0x2c00
	v_mul_u32_u24_e32 v35, v36, v38
	v_lshl_add_u32 v35, v37, 4, v35
	s_mov_b32 s28, s20
	s_cmp_ge_u32 s28, 0xb00
	s_cbranch_scc1 .Lcv_wf2_l0_end
	s_mov_b32 s12, s28
	s_lshr_b32 s13, s12, 5
	s_and_b32 s14, s12, 31
	s_mul_i32 s15, s13, 0x80000
	s_lshl_b32 s16, s14, 8
	s_add_u32 s15, s15, s16
	s_add_u32 s30, s24, s15
	s_addc_u32 s31, s25, 0
	global_load_dword v40, v34, s[30:31] nt
	s_add_u32 s30, s30, 0x10000
	s_addc_u32 s31, s31, 0
	global_load_dword v41, v34, s[30:31] nt
	s_add_u32 s30, s30, 0x10000
	s_addc_u32 s31, s31, 0
	global_load_dword v42, v34, s[30:31] nt
	s_add_u32 s30, s30, 0x10000
	s_addc_u32 s31, s31, 0
	global_load_dword v43, v34, s[30:31] nt
	s_add_u32 s30, s30, 0x10000
	s_addc_u32 s31, s31, 0
	global_load_dword v44, v34, s[30:31] nt
	s_add_u32 s30, s30, 0x10000
	s_addc_u32 s31, s31, 0
	global_load_dword v45, v34, s[30:31] nt
	s_add_u32 s30, s30, 0x10000
	s_addc_u32 s31, s31, 0
	global_load_dword v46, v34, s[30:31] nt
	s_add_u32 s30, s30, 0x10000
	s_addc_u32 s31, s31, 0
	global_load_dword v47, v34, s[30:31] nt
	s_mul_i32 s12, s21, 1
	s_add_u32 s12, s12, s28
	s_cmp_ge_u32 s12, 0xb00
	s_cbranch_scc1 .Lcv_wf2_l0_pro_done
	s_mul_i32 s12, s21, 1
	s_add_u32 s12, s12, s28
	s_lshr_b32 s13, s12, 5
	s_and_b32 s14, s12, 31
	s_mul_i32 s15, s13, 0x80000
	s_lshl_b32 s16, s14, 8
	s_add_u32 s15, s15, s16
	s_add_u32 s30, s24, s15
	s_addc_u32 s31, s25, 0
	global_load_dword v48, v34, s[30:31] nt
	s_add_u32 s30, s30, 0x10000
	s_addc_u32 s31, s31, 0
	global_load_dword v49, v34, s[30:31] nt
	s_add_u32 s30, s30, 0x10000
	s_addc_u32 s31, s31, 0
	global_load_dword v50, v34, s[30:31] nt
	s_add_u32 s30, s30, 0x10000
	s_addc_u32 s31, s31, 0
	global_load_dword v51, v34, s[30:31] nt
	s_add_u32 s30, s30, 0x10000
	s_addc_u32 s31, s31, 0
	global_load_dword v52, v34, s[30:31] nt
	s_add_u32 s30, s30, 0x10000
	s_addc_u32 s31, s31, 0
	global_load_dword v53, v34, s[30:31] nt
	s_add_u32 s30, s30, 0x10000
	s_addc_u32 s31, s31, 0
	global_load_dword v54, v34, s[30:31] nt
	s_add_u32 s30, s30, 0x10000
	s_addc_u32 s31, s31, 0
	global_load_dword v55, v34, s[30:31] nt
	s_mul_i32 s12, s21, 2
	s_add_u32 s12, s12, s28
	s_cmp_ge_u32 s12, 0xb00
	s_cbranch_scc1 .Lcv_wf2_l0_pro_done
	s_mul_i32 s12, s21, 2
	s_add_u32 s12, s12, s28
	s_lshr_b32 s13, s12, 5
	s_and_b32 s14, s12, 31
	s_mul_i32 s15, s13, 0x80000
	s_lshl_b32 s16, s14, 8
	s_add_u32 s15, s15, s16
	s_add_u32 s30, s24, s15
	s_addc_u32 s31, s25, 0
	global_load_dword v56, v34, s[30:31] nt
	s_add_u32 s30, s30, 0x10000
	s_addc_u32 s31, s31, 0
	global_load_dword v57, v34, s[30:31] nt
	s_add_u32 s30, s30, 0x10000
	s_addc_u32 s31, s31, 0
	global_load_dword v58, v34, s[30:31] nt
	s_add_u32 s30, s30, 0x10000
	s_addc_u32 s31, s31, 0
	global_load_dword v59, v34, s[30:31] nt
	s_add_u32 s30, s30, 0x10000
	s_addc_u32 s31, s31, 0
	global_load_dword v60, v34, s[30:31] nt
	s_add_u32 s30, s30, 0x10000
	s_addc_u32 s31, s31, 0
	global_load_dword v61, v34, s[30:31] nt
	s_add_u32 s30, s30, 0x10000
	s_addc_u32 s31, s31, 0
	global_load_dword v62, v34, s[30:31] nt
	s_add_u32 s30, s30, 0x10000
	s_addc_u32 s31, s31, 0
	global_load_dword v63, v34, s[30:31] nt
	s_mul_i32 s12, s21, 3
	s_add_u32 s12, s12, s28
	s_cmp_ge_u32 s12, 0xb00
	s_cbranch_scc1 .Lcv_wf2_l0_pro_done
	s_mul_i32 s12, s21, 3
	s_add_u32 s12, s12, s28
	s_lshr_b32 s13, s12, 5
	s_and_b32 s14, s12, 31
	s_mul_i32 s15, s13, 0x80000
	s_lshl_b32 s16, s14, 8
	s_add_u32 s15, s15, s16
	s_add_u32 s30, s24, s15
	s_addc_u32 s31, s25, 0
	global_load_dword v64, v34, s[30:31] nt
	s_add_u32 s30, s30, 0x10000
	s_addc_u32 s31, s31, 0
	global_load_dword v65, v34, s[30:31] nt
	s_add_u32 s30, s30, 0x10000
	s_addc_u32 s31, s31, 0
	global_load_dword v66, v34, s[30:31] nt
	s_add_u32 s30, s30, 0x10000
	s_addc_u32 s31, s31, 0
	global_load_dword v67, v34, s[30:31] nt
	s_add_u32 s30, s30, 0x10000
	s_addc_u32 s31, s31, 0
	global_load_dword v68, v34, s[30:31] nt
	s_add_u32 s30, s30, 0x10000
	s_addc_u32 s31, s31, 0
	global_load_dword v69, v34, s[30:31] nt
	s_add_u32 s30, s30, 0x10000
	s_addc_u32 s31, s31, 0
	global_load_dword v70, v34, s[30:31] nt
	s_add_u32 s30, s30, 0x10000
	s_addc_u32 s31, s31, 0
	global_load_dword v71, v34, s[30:31] nt

; DI int lbid() { int b = blockIdx.x; asm volatile("" : "+s"(b)); return b; }
; template <class Map>
; DI void conv_T(bf16_t* __restrict__ dst, const float* __restrict__ src, int K, int ldsrc, int nphys, Map map, const float* __restrict__ kscale, float* tile) {
;     ...
;   for (int tl = lbid(); tl < ntiles; tl += gridDim.x) {
;     const int k0 = (tl / ntn) << 6, n0 = (tl % ntn) << 6;
;     const int nn = tid & 63, sc = map(n0 + nn);
; #pragma unroll
;     for (int i = 0; i < 8; ++i) { const int kk = i * 8 + (tid >> 6);
;       float v = sc >= 0 ? __builtin_nontemporal_load(&src[(size_t)(k0 + kk) * ldsrc + sc]) : 0.f;
;       if (kscale) v *= kscale[k0 + kk];
;       tile[kk * 65 + nn] = v; }
; DI void convert_layer(const Params& p, int l, float* tile) {
;     ...
;   conv_T((bf16_t*)(ws + O_WF2), p.w_f2 + (size_t)l * DFF * 2048, DFF, 2048, 2048, MapId{0}, nullptr, tile);
.Lcv_wf2_l0_p0_after:
	ds_write_b32 v30, v40
	ds_write_b32 v30, v41 offset:2080
	ds_write_b32 v30, v42 offset:4160
	ds_write_b32 v30, v43 offset:6240
	ds_write_b32 v30, v44 offset:8320
	ds_write_b32 v30, v45 offset:10400
	ds_write_b32 v30, v46 offset:12480
	ds_write_b32 v30, v47 offset:14560
	s_mul_i32 s12, s21, 1
	s_add_u32 s12, s12, s28
	s_cmp_ge_u32 s12, 0xb00
	s_cbranch_scc1 .Lcv_wf2_l0_p0_wr_done
	ds_write_b32 v30, v48 offset:16640
	ds_write_b32 v30, v49 offset:18720
	ds_write_b32 v30, v50 offset:20800
	ds_write_b32 v30, v51 offset:22880
	ds_write_b32 v30, v52 offset:24960
	ds_write_b32 v30, v53 offset:27040
	ds_write_b32 v30, v54 offset:29120
	ds_write_b32 v30, v55 offset:31200
	s_mul_i32 s12, s21, 2
	s_add_u32 s12, s12, s28
	s_cmp_ge_u32 s12, 0xb00
	s_cbranch_scc1 .Lcv_wf2_l0_p0_wr_done
	ds_write_b32 v30, v56 offset:33280
	ds_write_b32 v30, v57 offset:35360
	ds_write_b32 v30, v58 offset:37440
	ds_write_b32 v30, v59 offset:39520
	ds_write_b32 v30, v60 offset:41600
	ds_write_b32 v30, v61 offset:43680
	ds_write_b32 v30, v62 offset:45760
	ds_write_b32 v30, v63 offset:47840
	s_mul_i32 s12, s21, 3
	s_add_u32 s12, s12, s28
	s_cmp_ge_u32 s12, 0xb00
	s_cbranch_scc1 .Lcv_wf2_l0_p0_wr_done
	ds_write_b32 v30, v64 offset:49920
	ds_write_b32 v30, v65 offset:52000
	ds_write_b32 v30, v66 offset:54080
	ds_write_b32 v30, v67 offset:56160
	ds_write_b32 v30, v68 offset:58240
	ds_write_b32 v30, v69 offset:60320
	ds_write_b32 v30, v70 offset:62400
	ds_write_b32 v30, v71 offset:64480
.Lcv_wf2_l0_p0_wr_done:
	s_mul_i32 s12, s21, 4
	s_add_u32 s12, s12, s28
	s_cmp_ge_u32 s12, 0xb00
	s_cbranch_scc1 .Lcv_wf2_l0_p0_pf_done
	s_mul_i32 s12, s21, 4
	s_add_u32 s12, s12, s28
	s_lshr_b32 s13, s12, 5
	s_and_b32 s14, s12, 31
	s_mul_i32 s15, s13, 0x80000
	s_lshl_b32 s16, s14, 8
	s_add_u32 s15, s15, s16
	s_add_u32 s30, s24, s15
	s_addc_u32 s31, s25, 0
	global_load_dword v88, v34, s[30:31] nt
	s_add_u32 s30, s30, 0x10000
	s_addc_u32 s31, s31, 0
	global_load_dword v89, v34, s[30:31] nt
	s_add_u32 s30, s30, 0x10000
	s_addc_u32 s31, s31, 0
	global_load_dword v90, v34, s[30:31] nt
	s_add_u32 s30, s30, 0x10000
	s_addc_u32 s31, s31, 0
	global_load_dword v91, v34, s[30:31] nt
	s_add_u32 s30, s30, 0x10000
	s_addc_u32 s31, s31, 0
	global_load_dword v92, v34, s[30:31] nt
	s_add_u32 s30, s30, 0x10000
	s_addc_u32 s31, s31, 0
	global_load_dword v93, v34, s[30:31] nt
	s_add_u32 s30, s30, 0x10000
	s_addc_u32 s31, s31, 0
	global_load_dword v94, v34, s[30:31] nt
	s_add_u32 s30, s30, 0x10000
	s_addc_u32 s31, s31, 0
	global_load_dword v95, v34, s[30:31] nt
	s_mul_i32 s12, s21, 5
	s_add_u32 s12, s12, s28
	s_cmp_ge_u32 s12, 0xb00
	s_cbranch_scc1 .Lcv_wf2_l0_p0_pf_done
	s_mul_i32 s12, s21, 5
	s_add_u32 s12, s12, s28
	s_lshr_b32 s13, s12, 5
	s_and_b32 s14, s12, 31
	s_mul_i32 s15, s13, 0x80000
	s_lshl_b32 s16, s14, 8
	s_add_u32 s15, s15, s16
	s_add_u32 s30, s24, s15
	s_addc_u32 s31, s25, 0
	global_load_dword v96, v34, s[30:31] nt
	s_add_u32 s30, s30, 0x10000
	s_addc_u32 s31, s31, 0
	global_load_dword v97, v34, s[30:31] nt
	s_add_u32 s30, s30, 0x10000
	s_addc_u32 s31, s31, 0
	global_load_dword v98, v34, s[30:31] nt
	s_add_u32 s30, s30, 0x10000
	s_addc_u32 s31, s31, 0
	global_load_dword v99, v34, s[30:31] nt
	s_add_u32 s30, s30, 0x10000
	s_addc_u32 s31, s31, 0
	global_load_dword v100, v34, s[30:31] nt
	s_add_u32 s30, s30, 0x10000
	s_addc_u32 s31, s31, 0
	global_load_dword v101, v34, s[30:31] nt
	s_add_u32 s30, s30, 0x10000
	s_addc_u32 s31, s31, 0
	global_load_dword v102, v34, s[30:31] nt
	s_add_u32 s30, s30, 0x10000
	s_addc_u32 s31, s31, 0
	global_load_dword v103, v34, s[30:31] nt
	s_mul_i32 s12, s21, 6
	s_add_u32 s12, s12, s28
	s_cmp_ge_u32 s12, 0xb00
	s_cbranch_scc1 .Lcv_wf2_l0_p0_pf_done
	s_mul_i32 s12, s21, 6
	s_add_u32 s12, s12, s28
	s_lshr_b32 s13, s12, 5
	s_and_b32 s14, s12, 31
	s_mul_i32 s15, s13, 0x80000
	s_lshl_b32 s16, s14, 8
	s_add_u32 s15, s15, s16
	s_add_u32 s30, s24, s15
	s_addc_u32 s31, s25, 0
	global_load_dword v104, v34, s[30:31] nt
	s_add_u32 s30, s30, 0x10000
	s_addc_u32 s31, s31, 0
	global_load_dword v105, v34, s[30:31] nt
	s_add_u32 s30, s30, 0x10000
	s_addc_u32 s31, s31, 0
	global_load_dword v106, v34, s[30:31] nt
	s_add_u32 s30, s30, 0x10000
	s_addc_u32 s31, s31, 0
	global_load_dword v107, v34, s[30:31] nt
	s_add_u32 s30, s30, 0x10000
	s_addc_u32 s31, s31, 0
	global_load_dword v108, v34, s[30:31] nt
	s_add_u32 s30, s30, 0x10000
	s_addc_u32 s31, s31, 0
	global_load_dword v109, v34, s[30:31] nt
	s_add_u32 s30, s30, 0x10000
	s_addc_u32 s31, s31, 0
	global_load_dword v110, v34, s[30:31] nt
	s_add_u32 s30, s30, 0x10000
	s_addc_u32 s31, s31, 0
	global_load_dword v111, v34, s[30:31] nt
	s_mul_i32 s12, s21, 7
	s_add_u32 s12, s12, s28
	s_cmp_ge_u32 s12, 0xb00
	s_cbranch_scc1 .Lcv_wf2_l0_p0_pf_done
	s_mul_i32 s12, s21, 7
	s_add_u32 s12, s12, s28
	s_lshr_b32 s13, s12, 5
	s_and_b32 s14, s12, 31
	s_mul_i32 s15, s13, 0x80000
	s_lshl_b32 s16, s14, 8
	s_add_u32 s15, s15, s16
	s_add_u32 s30, s24, s15
	s_addc_u32 s31, s25, 0
	global_load_dword v112, v34, s[30:31] nt
	s_add_u32 s30, s30, 0x10000
	s_addc_u32 s31, s31, 0
	global_load_dword v113, v34, s[30:31] nt
	s_add_u32 s30, s30, 0x10000
	s_addc_u32 s31, s31, 0
	global_load_dword v114, v34, s[30:31] nt
	s_add_u32 s30, s30, 0x10000
	s_addc_u32 s31, s31, 0
	global_load_dword v115, v34, s[30:31] nt
	s_add_u32 s30, s30, 0x10000
	s_addc_u32 s31, s31, 0
	global_load_dword v116, v34, s[30:31] nt
	s_add_u32 s30, s30, 0x10000
	s_addc_u32 s31, s31, 0
	global_load_dword v117, v34, s[30:31] nt
	s_add_u32 s30, s30, 0x10000
	s_addc_u32 s31, s31, 0
	global_load_dword v118, v34, s[30:31] nt
	s_add_u32 s30, s30, 0x10000
	s_addc_u32 s31, s31, 0
	global_load_dword v119, v34, s[30:31] nt
; DI unsigned cvtpk(float lo, float hi) { unsigned r; asm volatile("v_cvt_pk_bf16_f32 %0, %1, %2" : "=v"(r) : "v"(lo), "v"(hi)); return r; }
; template <class Map>
; DI void conv_T(bf16_t* __restrict__ dst, const float* __restrict__ src, int K, int ldsrc, int nphys, Map map, const float* __restrict__ kscale, float* tile) {
;     ...
;     __syncthreads();
;     const int np = tid >> 3, ks = tid & 7;
;     float v[8];
; #pragma unroll
;     for (int j = 0; j < 8; ++j) v[j] = tile[(ks * 8 + j) * 65 + np];
;     u32x4 w = {cvtpk(v[0], v[1]), cvtpk(v[2], v[3]), cvtpk(v[4], v[5]), cvtpk(v[6], v[7])};
;     *(u32x4*)(dst + (size_t)(n0 + np) * K + k0 + ks * 8) = w;
;     __syncthreads();
;   }
; DI void convert_layer(const Params& p, int l, float* tile) {
;     ...
;   conv_T((bf16_t*)(ws + O_WF2), p.w_f2 + (size_t)l * DFF * 2048, DFF, 2048, 2048, MapId{0}, nullptr, tile);
.Lcv_wf2_l0_p0_pf_done:
	s_waitcnt lgkmcnt(0)
	s_barrier
	ds_read_b32 v40, v32
	ds_read_b32 v41, v32 offset:260
	ds_read_b32 v42, v32 offset:520
	ds_read_b32 v43, v32 offset:780
	ds_read_b32 v44, v32 offset:1040
	ds_read_b32 v45, v32 offset:1300
	ds_read_b32 v46, v32 offset:1560
	ds_read_b32 v47, v32 offset:1820
	s_mul_i32 s12, s21, 1
	s_add_u32 s12, s12, s28
	s_cmp_ge_u32 s12, 0xb00
	s_cbranch_scc1 .Lcv_wf2_l0_p0_rd_done
	ds_read_b32 v48, v32 offset:16640
	ds_read_b32 v49, v32 offset:16900
	ds_read_b32 v50, v32 offset:17160
	ds_read_b32 v51, v32 offset:17420
	ds_read_b32 v52, v32 offset:17680
	ds_read_b32 v53, v32 offset:17940
	ds_read_b32 v54, v32 offset:18200
	ds_read_b32 v55, v32 offset:18460
	s_mul_i32 s12, s21, 2
	s_add_u32 s12, s12, s28
	s_cmp_ge_u32 s12, 0xb00
	s_cbranch_scc1 .Lcv_wf2_l0_p0_rd_done
	ds_read_b32 v56, v32 offset:33280
	ds_read_b32 v57, v32 offset:33540
	ds_read_b32 v58, v32 offset:33800
	ds_read_b32 v59, v32 offset:34060
	ds_read_b32 v60, v32 offset:34320
	ds_read_b32 v61, v32 offset:34580
	ds_read_b32 v62, v32 offset:34840
	ds_read_b32 v63, v32 offset:35100
	s_mul_i32 s12, s21, 3
	s_add_u32 s12, s12, s28
	s_cmp_ge_u32 s12, 0xb00
	s_cbranch_scc1 .Lcv_wf2_l0_p0_rd_done
	ds_read_b32 v64, v32 offset:49920
	ds_read_b32 v65, v32 offset:50180
	ds_read_b32 v66, v32 offset:50440
	ds_read_b32 v67, v32 offset:50700
	ds_read_b32 v68, v32 offset:50960
	ds_read_b32 v69, v32 offset:51220
	ds_read_b32 v70, v32 offset:51480
	ds_read_b32 v71, v32 offset:51740
.Lcv_wf2_l0_p0_rd_done:
	s_waitcnt lgkmcnt(0)
	s_mov_b32 s12, s28
	s_lshr_b32 s13, s12, 5
	s_and_b32 s14, s12, 31
	s_mul_i32 s15, s14, 0xb0000
	s_lshl_b32 s16, s13, 7
	s_add_u32 s15, s15, s16
	s_add_u32 s30, s26, s15
	s_addc_u32 s31, s27, 0
	v_cvt_pk_bf16_f32 v72, v40, v41
	v_cvt_pk_bf16_f32 v73, v42, v43
	v_cvt_pk_bf16_f32 v74, v44, v45
	v_cvt_pk_bf16_f32 v75, v46, v47
	global_store_dwordx4 v35, v[72:75], s[30:31]
	s_mul_i32 s12, s21, 1
	s_add_u32 s12, s12, s28
	s_cmp_ge_u32 s12, 0xb00
	s_cbranch_scc1 .Lcv_wf2_l0_p0_st_done
	s_mul_i32 s12, s21, 1
	s_add_u32 s12, s12, s28
	s_lshr_b32 s13, s12, 5
	s_and_b32 s14, s12, 31
	s_mul_i32 s15, s14, 0xb0000
	s_lshl_b32 s16, s13, 7
	s_add_u32 s15, s15, s16
	s_add_u32 s30, s26, s15
	s_addc_u32 s31, s27, 0
	v_cvt_pk_bf16_f32 v76, v48, v49
	v_cvt_pk_bf16_f32 v77, v50, v51
	v_cvt_pk_bf16_f32 v78, v52, v53
	v_cvt_pk_bf16_f32 v79, v54, v55
	global_store_dwordx4 v35, v[76:79], s[30:31]
	s_mul_i32 s12, s21, 2
	s_add_u32 s12, s12, s28
	s_cmp_ge_u32 s12, 0xb00
	s_cbranch_scc1 .Lcv_wf2_l0_p0_st_done
	s_mul_i32 s12, s21, 2
	s_add_u32 s12, s12, s28
	s_lshr_b32 s13, s12, 5
	s_and_b32 s14, s12, 31
	s_mul_i32 s15, s14, 0xb0000
	s_lshl_b32 s16, s13, 7
	s_add_u32 s15, s15, s16
	s_add_u32 s30, s26, s15
	s_addc_u32 s31, s27, 0
	v_cvt_pk_bf16_f32 v80, v56, v57
	v_cvt_pk_bf16_f32 v81, v58, v59
	v_cvt_pk_bf16_f32 v82, v60, v61
	v_cvt_pk_bf16_f32 v83, v62, v63
	global_store_dwordx4 v35, v[80:83], s[30:31]
	s_mul_i32 s12, s21, 3
	s_add_u32 s12, s12, s28
	s_cmp_ge_u32 s12, 0xb00
	s_cbranch_scc1 .Lcv_wf2_l0_p0_st_done
	s_mul_i32 s12, s21, 3
	s_add_u32 s12, s12, s28
	s_lshr_b32 s13, s12, 5
	s_and_b32 s14, s12, 31
	s_mul_i32 s15, s14, 0xb0000
	s_lshl_b32 s16, s13, 7
	s_add_u32 s15, s15, s16
	s_add_u32 s30, s26, s15
	s_addc_u32 s31, s27, 0
	v_cvt_pk_bf16_f32 v84, v64, v65
	v_cvt_pk_bf16_f32 v85, v66, v67
	v_cvt_pk_bf16_f32 v86, v68, v69
	v_cvt_pk_bf16_f32 v87, v70, v71
	global_store_dwordx4 v35, v[84:87], s[30:31]
.Lcv_wf2_l0_p0_st_done:
	s_lshl_b32 s12, s21, 2
	s_add_u32 s28, s28, s12
	s_cmp_ge_u32 s28, 0xb00
	s_cbranch_scc1 .Lcv_wf2_l0_end
	s_waitcnt vmcnt(4)
.Lcv_wf2_l0_p1_after:
	ds_write_b32 v31, v88
	ds_write_b32 v31, v89 offset:2080
	ds_write_b32 v31, v90 offset:4160
	ds_write_b32 v31, v91 offset:6240
	ds_write_b32 v31, v92 offset:8320
	ds_write_b32 v31, v93 offset:10400
	ds_write_b32 v31, v94 offset:12480
	ds_write_b32 v31, v95 offset:14560
	s_mul_i32 s12, s21, 1
	s_add_u32 s12, s12, s28
	s_cmp_ge_u32 s12, 0xb00
	s_cbranch_scc1 .Lcv_wf2_l0_p1_wr_done
	ds_write_b32 v31, v96 offset:16640
	ds_write_b32 v31, v97 offset:18720
	ds_write_b32 v31, v98 offset:20800
	ds_write_b32 v31, v99 offset:22880
	ds_write_b32 v31, v100 offset:24960
	ds_write_b32 v31, v101 offset:27040
	ds_write_b32 v31, v102 offset:29120
	ds_write_b32 v31, v103 offset:31200
	s_mul_i32 s12, s21, 2
	s_add_u32 s12, s12, s28
	s_cmp_ge_u32 s12, 0xb00
	s_cbranch_scc1 .Lcv_wf2_l0_p1_wr_done
	ds_write_b32 v31, v104 offset:33280
	ds_write_b32 v31, v105 offset:35360
	ds_write_b32 v31, v106 offset:37440
	ds_write_b32 v31, v107 offset:39520
	ds_write_b32 v31, v108 offset:41600
	ds_write_b32 v31, v109 offset:43680
	ds_write_b32 v31, v110 offset:45760
	ds_write_b32 v31, v111 offset:47840
	s_mul_i32 s12, s21, 3
	s_add_u32 s12, s12, s28
	s_cmp_ge_u32 s12, 0xb00
	s_cbranch_scc1 .Lcv_wf2_l0_p1_wr_done
	ds_write_b32 v31, v112 offset:49920
	ds_write_b32 v31, v113 offset:52000
	ds_write_b32 v31, v114 offset:54080
	ds_write_b32 v31, v115 offset:56160
	ds_write_b32 v31, v116 offset:58240
	ds_write_b32 v31, v117 offset:60320
	ds_write_b32 v31, v118 offset:62400
	ds_write_b32 v31, v119 offset:64480
; DI int lbid() { int b = blockIdx.x; asm volatile("" : "+s"(b)); return b; }
; template <class Map>
; DI void conv_T(bf16_t* __restrict__ dst, const float* __restrict__ src, int K, int ldsrc, int nphys, Map map, const float* __restrict__ kscale, float* tile) {
;     ...
;   for (int tl = lbid(); tl < ntiles; tl += gridDim.x) {
;     const int k0 = (tl / ntn) << 6, n0 = (tl % ntn) << 6;
;     const int nn = tid & 63, sc = map(n0 + nn);
; #pragma unroll
;     for (int i = 0; i < 8; ++i) { const int kk = i * 8 + (tid >> 6);
;       float v = sc >= 0 ? __builtin_nontemporal_load(&src[(size_t)(k0 + kk) * ldsrc + sc]) : 0.f;
; DI void convert_layer(const Params& p, int l, float* tile) {
;     ...
;   conv_T((bf16_t*)(ws + O_WF2), p.w_f2 + (size_t)l * DFF * 2048, DFF, 2048, 2048, MapId{0}, nullptr, tile);
.Lcv_wf2_l0_p1_wr_done:
	s_mul_i32 s12, s21, 4
	s_add_u32 s12, s12, s28
	s_cmp_ge_u32 s12, 0xb00
	s_cbranch_scc1 .Lcv_wf2_l0_p1_pf_done
	s_mul_i32 s12, s21, 4
	s_add_u32 s12, s12, s28
	s_lshr_b32 s13, s12, 5
	s_and_b32 s14, s12, 31
	s_mul_i32 s15, s13, 0x80000
	s_lshl_b32 s16, s14, 8
	s_add_u32 s15, s15, s16
	s_add_u32 s30, s24, s15
	s_addc_u32 s31, s25, 0
	global_load_dword v40, v34, s[30:31] nt
	s_add_u32 s30, s30, 0x10000
	s_addc_u32 s31, s31, 0
	global_load_dword v41, v34, s[30:31] nt
	s_add_u32 s30, s30, 0x10000
	s_addc_u32 s31, s31, 0
	global_load_dword v42, v34, s[30:31] nt
	s_add_u32 s30, s30, 0x10000
	s_addc_u32 s31, s31, 0
	global_load_dword v43, v34, s[30:31] nt
	s_add_u32 s30, s30, 0x10000
	s_addc_u32 s31, s31, 0
	global_load_dword v44, v34, s[30:31] nt
	s_add_u32 s30, s30, 0x10000
	s_addc_u32 s31, s31, 0
	global_load_dword v45, v34, s[30:31] nt
	s_add_u32 s30, s30, 0x10000
	s_addc_u32 s31, s31, 0
	global_load_dword v46, v34, s[30:31] nt
	s_add_u32 s30, s30, 0x10000
	s_addc_u32 s31, s31, 0
	global_load_dword v47, v34, s[30:31] nt
	s_mul_i32 s12, s21, 5
	s_add_u32 s12, s12, s28
	s_cmp_ge_u32 s12, 0xb00
	s_cbranch_scc1 .Lcv_wf2_l0_p1_pf_done
	s_mul_i32 s12, s21, 5
	s_add_u32 s12, s12, s28
	s_lshr_b32 s13, s12, 5
	s_and_b32 s14, s12, 31
	s_mul_i32 s15, s13, 0x80000
	s_lshl_b32 s16, s14, 8
	s_add_u32 s15, s15, s16
	s_add_u32 s30, s24, s15
	s_addc_u32 s31, s25, 0
	global_load_dword v48, v34, s[30:31] nt
	s_add_u32 s30, s30, 0x10000
	s_addc_u32 s31, s31, 0
	global_load_dword v49, v34, s[30:31] nt
	s_add_u32 s30, s30, 0x10000
	s_addc_u32 s31, s31, 0
	global_load_dword v50, v34, s[30:31] nt
	s_add_u32 s30, s30, 0x10000
	s_addc_u32 s31, s31, 0
	global_load_dword v51, v34, s[30:31] nt
	s_add_u32 s30, s30, 0x10000
	s_addc_u32 s31, s31, 0
	global_load_dword v52, v34, s[30:31] nt
	s_add_u32 s30, s30, 0x10000
	s_addc_u32 s31, s31, 0
	global_load_dword v53, v34, s[30:31] nt
	s_add_u32 s30, s30, 0x10000
	s_addc_u32 s31, s31, 0
	global_load_dword v54, v34, s[30:31] nt
	s_add_u32 s30, s30, 0x10000
	s_addc_u32 s31, s31, 0
	global_load_dword v55, v34, s[30:31] nt
	s_mul_i32 s12, s21, 6
	s_add_u32 s12, s12, s28
	s_cmp_ge_u32 s12, 0xb00
	s_cbranch_scc1 .Lcv_wf2_l0_p1_pf_done
	s_mul_i32 s12, s21, 6
	s_add_u32 s12, s12, s28
	s_lshr_b32 s13, s12, 5
	s_and_b32 s14, s12, 31
	s_mul_i32 s15, s13, 0x80000
	s_lshl_b32 s16, s14, 8
	s_add_u32 s15, s15, s16
	s_add_u32 s30, s24, s15
	s_addc_u32 s31, s25, 0
	global_load_dword v56, v34, s[30:31] nt
	s_add_u32 s30, s30, 0x10000
	s_addc_u32 s31, s31, 0
	global_load_dword v57, v34, s[30:31] nt
	s_add_u32 s30, s30, 0x10000
	s_addc_u32 s31, s31, 0
	global_load_dword v58, v34, s[30:31] nt
	s_add_u32 s30, s30, 0x10000
	s_addc_u32 s31, s31, 0
	global_load_dword v59, v34, s[30:31] nt
	s_add_u32 s30, s30, 0x10000
	s_addc_u32 s31, s31, 0
	global_load_dword v60, v34, s[30:31] nt
	s_add_u32 s30, s30, 0x10000
	s_addc_u32 s31, s31, 0
	global_load_dword v61, v34, s[30:31] nt
	s_add_u32 s30, s30, 0x10000
	s_addc_u32 s31, s31, 0
	global_load_dword v62, v34, s[30:31] nt
	s_add_u32 s30, s30, 0x10000
	s_addc_u32 s31, s31, 0
	global_load_dword v63, v34, s[30:31] nt
	s_mul_i32 s12, s21, 7
	s_add_u32 s12, s12, s28
	s_cmp_ge_u32 s12, 0xb00
	s_cbranch_scc1 .Lcv_wf2_l0_p1_pf_done
	s_mul_i32 s12, s21, 7
	s_add_u32 s12, s12, s28
	s_lshr_b32 s13, s12, 5
	s_and_b32 s14, s12, 31
	s_mul_i32 s15, s13, 0x80000
	s_lshl_b32 s16, s14, 8
	s_add_u32 s15, s15, s16
	s_add_u32 s30, s24, s15
	s_addc_u32 s31, s25, 0
	global_load_dword v64, v34, s[30:31] nt
	s_add_u32 s30, s30, 0x10000
	s_addc_u32 s31, s31, 0
	global_load_dword v65, v34, s[30:31] nt
	s_add_u32 s30, s30, 0x10000
	s_addc_u32 s31, s31, 0
	global_load_dword v66, v34, s[30:31] nt
	s_add_u32 s30, s30, 0x10000
	s_addc_u32 s31, s31, 0
	global_load_dword v67, v34, s[30:31] nt
	s_add_u32 s30, s30, 0x10000
	s_addc_u32 s31, s31, 0
	global_load_dword v68, v34, s[30:31] nt
	s_add_u32 s30, s30, 0x10000
	s_addc_u32 s31, s31, 0
	global_load_dword v69, v34, s[30:31] nt
	s_add_u32 s30, s30, 0x10000
	s_addc_u32 s31, s31, 0
	global_load_dword v70, v34, s[30:31] nt
	s_add_u32 s30, s30, 0x10000
	s_addc_u32 s31, s31, 0
	global_load_dword v71, v34, s[30:31] nt
; DI unsigned cvtpk(float lo, float hi) { unsigned r; asm volatile("v_cvt_pk_bf16_f32 %0, %1, %2" : "=v"(r) : "v"(lo), "v"(hi)); return r; }
; template <class Map>
; DI void conv_T(bf16_t* __restrict__ dst, const float* __restrict__ src, int K, int ldsrc, int nphys, Map map, const float* __restrict__ kscale, float* tile) {
;     ...
;     __syncthreads();
;     const int np = tid >> 3, ks = tid & 7;
;     float v[8];
; #pragma unroll
;     for (int j = 0; j < 8; ++j) v[j] = tile[(ks * 8 + j) * 65 + np];
;     u32x4 w = {cvtpk(v[0], v[1]), cvtpk(v[2], v[3]), cvtpk(v[4], v[5]), cvtpk(v[6], v[7])};
;     *(u32x4*)(dst + (size_t)(n0 + np) * K + k0 + ks * 8) = w;
;     __syncthreads();
;   }
; DI void convert_layer(const Params& p, int l, float* tile) {
;     ...
;   conv_T((bf16_t*)(ws + O_WMISC), p.w_in + (size_t)l * 2048 * NIN, 2048, NIN, 256, MapMisc{}, nullptr, tile);
.Lcv_wf2_l0_p1_pf_done:
	s_waitcnt lgkmcnt(0)
	s_barrier
	ds_read_b32 v88, v33
	ds_read_b32 v89, v33 offset:260
	ds_read_b32 v90, v33 offset:520
	ds_read_b32 v91, v33 offset:780
	ds_read_b32 v92, v33 offset:1040
	ds_read_b32 v93, v33 offset:1300
	ds_read_b32 v94, v33 offset:1560
	ds_read_b32 v95, v33 offset:1820
	s_mul_i32 s12, s21, 1
	s_add_u32 s12, s12, s28
	s_cmp_ge_u32 s12, 0xb00
	s_cbranch_scc1 .Lcv_wf2_l0_p1_rd_done
	ds_read_b32 v96, v33 offset:16640
	ds_read_b32 v97, v33 offset:16900
	ds_read_b32 v98, v33 offset:17160
	ds_read_b32 v99, v33 offset:17420
	ds_read_b32 v100, v33 offset:17680
	ds_read_b32 v101, v33 offset:17940
	ds_read_b32 v102, v33 offset:18200
	ds_read_b32 v103, v33 offset:18460
	s_mul_i32 s12, s21, 2
	s_add_u32 s12, s12, s28
	s_cmp_ge_u32 s12, 0xb00
	s_cbranch_scc1 .Lcv_wf2_l0_p1_rd_done
	ds_read_b32 v104, v33 offset:33280
	ds_read_b32 v105, v33 offset:33540
	ds_read_b32 v106, v33 offset:33800
	ds_read_b32 v107, v33 offset:34060
	ds_read_b32 v108, v33 offset:34320
	ds_read_b32 v109, v33 offset:34580
	ds_read_b32 v110, v33 offset:34840
	ds_read_b32 v111, v33 offset:35100
	s_mul_i32 s12, s21, 3
	s_add_u32 s12, s12, s28
	s_cmp_ge_u32 s12, 0xb00
	s_cbranch_scc1 .Lcv_wf2_l0_p1_rd_done
	ds_read_b32 v112, v33 offset:49920
	ds_read_b32 v113, v33 offset:50180
	ds_read_b32 v114, v33 offset:50440
	ds_read_b32 v115, v33 offset:50700
	ds_read_b32 v116, v33 offset:50960
	ds_read_b32 v117, v33 offset:51220
	ds_read_b32 v118, v33 offset:51480
	ds_read_b32 v119, v33 offset:51740
.Lcv_wf2_l0_p1_rd_done:
	s_waitcnt lgkmcnt(0)
	s_mov_b32 s12, s28
	s_lshr_b32 s13, s12, 5
	s_and_b32 s14, s12, 31
	s_mul_i32 s15, s14, 0xb0000
	s_lshl_b32 s16, s13, 7
	s_add_u32 s15, s15, s16
	s_add_u32 s30, s26, s15
	s_addc_u32 s31, s27, 0
	v_cvt_pk_bf16_f32 v72, v88, v89
	v_cvt_pk_bf16_f32 v73, v90, v91
	v_cvt_pk_bf16_f32 v74, v92, v93
	v_cvt_pk_bf16_f32 v75, v94, v95
	global_store_dwordx4 v35, v[72:75], s[30:31]
	s_mul_i32 s12, s21, 1
	s_add_u32 s12, s12, s28
	s_cmp_ge_u32 s12, 0xb00
	s_cbranch_scc1 .Lcv_wf2_l0_p1_st_done
	s_mul_i32 s12, s21, 1
	s_add_u32 s12, s12, s28
	s_lshr_b32 s13, s12, 5
	s_and_b32 s14, s12, 31
	s_mul_i32 s15, s14, 0xb0000
	s_lshl_b32 s16, s13, 7
	s_add_u32 s15, s15, s16
	s_add_u32 s30, s26, s15
	s_addc_u32 s31, s27, 0
	v_cvt_pk_bf16_f32 v76, v96, v97
	v_cvt_pk_bf16_f32 v77, v98, v99
	v_cvt_pk_bf16_f32 v78, v100, v101
	v_cvt_pk_bf16_f32 v79, v102, v103
	global_store_dwordx4 v35, v[76:79], s[30:31]
	s_mul_i32 s12, s21, 2
	s_add_u32 s12, s12, s28
	s_cmp_ge_u32 s12, 0xb00
	s_cbranch_scc1 .Lcv_wf2_l0_p1_st_done
	s_mul_i32 s12, s21, 2
	s_add_u32 s12, s12, s28
	s_lshr_b32 s13, s12, 5
	s_and_b32 s14, s12, 31
	s_mul_i32 s15, s14, 0xb0000
	s_lshl_b32 s16, s13, 7
	s_add_u32 s15, s15, s16
	s_add_u32 s30, s26, s15
	s_addc_u32 s31, s27, 0
	v_cvt_pk_bf16_f32 v80, v104, v105
	v_cvt_pk_bf16_f32 v81, v106, v107
	v_cvt_pk_bf16_f32 v82, v108, v109
	v_cvt_pk_bf16_f32 v83, v110, v111
	global_store_dwordx4 v35, v[80:83], s[30:31]
	s_mul_i32 s12, s21, 3
	s_add_u32 s12, s12, s28
	s_cmp_ge_u32 s12, 0xb00
	s_cbranch_scc1 .Lcv_wf2_l0_p1_st_done
	s_mul_i32 s12, s21, 3
	s_add_u32 s12, s12, s28
	s_lshr_b32 s13, s12, 5
	s_and_b32 s14, s12, 31
	s_mul_i32 s15, s14, 0xb0000
	s_lshl_b32 s16, s13, 7
	s_add_u32 s15, s15, s16
	s_add_u32 s30, s26, s15
	s_addc_u32 s31, s27, 0
	v_cvt_pk_bf16_f32 v84, v112, v113
	v_cvt_pk_bf16_f32 v85, v114, v115
	v_cvt_pk_bf16_f32 v86, v116, v117
	v_cvt_pk_bf16_f32 v87, v118, v119
	global_store_dwordx4 v35, v[84:87], s[30:31]
.Lcv_wf2_l0_p1_st_done:
	s_lshl_b32 s12, s21, 2
	s_add_u32 s28, s28, s12
	s_cmp_ge_u32 s28, 0xb00
	s_cbranch_scc0 .Lcv_wf2_l0_loop
.Lcv_wf2_l0_end:
	s_barrier
.LBB0_53:
	s_add_u32 s0, s54, 0x9200000
	s_addc_u32 s1, s55, 0
	v_writelane_b32 v249, s0, 26
	v_mov_b32_e32 v2, v248
	s_mov_b32 s6, s85
	v_writelane_b32 v249, s1, 27
	s_cmpk_gt_i32 s6, 0x7f
	s_cbranch_scc1 .LBB0_60
	v_and_b32_e32 v1, 63, v2
	v_ashrrev_i32_e32 v6, 6, v2
	v_ashrrev_i32_e32 v7, 3, v2
	v_lshlrev_b32_e32 v2, 3, v2
	v_and_b32_e32 v2, 56, v2
	v_lshl_add_u32 v5, v7, 2, 0
	s_movk_i32 s0, 0x104
	v_mul_u32_u24_e32 v9, 0x104, v2
	v_lshl_add_u32 v4, v1, 2, 0
	v_mov_b32_e32 v3, 0
	v_mul_lo_u32 v8, v6, s0
	v_add_u32_e32 v9, v5, v9
	s_lshl_b32 s7, s6, 6
	s_lshl_b32 s8, s56, 6
	s_movk_i32 s9, 0x50
	s_movk_i32 s10, 0x68
	v_add_u32_e32 v8, v4, v8
	s_mov_b32 s11, 0xe1a0
	v_lshlrev_b32_e32 v4, 1, v2
	v_mov_b32_e32 v5, v3
	v_add_u32_e32 v10, 0x400, v9
	s_branch .LBB0_56

; DI unsigned cvtpk(float lo, float hi) { unsigned r; asm volatile("v_cvt_pk_bf16_f32 %0, %1, %2" : "=v"(r) : "v"(lo), "v"(hi)); return r; }
; DI int ltid() { int t = threadIdx.x; asm volatile("" : "+v"(t)); return t; }
; DI int lbid() { int b = blockIdx.x; asm volatile("" : "+s"(b)); return b; }
; template <class Map>
; DI void conv_T(bf16_t* __restrict__ dst, const float* __restrict__ src, int K, int ldsrc, int nphys, Map map, const float* __restrict__ kscale, float* tile) {
;   const int tid = ltid(), ntn = nphys >> 6, ntiles = (K >> 6) * ntn;
;   for (int tl = lbid(); tl < ntiles; tl += gridDim.x) {
;     const int k0 = (tl / ntn) << 6, n0 = (tl % ntn) << 6;
;     const int nn = tid & 63, sc = map(n0 + nn);
; #pragma unroll
;     for (int i = 0; i < 8; ++i) { const int kk = i * 8 + (tid >> 6);
;       float v = sc >= 0 ? __builtin_nontemporal_load(&src[(size_t)(k0 + kk) * ldsrc + sc]) : 0.f;
;       if (kscale) v *= kscale[k0 + kk];
;       tile[kk * 65 + nn] = v; }
;     __syncthreads();
;     const int np = tid >> 3, ks = tid & 7;
;     float v[8];
; #pragma unroll
;     for (int j = 0; j < 8; ++j) v[j] = tile[(ks * 8 + j) * 65 + np];
;     u32x4 w = {cvtpk(v[0], v[1]), cvtpk(v[2], v[3]), cvtpk(v[4], v[5]), cvtpk(v[6], v[7])};
;     *(u32x4*)(dst + (size_t)(n0 + np) * K + k0 + ks * 8) = w;
;     __syncthreads();
;   }
; }
; DI void convert_layer(const Params& p, int l, float* tile) {
;     ...
;   for (int r = 0; r < 3; ++r)
;     conv_T((bf16_t*)(ws + O_WBR) + (size_t)r * 2048 * 1024, p.w_br + (size_t)(l * 3 + r) * 1024 * 2048, 1024, 2048, 2048, MapId{0}, nullptr, tile);
;   conv_T((bf16_t*)(ws + O_WO), p.w_o + (size_t)l * 2048 * 2048, 2048, 2048, 2048, MapId{0}, nullptr, tile);
;   conv_T((bf16_t*)(ws + O_WF1), p.w_f1 + (size_t)l * 2048 * 2 * DFF, 2048, 2 * DFF, 2 * DFF, MapF1{}, nullptr, tile);
;   conv_T((bf16_t*)(ws + O_WF2), p.w_f2 + (size_t)l * DFF * 2048, DFF, 2048, 2048, MapId{0}, nullptr, tile);
.LBB0_111:
	s_add_u32 s0, s54, 0x3c00000
	s_addc_u32 s1, s55, 0
	v_writelane_b32 v249, s0, 34
	v_mov_b32_e32 v2, v248
	s_mov_b32 s6, s85
	v_writelane_b32 v249, s1, 35
	s_branch .LBB0_118
.LBB0_118:
	s_add_u32 s0, s54, 0x4000000
	s_addc_u32 s1, s55, 0
	v_writelane_b32 v249, s0, 42
	v_mov_b32_e32 v2, v248
	s_mov_b32 s8, s85
	v_writelane_b32 v249, s1, 43
	s_branch .LBB0_125
.LBB0_125:
	s_add_u32 s0, s54, 0x4400000
	s_addc_u32 s1, s55, 0
	v_writelane_b32 v249, s0, 44
	v_mov_b32_e32 v2, v248
	s_mov_b32 s8, s85
	v_writelane_b32 v249, s1, 45
	s_branch .LBB0_132
.LBB0_132:
	s_add_u32 s0, s54, 0x4800000
	s_addc_u32 s1, s55, 0
	v_writelane_b32 v249, s0, 36
	v_mov_b32_e32 v2, v248
	s_mov_b32 s6, s85
	v_writelane_b32 v249, s1, 37
	s_branch .LBB0_139
.LBB0_139:
	s_add_u32 s0, s54, 0x5000000
	s_addc_u32 s1, s55, 0
	v_writelane_b32 v249, s0, 38
	v_mov_b32_e32 v2, v248
	s_mov_b32 s6, s85
	v_writelane_b32 v249, s1, 39
	s_branch .LBB0_146
.LBB0_146:
	s_add_u32 s0, s54, 0x7c00000
	s_addc_u32 s1, s55, 0
	v_writelane_b32 v249, s0, 40
	v_mov_b32_e32 v2, v248
	s_mov_b32 s6, s85
	v_writelane_b32 v249, s1, 41
	s_branch .LBB0_153

; DI int ltid() { int t = threadIdx.x; asm volatile("" : "+v"(t)); return t; }
; DI int lbid() { int b = blockIdx.x; asm volatile("" : "+s"(b)); return b; }
; template <class Map>
; DI void conv_T(bf16_t* __restrict__ dst, const float* __restrict__ src, int K, int ldsrc, int nphys, Map map, const float* __restrict__ kscale, float* tile) {
;   const int tid = ltid(), ntn = nphys >> 6, ntiles = (K >> 6) * ntn;
;   for (int tl = lbid(); tl < ntiles; tl += gridDim.x) {
;     const int k0 = (tl / ntn) << 6, n0 = (tl % ntn) << 6;
;     const int nn = tid & 63, sc = map(n0 + nn);
; #pragma unroll
;     for (int i = 0; i < 8; ++i) { const int kk = i * 8 + (tid >> 6);
;       float v = sc >= 0 ? __builtin_nontemporal_load(&src[(size_t)(k0 + kk) * ldsrc + sc]) : 0.f;
;       if (kscale) v *= kscale[k0 + kk];
;       tile[kk * 65 + nn] = v; }
.LBB0_2124:
	s_or_b64 exec, exec, s[0:1]
	v_mov_b32_e32 v0, v248
	s_mov_b32 s4, s85
	s_barrier
	v_readlane_b32 s18, v252, 21
	v_readlane_b32 s19, v252, 22
	v_readlane_b32 s20, v252, 40
	v_readlane_b32 s21, v251, 63
	v_lshrrev_b32_e32 v36, 6, v248
	v_and_b32_e32 v37, 63, v248
	v_mul_u32_u24_e32 v30, 0x104, v36
	v_lshl_add_u32 v30, v37, 2, v30
	v_add_u32_e32 v31, 0x10400, v30
	v_and_b32_e32 v36, 7, v248
	v_lshrrev_b32_e32 v37, 3, v248
	v_mul_u32_u24_e32 v32, 0x820, v36
	v_lshl_add_u32 v32, v37, 2, v32
	v_add_u32_e32 v33, 0x10400, v32
	v_readlane_b32 s22, v249, 16
	v_readlane_b32 s23, v249, 17
	s_sub_u32 s22, s22, 0xa0
	s_subb_u32 s23, s23, 0
	s_load_dwordx2 s[4:5], s[22:23], 0x20
	s_waitcnt lgkmcnt(0)
	s_add_u32 s4, s4, 0x70d0000
	s_addc_u32 s5, s5, 0
	s_add_u32 s6, s18, 0x0
	s_addc_u32 s7, s19, 0
	v_lshrrev_b32_e32 v36, 6, v248
	v_and_b32_e32 v37, 63, v248
	v_mov_b32_e32 v38, 0xe1a0
	v_mul_u32_u24_e32 v34, v36, v38
	v_lshl_add_u32 v34, v37, 2, v34
	v_lshrrev_b32_e32 v36, 3, v248
	v_and_b32_e32 v37, 7, v248
	v_mov_b32_e32 v38, 0x1000
	v_mul_u32_u24_e32 v35, v36, v38
	v_lshl_add_u32 v35, v37, 4, v35
	s_mov_b32 s8, s20
	s_cmp_ge_u32 s8, 0x1c00
	s_cbranch_scc1 .Lcv_win_l1_end
	s_mov_b32 s12, s8
	s_mul_i32 s13, s12, 0x4925
	s_lshr_b32 s13, s13, 22
	s_mul_i32 s14, s13, 224
	s_sub_u32 s14, s12, s14
	s_mul_i32 s15, s13, 0x386800
	s_lshl_b32 s16, s14, 8
	s_cmp_ge_u32 s14, 40
	s_cselect_b32 s12, 0x140, 0
	s_cmp_ge_u32 s14, 80
	s_cselect_b32 s12, 0x1a0, s12
	s_add_u32 s16, s16, s12
	s_add_u32 s15, s15, s16
	s_add_u32 s10, s4, s15
	s_addc_u32 s11, s5, 0
	global_load_dword v40, v34, s[10:11] nt
	s_add_u32 s10, s10, 0x70d00
	s_addc_u32 s11, s11, 0
	global_load_dword v41, v34, s[10:11] nt
	s_add_u32 s10, s10, 0x70d00
	s_addc_u32 s11, s11, 0
	global_load_dword v42, v34, s[10:11] nt
	s_add_u32 s10, s10, 0x70d00
	s_addc_u32 s11, s11, 0
	global_load_dword v43, v34, s[10:11] nt
	s_add_u32 s10, s10, 0x70d00
	s_addc_u32 s11, s11, 0
	global_load_dword v44, v34, s[10:11] nt
	s_add_u32 s10, s10, 0x70d00
	s_addc_u32 s11, s11, 0
	global_load_dword v45, v34, s[10:11] nt
	s_add_u32 s10, s10, 0x70d00
	s_addc_u32 s11, s11, 0
	global_load_dword v46, v34, s[10:11] nt
	s_add_u32 s10, s10, 0x70d00
	s_addc_u32 s11, s11, 0
	global_load_dword v47, v34, s[10:11] nt
	s_mul_i32 s12, s21, 1
	s_add_u32 s12, s12, s8
	s_cmp_ge_u32 s12, 0x1c00
	s_cbranch_scc1 .Lcv_win_l1_pro_done
	s_mul_i32 s12, s21, 1
	s_add_u32 s12, s12, s8
	s_mul_i32 s13, s12, 0x4925
	s_lshr_b32 s13, s13, 22
	s_mul_i32 s14, s13, 224
	s_sub_u32 s14, s12, s14
	s_mul_i32 s15, s13, 0x386800
	s_lshl_b32 s16, s14, 8
	s_cmp_ge_u32 s14, 40
	s_cselect_b32 s12, 0x140, 0
	s_cmp_ge_u32 s14, 80
	s_cselect_b32 s12, 0x1a0, s12
	s_add_u32 s16, s16, s12
	s_add_u32 s15, s15, s16
	s_add_u32 s10, s4, s15
	s_addc_u32 s11, s5, 0
	global_load_dword v48, v34, s[10:11] nt
	s_add_u32 s10, s10, 0x70d00
	s_addc_u32 s11, s11, 0
	global_load_dword v49, v34, s[10:11] nt
	s_add_u32 s10, s10, 0x70d00
	s_addc_u32 s11, s11, 0
	global_load_dword v50, v34, s[10:11] nt
	s_add_u32 s10, s10, 0x70d00
	s_addc_u32 s11, s11, 0
	global_load_dword v51, v34, s[10:11] nt
	s_add_u32 s10, s10, 0x70d00
	s_addc_u32 s11, s11, 0
	global_load_dword v52, v34, s[10:11] nt
	s_add_u32 s10, s10, 0x70d00
	s_addc_u32 s11, s11, 0
	global_load_dword v53, v34, s[10:11] nt
	s_add_u32 s10, s10, 0x70d00
	s_addc_u32 s11, s11, 0
	global_load_dword v54, v34, s[10:11] nt
	s_add_u32 s10, s10, 0x70d00
	s_addc_u32 s11, s11, 0
	global_load_dword v55, v34, s[10:11] nt
	s_mul_i32 s12, s21, 2
	s_add_u32 s12, s12, s8
	s_cmp_ge_u32 s12, 0x1c00
	s_cbranch_scc1 .Lcv_win_l1_pro_done
	s_mul_i32 s12, s21, 2
	s_add_u32 s12, s12, s8
	s_mul_i32 s13, s12, 0x4925
	s_lshr_b32 s13, s13, 22
	s_mul_i32 s14, s13, 224
	s_sub_u32 s14, s12, s14
	s_mul_i32 s15, s13, 0x386800
	s_lshl_b32 s16, s14, 8
	s_cmp_ge_u32 s14, 40
	s_cselect_b32 s12, 0x140, 0
	s_cmp_ge_u32 s14, 80
	s_cselect_b32 s12, 0x1a0, s12
	s_add_u32 s16, s16, s12
	s_add_u32 s15, s15, s16
	s_add_u32 s10, s4, s15
	s_addc_u32 s11, s5, 0
	global_load_dword v56, v34, s[10:11] nt
	s_add_u32 s10, s10, 0x70d00
	s_addc_u32 s11, s11, 0
	global_load_dword v57, v34, s[10:11] nt
	s_add_u32 s10, s10, 0x70d00
	s_addc_u32 s11, s11, 0
	global_load_dword v58, v34, s[10:11] nt
	s_add_u32 s10, s10, 0x70d00
	s_addc_u32 s11, s11, 0
	global_load_dword v59, v34, s[10:11] nt
	s_add_u32 s10, s10, 0x70d00
	s_addc_u32 s11, s11, 0
	global_load_dword v60, v34, s[10:11] nt
	s_add_u32 s10, s10, 0x70d00
	s_addc_u32 s11, s11, 0
	global_load_dword v61, v34, s[10:11] nt
	s_add_u32 s10, s10, 0x70d00
	s_addc_u32 s11, s11, 0
	global_load_dword v62, v34, s[10:11] nt
	s_add_u32 s10, s10, 0x70d00
	s_addc_u32 s11, s11, 0
	global_load_dword v63, v34, s[10:11] nt
	s_mul_i32 s12, s21, 3
	s_add_u32 s12, s12, s8
	s_cmp_ge_u32 s12, 0x1c00
	s_cbranch_scc1 .Lcv_win_l1_pro_done
	s_mul_i32 s12, s21, 3
	s_add_u32 s12, s12, s8
	s_mul_i32 s13, s12, 0x4925
	s_lshr_b32 s13, s13, 22
	s_mul_i32 s14, s13, 224
	s_sub_u32 s14, s12, s14
	s_mul_i32 s15, s13, 0x386800
	s_lshl_b32 s16, s14, 8
	s_cmp_ge_u32 s14, 40
	s_cselect_b32 s12, 0x140, 0
	s_cmp_ge_u32 s14, 80
	s_cselect_b32 s12, 0x1a0, s12
	s_add_u32 s16, s16, s12
	s_add_u32 s15, s15, s16
	s_add_u32 s10, s4, s15
	s_addc_u32 s11, s5, 0
	global_load_dword v64, v34, s[10:11] nt
	s_add_u32 s10, s10, 0x70d00
	s_addc_u32 s11, s11, 0
	global_load_dword v65, v34, s[10:11] nt
	s_add_u32 s10, s10, 0x70d00
	s_addc_u32 s11, s11, 0
	global_load_dword v66, v34, s[10:11] nt
	s_add_u32 s10, s10, 0x70d00
	s_addc_u32 s11, s11, 0
	global_load_dword v67, v34, s[10:11] nt
	s_add_u32 s10, s10, 0x70d00
	s_addc_u32 s11, s11, 0
	global_load_dword v68, v34, s[10:11] nt
	s_add_u32 s10, s10, 0x70d00
	s_addc_u32 s11, s11, 0
	global_load_dword v69, v34, s[10:11] nt
	s_add_u32 s10, s10, 0x70d00
	s_addc_u32 s11, s11, 0
	global_load_dword v70, v34, s[10:11] nt
	s_add_u32 s10, s10, 0x70d00
	s_addc_u32 s11, s11, 0
	global_load_dword v71, v34, s[10:11] nt

; DI int lbid() { int b = blockIdx.x; asm volatile("" : "+s"(b)); return b; }
; template <class Map>
; DI void conv_T(bf16_t* __restrict__ dst, const float* __restrict__ src, int K, int ldsrc, int nphys, Map map, const float* __restrict__ kscale, float* tile) {
;     ...
;   for (int tl = lbid(); tl < ntiles; tl += gridDim.x) {
;     const int k0 = (tl / ntn) << 6, n0 = (tl % ntn) << 6;
;     const int nn = tid & 63, sc = map(n0 + nn);
; #pragma unroll
;     for (int i = 0; i < 8; ++i) { const int kk = i * 8 + (tid >> 6);
;       float v = sc >= 0 ? __builtin_nontemporal_load(&src[(size_t)(k0 + kk) * ldsrc + sc]) : 0.f;
;       if (kscale) v *= kscale[k0 + kk];
;       tile[kk * 65 + nn] = v; }
.Lcv_win_l1_p0_after:
	ds_write_b32 v30, v40
	ds_write_b32 v30, v41 offset:2080
	ds_write_b32 v30, v42 offset:4160
	ds_write_b32 v30, v43 offset:6240
	ds_write_b32 v30, v44 offset:8320
	ds_write_b32 v30, v45 offset:10400
	ds_write_b32 v30, v46 offset:12480
	ds_write_b32 v30, v47 offset:14560
	s_mul_i32 s12, s21, 1
	s_add_u32 s12, s12, s8
	s_cmp_ge_u32 s12, 0x1c00
	s_cbranch_scc1 .Lcv_win_l1_p0_wr_done
	ds_write_b32 v30, v48 offset:16640
	ds_write_b32 v30, v49 offset:18720
	ds_write_b32 v30, v50 offset:20800
	ds_write_b32 v30, v51 offset:22880
	ds_write_b32 v30, v52 offset:24960
	ds_write_b32 v30, v53 offset:27040
	ds_write_b32 v30, v54 offset:29120
	ds_write_b32 v30, v55 offset:31200
	s_mul_i32 s12, s21, 2
	s_add_u32 s12, s12, s8
	s_cmp_ge_u32 s12, 0x1c00
	s_cbranch_scc1 .Lcv_win_l1_p0_wr_done
	ds_write_b32 v30, v56 offset:33280
	ds_write_b32 v30, v57 offset:35360
	ds_write_b32 v30, v58 offset:37440
	ds_write_b32 v30, v59 offset:39520
	ds_write_b32 v30, v60 offset:41600
	ds_write_b32 v30, v61 offset:43680
	ds_write_b32 v30, v62 offset:45760
	ds_write_b32 v30, v63 offset:47840
	s_mul_i32 s12, s21, 3
	s_add_u32 s12, s12, s8
	s_cmp_ge_u32 s12, 0x1c00
	s_cbranch_scc1 .Lcv_win_l1_p0_wr_done
	ds_write_b32 v30, v64 offset:49920
	ds_write_b32 v30, v65 offset:52000
	ds_write_b32 v30, v66 offset:54080
	ds_write_b32 v30, v67 offset:56160
	ds_write_b32 v30, v68 offset:58240
	ds_write_b32 v30, v69 offset:60320
	ds_write_b32 v30, v70 offset:62400
	ds_write_b32 v30, v71 offset:64480
.Lcv_win_l1_p0_wr_done:
	s_mul_i32 s12, s21, 4
	s_add_u32 s12, s12, s8
	s_cmp_ge_u32 s12, 0x1c00
	s_cbranch_scc1 .Lcv_win_l1_p0_pf_done
	s_mul_i32 s12, s21, 4
	s_add_u32 s12, s12, s8
	s_mul_i32 s13, s12, 0x4925
	s_lshr_b32 s13, s13, 22
	s_mul_i32 s14, s13, 224
	s_sub_u32 s14, s12, s14
	s_mul_i32 s15, s13, 0x386800
	s_lshl_b32 s16, s14, 8
	s_cmp_ge_u32 s14, 40
	s_cselect_b32 s12, 0x140, 0
	s_cmp_ge_u32 s14, 80
	s_cselect_b32 s12, 0x1a0, s12
	s_add_u32 s16, s16, s12
	s_add_u32 s15, s15, s16
	s_add_u32 s10, s4, s15
	s_addc_u32 s11, s5, 0
	global_load_dword v88, v34, s[10:11] nt
	s_add_u32 s10, s10, 0x70d00
	s_addc_u32 s11, s11, 0
	global_load_dword v89, v34, s[10:11] nt
	s_add_u32 s10, s10, 0x70d00
	s_addc_u32 s11, s11, 0
	global_load_dword v90, v34, s[10:11] nt
	s_add_u32 s10, s10, 0x70d00
	s_addc_u32 s11, s11, 0
	global_load_dword v91, v34, s[10:11] nt
	s_add_u32 s10, s10, 0x70d00
	s_addc_u32 s11, s11, 0
	global_load_dword v92, v34, s[10:11] nt
	s_add_u32 s10, s10, 0x70d00
	s_addc_u32 s11, s11, 0
	global_load_dword v93, v34, s[10:11] nt
	s_add_u32 s10, s10, 0x70d00
	s_addc_u32 s11, s11, 0
	global_load_dword v94, v34, s[10:11] nt
	s_add_u32 s10, s10, 0x70d00
	s_addc_u32 s11, s11, 0
	global_load_dword v95, v34, s[10:11] nt
	s_mul_i32 s12, s21, 5
	s_add_u32 s12, s12, s8
	s_cmp_ge_u32 s12, 0x1c00
	s_cbranch_scc1 .Lcv_win_l1_p0_pf_done
	s_mul_i32 s12, s21, 5
	s_add_u32 s12, s12, s8
	s_mul_i32 s13, s12, 0x4925
	s_lshr_b32 s13, s13, 22
	s_mul_i32 s14, s13, 224
	s_sub_u32 s14, s12, s14
	s_mul_i32 s15, s13, 0x386800
	s_lshl_b32 s16, s14, 8
	s_cmp_ge_u32 s14, 40
	s_cselect_b32 s12, 0x140, 0
	s_cmp_ge_u32 s14, 80
	s_cselect_b32 s12, 0x1a0, s12
	s_add_u32 s16, s16, s12
	s_add_u32 s15, s15, s16
	s_add_u32 s10, s4, s15
	s_addc_u32 s11, s5, 0
	global_load_dword v96, v34, s[10:11] nt
	s_add_u32 s10, s10, 0x70d00
	s_addc_u32 s11, s11, 0
	global_load_dword v97, v34, s[10:11] nt
	s_add_u32 s10, s10, 0x70d00
	s_addc_u32 s11, s11, 0
	global_load_dword v98, v34, s[10:11] nt
	s_add_u32 s10, s10, 0x70d00
	s_addc_u32 s11, s11, 0
	global_load_dword v99, v34, s[10:11] nt
	s_add_u32 s10, s10, 0x70d00
	s_addc_u32 s11, s11, 0
	global_load_dword v100, v34, s[10:11] nt
	s_add_u32 s10, s10, 0x70d00
	s_addc_u32 s11, s11, 0
	global_load_dword v101, v34, s[10:11] nt
	s_add_u32 s10, s10, 0x70d00
	s_addc_u32 s11, s11, 0
	global_load_dword v102, v34, s[10:11] nt
	s_add_u32 s10, s10, 0x70d00
	s_addc_u32 s11, s11, 0
	global_load_dword v103, v34, s[10:11] nt
	s_mul_i32 s12, s21, 6
	s_add_u32 s12, s12, s8
	s_cmp_ge_u32 s12, 0x1c00
	s_cbranch_scc1 .Lcv_win_l1_p0_pf_done
	s_mul_i32 s12, s21, 6
	s_add_u32 s12, s12, s8
	s_mul_i32 s13, s12, 0x4925
	s_lshr_b32 s13, s13, 22
	s_mul_i32 s14, s13, 224
	s_sub_u32 s14, s12, s14
	s_mul_i32 s15, s13, 0x386800
	s_lshl_b32 s16, s14, 8
	s_cmp_ge_u32 s14, 40
	s_cselect_b32 s12, 0x140, 0
	s_cmp_ge_u32 s14, 80
	s_cselect_b32 s12, 0x1a0, s12
	s_add_u32 s16, s16, s12
	s_add_u32 s15, s15, s16
	s_add_u32 s10, s4, s15
	s_addc_u32 s11, s5, 0
	global_load_dword v104, v34, s[10:11] nt
	s_add_u32 s10, s10, 0x70d00
	s_addc_u32 s11, s11, 0
	global_load_dword v105, v34, s[10:11] nt
	s_add_u32 s10, s10, 0x70d00
	s_addc_u32 s11, s11, 0
	global_load_dword v106, v34, s[10:11] nt
	s_add_u32 s10, s10, 0x70d00
	s_addc_u32 s11, s11, 0
	global_load_dword v107, v34, s[10:11] nt
	s_add_u32 s10, s10, 0x70d00
	s_addc_u32 s11, s11, 0
	global_load_dword v108, v34, s[10:11] nt
	s_add_u32 s10, s10, 0x70d00
	s_addc_u32 s11, s11, 0
	global_load_dword v109, v34, s[10:11] nt
	s_add_u32 s10, s10, 0x70d00
	s_addc_u32 s11, s11, 0
	global_load_dword v110, v34, s[10:11] nt
	s_add_u32 s10, s10, 0x70d00
	s_addc_u32 s11, s11, 0
	global_load_dword v111, v34, s[10:11] nt
	s_mul_i32 s12, s21, 7
	s_add_u32 s12, s12, s8
	s_cmp_ge_u32 s12, 0x1c00
	s_cbranch_scc1 .Lcv_win_l1_p0_pf_done
	s_mul_i32 s12, s21, 7
	s_add_u32 s12, s12, s8
	s_mul_i32 s13, s12, 0x4925
	s_lshr_b32 s13, s13, 22
	s_mul_i32 s14, s13, 224
	s_sub_u32 s14, s12, s14
	s_mul_i32 s15, s13, 0x386800
	s_lshl_b32 s16, s14, 8
	s_cmp_ge_u32 s14, 40
	s_cselect_b32 s12, 0x140, 0
	s_cmp_ge_u32 s14, 80
	s_cselect_b32 s12, 0x1a0, s12
	s_add_u32 s16, s16, s12
	s_add_u32 s15, s15, s16
	s_add_u32 s10, s4, s15
	s_addc_u32 s11, s5, 0
	global_load_dword v112, v34, s[10:11] nt
	s_add_u32 s10, s10, 0x70d00
	s_addc_u32 s11, s11, 0
	global_load_dword v113, v34, s[10:11] nt
	s_add_u32 s10, s10, 0x70d00
	s_addc_u32 s11, s11, 0
	global_load_dword v114, v34, s[10:11] nt
	s_add_u32 s10, s10, 0x70d00
	s_addc_u32 s11, s11, 0
	global_load_dword v115, v34, s[10:11] nt
	s_add_u32 s10, s10, 0x70d00
	s_addc_u32 s11, s11, 0
	global_load_dword v116, v34, s[10:11] nt
	s_add_u32 s10, s10, 0x70d00
	s_addc_u32 s11, s11, 0
	global_load_dword v117, v34, s[10:11] nt
	s_add_u32 s10, s10, 0x70d00
	s_addc_u32 s11, s11, 0
	global_load_dword v118, v34, s[10:11] nt
	s_add_u32 s10, s10, 0x70d00
	s_addc_u32 s11, s11, 0
	global_load_dword v119, v34, s[10:11] nt

; DI unsigned cvtpk(float lo, float hi) { unsigned r; asm volatile("v_cvt_pk_bf16_f32 %0, %1, %2" : "=v"(r) : "v"(lo), "v"(hi)); return r; }
; DI int lbid() { int b = blockIdx.x; asm volatile("" : "+s"(b)); return b; }
; template <class Map>
; DI void conv_T(bf16_t* __restrict__ dst, const float* __restrict__ src, int K, int ldsrc, int nphys, Map map, const float* __restrict__ kscale, float* tile) {
;     ...
;   for (int tl = lbid(); tl < ntiles; tl += gridDim.x) {
;     const int k0 = (tl / ntn) << 6, n0 = (tl % ntn) << 6;
;     const int nn = tid & 63, sc = map(n0 + nn);
; #pragma unroll
;     for (int i = 0; i < 8; ++i) { const int kk = i * 8 + (tid >> 6);
;       float v = sc >= 0 ? __builtin_nontemporal_load(&src[(size_t)(k0 + kk) * ldsrc + sc]) : 0.f;
;       if (kscale) v *= kscale[k0 + kk];
;       tile[kk * 65 + nn] = v; }
;     __syncthreads();
;     const int np = tid >> 3, ks = tid & 7;
;     float v[8];
; #pragma unroll
;     for (int j = 0; j < 8; ++j) v[j] = tile[(ks * 8 + j) * 65 + np];
;     u32x4 w = {cvtpk(v[0], v[1]), cvtpk(v[2], v[3]), cvtpk(v[4], v[5]), cvtpk(v[6], v[7])};
;     *(u32x4*)(dst + (size_t)(n0 + np) * K + k0 + ks * 8) = w;
;     __syncthreads();
.Lcv_win_l1_p0_rd_done:
	s_waitcnt lgkmcnt(0)
	s_mov_b32 s12, s8
	s_mul_i32 s13, s12, 0x4925
	s_lshr_b32 s13, s13, 22
	s_mul_i32 s14, s13, 224
	s_sub_u32 s14, s12, s14
	s_mul_i32 s15, s14, 0x40000
	s_lshl_b32 s16, s13, 7
	s_add_u32 s15, s15, s16
	s_add_u32 s10, s6, s15
	s_addc_u32 s11, s7, 0
	v_cvt_pk_bf16_f32 v72, v40, v41
	v_cvt_pk_bf16_f32 v73, v42, v43
	v_cvt_pk_bf16_f32 v74, v44, v45
	v_cvt_pk_bf16_f32 v75, v46, v47
	global_store_dwordx4 v35, v[72:75], s[10:11]
	s_mul_i32 s12, s21, 1
	s_add_u32 s12, s12, s8
	s_cmp_ge_u32 s12, 0x1c00
	s_cbranch_scc1 .Lcv_win_l1_p0_st_done
	s_mul_i32 s12, s21, 1
	s_add_u32 s12, s12, s8
	s_mul_i32 s13, s12, 0x4925
	s_lshr_b32 s13, s13, 22
	s_mul_i32 s14, s13, 224
	s_sub_u32 s14, s12, s14
	s_mul_i32 s15, s14, 0x40000
	s_lshl_b32 s16, s13, 7
	s_add_u32 s15, s15, s16
	s_add_u32 s10, s6, s15
	s_addc_u32 s11, s7, 0
	v_cvt_pk_bf16_f32 v76, v48, v49
	v_cvt_pk_bf16_f32 v77, v50, v51
	v_cvt_pk_bf16_f32 v78, v52, v53
	v_cvt_pk_bf16_f32 v79, v54, v55
	global_store_dwordx4 v35, v[76:79], s[10:11]
	s_mul_i32 s12, s21, 2
	s_add_u32 s12, s12, s8
	s_cmp_ge_u32 s12, 0x1c00
	s_cbranch_scc1 .Lcv_win_l1_p0_st_done
	s_mul_i32 s12, s21, 2
	s_add_u32 s12, s12, s8
	s_mul_i32 s13, s12, 0x4925
	s_lshr_b32 s13, s13, 22
	s_mul_i32 s14, s13, 224
	s_sub_u32 s14, s12, s14
	s_mul_i32 s15, s14, 0x40000
	s_lshl_b32 s16, s13, 7
	s_add_u32 s15, s15, s16
	s_add_u32 s10, s6, s15
	s_addc_u32 s11, s7, 0
	v_cvt_pk_bf16_f32 v80, v56, v57
	v_cvt_pk_bf16_f32 v81, v58, v59
	v_cvt_pk_bf16_f32 v82, v60, v61
	v_cvt_pk_bf16_f32 v83, v62, v63
	global_store_dwordx4 v35, v[80:83], s[10:11]
	s_mul_i32 s12, s21, 3
	s_add_u32 s12, s12, s8
	s_cmp_ge_u32 s12, 0x1c00
	s_cbranch_scc1 .Lcv_win_l1_p0_st_done
	s_mul_i32 s12, s21, 3
	s_add_u32 s12, s12, s8
	s_mul_i32 s13, s12, 0x4925
	s_lshr_b32 s13, s13, 22
	s_mul_i32 s14, s13, 224
	s_sub_u32 s14, s12, s14
	s_mul_i32 s15, s14, 0x40000
	s_lshl_b32 s16, s13, 7
	s_add_u32 s15, s15, s16
	s_add_u32 s10, s6, s15
	s_addc_u32 s11, s7, 0
	v_cvt_pk_bf16_f32 v84, v64, v65
	v_cvt_pk_bf16_f32 v85, v66, v67
	v_cvt_pk_bf16_f32 v86, v68, v69
	v_cvt_pk_bf16_f32 v87, v70, v71
	global_store_dwordx4 v35, v[84:87], s[10:11]
.Lcv_win_l1_p0_st_done:
	s_lshl_b32 s12, s21, 2
	s_add_u32 s8, s8, s12
	s_cmp_ge_u32 s8, 0x1c00
	s_cbranch_scc1 .Lcv_win_l1_end
	s_waitcnt vmcnt(4)
.Lcv_win_l1_p1_after:
	ds_write_b32 v31, v88
	ds_write_b32 v31, v89 offset:2080
	ds_write_b32 v31, v90 offset:4160
	ds_write_b32 v31, v91 offset:6240
	ds_write_b32 v31, v92 offset:8320
	ds_write_b32 v31, v93 offset:10400
	ds_write_b32 v31, v94 offset:12480
	ds_write_b32 v31, v95 offset:14560
	s_mul_i32 s12, s21, 1
	s_add_u32 s12, s12, s8
	s_cmp_ge_u32 s12, 0x1c00
	s_cbranch_scc1 .Lcv_win_l1_p1_wr_done
	ds_write_b32 v31, v96 offset:16640
	ds_write_b32 v31, v97 offset:18720
	ds_write_b32 v31, v98 offset:20800
	ds_write_b32 v31, v99 offset:22880
	ds_write_b32 v31, v100 offset:24960
	ds_write_b32 v31, v101 offset:27040
	ds_write_b32 v31, v102 offset:29120
	ds_write_b32 v31, v103 offset:31200
	s_mul_i32 s12, s21, 2
	s_add_u32 s12, s12, s8
	s_cmp_ge_u32 s12, 0x1c00
	s_cbranch_scc1 .Lcv_win_l1_p1_wr_done
	ds_write_b32 v31, v104 offset:33280
	ds_write_b32 v31, v105 offset:35360
	ds_write_b32 v31, v106 offset:37440
	ds_write_b32 v31, v107 offset:39520
	ds_write_b32 v31, v108 offset:41600
	ds_write_b32 v31, v109 offset:43680
	ds_write_b32 v31, v110 offset:45760
	ds_write_b32 v31, v111 offset:47840
	s_mul_i32 s12, s21, 3
	s_add_u32 s12, s12, s8
	s_cmp_ge_u32 s12, 0x1c00
	s_cbranch_scc1 .Lcv_win_l1_p1_wr_done
	ds_write_b32 v31, v112 offset:49920
	ds_write_b32 v31, v113 offset:52000
	ds_write_b32 v31, v114 offset:54080
	ds_write_b32 v31, v115 offset:56160
	ds_write_b32 v31, v116 offset:58240
	ds_write_b32 v31, v117 offset:60320
	ds_write_b32 v31, v118 offset:62400
	ds_write_b32 v31, v119 offset:64480
.Lcv_win_l1_p1_wr_done:
	s_mul_i32 s12, s21, 4
	s_add_u32 s12, s12, s8
	s_cmp_ge_u32 s12, 0x1c00
	s_cbranch_scc1 .Lcv_win_l1_p1_pf_done
	s_mul_i32 s12, s21, 4
	s_add_u32 s12, s12, s8
	s_mul_i32 s13, s12, 0x4925
	s_lshr_b32 s13, s13, 22
	s_mul_i32 s14, s13, 224
	s_sub_u32 s14, s12, s14
	s_mul_i32 s15, s13, 0x386800
	s_lshl_b32 s16, s14, 8
	s_cmp_ge_u32 s14, 40
	s_cselect_b32 s12, 0x140, 0
	s_cmp_ge_u32 s14, 80
	s_cselect_b32 s12, 0x1a0, s12
	s_add_u32 s16, s16, s12
	s_add_u32 s15, s15, s16
	s_add_u32 s10, s4, s15
	s_addc_u32 s11, s5, 0
	global_load_dword v40, v34, s[10:11] nt
	s_add_u32 s10, s10, 0x70d00
	s_addc_u32 s11, s11, 0
	global_load_dword v41, v34, s[10:11] nt
	s_add_u32 s10, s10, 0x70d00
	s_addc_u32 s11, s11, 0
	global_load_dword v42, v34, s[10:11] nt
	s_add_u32 s10, s10, 0x70d00
	s_addc_u32 s11, s11, 0
	global_load_dword v43, v34, s[10:11] nt
	s_add_u32 s10, s10, 0x70d00
	s_addc_u32 s11, s11, 0
	global_load_dword v44, v34, s[10:11] nt
	s_add_u32 s10, s10, 0x70d00
	s_addc_u32 s11, s11, 0
	global_load_dword v45, v34, s[10:11] nt
	s_add_u32 s10, s10, 0x70d00
	s_addc_u32 s11, s11, 0
	global_load_dword v46, v34, s[10:11] nt
	s_add_u32 s10, s10, 0x70d00
	s_addc_u32 s11, s11, 0
	global_load_dword v47, v34, s[10:11] nt
	s_mul_i32 s12, s21, 5
	s_add_u32 s12, s12, s8
	s_cmp_ge_u32 s12, 0x1c00
	s_cbranch_scc1 .Lcv_win_l1_p1_pf_done
; DI int lbid() { int b = blockIdx.x; asm volatile("" : "+s"(b)); return b; }
; template <class Map>
; DI void conv_T(bf16_t* __restrict__ dst, const float* __restrict__ src, int K, int ldsrc, int nphys, Map map, const float* __restrict__ kscale, float* tile) {
;     ...
;   for (int tl = lbid(); tl < ntiles; tl += gridDim.x) {
;     const int k0 = (tl / ntn) << 6, n0 = (tl % ntn) << 6;
;     const int nn = tid & 63, sc = map(n0 + nn);
; #pragma unroll
;     for (int i = 0; i < 8; ++i) { const int kk = i * 8 + (tid >> 6);
;       float v = sc >= 0 ? __builtin_nontemporal_load(&src[(size_t)(k0 + kk) * ldsrc + sc]) : 0.f;
;       if (kscale) v *= kscale[k0 + kk];
;       tile[kk * 65 + nn] = v; }
	s_mul_i32 s12, s21, 5
	s_add_u32 s12, s12, s8
	s_mul_i32 s13, s12, 0x4925
	s_lshr_b32 s13, s13, 22
	s_mul_i32 s14, s13, 224
	s_sub_u32 s14, s12, s14
	s_mul_i32 s15, s13, 0x386800
	s_lshl_b32 s16, s14, 8
	s_cmp_ge_u32 s14, 40
	s_cselect_b32 s12, 0x140, 0
	s_cmp_ge_u32 s14, 80
	s_cselect_b32 s12, 0x1a0, s12
	s_add_u32 s16, s16, s12
	s_add_u32 s15, s15, s16
	s_add_u32 s10, s4, s15
	s_addc_u32 s11, s5, 0
	global_load_dword v48, v34, s[10:11] nt
	s_add_u32 s10, s10, 0x70d00
	s_addc_u32 s11, s11, 0
	global_load_dword v49, v34, s[10:11] nt
	s_add_u32 s10, s10, 0x70d00
	s_addc_u32 s11, s11, 0
	global_load_dword v50, v34, s[10:11] nt
	s_add_u32 s10, s10, 0x70d00
	s_addc_u32 s11, s11, 0
	global_load_dword v51, v34, s[10:11] nt
	s_add_u32 s10, s10, 0x70d00
	s_addc_u32 s11, s11, 0
	global_load_dword v52, v34, s[10:11] nt
	s_add_u32 s10, s10, 0x70d00
	s_addc_u32 s11, s11, 0
	global_load_dword v53, v34, s[10:11] nt
	s_add_u32 s10, s10, 0x70d00
	s_addc_u32 s11, s11, 0
	global_load_dword v54, v34, s[10:11] nt
	s_add_u32 s10, s10, 0x70d00
	s_addc_u32 s11, s11, 0
	global_load_dword v55, v34, s[10:11] nt
	s_mul_i32 s12, s21, 6
	s_add_u32 s12, s12, s8
	s_cmp_ge_u32 s12, 0x1c00
	s_cbranch_scc1 .Lcv_win_l1_p1_pf_done
	s_mul_i32 s12, s21, 6
	s_add_u32 s12, s12, s8
	s_mul_i32 s13, s12, 0x4925
	s_lshr_b32 s13, s13, 22
	s_mul_i32 s14, s13, 224
	s_sub_u32 s14, s12, s14
	s_mul_i32 s15, s13, 0x386800
	s_lshl_b32 s16, s14, 8
	s_cmp_ge_u32 s14, 40
	s_cselect_b32 s12, 0x140, 0
	s_cmp_ge_u32 s14, 80
	s_cselect_b32 s12, 0x1a0, s12
	s_add_u32 s16, s16, s12
	s_add_u32 s15, s15, s16
	s_add_u32 s10, s4, s15
	s_addc_u32 s11, s5, 0
	global_load_dword v56, v34, s[10:11] nt
	s_add_u32 s10, s10, 0x70d00
	s_addc_u32 s11, s11, 0
	global_load_dword v57, v34, s[10:11] nt
	s_add_u32 s10, s10, 0x70d00
	s_addc_u32 s11, s11, 0
	global_load_dword v58, v34, s[10:11] nt
	s_add_u32 s10, s10, 0x70d00
	s_addc_u32 s11, s11, 0
	global_load_dword v59, v34, s[10:11] nt
	s_add_u32 s10, s10, 0x70d00
	s_addc_u32 s11, s11, 0
	global_load_dword v60, v34, s[10:11] nt
	s_add_u32 s10, s10, 0x70d00
	s_addc_u32 s11, s11, 0
	global_load_dword v61, v34, s[10:11] nt
	s_add_u32 s10, s10, 0x70d00
	s_addc_u32 s11, s11, 0
	global_load_dword v62, v34, s[10:11] nt
	s_add_u32 s10, s10, 0x70d00
	s_addc_u32 s11, s11, 0
	global_load_dword v63, v34, s[10:11] nt
	s_mul_i32 s12, s21, 7
	s_add_u32 s12, s12, s8
	s_cmp_ge_u32 s12, 0x1c00
	s_cbranch_scc1 .Lcv_win_l1_p1_pf_done
	s_mul_i32 s12, s21, 7
	s_add_u32 s12, s12, s8
	s_mul_i32 s13, s12, 0x4925
	s_lshr_b32 s13, s13, 22
	s_mul_i32 s14, s13, 224
	s_sub_u32 s14, s12, s14
	s_mul_i32 s15, s13, 0x386800
	s_lshl_b32 s16, s14, 8
	s_cmp_ge_u32 s14, 40
	s_cselect_b32 s12, 0x140, 0
	s_cmp_ge_u32 s14, 80
	s_cselect_b32 s12, 0x1a0, s12
	s_add_u32 s16, s16, s12
	s_add_u32 s15, s15, s16
	s_add_u32 s10, s4, s15
	s_addc_u32 s11, s5, 0
	global_load_dword v64, v34, s[10:11] nt
	s_add_u32 s10, s10, 0x70d00
	s_addc_u32 s11, s11, 0
	global_load_dword v65, v34, s[10:11] nt
	s_add_u32 s10, s10, 0x70d00
	s_addc_u32 s11, s11, 0
	global_load_dword v66, v34, s[10:11] nt
	s_add_u32 s10, s10, 0x70d00
	s_addc_u32 s11, s11, 0
	global_load_dword v67, v34, s[10:11] nt
	s_add_u32 s10, s10, 0x70d00
	s_addc_u32 s11, s11, 0
	global_load_dword v68, v34, s[10:11] nt
	s_add_u32 s10, s10, 0x70d00
	s_addc_u32 s11, s11, 0
	global_load_dword v69, v34, s[10:11] nt
	s_add_u32 s10, s10, 0x70d00
	s_addc_u32 s11, s11, 0
	global_load_dword v70, v34, s[10:11] nt
	s_add_u32 s10, s10, 0x70d00
	s_addc_u32 s11, s11, 0
	global_load_dword v71, v34, s[10:11] nt
; DI unsigned cvtpk(float lo, float hi) { unsigned r; asm volatile("v_cvt_pk_bf16_f32 %0, %1, %2" : "=v"(r) : "v"(lo), "v"(hi)); return r; }
; template <class Map>
; DI void conv_T(bf16_t* __restrict__ dst, const float* __restrict__ src, int K, int ldsrc, int nphys, Map map, const float* __restrict__ kscale, float* tile) {
;     ...
;     __syncthreads();
;     const int np = tid >> 3, ks = tid & 7;
;     float v[8];
; #pragma unroll
;     for (int j = 0; j < 8; ++j) v[j] = tile[(ks * 8 + j) * 65 + np];
;     u32x4 w = {cvtpk(v[0], v[1]), cvtpk(v[2], v[3]), cvtpk(v[4], v[5]), cvtpk(v[6], v[7])};
;     *(u32x4*)(dst + (size_t)(n0 + np) * K + k0 + ks * 8) = w;
;     __syncthreads();
.Lcv_win_l1_p1_pf_done:
	s_waitcnt lgkmcnt(0)
	s_barrier
	ds_read_b32 v88, v33
	ds_read_b32 v89, v33 offset:260
	ds_read_b32 v90, v33 offset:520
	ds_read_b32 v91, v33 offset:780
	ds_read_b32 v92, v33 offset:1040
	ds_read_b32 v93, v33 offset:1300
	ds_read_b32 v94, v33 offset:1560
	ds_read_b32 v95, v33 offset:1820
	s_mul_i32 s12, s21, 1
	s_add_u32 s12, s12, s8
	s_cmp_ge_u32 s12, 0x1c00
	s_cbranch_scc1 .Lcv_win_l1_p1_rd_done
	ds_read_b32 v96, v33 offset:16640
	ds_read_b32 v97, v33 offset:16900
	ds_read_b32 v98, v33 offset:17160
	ds_read_b32 v99, v33 offset:17420
	ds_read_b32 v100, v33 offset:17680
	ds_read_b32 v101, v33 offset:17940
	ds_read_b32 v102, v33 offset:18200
	ds_read_b32 v103, v33 offset:18460
	s_mul_i32 s12, s21, 2
	s_add_u32 s12, s12, s8
	s_cmp_ge_u32 s12, 0x1c00
	s_cbranch_scc1 .Lcv_win_l1_p1_rd_done
	ds_read_b32 v104, v33 offset:33280
	ds_read_b32 v105, v33 offset:33540
	ds_read_b32 v106, v33 offset:33800
	ds_read_b32 v107, v33 offset:34060
	ds_read_b32 v108, v33 offset:34320
	ds_read_b32 v109, v33 offset:34580
	ds_read_b32 v110, v33 offset:34840
	ds_read_b32 v111, v33 offset:35100
	s_mul_i32 s12, s21, 3
	s_add_u32 s12, s12, s8
	s_cmp_ge_u32 s12, 0x1c00
	s_cbranch_scc1 .Lcv_win_l1_p1_rd_done
	ds_read_b32 v112, v33 offset:49920
	ds_read_b32 v113, v33 offset:50180
	ds_read_b32 v114, v33 offset:50440
	ds_read_b32 v115, v33 offset:50700
	ds_read_b32 v116, v33 offset:50960
	ds_read_b32 v117, v33 offset:51220
	ds_read_b32 v118, v33 offset:51480
	ds_read_b32 v119, v33 offset:51740
.Lcv_win_l1_p1_rd_done:
	s_waitcnt lgkmcnt(0)
	s_mov_b32 s12, s8
	s_mul_i32 s13, s12, 0x4925
	s_lshr_b32 s13, s13, 22
	s_mul_i32 s14, s13, 224
	s_sub_u32 s14, s12, s14
	s_mul_i32 s15, s14, 0x40000
	s_lshl_b32 s16, s13, 7
	s_add_u32 s15, s15, s16
	s_add_u32 s10, s6, s15
	s_addc_u32 s11, s7, 0
	v_cvt_pk_bf16_f32 v72, v88, v89
	v_cvt_pk_bf16_f32 v73, v90, v91
	v_cvt_pk_bf16_f32 v74, v92, v93
	v_cvt_pk_bf16_f32 v75, v94, v95
	global_store_dwordx4 v35, v[72:75], s[10:11]
	s_mul_i32 s12, s21, 1
	s_add_u32 s12, s12, s8
	s_cmp_ge_u32 s12, 0x1c00
	s_cbranch_scc1 .Lcv_win_l1_p1_st_done
	s_mul_i32 s12, s21, 1
	s_add_u32 s12, s12, s8
	s_mul_i32 s13, s12, 0x4925
	s_lshr_b32 s13, s13, 22
	s_mul_i32 s14, s13, 224
	s_sub_u32 s14, s12, s14
	s_mul_i32 s15, s14, 0x40000
	s_lshl_b32 s16, s13, 7
	s_add_u32 s15, s15, s16
	s_add_u32 s10, s6, s15
	s_addc_u32 s11, s7, 0
	v_cvt_pk_bf16_f32 v76, v96, v97
	v_cvt_pk_bf16_f32 v77, v98, v99
	v_cvt_pk_bf16_f32 v78, v100, v101
	v_cvt_pk_bf16_f32 v79, v102, v103
	global_store_dwordx4 v35, v[76:79], s[10:11]
	s_mul_i32 s12, s21, 2
	s_add_u32 s12, s12, s8
	s_cmp_ge_u32 s12, 0x1c00
	s_cbranch_scc1 .Lcv_win_l1_p1_st_done
	s_mul_i32 s12, s21, 2
	s_add_u32 s12, s12, s8
	s_mul_i32 s13, s12, 0x4925
	s_lshr_b32 s13, s13, 22
	s_mul_i32 s14, s13, 224
	s_sub_u32 s14, s12, s14
	s_mul_i32 s15, s14, 0x40000
	s_lshl_b32 s16, s13, 7
	s_add_u32 s15, s15, s16
	s_add_u32 s10, s6, s15
	s_addc_u32 s11, s7, 0
	v_cvt_pk_bf16_f32 v80, v104, v105
	v_cvt_pk_bf16_f32 v81, v106, v107
	v_cvt_pk_bf16_f32 v82, v108, v109
	v_cvt_pk_bf16_f32 v83, v110, v111
	global_store_dwordx4 v35, v[80:83], s[10:11]
	s_mul_i32 s12, s21, 3
	s_add_u32 s12, s12, s8
	s_cmp_ge_u32 s12, 0x1c00
	s_cbranch_scc1 .Lcv_win_l1_p1_st_done
	s_mul_i32 s12, s21, 3
	s_add_u32 s12, s12, s8
	s_mul_i32 s13, s12, 0x4925
	s_lshr_b32 s13, s13, 22
	s_mul_i32 s14, s13, 224
	s_sub_u32 s14, s12, s14
	s_mul_i32 s15, s14, 0x40000
	s_lshl_b32 s16, s13, 7
	s_add_u32 s15, s15, s16
	s_add_u32 s10, s6, s15
	s_addc_u32 s11, s7, 0
	v_cvt_pk_bf16_f32 v84, v112, v113
	v_cvt_pk_bf16_f32 v85, v114, v115
	v_cvt_pk_bf16_f32 v86, v116, v117
	v_cvt_pk_bf16_f32 v87, v118, v119
	global_store_dwordx4 v35, v[84:87], s[10:11]

; DI int ltid() { int t = threadIdx.x; asm volatile("" : "+v"(t)); return t; }
; DI int lbid() { int b = blockIdx.x; asm volatile("" : "+s"(b)); return b; }
; template <class Map>
; DI void conv_T(bf16_t* __restrict__ dst, const float* __restrict__ src, int K, int ldsrc, int nphys, Map map, const float* __restrict__ kscale, float* tile) {
;   const int tid = ltid(), ntn = nphys >> 6, ntiles = (K >> 6) * ntn;
;   for (int tl = lbid(); tl < ntiles; tl += gridDim.x) {
;     const int k0 = (tl / ntn) << 6, n0 = (tl % ntn) << 6;
;     const int nn = tid & 63, sc = map(n0 + nn);
; #pragma unroll
;     for (int i = 0; i < 8; ++i) { const int kk = i * 8 + (tid >> 6);
;       float v = sc >= 0 ? __builtin_nontemporal_load(&src[(size_t)(k0 + kk) * ldsrc + sc]) : 0.f;
;       if (kscale) v *= kscale[k0 + kk];
;       tile[kk * 65 + nn] = v; }
; DI void convert_layer(const Params& p, int l, float* tile) {
;     ...
;   for (int r = 0; r < 3; ++r)
;     conv_T((bf16_t*)(ws + O_WBR) + (size_t)r * 2048 * 1024, p.w_br + (size_t)(l * 3 + r) * 1024 * 2048, 1024, 2048, 2048, MapId{0}, nullptr, tile);
.Lcv_win_l1_end:
	s_barrier
	v_readlane_b32 s4, v249, 8
	v_readlane_b32 s5, v249, 9
	s_add_u32 s4, s4, 0x1800000
	s_addc_u32 s5, s5, 0
	s_add_u32 s6, s18, 0x3c00000
	s_addc_u32 s7, s19, 0
	v_lshrrev_b32_e32 v36, 6, v248
	v_and_b32_e32 v37, 63, v248
	v_mov_b32_e32 v38, 0x2000
	v_mul_u32_u24_e32 v34, v36, v38
	v_lshl_add_u32 v34, v37, 2, v34
	v_lshrrev_b32_e32 v36, 3, v248
	v_and_b32_e32 v37, 7, v248
	v_mov_b32_e32 v38, 0x800
	v_mul_u32_u24_e32 v35, v36, v38
	v_lshl_add_u32 v35, v37, 4, v35
	s_mov_b32 s8, s20
	s_cmp_ge_u32 s8, 0x200
	s_cbranch_scc1 .Lcv_wbr0_l1_end
	s_mov_b32 s12, s8
	s_lshr_b32 s13, s12, 5
	s_and_b32 s14, s12, 31
	s_mul_i32 s15, s13, 0x80000
	s_lshl_b32 s16, s14, 8
	s_add_u32 s15, s15, s16
	s_add_u32 s10, s4, s15
	s_addc_u32 s11, s5, 0
	global_load_dword v40, v34, s[10:11] nt
	s_add_u32 s10, s10, 0x10000
	s_addc_u32 s11, s11, 0
	global_load_dword v41, v34, s[10:11] nt
	s_add_u32 s10, s10, 0x10000
	s_addc_u32 s11, s11, 0
	global_load_dword v42, v34, s[10:11] nt
	s_add_u32 s10, s10, 0x10000
	s_addc_u32 s11, s11, 0
	global_load_dword v43, v34, s[10:11] nt
	s_add_u32 s10, s10, 0x10000
	s_addc_u32 s11, s11, 0
	global_load_dword v44, v34, s[10:11] nt
	s_add_u32 s10, s10, 0x10000
	s_addc_u32 s11, s11, 0
	global_load_dword v45, v34, s[10:11] nt
	s_add_u32 s10, s10, 0x10000
	s_addc_u32 s11, s11, 0
	global_load_dword v46, v34, s[10:11] nt
	s_add_u32 s10, s10, 0x10000
	s_addc_u32 s11, s11, 0
	global_load_dword v47, v34, s[10:11] nt
	s_mul_i32 s12, s21, 1
	s_add_u32 s12, s12, s8
	s_cmp_ge_u32 s12, 0x200
	s_cbranch_scc1 .Lcv_wbr0_l1_pro_done
	s_mul_i32 s12, s21, 1
	s_add_u32 s12, s12, s8
	s_lshr_b32 s13, s12, 5
	s_and_b32 s14, s12, 31
	s_mul_i32 s15, s13, 0x80000
	s_lshl_b32 s16, s14, 8
	s_add_u32 s15, s15, s16
	s_add_u32 s10, s4, s15
	s_addc_u32 s11, s5, 0
	global_load_dword v48, v34, s[10:11] nt
	s_add_u32 s10, s10, 0x10000
	s_addc_u32 s11, s11, 0
	global_load_dword v49, v34, s[10:11] nt
	s_add_u32 s10, s10, 0x10000
	s_addc_u32 s11, s11, 0
	global_load_dword v50, v34, s[10:11] nt
	s_add_u32 s10, s10, 0x10000
	s_addc_u32 s11, s11, 0
	global_load_dword v51, v34, s[10:11] nt
	s_add_u32 s10, s10, 0x10000
	s_addc_u32 s11, s11, 0
	global_load_dword v52, v34, s[10:11] nt
	s_add_u32 s10, s10, 0x10000
	s_addc_u32 s11, s11, 0
	global_load_dword v53, v34, s[10:11] nt
	s_add_u32 s10, s10, 0x10000
	s_addc_u32 s11, s11, 0
	global_load_dword v54, v34, s[10:11] nt
	s_add_u32 s10, s10, 0x10000
	s_addc_u32 s11, s11, 0
	global_load_dword v55, v34, s[10:11] nt
	s_mul_i32 s12, s21, 2
	s_add_u32 s12, s12, s8
	s_cmp_ge_u32 s12, 0x200
	s_cbranch_scc1 .Lcv_wbr0_l1_pro_done
	s_mul_i32 s12, s21, 2
	s_add_u32 s12, s12, s8
	s_lshr_b32 s13, s12, 5
	s_and_b32 s14, s12, 31
	s_mul_i32 s15, s13, 0x80000
	s_lshl_b32 s16, s14, 8
	s_add_u32 s15, s15, s16
	s_add_u32 s10, s4, s15
	s_addc_u32 s11, s5, 0
	global_load_dword v56, v34, s[10:11] nt
	s_add_u32 s10, s10, 0x10000
	s_addc_u32 s11, s11, 0
	global_load_dword v57, v34, s[10:11] nt
	s_add_u32 s10, s10, 0x10000
	s_addc_u32 s11, s11, 0
	global_load_dword v58, v34, s[10:11] nt
	s_add_u32 s10, s10, 0x10000
	s_addc_u32 s11, s11, 0
	global_load_dword v59, v34, s[10:11] nt
	s_add_u32 s10, s10, 0x10000
	s_addc_u32 s11, s11, 0
	global_load_dword v60, v34, s[10:11] nt
	s_add_u32 s10, s10, 0x10000
	s_addc_u32 s11, s11, 0
	global_load_dword v61, v34, s[10:11] nt
	s_add_u32 s10, s10, 0x10000
	s_addc_u32 s11, s11, 0
	global_load_dword v62, v34, s[10:11] nt
	s_add_u32 s10, s10, 0x10000
	s_addc_u32 s11, s11, 0
	global_load_dword v63, v34, s[10:11] nt
	s_mul_i32 s12, s21, 3
	s_add_u32 s12, s12, s8
	s_cmp_ge_u32 s12, 0x200
	s_cbranch_scc1 .Lcv_wbr0_l1_pro_done
	s_mul_i32 s12, s21, 3
	s_add_u32 s12, s12, s8
	s_lshr_b32 s13, s12, 5
	s_and_b32 s14, s12, 31
	s_mul_i32 s15, s13, 0x80000
	s_lshl_b32 s16, s14, 8
	s_add_u32 s15, s15, s16
	s_add_u32 s10, s4, s15
	s_addc_u32 s11, s5, 0
	global_load_dword v64, v34, s[10:11] nt
	s_add_u32 s10, s10, 0x10000
	s_addc_u32 s11, s11, 0
	global_load_dword v65, v34, s[10:11] nt
	s_add_u32 s10, s10, 0x10000
	s_addc_u32 s11, s11, 0
	global_load_dword v66, v34, s[10:11] nt
	s_add_u32 s10, s10, 0x10000
	s_addc_u32 s11, s11, 0
	global_load_dword v67, v34, s[10:11] nt
	s_add_u32 s10, s10, 0x10000
	s_addc_u32 s11, s11, 0
	global_load_dword v68, v34, s[10:11] nt
	s_add_u32 s10, s10, 0x10000
	s_addc_u32 s11, s11, 0
	global_load_dword v69, v34, s[10:11] nt
	s_add_u32 s10, s10, 0x10000
	s_addc_u32 s11, s11, 0
	global_load_dword v70, v34, s[10:11] nt
	s_add_u32 s10, s10, 0x10000
	s_addc_u32 s11, s11, 0
	global_load_dword v71, v34, s[10:11] nt

; DI int lbid() { int b = blockIdx.x; asm volatile("" : "+s"(b)); return b; }
; template <class Map>
; DI void conv_T(bf16_t* __restrict__ dst, const float* __restrict__ src, int K, int ldsrc, int nphys, Map map, const float* __restrict__ kscale, float* tile) {
;     ...
;   for (int tl = lbid(); tl < ntiles; tl += gridDim.x) {
;     const int k0 = (tl / ntn) << 6, n0 = (tl % ntn) << 6;
;     const int nn = tid & 63, sc = map(n0 + nn);
; #pragma unroll
;     for (int i = 0; i < 8; ++i) { const int kk = i * 8 + (tid >> 6);
;       float v = sc >= 0 ? __builtin_nontemporal_load(&src[(size_t)(k0 + kk) * ldsrc + sc]) : 0.f;
;       if (kscale) v *= kscale[k0 + kk];
;       tile[kk * 65 + nn] = v; }
.Lcv_wbr0_l1_p0_after:
	ds_write_b32 v30, v40
	ds_write_b32 v30, v41 offset:2080
	ds_write_b32 v30, v42 offset:4160
	ds_write_b32 v30, v43 offset:6240
	ds_write_b32 v30, v44 offset:8320
	ds_write_b32 v30, v45 offset:10400
	ds_write_b32 v30, v46 offset:12480
	ds_write_b32 v30, v47 offset:14560
	s_mul_i32 s12, s21, 1
	s_add_u32 s12, s12, s8
	s_cmp_ge_u32 s12, 0x200
	s_cbranch_scc1 .Lcv_wbr0_l1_p0_wr_done
	ds_write_b32 v30, v48 offset:16640
	ds_write_b32 v30, v49 offset:18720
	ds_write_b32 v30, v50 offset:20800
	ds_write_b32 v30, v51 offset:22880
	ds_write_b32 v30, v52 offset:24960
	ds_write_b32 v30, v53 offset:27040
	ds_write_b32 v30, v54 offset:29120
	ds_write_b32 v30, v55 offset:31200
	s_mul_i32 s12, s21, 2
	s_add_u32 s12, s12, s8
	s_cmp_ge_u32 s12, 0x200
	s_cbranch_scc1 .Lcv_wbr0_l1_p0_wr_done
	ds_write_b32 v30, v56 offset:33280
	ds_write_b32 v30, v57 offset:35360
	ds_write_b32 v30, v58 offset:37440
	ds_write_b32 v30, v59 offset:39520
	ds_write_b32 v30, v60 offset:41600
	ds_write_b32 v30, v61 offset:43680
	ds_write_b32 v30, v62 offset:45760
	ds_write_b32 v30, v63 offset:47840
	s_mul_i32 s12, s21, 3
	s_add_u32 s12, s12, s8
	s_cmp_ge_u32 s12, 0x200
	s_cbranch_scc1 .Lcv_wbr0_l1_p0_wr_done
	ds_write_b32 v30, v64 offset:49920
	ds_write_b32 v30, v65 offset:52000
	ds_write_b32 v30, v66 offset:54080
	ds_write_b32 v30, v67 offset:56160
	ds_write_b32 v30, v68 offset:58240
	ds_write_b32 v30, v69 offset:60320
	ds_write_b32 v30, v70 offset:62400
	ds_write_b32 v30, v71 offset:64480
.Lcv_wbr0_l1_p0_wr_done:
	s_mul_i32 s12, s21, 4
	s_add_u32 s12, s12, s8
	s_cmp_ge_u32 s12, 0x200
	s_cbranch_scc1 .Lcv_wbr0_l1_p0_pf_done
	s_mul_i32 s12, s21, 4
	s_add_u32 s12, s12, s8
	s_lshr_b32 s13, s12, 5
	s_and_b32 s14, s12, 31
	s_mul_i32 s15, s13, 0x80000
	s_lshl_b32 s16, s14, 8
	s_add_u32 s15, s15, s16
	s_add_u32 s10, s4, s15
	s_addc_u32 s11, s5, 0
	global_load_dword v88, v34, s[10:11] nt
	s_add_u32 s10, s10, 0x10000
	s_addc_u32 s11, s11, 0
	global_load_dword v89, v34, s[10:11] nt
	s_add_u32 s10, s10, 0x10000
	s_addc_u32 s11, s11, 0
	global_load_dword v90, v34, s[10:11] nt
	s_add_u32 s10, s10, 0x10000
	s_addc_u32 s11, s11, 0
	global_load_dword v91, v34, s[10:11] nt
	s_add_u32 s10, s10, 0x10000
	s_addc_u32 s11, s11, 0
	global_load_dword v92, v34, s[10:11] nt
	s_add_u32 s10, s10, 0x10000
	s_addc_u32 s11, s11, 0
	global_load_dword v93, v34, s[10:11] nt
	s_add_u32 s10, s10, 0x10000
	s_addc_u32 s11, s11, 0
	global_load_dword v94, v34, s[10:11] nt
	s_add_u32 s10, s10, 0x10000
	s_addc_u32 s11, s11, 0
	global_load_dword v95, v34, s[10:11] nt
	s_mul_i32 s12, s21, 5
	s_add_u32 s12, s12, s8
	s_cmp_ge_u32 s12, 0x200
	s_cbranch_scc1 .Lcv_wbr0_l1_p0_pf_done
	s_mul_i32 s12, s21, 5
	s_add_u32 s12, s12, s8
	s_lshr_b32 s13, s12, 5
	s_and_b32 s14, s12, 31
	s_mul_i32 s15, s13, 0x80000
	s_lshl_b32 s16, s14, 8
	s_add_u32 s15, s15, s16
	s_add_u32 s10, s4, s15
	s_addc_u32 s11, s5, 0
	global_load_dword v96, v34, s[10:11] nt
	s_add_u32 s10, s10, 0x10000
	s_addc_u32 s11, s11, 0
	global_load_dword v97, v34, s[10:11] nt
	s_add_u32 s10, s10, 0x10000
	s_addc_u32 s11, s11, 0
	global_load_dword v98, v34, s[10:11] nt
	s_add_u32 s10, s10, 0x10000
	s_addc_u32 s11, s11, 0
	global_load_dword v99, v34, s[10:11] nt
	s_add_u32 s10, s10, 0x10000
	s_addc_u32 s11, s11, 0
	global_load_dword v100, v34, s[10:11] nt
	s_add_u32 s10, s10, 0x10000
	s_addc_u32 s11, s11, 0
	global_load_dword v101, v34, s[10:11] nt
	s_add_u32 s10, s10, 0x10000
	s_addc_u32 s11, s11, 0
	global_load_dword v102, v34, s[10:11] nt
	s_add_u32 s10, s10, 0x10000
	s_addc_u32 s11, s11, 0
	global_load_dword v103, v34, s[10:11] nt
	s_mul_i32 s12, s21, 6
	s_add_u32 s12, s12, s8
	s_cmp_ge_u32 s12, 0x200
	s_cbranch_scc1 .Lcv_wbr0_l1_p0_pf_done
	s_mul_i32 s12, s21, 6
	s_add_u32 s12, s12, s8
	s_lshr_b32 s13, s12, 5
	s_and_b32 s14, s12, 31
	s_mul_i32 s15, s13, 0x80000
	s_lshl_b32 s16, s14, 8
	s_add_u32 s15, s15, s16
	s_add_u32 s10, s4, s15
	s_addc_u32 s11, s5, 0
	global_load_dword v104, v34, s[10:11] nt
	s_add_u32 s10, s10, 0x10000
	s_addc_u32 s11, s11, 0
	global_load_dword v105, v34, s[10:11] nt
	s_add_u32 s10, s10, 0x10000
	s_addc_u32 s11, s11, 0
	global_load_dword v106, v34, s[10:11] nt
	s_add_u32 s10, s10, 0x10000
	s_addc_u32 s11, s11, 0
	global_load_dword v107, v34, s[10:11] nt
	s_add_u32 s10, s10, 0x10000
	s_addc_u32 s11, s11, 0
	global_load_dword v108, v34, s[10:11] nt
	s_add_u32 s10, s10, 0x10000
	s_addc_u32 s11, s11, 0
	global_load_dword v109, v34, s[10:11] nt
	s_add_u32 s10, s10, 0x10000
	s_addc_u32 s11, s11, 0
	global_load_dword v110, v34, s[10:11] nt
	s_add_u32 s10, s10, 0x10000
	s_addc_u32 s11, s11, 0
	global_load_dword v111, v34, s[10:11] nt
	s_mul_i32 s12, s21, 7
	s_add_u32 s12, s12, s8
	s_cmp_ge_u32 s12, 0x200
	s_cbranch_scc1 .Lcv_wbr0_l1_p0_pf_done
	s_mul_i32 s12, s21, 7
	s_add_u32 s12, s12, s8
	s_lshr_b32 s13, s12, 5
	s_and_b32 s14, s12, 31
	s_mul_i32 s15, s13, 0x80000
	s_lshl_b32 s16, s14, 8
	s_add_u32 s15, s15, s16
	s_add_u32 s10, s4, s15
	s_addc_u32 s11, s5, 0
	global_load_dword v112, v34, s[10:11] nt
	s_add_u32 s10, s10, 0x10000
	s_addc_u32 s11, s11, 0
	global_load_dword v113, v34, s[10:11] nt
	s_add_u32 s10, s10, 0x10000
	s_addc_u32 s11, s11, 0
	global_load_dword v114, v34, s[10:11] nt
	s_add_u32 s10, s10, 0x10000
	s_addc_u32 s11, s11, 0
	global_load_dword v115, v34, s[10:11] nt
	s_add_u32 s10, s10, 0x10000
	s_addc_u32 s11, s11, 0
	global_load_dword v116, v34, s[10:11] nt
	s_add_u32 s10, s10, 0x10000
	s_addc_u32 s11, s11, 0
	global_load_dword v117, v34, s[10:11] nt
	s_add_u32 s10, s10, 0x10000
	s_addc_u32 s11, s11, 0
	global_load_dword v118, v34, s[10:11] nt
	s_add_u32 s10, s10, 0x10000
	s_addc_u32 s11, s11, 0
	global_load_dword v119, v34, s[10:11] nt

; DI int lbid() { int b = blockIdx.x; asm volatile("" : "+s"(b)); return b; }
; template <class Map>
; DI void conv_T(bf16_t* __restrict__ dst, const float* __restrict__ src, int K, int ldsrc, int nphys, Map map, const float* __restrict__ kscale, float* tile) {
;     ...
;   for (int tl = lbid(); tl < ntiles; tl += gridDim.x) {
;     const int k0 = (tl / ntn) << 6, n0 = (tl % ntn) << 6;
;     const int nn = tid & 63, sc = map(n0 + nn);
; #pragma unroll
;     for (int i = 0; i < 8; ++i) { const int kk = i * 8 + (tid >> 6);
;       float v = sc >= 0 ? __builtin_nontemporal_load(&src[(size_t)(k0 + kk) * ldsrc + sc]) : 0.f;
;       if (kscale) v *= kscale[k0 + kk];
;       tile[kk * 65 + nn] = v; }
.Lcv_wbr0_l1_p0_st_done:
	s_lshl_b32 s12, s21, 2
	s_add_u32 s8, s8, s12
	s_cmp_ge_u32 s8, 0x200
	s_cbranch_scc1 .Lcv_wbr0_l1_end
	s_waitcnt vmcnt(4)
.Lcv_wbr0_l1_p1_after:
	ds_write_b32 v31, v88
	ds_write_b32 v31, v89 offset:2080
	ds_write_b32 v31, v90 offset:4160
	ds_write_b32 v31, v91 offset:6240
	ds_write_b32 v31, v92 offset:8320
	ds_write_b32 v31, v93 offset:10400
	ds_write_b32 v31, v94 offset:12480
	ds_write_b32 v31, v95 offset:14560
	s_mul_i32 s12, s21, 1
	s_add_u32 s12, s12, s8
	s_cmp_ge_u32 s12, 0x200
	s_cbranch_scc1 .Lcv_wbr0_l1_p1_wr_done
	ds_write_b32 v31, v96 offset:16640
	ds_write_b32 v31, v97 offset:18720
	ds_write_b32 v31, v98 offset:20800
	ds_write_b32 v31, v99 offset:22880
	ds_write_b32 v31, v100 offset:24960
	ds_write_b32 v31, v101 offset:27040
	ds_write_b32 v31, v102 offset:29120
	ds_write_b32 v31, v103 offset:31200
	s_mul_i32 s12, s21, 2
	s_add_u32 s12, s12, s8
	s_cmp_ge_u32 s12, 0x200
	s_cbranch_scc1 .Lcv_wbr0_l1_p1_wr_done
	ds_write_b32 v31, v104 offset:33280
	ds_write_b32 v31, v105 offset:35360
	ds_write_b32 v31, v106 offset:37440
	ds_write_b32 v31, v107 offset:39520
	ds_write_b32 v31, v108 offset:41600
	ds_write_b32 v31, v109 offset:43680
	ds_write_b32 v31, v110 offset:45760
	ds_write_b32 v31, v111 offset:47840
	s_mul_i32 s12, s21, 3
	s_add_u32 s12, s12, s8
	s_cmp_ge_u32 s12, 0x200
	s_cbranch_scc1 .Lcv_wbr0_l1_p1_wr_done
	ds_write_b32 v31, v112 offset:49920
	ds_write_b32 v31, v113 offset:52000
	ds_write_b32 v31, v114 offset:54080
	ds_write_b32 v31, v115 offset:56160
	ds_write_b32 v31, v116 offset:58240
	ds_write_b32 v31, v117 offset:60320
	ds_write_b32 v31, v118 offset:62400
	ds_write_b32 v31, v119 offset:64480
.Lcv_wbr0_l1_p1_wr_done:
	s_mul_i32 s12, s21, 4
	s_add_u32 s12, s12, s8
	s_cmp_ge_u32 s12, 0x200
	s_cbranch_scc1 .Lcv_wbr0_l1_p1_pf_done
	s_mul_i32 s12, s21, 4
	s_add_u32 s12, s12, s8
	s_lshr_b32 s13, s12, 5
	s_and_b32 s14, s12, 31
	s_mul_i32 s15, s13, 0x80000
	s_lshl_b32 s16, s14, 8
	s_add_u32 s15, s15, s16
	s_add_u32 s10, s4, s15
	s_addc_u32 s11, s5, 0
	global_load_dword v40, v34, s[10:11] nt
	s_add_u32 s10, s10, 0x10000
	s_addc_u32 s11, s11, 0
	global_load_dword v41, v34, s[10:11] nt
	s_add_u32 s10, s10, 0x10000
	s_addc_u32 s11, s11, 0
	global_load_dword v42, v34, s[10:11] nt
	s_add_u32 s10, s10, 0x10000
	s_addc_u32 s11, s11, 0
	global_load_dword v43, v34, s[10:11] nt
	s_add_u32 s10, s10, 0x10000
	s_addc_u32 s11, s11, 0
	global_load_dword v44, v34, s[10:11] nt
	s_add_u32 s10, s10, 0x10000
	s_addc_u32 s11, s11, 0
	global_load_dword v45, v34, s[10:11] nt
	s_add_u32 s10, s10, 0x10000
	s_addc_u32 s11, s11, 0
	global_load_dword v46, v34, s[10:11] nt
	s_add_u32 s10, s10, 0x10000
	s_addc_u32 s11, s11, 0
	global_load_dword v47, v34, s[10:11] nt
	s_mul_i32 s12, s21, 5
	s_add_u32 s12, s12, s8
	s_cmp_ge_u32 s12, 0x200
	s_cbranch_scc1 .Lcv_wbr0_l1_p1_pf_done
	s_mul_i32 s12, s21, 5
	s_add_u32 s12, s12, s8
	s_lshr_b32 s13, s12, 5
	s_and_b32 s14, s12, 31
	s_mul_i32 s15, s13, 0x80000
	s_lshl_b32 s16, s14, 8
	s_add_u32 s15, s15, s16
	s_add_u32 s10, s4, s15
	s_addc_u32 s11, s5, 0
	global_load_dword v48, v34, s[10:11] nt
	s_add_u32 s10, s10, 0x10000
	s_addc_u32 s11, s11, 0
	global_load_dword v49, v34, s[10:11] nt
	s_add_u32 s10, s10, 0x10000
	s_addc_u32 s11, s11, 0
	global_load_dword v50, v34, s[10:11] nt
	s_add_u32 s10, s10, 0x10000
	s_addc_u32 s11, s11, 0
	global_load_dword v51, v34, s[10:11] nt
	s_add_u32 s10, s10, 0x10000
	s_addc_u32 s11, s11, 0
	global_load_dword v52, v34, s[10:11] nt
	s_add_u32 s10, s10, 0x10000
	s_addc_u32 s11, s11, 0
	global_load_dword v53, v34, s[10:11] nt
	s_add_u32 s10, s10, 0x10000
	s_addc_u32 s11, s11, 0
	global_load_dword v54, v34, s[10:11] nt
	s_add_u32 s10, s10, 0x10000
	s_addc_u32 s11, s11, 0
	global_load_dword v55, v34, s[10:11] nt
	s_mul_i32 s12, s21, 6
	s_add_u32 s12, s12, s8
	s_cmp_ge_u32 s12, 0x200
	s_cbranch_scc1 .Lcv_wbr0_l1_p1_pf_done
	s_mul_i32 s12, s21, 6
	s_add_u32 s12, s12, s8
	s_lshr_b32 s13, s12, 5
	s_and_b32 s14, s12, 31
	s_mul_i32 s15, s13, 0x80000
	s_lshl_b32 s16, s14, 8
	s_add_u32 s15, s15, s16
	s_add_u32 s10, s4, s15
	s_addc_u32 s11, s5, 0
	global_load_dword v56, v34, s[10:11] nt
	s_add_u32 s10, s10, 0x10000
	s_addc_u32 s11, s11, 0
	global_load_dword v57, v34, s[10:11] nt
	s_add_u32 s10, s10, 0x10000
	s_addc_u32 s11, s11, 0
	global_load_dword v58, v34, s[10:11] nt
	s_add_u32 s10, s10, 0x10000
	s_addc_u32 s11, s11, 0
	global_load_dword v59, v34, s[10:11] nt
	s_add_u32 s10, s10, 0x10000
	s_addc_u32 s11, s11, 0
	global_load_dword v60, v34, s[10:11] nt
	s_add_u32 s10, s10, 0x10000
	s_addc_u32 s11, s11, 0
	global_load_dword v61, v34, s[10:11] nt
	s_add_u32 s10, s10, 0x10000
	s_addc_u32 s11, s11, 0
	global_load_dword v62, v34, s[10:11] nt
	s_add_u32 s10, s10, 0x10000
	s_addc_u32 s11, s11, 0
	global_load_dword v63, v34, s[10:11] nt
	s_mul_i32 s12, s21, 7
	s_add_u32 s12, s12, s8
	s_cmp_ge_u32 s12, 0x200
	s_cbranch_scc1 .Lcv_wbr0_l1_p1_pf_done
	s_mul_i32 s12, s21, 7
	s_add_u32 s12, s12, s8
	s_lshr_b32 s13, s12, 5
	s_and_b32 s14, s12, 31
	s_mul_i32 s15, s13, 0x80000
	s_lshl_b32 s16, s14, 8
	s_add_u32 s15, s15, s16
	s_add_u32 s10, s4, s15
	s_addc_u32 s11, s5, 0
	global_load_dword v64, v34, s[10:11] nt
	s_add_u32 s10, s10, 0x10000
	s_addc_u32 s11, s11, 0
	global_load_dword v65, v34, s[10:11] nt
	s_add_u32 s10, s10, 0x10000
	s_addc_u32 s11, s11, 0
	global_load_dword v66, v34, s[10:11] nt
	s_add_u32 s10, s10, 0x10000
	s_addc_u32 s11, s11, 0
	global_load_dword v67, v34, s[10:11] nt
	s_add_u32 s10, s10, 0x10000
	s_addc_u32 s11, s11, 0
	global_load_dword v68, v34, s[10:11] nt
	s_add_u32 s10, s10, 0x10000
	s_addc_u32 s11, s11, 0
	global_load_dword v69, v34, s[10:11] nt
	s_add_u32 s10, s10, 0x10000
	s_addc_u32 s11, s11, 0
	global_load_dword v70, v34, s[10:11] nt
	s_add_u32 s10, s10, 0x10000
	s_addc_u32 s11, s11, 0
	global_load_dword v71, v34, s[10:11] nt
; DI unsigned cvtpk(float lo, float hi) { unsigned r; asm volatile("v_cvt_pk_bf16_f32 %0, %1, %2" : "=v"(r) : "v"(lo), "v"(hi)); return r; }
; template <class Map>
; DI void conv_T(bf16_t* __restrict__ dst, const float* __restrict__ src, int K, int ldsrc, int nphys, Map map, const float* __restrict__ kscale, float* tile) {
;     ...
;     __syncthreads();
;     const int np = tid >> 3, ks = tid & 7;
;     float v[8];
; #pragma unroll
;     for (int j = 0; j < 8; ++j) v[j] = tile[(ks * 8 + j) * 65 + np];
;     u32x4 w = {cvtpk(v[0], v[1]), cvtpk(v[2], v[3]), cvtpk(v[4], v[5]), cvtpk(v[6], v[7])};
;     *(u32x4*)(dst + (size_t)(n0 + np) * K + k0 + ks * 8) = w;
;     __syncthreads();
.Lcv_wbr0_l1_p1_pf_done:
	s_waitcnt lgkmcnt(0)
	s_barrier
	ds_read_b32 v88, v33
	ds_read_b32 v89, v33 offset:260
	ds_read_b32 v90, v33 offset:520
	ds_read_b32 v91, v33 offset:780
	ds_read_b32 v92, v33 offset:1040
	ds_read_b32 v93, v33 offset:1300
	ds_read_b32 v94, v33 offset:1560
	ds_read_b32 v95, v33 offset:1820
	s_mul_i32 s12, s21, 1
	s_add_u32 s12, s12, s8
	s_cmp_ge_u32 s12, 0x200
	s_cbranch_scc1 .Lcv_wbr0_l1_p1_rd_done
	ds_read_b32 v96, v33 offset:16640
	ds_read_b32 v97, v33 offset:16900
	ds_read_b32 v98, v33 offset:17160
	ds_read_b32 v99, v33 offset:17420
	ds_read_b32 v100, v33 offset:17680
	ds_read_b32 v101, v33 offset:17940
	ds_read_b32 v102, v33 offset:18200
	ds_read_b32 v103, v33 offset:18460
	s_mul_i32 s12, s21, 2
	s_add_u32 s12, s12, s8
	s_cmp_ge_u32 s12, 0x200
	s_cbranch_scc1 .Lcv_wbr0_l1_p1_rd_done
	ds_read_b32 v104, v33 offset:33280
	ds_read_b32 v105, v33 offset:33540
	ds_read_b32 v106, v33 offset:33800
	ds_read_b32 v107, v33 offset:34060
	ds_read_b32 v108, v33 offset:34320
	ds_read_b32 v109, v33 offset:34580
	ds_read_b32 v110, v33 offset:34840
	ds_read_b32 v111, v33 offset:35100
	s_mul_i32 s12, s21, 3
	s_add_u32 s12, s12, s8
	s_cmp_ge_u32 s12, 0x200
	s_cbranch_scc1 .Lcv_wbr0_l1_p1_rd_done
	ds_read_b32 v112, v33 offset:49920
	ds_read_b32 v113, v33 offset:50180
	ds_read_b32 v114, v33 offset:50440
	ds_read_b32 v115, v33 offset:50700
	ds_read_b32 v116, v33 offset:50960
	ds_read_b32 v117, v33 offset:51220
	ds_read_b32 v118, v33 offset:51480
	ds_read_b32 v119, v33 offset:51740
.Lcv_wbr0_l1_p1_rd_done:
	s_waitcnt lgkmcnt(0)
	s_mov_b32 s12, s8
	s_lshr_b32 s13, s12, 5
	s_and_b32 s14, s12, 31
	s_mul_i32 s15, s14, 0x20000
	s_lshl_b32 s16, s13, 7
	s_add_u32 s15, s15, s16
	s_add_u32 s10, s6, s15
	s_addc_u32 s11, s7, 0
	v_cvt_pk_bf16_f32 v72, v88, v89
	v_cvt_pk_bf16_f32 v73, v90, v91
	v_cvt_pk_bf16_f32 v74, v92, v93
	v_cvt_pk_bf16_f32 v75, v94, v95
	global_store_dwordx4 v35, v[72:75], s[10:11]
	s_mul_i32 s12, s21, 1
	s_add_u32 s12, s12, s8
	s_cmp_ge_u32 s12, 0x200
	s_cbranch_scc1 .Lcv_wbr0_l1_p1_st_done
	s_mul_i32 s12, s21, 1
	s_add_u32 s12, s12, s8
	s_lshr_b32 s13, s12, 5
	s_and_b32 s14, s12, 31
	s_mul_i32 s15, s14, 0x20000
	s_lshl_b32 s16, s13, 7
	s_add_u32 s15, s15, s16
	s_add_u32 s10, s6, s15
	s_addc_u32 s11, s7, 0
	v_cvt_pk_bf16_f32 v76, v96, v97
	v_cvt_pk_bf16_f32 v77, v98, v99
	v_cvt_pk_bf16_f32 v78, v100, v101
	v_cvt_pk_bf16_f32 v79, v102, v103
	global_store_dwordx4 v35, v[76:79], s[10:11]
	s_mul_i32 s12, s21, 2
	s_add_u32 s12, s12, s8
	s_cmp_ge_u32 s12, 0x200
	s_cbranch_scc1 .Lcv_wbr0_l1_p1_st_done
	s_mul_i32 s12, s21, 2
	s_add_u32 s12, s12, s8
	s_lshr_b32 s13, s12, 5
	s_and_b32 s14, s12, 31
	s_mul_i32 s15, s14, 0x20000
	s_lshl_b32 s16, s13, 7
	s_add_u32 s15, s15, s16
	s_add_u32 s10, s6, s15
	s_addc_u32 s11, s7, 0
	v_cvt_pk_bf16_f32 v80, v104, v105
	v_cvt_pk_bf16_f32 v81, v106, v107
	v_cvt_pk_bf16_f32 v82, v108, v109
	v_cvt_pk_bf16_f32 v83, v110, v111
	global_store_dwordx4 v35, v[80:83], s[10:11]
	s_mul_i32 s12, s21, 3
	s_add_u32 s12, s12, s8
	s_cmp_ge_u32 s12, 0x200
	s_cbranch_scc1 .Lcv_wbr0_l1_p1_st_done
	s_mul_i32 s12, s21, 3
	s_add_u32 s12, s12, s8
	s_lshr_b32 s13, s12, 5
	s_and_b32 s14, s12, 31
	s_mul_i32 s15, s14, 0x20000
	s_lshl_b32 s16, s13, 7
	s_add_u32 s15, s15, s16
	s_add_u32 s10, s6, s15
	s_addc_u32 s11, s7, 0
	v_cvt_pk_bf16_f32 v84, v112, v113
	v_cvt_pk_bf16_f32 v85, v114, v115
	v_cvt_pk_bf16_f32 v86, v116, v117
	v_cvt_pk_bf16_f32 v87, v118, v119
	global_store_dwordx4 v35, v[84:87], s[10:11]

; DI int ltid() { int t = threadIdx.x; asm volatile("" : "+v"(t)); return t; }
; DI int lbid() { int b = blockIdx.x; asm volatile("" : "+s"(b)); return b; }
; template <class Map>
; DI void conv_T(bf16_t* __restrict__ dst, const float* __restrict__ src, int K, int ldsrc, int nphys, Map map, const float* __restrict__ kscale, float* tile) {
;   const int tid = ltid(), ntn = nphys >> 6, ntiles = (K >> 6) * ntn;
;   for (int tl = lbid(); tl < ntiles; tl += gridDim.x) {
;     const int k0 = (tl / ntn) << 6, n0 = (tl % ntn) << 6;
;     const int nn = tid & 63, sc = map(n0 + nn);
; #pragma unroll
;     for (int i = 0; i < 8; ++i) { const int kk = i * 8 + (tid >> 6);
;       float v = sc >= 0 ? __builtin_nontemporal_load(&src[(size_t)(k0 + kk) * ldsrc + sc]) : 0.f;
;       if (kscale) v *= kscale[k0 + kk];
;       tile[kk * 65 + nn] = v; }
; DI void convert_layer(const Params& p, int l, float* tile) {
;     ...
;   for (int r = 0; r < 3; ++r)
;     conv_T((bf16_t*)(ws + O_WBR) + (size_t)r * 2048 * 1024, p.w_br + (size_t)(l * 3 + r) * 1024 * 2048, 1024, 2048, 2048, MapId{0}, nullptr, tile);
.Lcv_wbr0_l1_end:
	s_barrier
	v_readlane_b32 s4, v249, 8
	v_readlane_b32 s5, v249, 9
	s_add_u32 s4, s4, 0x2000000
	s_addc_u32 s5, s5, 0
	s_add_u32 s6, s18, 0x4000000
	s_addc_u32 s7, s19, 0
	v_lshrrev_b32_e32 v36, 6, v248
	v_and_b32_e32 v37, 63, v248
	v_mov_b32_e32 v38, 0x2000
	v_mul_u32_u24_e32 v34, v36, v38
	v_lshl_add_u32 v34, v37, 2, v34
	v_lshrrev_b32_e32 v36, 3, v248
	v_and_b32_e32 v37, 7, v248
	v_mov_b32_e32 v38, 0x800
	v_mul_u32_u24_e32 v35, v36, v38
	v_lshl_add_u32 v35, v37, 4, v35
	s_mov_b32 s8, s20
	s_cmp_ge_u32 s8, 0x200
	s_cbranch_scc1 .Lcv_wbr1_l1_end
	s_mov_b32 s12, s8
	s_lshr_b32 s13, s12, 5
	s_and_b32 s14, s12, 31
	s_mul_i32 s15, s13, 0x80000
	s_lshl_b32 s16, s14, 8
	s_add_u32 s15, s15, s16
	s_add_u32 s10, s4, s15
	s_addc_u32 s11, s5, 0
	global_load_dword v40, v34, s[10:11] nt
	s_add_u32 s10, s10, 0x10000
	s_addc_u32 s11, s11, 0
	global_load_dword v41, v34, s[10:11] nt
	s_add_u32 s10, s10, 0x10000
	s_addc_u32 s11, s11, 0
	global_load_dword v42, v34, s[10:11] nt
	s_add_u32 s10, s10, 0x10000
	s_addc_u32 s11, s11, 0
	global_load_dword v43, v34, s[10:11] nt
	s_add_u32 s10, s10, 0x10000
	s_addc_u32 s11, s11, 0
	global_load_dword v44, v34, s[10:11] nt
	s_add_u32 s10, s10, 0x10000
	s_addc_u32 s11, s11, 0
	global_load_dword v45, v34, s[10:11] nt
	s_add_u32 s10, s10, 0x10000
	s_addc_u32 s11, s11, 0
	global_load_dword v46, v34, s[10:11] nt
	s_add_u32 s10, s10, 0x10000
	s_addc_u32 s11, s11, 0
	global_load_dword v47, v34, s[10:11] nt
	s_mul_i32 s12, s21, 1
	s_add_u32 s12, s12, s8
	s_cmp_ge_u32 s12, 0x200
	s_cbranch_scc1 .Lcv_wbr1_l1_pro_done
	s_mul_i32 s12, s21, 1
	s_add_u32 s12, s12, s8
	s_lshr_b32 s13, s12, 5
	s_and_b32 s14, s12, 31
	s_mul_i32 s15, s13, 0x80000
	s_lshl_b32 s16, s14, 8
	s_add_u32 s15, s15, s16
	s_add_u32 s10, s4, s15
	s_addc_u32 s11, s5, 0
	global_load_dword v48, v34, s[10:11] nt
	s_add_u32 s10, s10, 0x10000
	s_addc_u32 s11, s11, 0
	global_load_dword v49, v34, s[10:11] nt
	s_add_u32 s10, s10, 0x10000
	s_addc_u32 s11, s11, 0
	global_load_dword v50, v34, s[10:11] nt
	s_add_u32 s10, s10, 0x10000
	s_addc_u32 s11, s11, 0
	global_load_dword v51, v34, s[10:11] nt
	s_add_u32 s10, s10, 0x10000
	s_addc_u32 s11, s11, 0
	global_load_dword v52, v34, s[10:11] nt
	s_add_u32 s10, s10, 0x10000
	s_addc_u32 s11, s11, 0
	global_load_dword v53, v34, s[10:11] nt
	s_add_u32 s10, s10, 0x10000
	s_addc_u32 s11, s11, 0
	global_load_dword v54, v34, s[10:11] nt
	s_add_u32 s10, s10, 0x10000
	s_addc_u32 s11, s11, 0
	global_load_dword v55, v34, s[10:11] nt
	s_mul_i32 s12, s21, 2
	s_add_u32 s12, s12, s8
	s_cmp_ge_u32 s12, 0x200
	s_cbranch_scc1 .Lcv_wbr1_l1_pro_done
	s_mul_i32 s12, s21, 2
	s_add_u32 s12, s12, s8
	s_lshr_b32 s13, s12, 5
	s_and_b32 s14, s12, 31
	s_mul_i32 s15, s13, 0x80000
	s_lshl_b32 s16, s14, 8
	s_add_u32 s15, s15, s16
	s_add_u32 s10, s4, s15
	s_addc_u32 s11, s5, 0
	global_load_dword v56, v34, s[10:11] nt
	s_add_u32 s10, s10, 0x10000
	s_addc_u32 s11, s11, 0
	global_load_dword v57, v34, s[10:11] nt
	s_add_u32 s10, s10, 0x10000
	s_addc_u32 s11, s11, 0
	global_load_dword v58, v34, s[10:11] nt
	s_add_u32 s10, s10, 0x10000
	s_addc_u32 s11, s11, 0
	global_load_dword v59, v34, s[10:11] nt
	s_add_u32 s10, s10, 0x10000
	s_addc_u32 s11, s11, 0
	global_load_dword v60, v34, s[10:11] nt
	s_add_u32 s10, s10, 0x10000
	s_addc_u32 s11, s11, 0
	global_load_dword v61, v34, s[10:11] nt
	s_add_u32 s10, s10, 0x10000
	s_addc_u32 s11, s11, 0
	global_load_dword v62, v34, s[10:11] nt
	s_add_u32 s10, s10, 0x10000
	s_addc_u32 s11, s11, 0
	global_load_dword v63, v34, s[10:11] nt
	s_mul_i32 s12, s21, 3
	s_add_u32 s12, s12, s8
	s_cmp_ge_u32 s12, 0x200
	s_cbranch_scc1 .Lcv_wbr1_l1_pro_done
	s_mul_i32 s12, s21, 3
	s_add_u32 s12, s12, s8
	s_lshr_b32 s13, s12, 5
	s_and_b32 s14, s12, 31
	s_mul_i32 s15, s13, 0x80000
	s_lshl_b32 s16, s14, 8
	s_add_u32 s15, s15, s16
	s_add_u32 s10, s4, s15
	s_addc_u32 s11, s5, 0
	global_load_dword v64, v34, s[10:11] nt
	s_add_u32 s10, s10, 0x10000
	s_addc_u32 s11, s11, 0
	global_load_dword v65, v34, s[10:11] nt
	s_add_u32 s10, s10, 0x10000
	s_addc_u32 s11, s11, 0
	global_load_dword v66, v34, s[10:11] nt
	s_add_u32 s10, s10, 0x10000
	s_addc_u32 s11, s11, 0
	global_load_dword v67, v34, s[10:11] nt
	s_add_u32 s10, s10, 0x10000
	s_addc_u32 s11, s11, 0
	global_load_dword v68, v34, s[10:11] nt
	s_add_u32 s10, s10, 0x10000
	s_addc_u32 s11, s11, 0
	global_load_dword v69, v34, s[10:11] nt
	s_add_u32 s10, s10, 0x10000
	s_addc_u32 s11, s11, 0
	global_load_dword v70, v34, s[10:11] nt
	s_add_u32 s10, s10, 0x10000
	s_addc_u32 s11, s11, 0
	global_load_dword v71, v34, s[10:11] nt

; DI int ltid() { int t = threadIdx.x; asm volatile("" : "+v"(t)); return t; }
; DI int lbid() { int b = blockIdx.x; asm volatile("" : "+s"(b)); return b; }
; template <class Map>
; DI void conv_T(bf16_t* __restrict__ dst, const float* __restrict__ src, int K, int ldsrc, int nphys, Map map, const float* __restrict__ kscale, float* tile) {
;   const int tid = ltid(), ntn = nphys >> 6, ntiles = (K >> 6) * ntn;
;   for (int tl = lbid(); tl < ntiles; tl += gridDim.x) {
;     const int k0 = (tl / ntn) << 6, n0 = (tl % ntn) << 6;
;     const int nn = tid & 63, sc = map(n0 + nn);
; #pragma unroll
;     for (int i = 0; i < 8; ++i) { const int kk = i * 8 + (tid >> 6);
;       float v = sc >= 0 ? __builtin_nontemporal_load(&src[(size_t)(k0 + kk) * ldsrc + sc]) : 0.f;
;       if (kscale) v *= kscale[k0 + kk];
;       tile[kk * 65 + nn] = v; }
; DI void convert_layer(const Params& p, int l, float* tile) {
;     ...
;   for (int r = 0; r < 3; ++r)
;     conv_T((bf16_t*)(ws + O_WBR) + (size_t)r * 2048 * 1024, p.w_br + (size_t)(l * 3 + r) * 1024 * 2048, 1024, 2048, 2048, MapId{0}, nullptr, tile);
.Lcv_wbr1_l1_end:
	s_barrier
	v_readlane_b32 s4, v249, 8
	v_readlane_b32 s5, v249, 9
	s_add_u32 s4, s4, 0x2800000
	s_addc_u32 s5, s5, 0
	s_add_u32 s6, s18, 0x4400000
	s_addc_u32 s7, s19, 0
	v_lshrrev_b32_e32 v36, 6, v248
	v_and_b32_e32 v37, 63, v248
	v_mov_b32_e32 v38, 0x2000
	v_mul_u32_u24_e32 v34, v36, v38
	v_lshl_add_u32 v34, v37, 2, v34
	v_lshrrev_b32_e32 v36, 3, v248
	v_and_b32_e32 v37, 7, v248
	v_mov_b32_e32 v38, 0x800
	v_mul_u32_u24_e32 v35, v36, v38
	v_lshl_add_u32 v35, v37, 4, v35
	s_mov_b32 s8, s20
	s_cmp_ge_u32 s8, 0x200
	s_cbranch_scc1 .Lcv_wbr2_l1_end
	s_mov_b32 s12, s8
	s_lshr_b32 s13, s12, 5
	s_and_b32 s14, s12, 31
	s_mul_i32 s15, s13, 0x80000
	s_lshl_b32 s16, s14, 8
	s_add_u32 s15, s15, s16
	s_add_u32 s10, s4, s15
	s_addc_u32 s11, s5, 0
	global_load_dword v40, v34, s[10:11] nt
	s_add_u32 s10, s10, 0x10000
	s_addc_u32 s11, s11, 0
	global_load_dword v41, v34, s[10:11] nt
	s_add_u32 s10, s10, 0x10000
	s_addc_u32 s11, s11, 0
	global_load_dword v42, v34, s[10:11] nt
	s_add_u32 s10, s10, 0x10000
	s_addc_u32 s11, s11, 0
	global_load_dword v43, v34, s[10:11] nt
	s_add_u32 s10, s10, 0x10000
	s_addc_u32 s11, s11, 0
	global_load_dword v44, v34, s[10:11] nt
	s_add_u32 s10, s10, 0x10000
	s_addc_u32 s11, s11, 0
	global_load_dword v45, v34, s[10:11] nt
	s_add_u32 s10, s10, 0x10000
	s_addc_u32 s11, s11, 0
	global_load_dword v46, v34, s[10:11] nt
	s_add_u32 s10, s10, 0x10000
	s_addc_u32 s11, s11, 0
	global_load_dword v47, v34, s[10:11] nt
	s_mul_i32 s12, s21, 1
	s_add_u32 s12, s12, s8
	s_cmp_ge_u32 s12, 0x200
	s_cbranch_scc1 .Lcv_wbr2_l1_pro_done
	s_mul_i32 s12, s21, 1
	s_add_u32 s12, s12, s8
	s_lshr_b32 s13, s12, 5
	s_and_b32 s14, s12, 31
	s_mul_i32 s15, s13, 0x80000
	s_lshl_b32 s16, s14, 8
	s_add_u32 s15, s15, s16
	s_add_u32 s10, s4, s15
	s_addc_u32 s11, s5, 0
	global_load_dword v48, v34, s[10:11] nt
	s_add_u32 s10, s10, 0x10000
	s_addc_u32 s11, s11, 0
	global_load_dword v49, v34, s[10:11] nt
	s_add_u32 s10, s10, 0x10000
	s_addc_u32 s11, s11, 0
	global_load_dword v50, v34, s[10:11] nt
	s_add_u32 s10, s10, 0x10000
	s_addc_u32 s11, s11, 0
	global_load_dword v51, v34, s[10:11] nt
	s_add_u32 s10, s10, 0x10000
	s_addc_u32 s11, s11, 0
	global_load_dword v52, v34, s[10:11] nt
	s_add_u32 s10, s10, 0x10000
	s_addc_u32 s11, s11, 0
	global_load_dword v53, v34, s[10:11] nt
	s_add_u32 s10, s10, 0x10000
	s_addc_u32 s11, s11, 0
	global_load_dword v54, v34, s[10:11] nt
	s_add_u32 s10, s10, 0x10000
	s_addc_u32 s11, s11, 0
	global_load_dword v55, v34, s[10:11] nt
	s_mul_i32 s12, s21, 2
	s_add_u32 s12, s12, s8
	s_cmp_ge_u32 s12, 0x200
	s_cbranch_scc1 .Lcv_wbr2_l1_pro_done
	s_mul_i32 s12, s21, 2
	s_add_u32 s12, s12, s8
	s_lshr_b32 s13, s12, 5
	s_and_b32 s14, s12, 31
	s_mul_i32 s15, s13, 0x80000
	s_lshl_b32 s16, s14, 8
	s_add_u32 s15, s15, s16
	s_add_u32 s10, s4, s15
	s_addc_u32 s11, s5, 0
	global_load_dword v56, v34, s[10:11] nt
	s_add_u32 s10, s10, 0x10000
	s_addc_u32 s11, s11, 0
	global_load_dword v57, v34, s[10:11] nt
	s_add_u32 s10, s10, 0x10000
	s_addc_u32 s11, s11, 0
	global_load_dword v58, v34, s[10:11] nt
	s_add_u32 s10, s10, 0x10000
	s_addc_u32 s11, s11, 0
	global_load_dword v59, v34, s[10:11] nt
	s_add_u32 s10, s10, 0x10000
	s_addc_u32 s11, s11, 0
	global_load_dword v60, v34, s[10:11] nt
	s_add_u32 s10, s10, 0x10000
	s_addc_u32 s11, s11, 0
	global_load_dword v61, v34, s[10:11] nt
	s_add_u32 s10, s10, 0x10000
	s_addc_u32 s11, s11, 0
	global_load_dword v62, v34, s[10:11] nt
	s_add_u32 s10, s10, 0x10000
	s_addc_u32 s11, s11, 0
	global_load_dword v63, v34, s[10:11] nt
	s_mul_i32 s12, s21, 3
	s_add_u32 s12, s12, s8
	s_cmp_ge_u32 s12, 0x200
	s_cbranch_scc1 .Lcv_wbr2_l1_pro_done
	s_mul_i32 s12, s21, 3
	s_add_u32 s12, s12, s8
	s_lshr_b32 s13, s12, 5
	s_and_b32 s14, s12, 31
	s_mul_i32 s15, s13, 0x80000
	s_lshl_b32 s16, s14, 8
	s_add_u32 s15, s15, s16
	s_add_u32 s10, s4, s15
	s_addc_u32 s11, s5, 0
	global_load_dword v64, v34, s[10:11] nt
	s_add_u32 s10, s10, 0x10000
	s_addc_u32 s11, s11, 0
	global_load_dword v65, v34, s[10:11] nt
	s_add_u32 s10, s10, 0x10000
	s_addc_u32 s11, s11, 0
	global_load_dword v66, v34, s[10:11] nt
	s_add_u32 s10, s10, 0x10000
	s_addc_u32 s11, s11, 0
	global_load_dword v67, v34, s[10:11] nt
	s_add_u32 s10, s10, 0x10000
	s_addc_u32 s11, s11, 0
	global_load_dword v68, v34, s[10:11] nt
	s_add_u32 s10, s10, 0x10000
	s_addc_u32 s11, s11, 0
	global_load_dword v69, v34, s[10:11] nt
	s_add_u32 s10, s10, 0x10000
	s_addc_u32 s11, s11, 0
	global_load_dword v70, v34, s[10:11] nt
	s_add_u32 s10, s10, 0x10000
	s_addc_u32 s11, s11, 0
	global_load_dword v71, v34, s[10:11] nt

; DI int ltid() { int t = threadIdx.x; asm volatile("" : "+v"(t)); return t; }
; DI int lbid() { int b = blockIdx.x; asm volatile("" : "+s"(b)); return b; }
; template <class Map>
; DI void conv_T(bf16_t* __restrict__ dst, const float* __restrict__ src, int K, int ldsrc, int nphys, Map map, const float* __restrict__ kscale, float* tile) {
;   const int tid = ltid(), ntn = nphys >> 6, ntiles = (K >> 6) * ntn;
;   for (int tl = lbid(); tl < ntiles; tl += gridDim.x) {
;     const int k0 = (tl / ntn) << 6, n0 = (tl % ntn) << 6;
;     const int nn = tid & 63, sc = map(n0 + nn);
; #pragma unroll
;     for (int i = 0; i < 8; ++i) { const int kk = i * 8 + (tid >> 6);
;       float v = sc >= 0 ? __builtin_nontemporal_load(&src[(size_t)(k0 + kk) * ldsrc + sc]) : 0.f;
;       if (kscale) v *= kscale[k0 + kk];
;       tile[kk * 65 + nn] = v; }
; DI void convert_layer(const Params& p, int l, float* tile) {
;     ...
;   conv_T((bf16_t*)(ws + O_WO), p.w_o + (size_t)l * 2048 * 2048, 2048, 2048, 2048, MapId{0}, nullptr, tile);
.Lcv_wbr2_l1_end:
	s_barrier
	v_readlane_b32 s4, v249, 10
	v_readlane_b32 s5, v249, 11
	s_add_u32 s4, s4, 0x1000000
	s_addc_u32 s5, s5, 0
	s_add_u32 s6, s18, 0x4800000
	s_addc_u32 s7, s19, 0
	v_lshrrev_b32_e32 v36, 6, v248
	v_and_b32_e32 v37, 63, v248
	v_mov_b32_e32 v38, 0x2000
	v_mul_u32_u24_e32 v34, v36, v38
	v_lshl_add_u32 v34, v37, 2, v34
	v_lshrrev_b32_e32 v36, 3, v248
	v_and_b32_e32 v37, 7, v248
	v_mov_b32_e32 v38, 0x1000
	v_mul_u32_u24_e32 v35, v36, v38
	v_lshl_add_u32 v35, v37, 4, v35
	s_mov_b32 s8, s20
	s_cmp_ge_u32 s8, 0x400
	s_cbranch_scc1 .Lcv_wo_l1_end
	s_mov_b32 s12, s8
	s_lshr_b32 s13, s12, 5
	s_and_b32 s14, s12, 31
	s_mul_i32 s15, s13, 0x80000
	s_lshl_b32 s16, s14, 8
	s_add_u32 s15, s15, s16
	s_add_u32 s10, s4, s15
	s_addc_u32 s11, s5, 0
	global_load_dword v40, v34, s[10:11] nt
	s_add_u32 s10, s10, 0x10000
	s_addc_u32 s11, s11, 0
	global_load_dword v41, v34, s[10:11] nt
	s_add_u32 s10, s10, 0x10000
	s_addc_u32 s11, s11, 0
	global_load_dword v42, v34, s[10:11] nt
	s_add_u32 s10, s10, 0x10000
	s_addc_u32 s11, s11, 0
	global_load_dword v43, v34, s[10:11] nt
	s_add_u32 s10, s10, 0x10000
	s_addc_u32 s11, s11, 0
	global_load_dword v44, v34, s[10:11] nt
	s_add_u32 s10, s10, 0x10000
	s_addc_u32 s11, s11, 0
	global_load_dword v45, v34, s[10:11] nt
	s_add_u32 s10, s10, 0x10000
	s_addc_u32 s11, s11, 0
	global_load_dword v46, v34, s[10:11] nt
	s_add_u32 s10, s10, 0x10000
	s_addc_u32 s11, s11, 0
	global_load_dword v47, v34, s[10:11] nt
	s_mul_i32 s12, s21, 1
	s_add_u32 s12, s12, s8
	s_cmp_ge_u32 s12, 0x400
	s_cbranch_scc1 .Lcv_wo_l1_pro_done
	s_mul_i32 s12, s21, 1
	s_add_u32 s12, s12, s8
	s_lshr_b32 s13, s12, 5
	s_and_b32 s14, s12, 31
	s_mul_i32 s15, s13, 0x80000
	s_lshl_b32 s16, s14, 8
	s_add_u32 s15, s15, s16
	s_add_u32 s10, s4, s15
	s_addc_u32 s11, s5, 0
	global_load_dword v48, v34, s[10:11] nt
	s_add_u32 s10, s10, 0x10000
	s_addc_u32 s11, s11, 0
	global_load_dword v49, v34, s[10:11] nt
	s_add_u32 s10, s10, 0x10000
	s_addc_u32 s11, s11, 0
	global_load_dword v50, v34, s[10:11] nt
	s_add_u32 s10, s10, 0x10000
	s_addc_u32 s11, s11, 0
	global_load_dword v51, v34, s[10:11] nt
	s_add_u32 s10, s10, 0x10000
	s_addc_u32 s11, s11, 0
	global_load_dword v52, v34, s[10:11] nt
	s_add_u32 s10, s10, 0x10000
	s_addc_u32 s11, s11, 0
	global_load_dword v53, v34, s[10:11] nt
	s_add_u32 s10, s10, 0x10000
	s_addc_u32 s11, s11, 0
	global_load_dword v54, v34, s[10:11] nt
	s_add_u32 s10, s10, 0x10000
	s_addc_u32 s11, s11, 0
	global_load_dword v55, v34, s[10:11] nt
	s_mul_i32 s12, s21, 2
	s_add_u32 s12, s12, s8
	s_cmp_ge_u32 s12, 0x400
	s_cbranch_scc1 .Lcv_wo_l1_pro_done
	s_mul_i32 s12, s21, 2
	s_add_u32 s12, s12, s8
	s_lshr_b32 s13, s12, 5
	s_and_b32 s14, s12, 31
	s_mul_i32 s15, s13, 0x80000
	s_lshl_b32 s16, s14, 8
	s_add_u32 s15, s15, s16
	s_add_u32 s10, s4, s15
	s_addc_u32 s11, s5, 0
	global_load_dword v56, v34, s[10:11] nt
	s_add_u32 s10, s10, 0x10000
	s_addc_u32 s11, s11, 0
	global_load_dword v57, v34, s[10:11] nt
	s_add_u32 s10, s10, 0x10000
	s_addc_u32 s11, s11, 0
	global_load_dword v58, v34, s[10:11] nt
	s_add_u32 s10, s10, 0x10000
	s_addc_u32 s11, s11, 0
	global_load_dword v59, v34, s[10:11] nt
	s_add_u32 s10, s10, 0x10000
	s_addc_u32 s11, s11, 0
	global_load_dword v60, v34, s[10:11] nt
	s_add_u32 s10, s10, 0x10000
	s_addc_u32 s11, s11, 0
	global_load_dword v61, v34, s[10:11] nt
	s_add_u32 s10, s10, 0x10000
	s_addc_u32 s11, s11, 0
	global_load_dword v62, v34, s[10:11] nt
	s_add_u32 s10, s10, 0x10000
	s_addc_u32 s11, s11, 0
	global_load_dword v63, v34, s[10:11] nt
	s_mul_i32 s12, s21, 3
	s_add_u32 s12, s12, s8
	s_cmp_ge_u32 s12, 0x400
	s_cbranch_scc1 .Lcv_wo_l1_pro_done
	s_mul_i32 s12, s21, 3
	s_add_u32 s12, s12, s8
	s_lshr_b32 s13, s12, 5
	s_and_b32 s14, s12, 31
	s_mul_i32 s15, s13, 0x80000
	s_lshl_b32 s16, s14, 8
	s_add_u32 s15, s15, s16
	s_add_u32 s10, s4, s15
	s_addc_u32 s11, s5, 0
	global_load_dword v64, v34, s[10:11] nt
	s_add_u32 s10, s10, 0x10000
	s_addc_u32 s11, s11, 0
	global_load_dword v65, v34, s[10:11] nt
	s_add_u32 s10, s10, 0x10000
	s_addc_u32 s11, s11, 0
	global_load_dword v66, v34, s[10:11] nt
	s_add_u32 s10, s10, 0x10000
	s_addc_u32 s11, s11, 0
	global_load_dword v67, v34, s[10:11] nt
	s_add_u32 s10, s10, 0x10000
	s_addc_u32 s11, s11, 0
	global_load_dword v68, v34, s[10:11] nt
	s_add_u32 s10, s10, 0x10000
	s_addc_u32 s11, s11, 0
	global_load_dword v69, v34, s[10:11] nt
	s_add_u32 s10, s10, 0x10000
	s_addc_u32 s11, s11, 0
	global_load_dword v70, v34, s[10:11] nt
	s_add_u32 s10, s10, 0x10000
	s_addc_u32 s11, s11, 0
	global_load_dword v71, v34, s[10:11] nt

; DI int lbid() { int b = blockIdx.x; asm volatile("" : "+s"(b)); return b; }
; template <class Map>
; DI void conv_T(bf16_t* __restrict__ dst, const float* __restrict__ src, int K, int ldsrc, int nphys, Map map, const float* __restrict__ kscale, float* tile) {
;     ...
;   for (int tl = lbid(); tl < ntiles; tl += gridDim.x) {
;     const int k0 = (tl / ntn) << 6, n0 = (tl % ntn) << 6;
;     const int nn = tid & 63, sc = map(n0 + nn);
; #pragma unroll
;     for (int i = 0; i < 8; ++i) { const int kk = i * 8 + (tid >> 6);
;       float v = sc >= 0 ? __builtin_nontemporal_load(&src[(size_t)(k0 + kk) * ldsrc + sc]) : 0.f;
;       if (kscale) v *= kscale[k0 + kk];
;       tile[kk * 65 + nn] = v; }
.Lcv_wo_l1_p0_after:
	ds_write_b32 v30, v40
	ds_write_b32 v30, v41 offset:2080
	ds_write_b32 v30, v42 offset:4160
	ds_write_b32 v30, v43 offset:6240
	ds_write_b32 v30, v44 offset:8320
	ds_write_b32 v30, v45 offset:10400
	ds_write_b32 v30, v46 offset:12480
	ds_write_b32 v30, v47 offset:14560
	s_mul_i32 s12, s21, 1
	s_add_u32 s12, s12, s8
	s_cmp_ge_u32 s12, 0x400
	s_cbranch_scc1 .Lcv_wo_l1_p0_wr_done
	ds_write_b32 v30, v48 offset:16640
	ds_write_b32 v30, v49 offset:18720
	ds_write_b32 v30, v50 offset:20800
	ds_write_b32 v30, v51 offset:22880
	ds_write_b32 v30, v52 offset:24960
	ds_write_b32 v30, v53 offset:27040
	ds_write_b32 v30, v54 offset:29120
	ds_write_b32 v30, v55 offset:31200
	s_mul_i32 s12, s21, 2
	s_add_u32 s12, s12, s8
	s_cmp_ge_u32 s12, 0x400
	s_cbranch_scc1 .Lcv_wo_l1_p0_wr_done
	ds_write_b32 v30, v56 offset:33280
	ds_write_b32 v30, v57 offset:35360
	ds_write_b32 v30, v58 offset:37440
	ds_write_b32 v30, v59 offset:39520
	ds_write_b32 v30, v60 offset:41600
	ds_write_b32 v30, v61 offset:43680
	ds_write_b32 v30, v62 offset:45760
	ds_write_b32 v30, v63 offset:47840
	s_mul_i32 s12, s21, 3
	s_add_u32 s12, s12, s8
	s_cmp_ge_u32 s12, 0x400
	s_cbranch_scc1 .Lcv_wo_l1_p0_wr_done
	ds_write_b32 v30, v64 offset:49920
	ds_write_b32 v30, v65 offset:52000
	ds_write_b32 v30, v66 offset:54080
	ds_write_b32 v30, v67 offset:56160
	ds_write_b32 v30, v68 offset:58240
	ds_write_b32 v30, v69 offset:60320
	ds_write_b32 v30, v70 offset:62400
	ds_write_b32 v30, v71 offset:64480
.Lcv_wo_l1_p0_wr_done:
	s_mul_i32 s12, s21, 4
	s_add_u32 s12, s12, s8
	s_cmp_ge_u32 s12, 0x400
	s_cbranch_scc1 .Lcv_wo_l1_p0_pf_done
	s_mul_i32 s12, s21, 4
	s_add_u32 s12, s12, s8
	s_lshr_b32 s13, s12, 5
	s_and_b32 s14, s12, 31
	s_mul_i32 s15, s13, 0x80000
	s_lshl_b32 s16, s14, 8
	s_add_u32 s15, s15, s16
	s_add_u32 s10, s4, s15
	s_addc_u32 s11, s5, 0
	global_load_dword v88, v34, s[10:11] nt
	s_add_u32 s10, s10, 0x10000
	s_addc_u32 s11, s11, 0
	global_load_dword v89, v34, s[10:11] nt
	s_add_u32 s10, s10, 0x10000
	s_addc_u32 s11, s11, 0
	global_load_dword v90, v34, s[10:11] nt
	s_add_u32 s10, s10, 0x10000
	s_addc_u32 s11, s11, 0
	global_load_dword v91, v34, s[10:11] nt
	s_add_u32 s10, s10, 0x10000
	s_addc_u32 s11, s11, 0
	global_load_dword v92, v34, s[10:11] nt
	s_add_u32 s10, s10, 0x10000
	s_addc_u32 s11, s11, 0
	global_load_dword v93, v34, s[10:11] nt
	s_add_u32 s10, s10, 0x10000
	s_addc_u32 s11, s11, 0
	global_load_dword v94, v34, s[10:11] nt
	s_add_u32 s10, s10, 0x10000
	s_addc_u32 s11, s11, 0
	global_load_dword v95, v34, s[10:11] nt
	s_mul_i32 s12, s21, 5
	s_add_u32 s12, s12, s8
	s_cmp_ge_u32 s12, 0x400
	s_cbranch_scc1 .Lcv_wo_l1_p0_pf_done
	s_mul_i32 s12, s21, 5
	s_add_u32 s12, s12, s8
	s_lshr_b32 s13, s12, 5
	s_and_b32 s14, s12, 31
	s_mul_i32 s15, s13, 0x80000
	s_lshl_b32 s16, s14, 8
	s_add_u32 s15, s15, s16
	s_add_u32 s10, s4, s15
	s_addc_u32 s11, s5, 0
	global_load_dword v96, v34, s[10:11] nt
	s_add_u32 s10, s10, 0x10000
	s_addc_u32 s11, s11, 0
	global_load_dword v97, v34, s[10:11] nt
	s_add_u32 s10, s10, 0x10000
	s_addc_u32 s11, s11, 0
	global_load_dword v98, v34, s[10:11] nt
	s_add_u32 s10, s10, 0x10000
	s_addc_u32 s11, s11, 0
	global_load_dword v99, v34, s[10:11] nt
	s_add_u32 s10, s10, 0x10000
	s_addc_u32 s11, s11, 0
	global_load_dword v100, v34, s[10:11] nt
	s_add_u32 s10, s10, 0x10000
	s_addc_u32 s11, s11, 0
	global_load_dword v101, v34, s[10:11] nt
	s_add_u32 s10, s10, 0x10000
	s_addc_u32 s11, s11, 0
	global_load_dword v102, v34, s[10:11] nt
	s_add_u32 s10, s10, 0x10000
	s_addc_u32 s11, s11, 0
	global_load_dword v103, v34, s[10:11] nt
	s_mul_i32 s12, s21, 6
	s_add_u32 s12, s12, s8
	s_cmp_ge_u32 s12, 0x400
	s_cbranch_scc1 .Lcv_wo_l1_p0_pf_done
	s_mul_i32 s12, s21, 6
	s_add_u32 s12, s12, s8
	s_lshr_b32 s13, s12, 5
	s_and_b32 s14, s12, 31
	s_mul_i32 s15, s13, 0x80000
	s_lshl_b32 s16, s14, 8
	s_add_u32 s15, s15, s16
	s_add_u32 s10, s4, s15
	s_addc_u32 s11, s5, 0
	global_load_dword v104, v34, s[10:11] nt
	s_add_u32 s10, s10, 0x10000
	s_addc_u32 s11, s11, 0
	global_load_dword v105, v34, s[10:11] nt
	s_add_u32 s10, s10, 0x10000
	s_addc_u32 s11, s11, 0
	global_load_dword v106, v34, s[10:11] nt
	s_add_u32 s10, s10, 0x10000
	s_addc_u32 s11, s11, 0
	global_load_dword v107, v34, s[10:11] nt
	s_add_u32 s10, s10, 0x10000
	s_addc_u32 s11, s11, 0
	global_load_dword v108, v34, s[10:11] nt
	s_add_u32 s10, s10, 0x10000
	s_addc_u32 s11, s11, 0
	global_load_dword v109, v34, s[10:11] nt
	s_add_u32 s10, s10, 0x10000
	s_addc_u32 s11, s11, 0
	global_load_dword v110, v34, s[10:11] nt
	s_add_u32 s10, s10, 0x10000
	s_addc_u32 s11, s11, 0
	global_load_dword v111, v34, s[10:11] nt
	s_mul_i32 s12, s21, 7
	s_add_u32 s12, s12, s8
	s_cmp_ge_u32 s12, 0x400
	s_cbranch_scc1 .Lcv_wo_l1_p0_pf_done
	s_mul_i32 s12, s21, 7
	s_add_u32 s12, s12, s8
	s_lshr_b32 s13, s12, 5
	s_and_b32 s14, s12, 31
	s_mul_i32 s15, s13, 0x80000
	s_lshl_b32 s16, s14, 8
	s_add_u32 s15, s15, s16
	s_add_u32 s10, s4, s15
	s_addc_u32 s11, s5, 0
	global_load_dword v112, v34, s[10:11] nt
	s_add_u32 s10, s10, 0x10000
	s_addc_u32 s11, s11, 0
	global_load_dword v113, v34, s[10:11] nt
	s_add_u32 s10, s10, 0x10000
	s_addc_u32 s11, s11, 0
	global_load_dword v114, v34, s[10:11] nt
	s_add_u32 s10, s10, 0x10000
	s_addc_u32 s11, s11, 0
	global_load_dword v115, v34, s[10:11] nt
	s_add_u32 s10, s10, 0x10000
	s_addc_u32 s11, s11, 0
	global_load_dword v116, v34, s[10:11] nt
	s_add_u32 s10, s10, 0x10000
	s_addc_u32 s11, s11, 0
	global_load_dword v117, v34, s[10:11] nt
	s_add_u32 s10, s10, 0x10000
	s_addc_u32 s11, s11, 0
	global_load_dword v118, v34, s[10:11] nt
	s_add_u32 s10, s10, 0x10000
	s_addc_u32 s11, s11, 0
	global_load_dword v119, v34, s[10:11] nt

; DI int lbid() { int b = blockIdx.x; asm volatile("" : "+s"(b)); return b; }
; template <class Map>
; DI void conv_T(bf16_t* __restrict__ dst, const float* __restrict__ src, int K, int ldsrc, int nphys, Map map, const float* __restrict__ kscale, float* tile) {
;     ...
;   for (int tl = lbid(); tl < ntiles; tl += gridDim.x) {
;     const int k0 = (tl / ntn) << 6, n0 = (tl % ntn) << 6;
;     const int nn = tid & 63, sc = map(n0 + nn);
; #pragma unroll
;     for (int i = 0; i < 8; ++i) { const int kk = i * 8 + (tid >> 6);
;       float v = sc >= 0 ? __builtin_nontemporal_load(&src[(size_t)(k0 + kk) * ldsrc + sc]) : 0.f;
;       if (kscale) v *= kscale[k0 + kk];
;       tile[kk * 65 + nn] = v; }
.Lcv_wo_l1_p0_st_done:
	s_lshl_b32 s12, s21, 2
	s_add_u32 s8, s8, s12
	s_cmp_ge_u32 s8, 0x400
	s_cbranch_scc1 .Lcv_wo_l1_end
	s_waitcnt vmcnt(4)
.Lcv_wo_l1_p1_after:
	ds_write_b32 v31, v88
	ds_write_b32 v31, v89 offset:2080
	ds_write_b32 v31, v90 offset:4160
	ds_write_b32 v31, v91 offset:6240
	ds_write_b32 v31, v92 offset:8320
	ds_write_b32 v31, v93 offset:10400
	ds_write_b32 v31, v94 offset:12480
	ds_write_b32 v31, v95 offset:14560
	s_mul_i32 s12, s21, 1
	s_add_u32 s12, s12, s8
	s_cmp_ge_u32 s12, 0x400
	s_cbranch_scc1 .Lcv_wo_l1_p1_wr_done
	ds_write_b32 v31, v96 offset:16640
	ds_write_b32 v31, v97 offset:18720
	ds_write_b32 v31, v98 offset:20800
	ds_write_b32 v31, v99 offset:22880
	ds_write_b32 v31, v100 offset:24960
	ds_write_b32 v31, v101 offset:27040
	ds_write_b32 v31, v102 offset:29120
	ds_write_b32 v31, v103 offset:31200
	s_mul_i32 s12, s21, 2
	s_add_u32 s12, s12, s8
	s_cmp_ge_u32 s12, 0x400
	s_cbranch_scc1 .Lcv_wo_l1_p1_wr_done
	ds_write_b32 v31, v104 offset:33280
	ds_write_b32 v31, v105 offset:35360
	ds_write_b32 v31, v106 offset:37440
	ds_write_b32 v31, v107 offset:39520
	ds_write_b32 v31, v108 offset:41600
	ds_write_b32 v31, v109 offset:43680
	ds_write_b32 v31, v110 offset:45760
	ds_write_b32 v31, v111 offset:47840
	s_mul_i32 s12, s21, 3
	s_add_u32 s12, s12, s8
	s_cmp_ge_u32 s12, 0x400
	s_cbranch_scc1 .Lcv_wo_l1_p1_wr_done
	ds_write_b32 v31, v112 offset:49920
	ds_write_b32 v31, v113 offset:52000
	ds_write_b32 v31, v114 offset:54080
	ds_write_b32 v31, v115 offset:56160
	ds_write_b32 v31, v116 offset:58240
	ds_write_b32 v31, v117 offset:60320
	ds_write_b32 v31, v118 offset:62400
	ds_write_b32 v31, v119 offset:64480
.Lcv_wo_l1_p1_wr_done:
	s_mul_i32 s12, s21, 4
	s_add_u32 s12, s12, s8
	s_cmp_ge_u32 s12, 0x400
	s_cbranch_scc1 .Lcv_wo_l1_p1_pf_done
	s_mul_i32 s12, s21, 4
	s_add_u32 s12, s12, s8
	s_lshr_b32 s13, s12, 5
	s_and_b32 s14, s12, 31
	s_mul_i32 s15, s13, 0x80000
	s_lshl_b32 s16, s14, 8
	s_add_u32 s15, s15, s16
	s_add_u32 s10, s4, s15
	s_addc_u32 s11, s5, 0
	global_load_dword v40, v34, s[10:11] nt
	s_add_u32 s10, s10, 0x10000
	s_addc_u32 s11, s11, 0
	global_load_dword v41, v34, s[10:11] nt
	s_add_u32 s10, s10, 0x10000
	s_addc_u32 s11, s11, 0
	global_load_dword v42, v34, s[10:11] nt
	s_add_u32 s10, s10, 0x10000
	s_addc_u32 s11, s11, 0
	global_load_dword v43, v34, s[10:11] nt
	s_add_u32 s10, s10, 0x10000
	s_addc_u32 s11, s11, 0
	global_load_dword v44, v34, s[10:11] nt
	s_add_u32 s10, s10, 0x10000
	s_addc_u32 s11, s11, 0
	global_load_dword v45, v34, s[10:11] nt
	s_add_u32 s10, s10, 0x10000
	s_addc_u32 s11, s11, 0
	global_load_dword v46, v34, s[10:11] nt
	s_add_u32 s10, s10, 0x10000
	s_addc_u32 s11, s11, 0
	global_load_dword v47, v34, s[10:11] nt
	s_mul_i32 s12, s21, 5
	s_add_u32 s12, s12, s8
	s_cmp_ge_u32 s12, 0x400
	s_cbranch_scc1 .Lcv_wo_l1_p1_pf_done
	s_mul_i32 s12, s21, 5
	s_add_u32 s12, s12, s8
	s_lshr_b32 s13, s12, 5
	s_and_b32 s14, s12, 31
	s_mul_i32 s15, s13, 0x80000
	s_lshl_b32 s16, s14, 8
	s_add_u32 s15, s15, s16
	s_add_u32 s10, s4, s15
	s_addc_u32 s11, s5, 0
	global_load_dword v48, v34, s[10:11] nt
	s_add_u32 s10, s10, 0x10000
	s_addc_u32 s11, s11, 0
	global_load_dword v49, v34, s[10:11] nt
	s_add_u32 s10, s10, 0x10000
	s_addc_u32 s11, s11, 0
	global_load_dword v50, v34, s[10:11] nt
	s_add_u32 s10, s10, 0x10000
	s_addc_u32 s11, s11, 0
	global_load_dword v51, v34, s[10:11] nt
	s_add_u32 s10, s10, 0x10000
	s_addc_u32 s11, s11, 0
	global_load_dword v52, v34, s[10:11] nt
	s_add_u32 s10, s10, 0x10000
	s_addc_u32 s11, s11, 0
	global_load_dword v53, v34, s[10:11] nt
	s_add_u32 s10, s10, 0x10000
	s_addc_u32 s11, s11, 0
	global_load_dword v54, v34, s[10:11] nt
	s_add_u32 s10, s10, 0x10000
	s_addc_u32 s11, s11, 0
	global_load_dword v55, v34, s[10:11] nt
	s_mul_i32 s12, s21, 6
	s_add_u32 s12, s12, s8
	s_cmp_ge_u32 s12, 0x400
	s_cbranch_scc1 .Lcv_wo_l1_p1_pf_done
	s_mul_i32 s12, s21, 6
	s_add_u32 s12, s12, s8
	s_lshr_b32 s13, s12, 5
	s_and_b32 s14, s12, 31
	s_mul_i32 s15, s13, 0x80000
	s_lshl_b32 s16, s14, 8
	s_add_u32 s15, s15, s16
	s_add_u32 s10, s4, s15
	s_addc_u32 s11, s5, 0
	global_load_dword v56, v34, s[10:11] nt
	s_add_u32 s10, s10, 0x10000
	s_addc_u32 s11, s11, 0
	global_load_dword v57, v34, s[10:11] nt
	s_add_u32 s10, s10, 0x10000
	s_addc_u32 s11, s11, 0
	global_load_dword v58, v34, s[10:11] nt
	s_add_u32 s10, s10, 0x10000
	s_addc_u32 s11, s11, 0
	global_load_dword v59, v34, s[10:11] nt
	s_add_u32 s10, s10, 0x10000
	s_addc_u32 s11, s11, 0
	global_load_dword v60, v34, s[10:11] nt
	s_add_u32 s10, s10, 0x10000
	s_addc_u32 s11, s11, 0
	global_load_dword v61, v34, s[10:11] nt
	s_add_u32 s10, s10, 0x10000
	s_addc_u32 s11, s11, 0
	global_load_dword v62, v34, s[10:11] nt
	s_add_u32 s10, s10, 0x10000
	s_addc_u32 s11, s11, 0
	global_load_dword v63, v34, s[10:11] nt
	s_mul_i32 s12, s21, 7
	s_add_u32 s12, s12, s8
	s_cmp_ge_u32 s12, 0x400
	s_cbranch_scc1 .Lcv_wo_l1_p1_pf_done
	s_mul_i32 s12, s21, 7
	s_add_u32 s12, s12, s8
	s_lshr_b32 s13, s12, 5
	s_and_b32 s14, s12, 31
	s_mul_i32 s15, s13, 0x80000
	s_lshl_b32 s16, s14, 8
	s_add_u32 s15, s15, s16
	s_add_u32 s10, s4, s15
	s_addc_u32 s11, s5, 0
	global_load_dword v64, v34, s[10:11] nt
	s_add_u32 s10, s10, 0x10000
	s_addc_u32 s11, s11, 0
	global_load_dword v65, v34, s[10:11] nt
	s_add_u32 s10, s10, 0x10000
	s_addc_u32 s11, s11, 0
	global_load_dword v66, v34, s[10:11] nt
	s_add_u32 s10, s10, 0x10000
	s_addc_u32 s11, s11, 0
	global_load_dword v67, v34, s[10:11] nt
	s_add_u32 s10, s10, 0x10000
	s_addc_u32 s11, s11, 0
	global_load_dword v68, v34, s[10:11] nt
	s_add_u32 s10, s10, 0x10000
	s_addc_u32 s11, s11, 0
	global_load_dword v69, v34, s[10:11] nt
	s_add_u32 s10, s10, 0x10000
	s_addc_u32 s11, s11, 0
	global_load_dword v70, v34, s[10:11] nt
	s_add_u32 s10, s10, 0x10000
	s_addc_u32 s11, s11, 0
	global_load_dword v71, v34, s[10:11] nt
; DI unsigned cvtpk(float lo, float hi) { unsigned r; asm volatile("v_cvt_pk_bf16_f32 %0, %1, %2" : "=v"(r) : "v"(lo), "v"(hi)); return r; }
; template <class Map>
; DI void conv_T(bf16_t* __restrict__ dst, const float* __restrict__ src, int K, int ldsrc, int nphys, Map map, const float* __restrict__ kscale, float* tile) {
;     ...
;     __syncthreads();
;     const int np = tid >> 3, ks = tid & 7;
;     float v[8];
; #pragma unroll
;     for (int j = 0; j < 8; ++j) v[j] = tile[(ks * 8 + j) * 65 + np];
;     u32x4 w = {cvtpk(v[0], v[1]), cvtpk(v[2], v[3]), cvtpk(v[4], v[5]), cvtpk(v[6], v[7])};
;     *(u32x4*)(dst + (size_t)(n0 + np) * K + k0 + ks * 8) = w;
;     __syncthreads();
.Lcv_wo_l1_p1_pf_done:
	s_waitcnt lgkmcnt(0)
	s_barrier
	ds_read_b32 v88, v33
	ds_read_b32 v89, v33 offset:260
	ds_read_b32 v90, v33 offset:520
	ds_read_b32 v91, v33 offset:780
	ds_read_b32 v92, v33 offset:1040
	ds_read_b32 v93, v33 offset:1300
	ds_read_b32 v94, v33 offset:1560
	ds_read_b32 v95, v33 offset:1820
	s_mul_i32 s12, s21, 1
	s_add_u32 s12, s12, s8
	s_cmp_ge_u32 s12, 0x400
	s_cbranch_scc1 .Lcv_wo_l1_p1_rd_done
	ds_read_b32 v96, v33 offset:16640
	ds_read_b32 v97, v33 offset:16900
	ds_read_b32 v98, v33 offset:17160
	ds_read_b32 v99, v33 offset:17420
	ds_read_b32 v100, v33 offset:17680
	ds_read_b32 v101, v33 offset:17940
	ds_read_b32 v102, v33 offset:18200
	ds_read_b32 v103, v33 offset:18460
	s_mul_i32 s12, s21, 2
	s_add_u32 s12, s12, s8
	s_cmp_ge_u32 s12, 0x400
	s_cbranch_scc1 .Lcv_wo_l1_p1_rd_done
	ds_read_b32 v104, v33 offset:33280
	ds_read_b32 v105, v33 offset:33540
	ds_read_b32 v106, v33 offset:33800
	ds_read_b32 v107, v33 offset:34060
	ds_read_b32 v108, v33 offset:34320
	ds_read_b32 v109, v33 offset:34580
	ds_read_b32 v110, v33 offset:34840
	ds_read_b32 v111, v33 offset:35100
	s_mul_i32 s12, s21, 3
	s_add_u32 s12, s12, s8
	s_cmp_ge_u32 s12, 0x400
	s_cbranch_scc1 .Lcv_wo_l1_p1_rd_done
	ds_read_b32 v112, v33 offset:49920
	ds_read_b32 v113, v33 offset:50180
	ds_read_b32 v114, v33 offset:50440
	ds_read_b32 v115, v33 offset:50700
	ds_read_b32 v116, v33 offset:50960
	ds_read_b32 v117, v33 offset:51220
	ds_read_b32 v118, v33 offset:51480
	ds_read_b32 v119, v33 offset:51740
.Lcv_wo_l1_p1_rd_done:
	s_waitcnt lgkmcnt(0)
	s_mov_b32 s12, s8
	s_lshr_b32 s13, s12, 5
	s_and_b32 s14, s12, 31
	s_mul_i32 s15, s14, 0x40000
	s_lshl_b32 s16, s13, 7
	s_add_u32 s15, s15, s16
	s_add_u32 s10, s6, s15
	s_addc_u32 s11, s7, 0
	v_cvt_pk_bf16_f32 v72, v88, v89
	v_cvt_pk_bf16_f32 v73, v90, v91
	v_cvt_pk_bf16_f32 v74, v92, v93
	v_cvt_pk_bf16_f32 v75, v94, v95
	global_store_dwordx4 v35, v[72:75], s[10:11]
	s_mul_i32 s12, s21, 1
	s_add_u32 s12, s12, s8
	s_cmp_ge_u32 s12, 0x400
	s_cbranch_scc1 .Lcv_wo_l1_p1_st_done
	s_mul_i32 s12, s21, 1
	s_add_u32 s12, s12, s8
	s_lshr_b32 s13, s12, 5
	s_and_b32 s14, s12, 31
	s_mul_i32 s15, s14, 0x40000
	s_lshl_b32 s16, s13, 7
	s_add_u32 s15, s15, s16
	s_add_u32 s10, s6, s15
	s_addc_u32 s11, s7, 0
	v_cvt_pk_bf16_f32 v76, v96, v97
	v_cvt_pk_bf16_f32 v77, v98, v99
	v_cvt_pk_bf16_f32 v78, v100, v101
	v_cvt_pk_bf16_f32 v79, v102, v103
	global_store_dwordx4 v35, v[76:79], s[10:11]
	s_mul_i32 s12, s21, 2
	s_add_u32 s12, s12, s8
	s_cmp_ge_u32 s12, 0x400
	s_cbranch_scc1 .Lcv_wo_l1_p1_st_done
	s_mul_i32 s12, s21, 2
	s_add_u32 s12, s12, s8
	s_lshr_b32 s13, s12, 5
	s_and_b32 s14, s12, 31
	s_mul_i32 s15, s14, 0x40000
	s_lshl_b32 s16, s13, 7
	s_add_u32 s15, s15, s16
	s_add_u32 s10, s6, s15
	s_addc_u32 s11, s7, 0
	v_cvt_pk_bf16_f32 v80, v104, v105
	v_cvt_pk_bf16_f32 v81, v106, v107
	v_cvt_pk_bf16_f32 v82, v108, v109
	v_cvt_pk_bf16_f32 v83, v110, v111
	global_store_dwordx4 v35, v[80:83], s[10:11]
	s_mul_i32 s12, s21, 3
	s_add_u32 s12, s12, s8
	s_cmp_ge_u32 s12, 0x400
	s_cbranch_scc1 .Lcv_wo_l1_p1_st_done
	s_mul_i32 s12, s21, 3
	s_add_u32 s12, s12, s8
	s_lshr_b32 s13, s12, 5
	s_and_b32 s14, s12, 31
	s_mul_i32 s15, s14, 0x40000
	s_lshl_b32 s16, s13, 7
	s_add_u32 s15, s15, s16
	s_add_u32 s10, s6, s15
	s_addc_u32 s11, s7, 0
	v_cvt_pk_bf16_f32 v84, v112, v113
	v_cvt_pk_bf16_f32 v85, v114, v115
	v_cvt_pk_bf16_f32 v86, v116, v117
	v_cvt_pk_bf16_f32 v87, v118, v119
	global_store_dwordx4 v35, v[84:87], s[10:11]

; DI int ltid() { int t = threadIdx.x; asm volatile("" : "+v"(t)); return t; }
; DI int lbid() { int b = blockIdx.x; asm volatile("" : "+s"(b)); return b; }
; template <class Map>
; DI void conv_T(bf16_t* __restrict__ dst, const float* __restrict__ src, int K, int ldsrc, int nphys, Map map, const float* __restrict__ kscale, float* tile) {
;   const int tid = ltid(), ntn = nphys >> 6, ntiles = (K >> 6) * ntn;
;   for (int tl = lbid(); tl < ntiles; tl += gridDim.x) {
;     const int k0 = (tl / ntn) << 6, n0 = (tl % ntn) << 6;
;     const int nn = tid & 63, sc = map(n0 + nn);
; #pragma unroll
;     for (int i = 0; i < 8; ++i) { const int kk = i * 8 + (tid >> 6);
;       float v = sc >= 0 ? __builtin_nontemporal_load(&src[(size_t)(k0 + kk) * ldsrc + sc]) : 0.f;
;       if (kscale) v *= kscale[k0 + kk];
;       tile[kk * 65 + nn] = v; }
; DI void convert_layer(const Params& p, int l, float* tile) {
;     ...
;   conv_T((bf16_t*)(ws + O_WF1), p.w_f1 + (size_t)l * 2048 * 2 * DFF, 2048, 2 * DFF, 2 * DFF, MapF1{}, nullptr, tile);
.Lcv_wo_l1_end:
	s_barrier
	v_readlane_b32 s4, v249, 12
	v_readlane_b32 s5, v249, 13
	s_add_u32 s4, s4, 0x5800000
	s_addc_u32 s5, s5, 0
	s_add_u32 s6, s18, 0x5000000
	s_addc_u32 s7, s19, 0
	v_lshrrev_b32_e32 v36, 6, v248
	v_and_b32_e32 v37, 63, v248
	v_mov_b32_e32 v38, 0xb000
	v_mul_u32_u24_e32 v34, v36, v38
	v_lshrrev_b32_e32 v36, 5, v37
	v_and_b32_e32 v38, 31, v37
	v_lshl_add_u32 v36, v36, 4, v38
	v_and_b32_e32 v38, 16, v37
	v_mul_u32_u24_e32 v38, 0x15f, v38
	v_add_u32_e32 v37, v36, v38
	v_lshl_add_u32 v34, v37, 2, v34
	v_lshrrev_b32_e32 v36, 3, v248
	v_and_b32_e32 v37, 7, v248
	v_mov_b32_e32 v38, 0x1000
	v_mul_u32_u24_e32 v35, v36, v38
	v_lshl_add_u32 v35, v37, 4, v35
	s_mov_b32 s8, s20
	s_cmp_ge_u32 s8, 0x1600
	s_cbranch_scc1 .Lcv_wf1_l1_end
	s_mov_b32 s12, s8
	s_mul_i32 s13, s12, 0xba3
	s_lshr_b32 s13, s13, 19
	s_mul_i32 s14, s13, 176
	s_sub_u32 s14, s12, s14
	s_mul_i32 s15, s13, 0x2c0000
	s_lshl_b32 s16, s14, 7
	s_add_u32 s15, s15, s16
	s_add_u32 s10, s4, s15
	s_addc_u32 s11, s5, 0
	global_load_dword v40, v34, s[10:11] nt
	s_add_u32 s10, s10, 0x58000
	s_addc_u32 s11, s11, 0
	global_load_dword v41, v34, s[10:11] nt
	s_add_u32 s10, s10, 0x58000
	s_addc_u32 s11, s11, 0
	global_load_dword v42, v34, s[10:11] nt
	s_add_u32 s10, s10, 0x58000
	s_addc_u32 s11, s11, 0
	global_load_dword v43, v34, s[10:11] nt
	s_add_u32 s10, s10, 0x58000
	s_addc_u32 s11, s11, 0
	global_load_dword v44, v34, s[10:11] nt
	s_add_u32 s10, s10, 0x58000
	s_addc_u32 s11, s11, 0
	global_load_dword v45, v34, s[10:11] nt
	s_add_u32 s10, s10, 0x58000
	s_addc_u32 s11, s11, 0
	global_load_dword v46, v34, s[10:11] nt
	s_add_u32 s10, s10, 0x58000
	s_addc_u32 s11, s11, 0
	global_load_dword v47, v34, s[10:11] nt
	s_mul_i32 s12, s21, 1
	s_add_u32 s12, s12, s8
	s_cmp_ge_u32 s12, 0x1600
	s_cbranch_scc1 .Lcv_wf1_l1_pro_done
	s_mul_i32 s12, s21, 1
	s_add_u32 s12, s12, s8
	s_mul_i32 s13, s12, 0xba3
	s_lshr_b32 s13, s13, 19
	s_mul_i32 s14, s13, 176
	s_sub_u32 s14, s12, s14
	s_mul_i32 s15, s13, 0x2c0000
	s_lshl_b32 s16, s14, 7
	s_add_u32 s15, s15, s16
	s_add_u32 s10, s4, s15
	s_addc_u32 s11, s5, 0
	global_load_dword v48, v34, s[10:11] nt
	s_add_u32 s10, s10, 0x58000
	s_addc_u32 s11, s11, 0
	global_load_dword v49, v34, s[10:11] nt
	s_add_u32 s10, s10, 0x58000
	s_addc_u32 s11, s11, 0
	global_load_dword v50, v34, s[10:11] nt
	s_add_u32 s10, s10, 0x58000
	s_addc_u32 s11, s11, 0
	global_load_dword v51, v34, s[10:11] nt
	s_add_u32 s10, s10, 0x58000
	s_addc_u32 s11, s11, 0
	global_load_dword v52, v34, s[10:11] nt
	s_add_u32 s10, s10, 0x58000
	s_addc_u32 s11, s11, 0
	global_load_dword v53, v34, s[10:11] nt
	s_add_u32 s10, s10, 0x58000
	s_addc_u32 s11, s11, 0
	global_load_dword v54, v34, s[10:11] nt
	s_add_u32 s10, s10, 0x58000
	s_addc_u32 s11, s11, 0
	global_load_dword v55, v34, s[10:11] nt
	s_mul_i32 s12, s21, 2
	s_add_u32 s12, s12, s8
	s_cmp_ge_u32 s12, 0x1600
	s_cbranch_scc1 .Lcv_wf1_l1_pro_done
	s_mul_i32 s12, s21, 2
	s_add_u32 s12, s12, s8
	s_mul_i32 s13, s12, 0xba3
	s_lshr_b32 s13, s13, 19
	s_mul_i32 s14, s13, 176
	s_sub_u32 s14, s12, s14
	s_mul_i32 s15, s13, 0x2c0000
	s_lshl_b32 s16, s14, 7
	s_add_u32 s15, s15, s16
	s_add_u32 s10, s4, s15
	s_addc_u32 s11, s5, 0
	global_load_dword v56, v34, s[10:11] nt
	s_add_u32 s10, s10, 0x58000
	s_addc_u32 s11, s11, 0
	global_load_dword v57, v34, s[10:11] nt
	s_add_u32 s10, s10, 0x58000
	s_addc_u32 s11, s11, 0
	global_load_dword v58, v34, s[10:11] nt
	s_add_u32 s10, s10, 0x58000
	s_addc_u32 s11, s11, 0
	global_load_dword v59, v34, s[10:11] nt
	s_add_u32 s10, s10, 0x58000
	s_addc_u32 s11, s11, 0
	global_load_dword v60, v34, s[10:11] nt
	s_add_u32 s10, s10, 0x58000
	s_addc_u32 s11, s11, 0
	global_load_dword v61, v34, s[10:11] nt
	s_add_u32 s10, s10, 0x58000
	s_addc_u32 s11, s11, 0
	global_load_dword v62, v34, s[10:11] nt
	s_add_u32 s10, s10, 0x58000
	s_addc_u32 s11, s11, 0
	global_load_dword v63, v34, s[10:11] nt
	s_mul_i32 s12, s21, 3
	s_add_u32 s12, s12, s8
	s_cmp_ge_u32 s12, 0x1600
	s_cbranch_scc1 .Lcv_wf1_l1_pro_done
	s_mul_i32 s12, s21, 3
	s_add_u32 s12, s12, s8
	s_mul_i32 s13, s12, 0xba3
	s_lshr_b32 s13, s13, 19
	s_mul_i32 s14, s13, 176
	s_sub_u32 s14, s12, s14
	s_mul_i32 s15, s13, 0x2c0000
	s_lshl_b32 s16, s14, 7
	s_add_u32 s15, s15, s16
	s_add_u32 s10, s4, s15
	s_addc_u32 s11, s5, 0
	global_load_dword v64, v34, s[10:11] nt
	s_add_u32 s10, s10, 0x58000
	s_addc_u32 s11, s11, 0
	global_load_dword v65, v34, s[10:11] nt
	s_add_u32 s10, s10, 0x58000
	s_addc_u32 s11, s11, 0
	global_load_dword v66, v34, s[10:11] nt
	s_add_u32 s10, s10, 0x58000
	s_addc_u32 s11, s11, 0
	global_load_dword v67, v34, s[10:11] nt
	s_add_u32 s10, s10, 0x58000
	s_addc_u32 s11, s11, 0
	global_load_dword v68, v34, s[10:11] nt
	s_add_u32 s10, s10, 0x58000
	s_addc_u32 s11, s11, 0
	global_load_dword v69, v34, s[10:11] nt
	s_add_u32 s10, s10, 0x58000
	s_addc_u32 s11, s11, 0
	global_load_dword v70, v34, s[10:11] nt
	s_add_u32 s10, s10, 0x58000
	s_addc_u32 s11, s11, 0
	global_load_dword v71, v34, s[10:11] nt

; DI int lbid() { int b = blockIdx.x; asm volatile("" : "+s"(b)); return b; }
; template <class Map>
; DI void conv_T(bf16_t* __restrict__ dst, const float* __restrict__ src, int K, int ldsrc, int nphys, Map map, const float* __restrict__ kscale, float* tile) {
;     ...
;   for (int tl = lbid(); tl < ntiles; tl += gridDim.x) {
;     const int k0 = (tl / ntn) << 6, n0 = (tl % ntn) << 6;
;     const int nn = tid & 63, sc = map(n0 + nn);
; #pragma unroll
;     for (int i = 0; i < 8; ++i) { const int kk = i * 8 + (tid >> 6);
;       float v = sc >= 0 ? __builtin_nontemporal_load(&src[(size_t)(k0 + kk) * ldsrc + sc]) : 0.f;
;       if (kscale) v *= kscale[k0 + kk];
;       tile[kk * 65 + nn] = v; }
.Lcv_wf1_l1_p0_after:
	ds_write_b32 v30, v40
	ds_write_b32 v30, v41 offset:2080
	ds_write_b32 v30, v42 offset:4160
	ds_write_b32 v30, v43 offset:6240
	ds_write_b32 v30, v44 offset:8320
	ds_write_b32 v30, v45 offset:10400
	ds_write_b32 v30, v46 offset:12480
	ds_write_b32 v30, v47 offset:14560
	s_mul_i32 s12, s21, 1
	s_add_u32 s12, s12, s8
	s_cmp_ge_u32 s12, 0x1600
	s_cbranch_scc1 .Lcv_wf1_l1_p0_wr_done
	ds_write_b32 v30, v48 offset:16640
	ds_write_b32 v30, v49 offset:18720
	ds_write_b32 v30, v50 offset:20800
	ds_write_b32 v30, v51 offset:22880
	ds_write_b32 v30, v52 offset:24960
	ds_write_b32 v30, v53 offset:27040
	ds_write_b32 v30, v54 offset:29120
	ds_write_b32 v30, v55 offset:31200
	s_mul_i32 s12, s21, 2
	s_add_u32 s12, s12, s8
	s_cmp_ge_u32 s12, 0x1600
	s_cbranch_scc1 .Lcv_wf1_l1_p0_wr_done
	ds_write_b32 v30, v56 offset:33280
	ds_write_b32 v30, v57 offset:35360
	ds_write_b32 v30, v58 offset:37440
	ds_write_b32 v30, v59 offset:39520
	ds_write_b32 v30, v60 offset:41600
	ds_write_b32 v30, v61 offset:43680
	ds_write_b32 v30, v62 offset:45760
	ds_write_b32 v30, v63 offset:47840
	s_mul_i32 s12, s21, 3
	s_add_u32 s12, s12, s8
	s_cmp_ge_u32 s12, 0x1600
	s_cbranch_scc1 .Lcv_wf1_l1_p0_wr_done
	ds_write_b32 v30, v64 offset:49920
	ds_write_b32 v30, v65 offset:52000
	ds_write_b32 v30, v66 offset:54080
	ds_write_b32 v30, v67 offset:56160
	ds_write_b32 v30, v68 offset:58240
	ds_write_b32 v30, v69 offset:60320
	ds_write_b32 v30, v70 offset:62400
	ds_write_b32 v30, v71 offset:64480
.Lcv_wf1_l1_p0_wr_done:
	s_mul_i32 s12, s21, 4
	s_add_u32 s12, s12, s8
	s_cmp_ge_u32 s12, 0x1600
	s_cbranch_scc1 .Lcv_wf1_l1_p0_pf_done
	s_mul_i32 s12, s21, 4
	s_add_u32 s12, s12, s8
	s_mul_i32 s13, s12, 0xba3
	s_lshr_b32 s13, s13, 19
	s_mul_i32 s14, s13, 176
	s_sub_u32 s14, s12, s14
	s_mul_i32 s15, s13, 0x2c0000
	s_lshl_b32 s16, s14, 7
	s_add_u32 s15, s15, s16
	s_add_u32 s10, s4, s15
	s_addc_u32 s11, s5, 0
	global_load_dword v88, v34, s[10:11] nt
	s_add_u32 s10, s10, 0x58000
	s_addc_u32 s11, s11, 0
	global_load_dword v89, v34, s[10:11] nt
	s_add_u32 s10, s10, 0x58000
	s_addc_u32 s11, s11, 0
	global_load_dword v90, v34, s[10:11] nt
	s_add_u32 s10, s10, 0x58000
	s_addc_u32 s11, s11, 0
	global_load_dword v91, v34, s[10:11] nt
	s_add_u32 s10, s10, 0x58000
	s_addc_u32 s11, s11, 0
	global_load_dword v92, v34, s[10:11] nt
	s_add_u32 s10, s10, 0x58000
	s_addc_u32 s11, s11, 0
	global_load_dword v93, v34, s[10:11] nt
	s_add_u32 s10, s10, 0x58000
	s_addc_u32 s11, s11, 0
	global_load_dword v94, v34, s[10:11] nt
	s_add_u32 s10, s10, 0x58000
	s_addc_u32 s11, s11, 0
	global_load_dword v95, v34, s[10:11] nt
	s_mul_i32 s12, s21, 5
	s_add_u32 s12, s12, s8
	s_cmp_ge_u32 s12, 0x1600
	s_cbranch_scc1 .Lcv_wf1_l1_p0_pf_done
	s_mul_i32 s12, s21, 5
	s_add_u32 s12, s12, s8
	s_mul_i32 s13, s12, 0xba3
	s_lshr_b32 s13, s13, 19
	s_mul_i32 s14, s13, 176
	s_sub_u32 s14, s12, s14
	s_mul_i32 s15, s13, 0x2c0000
	s_lshl_b32 s16, s14, 7
	s_add_u32 s15, s15, s16
	s_add_u32 s10, s4, s15
	s_addc_u32 s11, s5, 0
	global_load_dword v96, v34, s[10:11] nt
	s_add_u32 s10, s10, 0x58000
	s_addc_u32 s11, s11, 0
	global_load_dword v97, v34, s[10:11] nt
	s_add_u32 s10, s10, 0x58000
	s_addc_u32 s11, s11, 0
	global_load_dword v98, v34, s[10:11] nt
	s_add_u32 s10, s10, 0x58000
	s_addc_u32 s11, s11, 0
	global_load_dword v99, v34, s[10:11] nt
	s_add_u32 s10, s10, 0x58000
	s_addc_u32 s11, s11, 0
	global_load_dword v100, v34, s[10:11] nt
	s_add_u32 s10, s10, 0x58000
	s_addc_u32 s11, s11, 0
	global_load_dword v101, v34, s[10:11] nt
	s_add_u32 s10, s10, 0x58000
	s_addc_u32 s11, s11, 0
	global_load_dword v102, v34, s[10:11] nt
	s_add_u32 s10, s10, 0x58000
	s_addc_u32 s11, s11, 0
	global_load_dword v103, v34, s[10:11] nt
	s_mul_i32 s12, s21, 6
	s_add_u32 s12, s12, s8
	s_cmp_ge_u32 s12, 0x1600
	s_cbranch_scc1 .Lcv_wf1_l1_p0_pf_done
	s_mul_i32 s12, s21, 6
	s_add_u32 s12, s12, s8
	s_mul_i32 s13, s12, 0xba3
	s_lshr_b32 s13, s13, 19
	s_mul_i32 s14, s13, 176
	s_sub_u32 s14, s12, s14
	s_mul_i32 s15, s13, 0x2c0000
	s_lshl_b32 s16, s14, 7
	s_add_u32 s15, s15, s16
	s_add_u32 s10, s4, s15
	s_addc_u32 s11, s5, 0
	global_load_dword v104, v34, s[10:11] nt
	s_add_u32 s10, s10, 0x58000
	s_addc_u32 s11, s11, 0
	global_load_dword v105, v34, s[10:11] nt
	s_add_u32 s10, s10, 0x58000
	s_addc_u32 s11, s11, 0
	global_load_dword v106, v34, s[10:11] nt
	s_add_u32 s10, s10, 0x58000
	s_addc_u32 s11, s11, 0
	global_load_dword v107, v34, s[10:11] nt
	s_add_u32 s10, s10, 0x58000
	s_addc_u32 s11, s11, 0
	global_load_dword v108, v34, s[10:11] nt
	s_add_u32 s10, s10, 0x58000
	s_addc_u32 s11, s11, 0
	global_load_dword v109, v34, s[10:11] nt
	s_add_u32 s10, s10, 0x58000
	s_addc_u32 s11, s11, 0
	global_load_dword v110, v34, s[10:11] nt
	s_add_u32 s10, s10, 0x58000
	s_addc_u32 s11, s11, 0
	global_load_dword v111, v34, s[10:11] nt
	s_mul_i32 s12, s21, 7
	s_add_u32 s12, s12, s8
	s_cmp_ge_u32 s12, 0x1600
	s_cbranch_scc1 .Lcv_wf1_l1_p0_pf_done
	s_mul_i32 s12, s21, 7
	s_add_u32 s12, s12, s8
	s_mul_i32 s13, s12, 0xba3
	s_lshr_b32 s13, s13, 19
	s_mul_i32 s14, s13, 176
	s_sub_u32 s14, s12, s14
	s_mul_i32 s15, s13, 0x2c0000
	s_lshl_b32 s16, s14, 7
	s_add_u32 s15, s15, s16
	s_add_u32 s10, s4, s15
	s_addc_u32 s11, s5, 0
	global_load_dword v112, v34, s[10:11] nt
	s_add_u32 s10, s10, 0x58000
	s_addc_u32 s11, s11, 0
	global_load_dword v113, v34, s[10:11] nt
	s_add_u32 s10, s10, 0x58000
	s_addc_u32 s11, s11, 0
	global_load_dword v114, v34, s[10:11] nt
	s_add_u32 s10, s10, 0x58000
	s_addc_u32 s11, s11, 0
	global_load_dword v115, v34, s[10:11] nt
	s_add_u32 s10, s10, 0x58000
	s_addc_u32 s11, s11, 0
	global_load_dword v116, v34, s[10:11] nt
	s_add_u32 s10, s10, 0x58000
	s_addc_u32 s11, s11, 0
	global_load_dword v117, v34, s[10:11] nt
	s_add_u32 s10, s10, 0x58000
	s_addc_u32 s11, s11, 0
	global_load_dword v118, v34, s[10:11] nt
	s_add_u32 s10, s10, 0x58000
	s_addc_u32 s11, s11, 0
	global_load_dword v119, v34, s[10:11] nt

; DI int lbid() { int b = blockIdx.x; asm volatile("" : "+s"(b)); return b; }
; template <class Map>
; DI void conv_T(bf16_t* __restrict__ dst, const float* __restrict__ src, int K, int ldsrc, int nphys, Map map, const float* __restrict__ kscale, float* tile) {
;     ...
;   for (int tl = lbid(); tl < ntiles; tl += gridDim.x) {
;     const int k0 = (tl / ntn) << 6, n0 = (tl % ntn) << 6;
;     const int nn = tid & 63, sc = map(n0 + nn);
; #pragma unroll
;     for (int i = 0; i < 8; ++i) { const int kk = i * 8 + (tid >> 6);
;       float v = sc >= 0 ? __builtin_nontemporal_load(&src[(size_t)(k0 + kk) * ldsrc + sc]) : 0.f;
;       if (kscale) v *= kscale[k0 + kk];
;       tile[kk * 65 + nn] = v; }
.Lcv_wf1_l1_p0_st_done:
	s_lshl_b32 s12, s21, 2
	s_add_u32 s8, s8, s12
	s_cmp_ge_u32 s8, 0x1600
	s_cbranch_scc1 .Lcv_wf1_l1_end
	s_waitcnt vmcnt(4)
.Lcv_wf1_l1_p1_after:
	ds_write_b32 v31, v88
	ds_write_b32 v31, v89 offset:2080
	ds_write_b32 v31, v90 offset:4160
	ds_write_b32 v31, v91 offset:6240
	ds_write_b32 v31, v92 offset:8320
	ds_write_b32 v31, v93 offset:10400
	ds_write_b32 v31, v94 offset:12480
	ds_write_b32 v31, v95 offset:14560
	s_mul_i32 s12, s21, 1
	s_add_u32 s12, s12, s8
	s_cmp_ge_u32 s12, 0x1600
	s_cbranch_scc1 .Lcv_wf1_l1_p1_wr_done
	ds_write_b32 v31, v96 offset:16640
	ds_write_b32 v31, v97 offset:18720
	ds_write_b32 v31, v98 offset:20800
	ds_write_b32 v31, v99 offset:22880
	ds_write_b32 v31, v100 offset:24960
	ds_write_b32 v31, v101 offset:27040
	ds_write_b32 v31, v102 offset:29120
	ds_write_b32 v31, v103 offset:31200
	s_mul_i32 s12, s21, 2
	s_add_u32 s12, s12, s8
	s_cmp_ge_u32 s12, 0x1600
	s_cbranch_scc1 .Lcv_wf1_l1_p1_wr_done
	ds_write_b32 v31, v104 offset:33280
	ds_write_b32 v31, v105 offset:35360
	ds_write_b32 v31, v106 offset:37440
	ds_write_b32 v31, v107 offset:39520
	ds_write_b32 v31, v108 offset:41600
	ds_write_b32 v31, v109 offset:43680
	ds_write_b32 v31, v110 offset:45760
	ds_write_b32 v31, v111 offset:47840
	s_mul_i32 s12, s21, 3
	s_add_u32 s12, s12, s8
	s_cmp_ge_u32 s12, 0x1600
	s_cbranch_scc1 .Lcv_wf1_l1_p1_wr_done
	ds_write_b32 v31, v112 offset:49920
	ds_write_b32 v31, v113 offset:52000
	ds_write_b32 v31, v114 offset:54080
	ds_write_b32 v31, v115 offset:56160
	ds_write_b32 v31, v116 offset:58240
	ds_write_b32 v31, v117 offset:60320
	ds_write_b32 v31, v118 offset:62400
	ds_write_b32 v31, v119 offset:64480
.Lcv_wf1_l1_p1_wr_done:
	s_mul_i32 s12, s21, 4
	s_add_u32 s12, s12, s8
	s_cmp_ge_u32 s12, 0x1600
	s_cbranch_scc1 .Lcv_wf1_l1_p1_pf_done
	s_mul_i32 s12, s21, 4
	s_add_u32 s12, s12, s8
	s_mul_i32 s13, s12, 0xba3
	s_lshr_b32 s13, s13, 19
	s_mul_i32 s14, s13, 176
	s_sub_u32 s14, s12, s14
	s_mul_i32 s15, s13, 0x2c0000
	s_lshl_b32 s16, s14, 7
	s_add_u32 s15, s15, s16
	s_add_u32 s10, s4, s15
	s_addc_u32 s11, s5, 0
	global_load_dword v40, v34, s[10:11] nt
	s_add_u32 s10, s10, 0x58000
	s_addc_u32 s11, s11, 0
	global_load_dword v41, v34, s[10:11] nt
	s_add_u32 s10, s10, 0x58000
	s_addc_u32 s11, s11, 0
	global_load_dword v42, v34, s[10:11] nt
	s_add_u32 s10, s10, 0x58000
	s_addc_u32 s11, s11, 0
	global_load_dword v43, v34, s[10:11] nt
	s_add_u32 s10, s10, 0x58000
	s_addc_u32 s11, s11, 0
	global_load_dword v44, v34, s[10:11] nt
	s_add_u32 s10, s10, 0x58000
	s_addc_u32 s11, s11, 0
	global_load_dword v45, v34, s[10:11] nt
	s_add_u32 s10, s10, 0x58000
	s_addc_u32 s11, s11, 0
	global_load_dword v46, v34, s[10:11] nt
	s_add_u32 s10, s10, 0x58000
	s_addc_u32 s11, s11, 0
	global_load_dword v47, v34, s[10:11] nt
	s_mul_i32 s12, s21, 5
	s_add_u32 s12, s12, s8
	s_cmp_ge_u32 s12, 0x1600
	s_cbranch_scc1 .Lcv_wf1_l1_p1_pf_done
	s_mul_i32 s12, s21, 5
	s_add_u32 s12, s12, s8
	s_mul_i32 s13, s12, 0xba3
	s_lshr_b32 s13, s13, 19
	s_mul_i32 s14, s13, 176
	s_sub_u32 s14, s12, s14
	s_mul_i32 s15, s13, 0x2c0000
	s_lshl_b32 s16, s14, 7
	s_add_u32 s15, s15, s16
	s_add_u32 s10, s4, s15
	s_addc_u32 s11, s5, 0
	global_load_dword v48, v34, s[10:11] nt
	s_add_u32 s10, s10, 0x58000
	s_addc_u32 s11, s11, 0
	global_load_dword v49, v34, s[10:11] nt
	s_add_u32 s10, s10, 0x58000
	s_addc_u32 s11, s11, 0
	global_load_dword v50, v34, s[10:11] nt
	s_add_u32 s10, s10, 0x58000
	s_addc_u32 s11, s11, 0
	global_load_dword v51, v34, s[10:11] nt
	s_add_u32 s10, s10, 0x58000
	s_addc_u32 s11, s11, 0
	global_load_dword v52, v34, s[10:11] nt
	s_add_u32 s10, s10, 0x58000
	s_addc_u32 s11, s11, 0
	global_load_dword v53, v34, s[10:11] nt
	s_add_u32 s10, s10, 0x58000
	s_addc_u32 s11, s11, 0
	global_load_dword v54, v34, s[10:11] nt
	s_add_u32 s10, s10, 0x58000
	s_addc_u32 s11, s11, 0
	global_load_dword v55, v34, s[10:11] nt
	s_mul_i32 s12, s21, 6
	s_add_u32 s12, s12, s8
	s_cmp_ge_u32 s12, 0x1600
	s_cbranch_scc1 .Lcv_wf1_l1_p1_pf_done
	s_mul_i32 s12, s21, 6
	s_add_u32 s12, s12, s8
	s_mul_i32 s13, s12, 0xba3
	s_lshr_b32 s13, s13, 19
	s_mul_i32 s14, s13, 176
	s_sub_u32 s14, s12, s14
	s_mul_i32 s15, s13, 0x2c0000
	s_lshl_b32 s16, s14, 7
	s_add_u32 s15, s15, s16
	s_add_u32 s10, s4, s15
	s_addc_u32 s11, s5, 0
	global_load_dword v56, v34, s[10:11] nt
	s_add_u32 s10, s10, 0x58000
	s_addc_u32 s11, s11, 0
	global_load_dword v57, v34, s[10:11] nt
	s_add_u32 s10, s10, 0x58000
	s_addc_u32 s11, s11, 0
	global_load_dword v58, v34, s[10:11] nt
	s_add_u32 s10, s10, 0x58000
	s_addc_u32 s11, s11, 0
	global_load_dword v59, v34, s[10:11] nt
	s_add_u32 s10, s10, 0x58000
	s_addc_u32 s11, s11, 0
	global_load_dword v60, v34, s[10:11] nt
	s_add_u32 s10, s10, 0x58000
	s_addc_u32 s11, s11, 0
	global_load_dword v61, v34, s[10:11] nt
	s_add_u32 s10, s10, 0x58000
	s_addc_u32 s11, s11, 0
	global_load_dword v62, v34, s[10:11] nt
	s_add_u32 s10, s10, 0x58000
	s_addc_u32 s11, s11, 0
	global_load_dword v63, v34, s[10:11] nt
	s_mul_i32 s12, s21, 7
	s_add_u32 s12, s12, s8
	s_cmp_ge_u32 s12, 0x1600
	s_cbranch_scc1 .Lcv_wf1_l1_p1_pf_done
	s_mul_i32 s12, s21, 7
	s_add_u32 s12, s12, s8
	s_mul_i32 s13, s12, 0xba3
	s_lshr_b32 s13, s13, 19
	s_mul_i32 s14, s13, 176
	s_sub_u32 s14, s12, s14
	s_mul_i32 s15, s13, 0x2c0000
	s_lshl_b32 s16, s14, 7
	s_add_u32 s15, s15, s16
	s_add_u32 s10, s4, s15
	s_addc_u32 s11, s5, 0
	global_load_dword v64, v34, s[10:11] nt
	s_add_u32 s10, s10, 0x58000
	s_addc_u32 s11, s11, 0
	global_load_dword v65, v34, s[10:11] nt
	s_add_u32 s10, s10, 0x58000
	s_addc_u32 s11, s11, 0
	global_load_dword v66, v34, s[10:11] nt
	s_add_u32 s10, s10, 0x58000
	s_addc_u32 s11, s11, 0
	global_load_dword v67, v34, s[10:11] nt
	s_add_u32 s10, s10, 0x58000
	s_addc_u32 s11, s11, 0
	global_load_dword v68, v34, s[10:11] nt
	s_add_u32 s10, s10, 0x58000
	s_addc_u32 s11, s11, 0
	global_load_dword v69, v34, s[10:11] nt
	s_add_u32 s10, s10, 0x58000
	s_addc_u32 s11, s11, 0
	global_load_dword v70, v34, s[10:11] nt
	s_add_u32 s10, s10, 0x58000
	s_addc_u32 s11, s11, 0
	global_load_dword v71, v34, s[10:11] nt
; DI unsigned cvtpk(float lo, float hi) { unsigned r; asm volatile("v_cvt_pk_bf16_f32 %0, %1, %2" : "=v"(r) : "v"(lo), "v"(hi)); return r; }
; template <class Map>
; DI void conv_T(bf16_t* __restrict__ dst, const float* __restrict__ src, int K, int ldsrc, int nphys, Map map, const float* __restrict__ kscale, float* tile) {
;     ...
;     __syncthreads();
;     const int np = tid >> 3, ks = tid & 7;
;     float v[8];
; #pragma unroll
;     for (int j = 0; j < 8; ++j) v[j] = tile[(ks * 8 + j) * 65 + np];
;     u32x4 w = {cvtpk(v[0], v[1]), cvtpk(v[2], v[3]), cvtpk(v[4], v[5]), cvtpk(v[6], v[7])};
;     *(u32x4*)(dst + (size_t)(n0 + np) * K + k0 + ks * 8) = w;
;     __syncthreads();
.Lcv_wf1_l1_p1_pf_done:
	s_waitcnt lgkmcnt(0)
	s_barrier
	ds_read_b32 v88, v33
	ds_read_b32 v89, v33 offset:260
	ds_read_b32 v90, v33 offset:520
	ds_read_b32 v91, v33 offset:780
	ds_read_b32 v92, v33 offset:1040
	ds_read_b32 v93, v33 offset:1300
	ds_read_b32 v94, v33 offset:1560
	ds_read_b32 v95, v33 offset:1820
	s_mul_i32 s12, s21, 1
	s_add_u32 s12, s12, s8
	s_cmp_ge_u32 s12, 0x1600
	s_cbranch_scc1 .Lcv_wf1_l1_p1_rd_done
	ds_read_b32 v96, v33 offset:16640
	ds_read_b32 v97, v33 offset:16900
	ds_read_b32 v98, v33 offset:17160
	ds_read_b32 v99, v33 offset:17420
	ds_read_b32 v100, v33 offset:17680
	ds_read_b32 v101, v33 offset:17940
	ds_read_b32 v102, v33 offset:18200
	ds_read_b32 v103, v33 offset:18460
	s_mul_i32 s12, s21, 2
	s_add_u32 s12, s12, s8
	s_cmp_ge_u32 s12, 0x1600
	s_cbranch_scc1 .Lcv_wf1_l1_p1_rd_done
	ds_read_b32 v104, v33 offset:33280
	ds_read_b32 v105, v33 offset:33540
	ds_read_b32 v106, v33 offset:33800
	ds_read_b32 v107, v33 offset:34060
	ds_read_b32 v108, v33 offset:34320
	ds_read_b32 v109, v33 offset:34580
	ds_read_b32 v110, v33 offset:34840
	ds_read_b32 v111, v33 offset:35100
	s_mul_i32 s12, s21, 3
	s_add_u32 s12, s12, s8
	s_cmp_ge_u32 s12, 0x1600
	s_cbranch_scc1 .Lcv_wf1_l1_p1_rd_done
	ds_read_b32 v112, v33 offset:49920
	ds_read_b32 v113, v33 offset:50180
	ds_read_b32 v114, v33 offset:50440
	ds_read_b32 v115, v33 offset:50700
	ds_read_b32 v116, v33 offset:50960
	ds_read_b32 v117, v33 offset:51220
	ds_read_b32 v118, v33 offset:51480
	ds_read_b32 v119, v33 offset:51740
.Lcv_wf1_l1_p1_rd_done:
	s_waitcnt lgkmcnt(0)
	s_mov_b32 s12, s8
	s_mul_i32 s13, s12, 0xba3
	s_lshr_b32 s13, s13, 19
	s_mul_i32 s14, s13, 176
	s_sub_u32 s14, s12, s14
	s_mul_i32 s15, s14, 0x40000
	s_lshl_b32 s16, s13, 7
	s_add_u32 s15, s15, s16
	s_add_u32 s10, s6, s15
	s_addc_u32 s11, s7, 0
	v_cvt_pk_bf16_f32 v72, v88, v89
	v_cvt_pk_bf16_f32 v73, v90, v91
	v_cvt_pk_bf16_f32 v74, v92, v93
	v_cvt_pk_bf16_f32 v75, v94, v95
	global_store_dwordx4 v35, v[72:75], s[10:11]
	s_mul_i32 s12, s21, 1
	s_add_u32 s12, s12, s8
	s_cmp_ge_u32 s12, 0x1600
	s_cbranch_scc1 .Lcv_wf1_l1_p1_st_done
	s_mul_i32 s12, s21, 1
	s_add_u32 s12, s12, s8
	s_mul_i32 s13, s12, 0xba3
	s_lshr_b32 s13, s13, 19
	s_mul_i32 s14, s13, 176
	s_sub_u32 s14, s12, s14
	s_mul_i32 s15, s14, 0x40000
	s_lshl_b32 s16, s13, 7
	s_add_u32 s15, s15, s16
	s_add_u32 s10, s6, s15
	s_addc_u32 s11, s7, 0
	v_cvt_pk_bf16_f32 v76, v96, v97
	v_cvt_pk_bf16_f32 v77, v98, v99
	v_cvt_pk_bf16_f32 v78, v100, v101
	v_cvt_pk_bf16_f32 v79, v102, v103
	global_store_dwordx4 v35, v[76:79], s[10:11]
	s_mul_i32 s12, s21, 2
	s_add_u32 s12, s12, s8
	s_cmp_ge_u32 s12, 0x1600
	s_cbranch_scc1 .Lcv_wf1_l1_p1_st_done
	s_mul_i32 s12, s21, 2
	s_add_u32 s12, s12, s8
	s_mul_i32 s13, s12, 0xba3
	s_lshr_b32 s13, s13, 19
	s_mul_i32 s14, s13, 176
	s_sub_u32 s14, s12, s14
	s_mul_i32 s15, s14, 0x40000
	s_lshl_b32 s16, s13, 7
	s_add_u32 s15, s15, s16
	s_add_u32 s10, s6, s15
	s_addc_u32 s11, s7, 0
	v_cvt_pk_bf16_f32 v80, v104, v105
	v_cvt_pk_bf16_f32 v81, v106, v107
	v_cvt_pk_bf16_f32 v82, v108, v109
	v_cvt_pk_bf16_f32 v83, v110, v111
	global_store_dwordx4 v35, v[80:83], s[10:11]
	s_mul_i32 s12, s21, 3
	s_add_u32 s12, s12, s8
	s_cmp_ge_u32 s12, 0x1600
	s_cbranch_scc1 .Lcv_wf1_l1_p1_st_done
	s_mul_i32 s12, s21, 3
	s_add_u32 s12, s12, s8
	s_mul_i32 s13, s12, 0xba3
	s_lshr_b32 s13, s13, 19
	s_mul_i32 s14, s13, 176
	s_sub_u32 s14, s12, s14
	s_mul_i32 s15, s14, 0x40000
	s_lshl_b32 s16, s13, 7
	s_add_u32 s15, s15, s16
	s_add_u32 s10, s6, s15
	s_addc_u32 s11, s7, 0
	v_cvt_pk_bf16_f32 v84, v112, v113
	v_cvt_pk_bf16_f32 v85, v114, v115
	v_cvt_pk_bf16_f32 v86, v116, v117
	v_cvt_pk_bf16_f32 v87, v118, v119
	global_store_dwordx4 v35, v[84:87], s[10:11]

; DI int ltid() { int t = threadIdx.x; asm volatile("" : "+v"(t)); return t; }
; DI int lbid() { int b = blockIdx.x; asm volatile("" : "+s"(b)); return b; }
; template <class Map>
; DI void conv_T(bf16_t* __restrict__ dst, const float* __restrict__ src, int K, int ldsrc, int nphys, Map map, const float* __restrict__ kscale, float* tile) {
;   const int tid = ltid(), ntn = nphys >> 6, ntiles = (K >> 6) * ntn;
;   for (int tl = lbid(); tl < ntiles; tl += gridDim.x) {
;     const int k0 = (tl / ntn) << 6, n0 = (tl % ntn) << 6;
;     const int nn = tid & 63, sc = map(n0 + nn);
; #pragma unroll
;     for (int i = 0; i < 8; ++i) { const int kk = i * 8 + (tid >> 6);
;       float v = sc >= 0 ? __builtin_nontemporal_load(&src[(size_t)(k0 + kk) * ldsrc + sc]) : 0.f;
;       if (kscale) v *= kscale[k0 + kk];
;       tile[kk * 65 + nn] = v; }
; DI void convert_layer(const Params& p, int l, float* tile) {
;     ...
;   conv_T((bf16_t*)(ws + O_WF2), p.w_f2 + (size_t)l * DFF * 2048, DFF, 2048, 2048, MapId{0}, nullptr, tile);
.Lcv_wf1_l1_end:
	s_barrier
	v_readlane_b32 s4, v249, 14
	v_readlane_b32 s5, v249, 15
	s_add_u32 s4, s4, 0x2c00000
	s_addc_u32 s5, s5, 0
	s_add_u32 s6, s18, 0x7c00000
	s_addc_u32 s7, s19, 0
	v_lshrrev_b32_e32 v36, 6, v248
	v_and_b32_e32 v37, 63, v248
	v_mov_b32_e32 v38, 0x2000
	v_mul_u32_u24_e32 v34, v36, v38
	v_lshl_add_u32 v34, v37, 2, v34
	v_lshrrev_b32_e32 v36, 3, v248
	v_and_b32_e32 v37, 7, v248
	v_mov_b32_e32 v38, 0x2c00
	v_mul_u32_u24_e32 v35, v36, v38
	v_lshl_add_u32 v35, v37, 4, v35
	s_mov_b32 s8, s20
	s_cmp_ge_u32 s8, 0xb00
	s_cbranch_scc1 .Lcv_wf2_l1_end
	s_mov_b32 s12, s8
	s_lshr_b32 s13, s12, 5
	s_and_b32 s14, s12, 31
	s_mul_i32 s15, s13, 0x80000
	s_lshl_b32 s16, s14, 8
	s_add_u32 s15, s15, s16
	s_add_u32 s10, s4, s15
	s_addc_u32 s11, s5, 0
	global_load_dword v40, v34, s[10:11] nt
	s_add_u32 s10, s10, 0x10000
	s_addc_u32 s11, s11, 0
	global_load_dword v41, v34, s[10:11] nt
	s_add_u32 s10, s10, 0x10000
	s_addc_u32 s11, s11, 0
	global_load_dword v42, v34, s[10:11] nt
	s_add_u32 s10, s10, 0x10000
	s_addc_u32 s11, s11, 0
	global_load_dword v43, v34, s[10:11] nt
	s_add_u32 s10, s10, 0x10000
	s_addc_u32 s11, s11, 0
	global_load_dword v44, v34, s[10:11] nt
	s_add_u32 s10, s10, 0x10000
	s_addc_u32 s11, s11, 0
	global_load_dword v45, v34, s[10:11] nt
	s_add_u32 s10, s10, 0x10000
	s_addc_u32 s11, s11, 0
	global_load_dword v46, v34, s[10:11] nt
	s_add_u32 s10, s10, 0x10000
	s_addc_u32 s11, s11, 0
	global_load_dword v47, v34, s[10:11] nt
	s_mul_i32 s12, s21, 1
	s_add_u32 s12, s12, s8
	s_cmp_ge_u32 s12, 0xb00
	s_cbranch_scc1 .Lcv_wf2_l1_pro_done
	s_mul_i32 s12, s21, 1
	s_add_u32 s12, s12, s8
	s_lshr_b32 s13, s12, 5
	s_and_b32 s14, s12, 31
	s_mul_i32 s15, s13, 0x80000
	s_lshl_b32 s16, s14, 8
	s_add_u32 s15, s15, s16
	s_add_u32 s10, s4, s15
	s_addc_u32 s11, s5, 0
	global_load_dword v48, v34, s[10:11] nt
	s_add_u32 s10, s10, 0x10000
	s_addc_u32 s11, s11, 0
	global_load_dword v49, v34, s[10:11] nt
	s_add_u32 s10, s10, 0x10000
	s_addc_u32 s11, s11, 0
	global_load_dword v50, v34, s[10:11] nt
	s_add_u32 s10, s10, 0x10000
	s_addc_u32 s11, s11, 0
	global_load_dword v51, v34, s[10:11] nt
	s_add_u32 s10, s10, 0x10000
	s_addc_u32 s11, s11, 0
	global_load_dword v52, v34, s[10:11] nt
	s_add_u32 s10, s10, 0x10000
	s_addc_u32 s11, s11, 0
	global_load_dword v53, v34, s[10:11] nt
	s_add_u32 s10, s10, 0x10000
	s_addc_u32 s11, s11, 0
	global_load_dword v54, v34, s[10:11] nt
	s_add_u32 s10, s10, 0x10000
	s_addc_u32 s11, s11, 0
	global_load_dword v55, v34, s[10:11] nt
	s_mul_i32 s12, s21, 2
	s_add_u32 s12, s12, s8
	s_cmp_ge_u32 s12, 0xb00
	s_cbranch_scc1 .Lcv_wf2_l1_pro_done
	s_mul_i32 s12, s21, 2
	s_add_u32 s12, s12, s8
	s_lshr_b32 s13, s12, 5
	s_and_b32 s14, s12, 31
	s_mul_i32 s15, s13, 0x80000
	s_lshl_b32 s16, s14, 8
	s_add_u32 s15, s15, s16
	s_add_u32 s10, s4, s15
	s_addc_u32 s11, s5, 0
	global_load_dword v56, v34, s[10:11] nt
	s_add_u32 s10, s10, 0x10000
	s_addc_u32 s11, s11, 0
	global_load_dword v57, v34, s[10:11] nt
	s_add_u32 s10, s10, 0x10000
	s_addc_u32 s11, s11, 0
	global_load_dword v58, v34, s[10:11] nt
	s_add_u32 s10, s10, 0x10000
	s_addc_u32 s11, s11, 0
	global_load_dword v59, v34, s[10:11] nt
	s_add_u32 s10, s10, 0x10000
	s_addc_u32 s11, s11, 0
	global_load_dword v60, v34, s[10:11] nt
	s_add_u32 s10, s10, 0x10000
	s_addc_u32 s11, s11, 0
	global_load_dword v61, v34, s[10:11] nt
	s_add_u32 s10, s10, 0x10000
	s_addc_u32 s11, s11, 0
	global_load_dword v62, v34, s[10:11] nt
	s_add_u32 s10, s10, 0x10000
	s_addc_u32 s11, s11, 0
	global_load_dword v63, v34, s[10:11] nt
	s_mul_i32 s12, s21, 3
	s_add_u32 s12, s12, s8
	s_cmp_ge_u32 s12, 0xb00
	s_cbranch_scc1 .Lcv_wf2_l1_pro_done
	s_mul_i32 s12, s21, 3
	s_add_u32 s12, s12, s8
	s_lshr_b32 s13, s12, 5
	s_and_b32 s14, s12, 31
	s_mul_i32 s15, s13, 0x80000
	s_lshl_b32 s16, s14, 8
	s_add_u32 s15, s15, s16
	s_add_u32 s10, s4, s15
	s_addc_u32 s11, s5, 0
	global_load_dword v64, v34, s[10:11] nt
	s_add_u32 s10, s10, 0x10000
	s_addc_u32 s11, s11, 0
	global_load_dword v65, v34, s[10:11] nt
	s_add_u32 s10, s10, 0x10000
	s_addc_u32 s11, s11, 0
	global_load_dword v66, v34, s[10:11] nt
	s_add_u32 s10, s10, 0x10000
	s_addc_u32 s11, s11, 0
	global_load_dword v67, v34, s[10:11] nt
	s_add_u32 s10, s10, 0x10000
	s_addc_u32 s11, s11, 0
	global_load_dword v68, v34, s[10:11] nt
	s_add_u32 s10, s10, 0x10000
	s_addc_u32 s11, s11, 0
	global_load_dword v69, v34, s[10:11] nt
	s_add_u32 s10, s10, 0x10000
	s_addc_u32 s11, s11, 0
	global_load_dword v70, v34, s[10:11] nt
	s_add_u32 s10, s10, 0x10000
	s_addc_u32 s11, s11, 0
	global_load_dword v71, v34, s[10:11] nt

; DI int lbid() { int b = blockIdx.x; asm volatile("" : "+s"(b)); return b; }
; template <class Map>
; DI void conv_T(bf16_t* __restrict__ dst, const float* __restrict__ src, int K, int ldsrc, int nphys, Map map, const float* __restrict__ kscale, float* tile) {
;     ...
;   for (int tl = lbid(); tl < ntiles; tl += gridDim.x) {
;     const int k0 = (tl / ntn) << 6, n0 = (tl % ntn) << 6;
;     const int nn = tid & 63, sc = map(n0 + nn);
; #pragma unroll
;     for (int i = 0; i < 8; ++i) { const int kk = i * 8 + (tid >> 6);
;       float v = sc >= 0 ? __builtin_nontemporal_load(&src[(size_t)(k0 + kk) * ldsrc + sc]) : 0.f;
;       if (kscale) v *= kscale[k0 + kk];
;       tile[kk * 65 + nn] = v; }
.Lcv_wf2_l1_p0_after:
	ds_write_b32 v30, v40
	ds_write_b32 v30, v41 offset:2080
	ds_write_b32 v30, v42 offset:4160
	ds_write_b32 v30, v43 offset:6240
	ds_write_b32 v30, v44 offset:8320
	ds_write_b32 v30, v45 offset:10400
	ds_write_b32 v30, v46 offset:12480
	ds_write_b32 v30, v47 offset:14560
	s_mul_i32 s12, s21, 1
	s_add_u32 s12, s12, s8
	s_cmp_ge_u32 s12, 0xb00
	s_cbranch_scc1 .Lcv_wf2_l1_p0_wr_done
	ds_write_b32 v30, v48 offset:16640
	ds_write_b32 v30, v49 offset:18720
	ds_write_b32 v30, v50 offset:20800
	ds_write_b32 v30, v51 offset:22880
	ds_write_b32 v30, v52 offset:24960
	ds_write_b32 v30, v53 offset:27040
	ds_write_b32 v30, v54 offset:29120
	ds_write_b32 v30, v55 offset:31200
	s_mul_i32 s12, s21, 2
	s_add_u32 s12, s12, s8
	s_cmp_ge_u32 s12, 0xb00
	s_cbranch_scc1 .Lcv_wf2_l1_p0_wr_done
	ds_write_b32 v30, v56 offset:33280
	ds_write_b32 v30, v57 offset:35360
	ds_write_b32 v30, v58 offset:37440
	ds_write_b32 v30, v59 offset:39520
	ds_write_b32 v30, v60 offset:41600
	ds_write_b32 v30, v61 offset:43680
	ds_write_b32 v30, v62 offset:45760
	ds_write_b32 v30, v63 offset:47840
	s_mul_i32 s12, s21, 3
	s_add_u32 s12, s12, s8
	s_cmp_ge_u32 s12, 0xb00
	s_cbranch_scc1 .Lcv_wf2_l1_p0_wr_done
	ds_write_b32 v30, v64 offset:49920
	ds_write_b32 v30, v65 offset:52000
	ds_write_b32 v30, v66 offset:54080
	ds_write_b32 v30, v67 offset:56160
	ds_write_b32 v30, v68 offset:58240
	ds_write_b32 v30, v69 offset:60320
	ds_write_b32 v30, v70 offset:62400
	ds_write_b32 v30, v71 offset:64480
.Lcv_wf2_l1_p0_wr_done:
	s_mul_i32 s12, s21, 4
	s_add_u32 s12, s12, s8
	s_cmp_ge_u32 s12, 0xb00
	s_cbranch_scc1 .Lcv_wf2_l1_p0_pf_done
	s_mul_i32 s12, s21, 4
	s_add_u32 s12, s12, s8
	s_lshr_b32 s13, s12, 5
	s_and_b32 s14, s12, 31
	s_mul_i32 s15, s13, 0x80000
	s_lshl_b32 s16, s14, 8
	s_add_u32 s15, s15, s16
	s_add_u32 s10, s4, s15
	s_addc_u32 s11, s5, 0
	global_load_dword v88, v34, s[10:11] nt
	s_add_u32 s10, s10, 0x10000
	s_addc_u32 s11, s11, 0
	global_load_dword v89, v34, s[10:11] nt
	s_add_u32 s10, s10, 0x10000
	s_addc_u32 s11, s11, 0
	global_load_dword v90, v34, s[10:11] nt
	s_add_u32 s10, s10, 0x10000
	s_addc_u32 s11, s11, 0
	global_load_dword v91, v34, s[10:11] nt
	s_add_u32 s10, s10, 0x10000
	s_addc_u32 s11, s11, 0
	global_load_dword v92, v34, s[10:11] nt
	s_add_u32 s10, s10, 0x10000
	s_addc_u32 s11, s11, 0
	global_load_dword v93, v34, s[10:11] nt
	s_add_u32 s10, s10, 0x10000
	s_addc_u32 s11, s11, 0
	global_load_dword v94, v34, s[10:11] nt
	s_add_u32 s10, s10, 0x10000
	s_addc_u32 s11, s11, 0
	global_load_dword v95, v34, s[10:11] nt
	s_mul_i32 s12, s21, 5
	s_add_u32 s12, s12, s8
	s_cmp_ge_u32 s12, 0xb00
	s_cbranch_scc1 .Lcv_wf2_l1_p0_pf_done
	s_mul_i32 s12, s21, 5
	s_add_u32 s12, s12, s8
	s_lshr_b32 s13, s12, 5
	s_and_b32 s14, s12, 31
	s_mul_i32 s15, s13, 0x80000
	s_lshl_b32 s16, s14, 8
	s_add_u32 s15, s15, s16
	s_add_u32 s10, s4, s15
	s_addc_u32 s11, s5, 0
	global_load_dword v96, v34, s[10:11] nt
	s_add_u32 s10, s10, 0x10000
	s_addc_u32 s11, s11, 0
	global_load_dword v97, v34, s[10:11] nt
	s_add_u32 s10, s10, 0x10000
	s_addc_u32 s11, s11, 0
	global_load_dword v98, v34, s[10:11] nt
	s_add_u32 s10, s10, 0x10000
	s_addc_u32 s11, s11, 0
	global_load_dword v99, v34, s[10:11] nt
	s_add_u32 s10, s10, 0x10000
	s_addc_u32 s11, s11, 0
	global_load_dword v100, v34, s[10:11] nt
	s_add_u32 s10, s10, 0x10000
	s_addc_u32 s11, s11, 0
	global_load_dword v101, v34, s[10:11] nt
	s_add_u32 s10, s10, 0x10000
	s_addc_u32 s11, s11, 0
	global_load_dword v102, v34, s[10:11] nt
	s_add_u32 s10, s10, 0x10000
	s_addc_u32 s11, s11, 0
	global_load_dword v103, v34, s[10:11] nt
	s_mul_i32 s12, s21, 6
	s_add_u32 s12, s12, s8
	s_cmp_ge_u32 s12, 0xb00
	s_cbranch_scc1 .Lcv_wf2_l1_p0_pf_done
	s_mul_i32 s12, s21, 6
	s_add_u32 s12, s12, s8
	s_lshr_b32 s13, s12, 5
	s_and_b32 s14, s12, 31
	s_mul_i32 s15, s13, 0x80000
	s_lshl_b32 s16, s14, 8
	s_add_u32 s15, s15, s16
	s_add_u32 s10, s4, s15
	s_addc_u32 s11, s5, 0
	global_load_dword v104, v34, s[10:11] nt
	s_add_u32 s10, s10, 0x10000
	s_addc_u32 s11, s11, 0
	global_load_dword v105, v34, s[10:11] nt
	s_add_u32 s10, s10, 0x10000
	s_addc_u32 s11, s11, 0
	global_load_dword v106, v34, s[10:11] nt
	s_add_u32 s10, s10, 0x10000
	s_addc_u32 s11, s11, 0
	global_load_dword v107, v34, s[10:11] nt
	s_add_u32 s10, s10, 0x10000
	s_addc_u32 s11, s11, 0
	global_load_dword v108, v34, s[10:11] nt
	s_add_u32 s10, s10, 0x10000
	s_addc_u32 s11, s11, 0
	global_load_dword v109, v34, s[10:11] nt
	s_add_u32 s10, s10, 0x10000
	s_addc_u32 s11, s11, 0
	global_load_dword v110, v34, s[10:11] nt
	s_add_u32 s10, s10, 0x10000
	s_addc_u32 s11, s11, 0
	global_load_dword v111, v34, s[10:11] nt
	s_mul_i32 s12, s21, 7
	s_add_u32 s12, s12, s8
	s_cmp_ge_u32 s12, 0xb00
	s_cbranch_scc1 .Lcv_wf2_l1_p0_pf_done
	s_mul_i32 s12, s21, 7
	s_add_u32 s12, s12, s8
	s_lshr_b32 s13, s12, 5
	s_and_b32 s14, s12, 31
	s_mul_i32 s15, s13, 0x80000
	s_lshl_b32 s16, s14, 8
	s_add_u32 s15, s15, s16
	s_add_u32 s10, s4, s15
	s_addc_u32 s11, s5, 0
	global_load_dword v112, v34, s[10:11] nt
	s_add_u32 s10, s10, 0x10000
	s_addc_u32 s11, s11, 0
	global_load_dword v113, v34, s[10:11] nt
	s_add_u32 s10, s10, 0x10000
	s_addc_u32 s11, s11, 0
	global_load_dword v114, v34, s[10:11] nt
	s_add_u32 s10, s10, 0x10000
	s_addc_u32 s11, s11, 0
	global_load_dword v115, v34, s[10:11] nt
	s_add_u32 s10, s10, 0x10000
	s_addc_u32 s11, s11, 0
	global_load_dword v116, v34, s[10:11] nt
	s_add_u32 s10, s10, 0x10000
	s_addc_u32 s11, s11, 0
	global_load_dword v117, v34, s[10:11] nt
	s_add_u32 s10, s10, 0x10000
	s_addc_u32 s11, s11, 0
	global_load_dword v118, v34, s[10:11] nt
	s_add_u32 s10, s10, 0x10000
	s_addc_u32 s11, s11, 0
	global_load_dword v119, v34, s[10:11] nt

; DI int lbid() { int b = blockIdx.x; asm volatile("" : "+s"(b)); return b; }
; template <class Map>
; DI void conv_T(bf16_t* __restrict__ dst, const float* __restrict__ src, int K, int ldsrc, int nphys, Map map, const float* __restrict__ kscale, float* tile) {
;     ...
;   for (int tl = lbid(); tl < ntiles; tl += gridDim.x) {
;     const int k0 = (tl / ntn) << 6, n0 = (tl % ntn) << 6;
;     const int nn = tid & 63, sc = map(n0 + nn);
; #pragma unroll
;     for (int i = 0; i < 8; ++i) { const int kk = i * 8 + (tid >> 6);
;       float v = sc >= 0 ? __builtin_nontemporal_load(&src[(size_t)(k0 + kk) * ldsrc + sc]) : 0.f;
;       if (kscale) v *= kscale[k0 + kk];
;       tile[kk * 65 + nn] = v; }
.Lcv_wf2_l1_p0_st_done:
	s_lshl_b32 s12, s21, 2
	s_add_u32 s8, s8, s12
	s_cmp_ge_u32 s8, 0xb00
	s_cbranch_scc1 .Lcv_wf2_l1_end
	s_waitcnt vmcnt(4)
.Lcv_wf2_l1_p1_after:
	ds_write_b32 v31, v88
	ds_write_b32 v31, v89 offset:2080
	ds_write_b32 v31, v90 offset:4160
	ds_write_b32 v31, v91 offset:6240
	ds_write_b32 v31, v92 offset:8320
	ds_write_b32 v31, v93 offset:10400
	ds_write_b32 v31, v94 offset:12480
	ds_write_b32 v31, v95 offset:14560
	s_mul_i32 s12, s21, 1
	s_add_u32 s12, s12, s8
	s_cmp_ge_u32 s12, 0xb00
	s_cbranch_scc1 .Lcv_wf2_l1_p1_wr_done
	ds_write_b32 v31, v96 offset:16640
	ds_write_b32 v31, v97 offset:18720
	ds_write_b32 v31, v98 offset:20800
	ds_write_b32 v31, v99 offset:22880
	ds_write_b32 v31, v100 offset:24960
	ds_write_b32 v31, v101 offset:27040
	ds_write_b32 v31, v102 offset:29120
	ds_write_b32 v31, v103 offset:31200
	s_mul_i32 s12, s21, 2
	s_add_u32 s12, s12, s8
	s_cmp_ge_u32 s12, 0xb00
	s_cbranch_scc1 .Lcv_wf2_l1_p1_wr_done
	ds_write_b32 v31, v104 offset:33280
	ds_write_b32 v31, v105 offset:35360
	ds_write_b32 v31, v106 offset:37440
	ds_write_b32 v31, v107 offset:39520
	ds_write_b32 v31, v108 offset:41600
	ds_write_b32 v31, v109 offset:43680
	ds_write_b32 v31, v110 offset:45760
	ds_write_b32 v31, v111 offset:47840
	s_mul_i32 s12, s21, 3
	s_add_u32 s12, s12, s8
	s_cmp_ge_u32 s12, 0xb00
	s_cbranch_scc1 .Lcv_wf2_l1_p1_wr_done
	ds_write_b32 v31, v112 offset:49920
	ds_write_b32 v31, v113 offset:52000
	ds_write_b32 v31, v114 offset:54080
	ds_write_b32 v31, v115 offset:56160
	ds_write_b32 v31, v116 offset:58240
	ds_write_b32 v31, v117 offset:60320
	ds_write_b32 v31, v118 offset:62400
	ds_write_b32 v31, v119 offset:64480
.Lcv_wf2_l1_p1_wr_done:
	s_mul_i32 s12, s21, 4
	s_add_u32 s12, s12, s8
	s_cmp_ge_u32 s12, 0xb00
	s_cbranch_scc1 .Lcv_wf2_l1_p1_pf_done
	s_mul_i32 s12, s21, 4
	s_add_u32 s12, s12, s8
	s_lshr_b32 s13, s12, 5
	s_and_b32 s14, s12, 31
	s_mul_i32 s15, s13, 0x80000
	s_lshl_b32 s16, s14, 8
	s_add_u32 s15, s15, s16
	s_add_u32 s10, s4, s15
	s_addc_u32 s11, s5, 0
	global_load_dword v40, v34, s[10:11] nt
	s_add_u32 s10, s10, 0x10000
	s_addc_u32 s11, s11, 0
	global_load_dword v41, v34, s[10:11] nt
	s_add_u32 s10, s10, 0x10000
	s_addc_u32 s11, s11, 0
	global_load_dword v42, v34, s[10:11] nt
	s_add_u32 s10, s10, 0x10000
	s_addc_u32 s11, s11, 0
	global_load_dword v43, v34, s[10:11] nt
	s_add_u32 s10, s10, 0x10000
	s_addc_u32 s11, s11, 0
	global_load_dword v44, v34, s[10:11] nt
	s_add_u32 s10, s10, 0x10000
	s_addc_u32 s11, s11, 0
	global_load_dword v45, v34, s[10:11] nt
	s_add_u32 s10, s10, 0x10000
	s_addc_u32 s11, s11, 0
	global_load_dword v46, v34, s[10:11] nt
	s_add_u32 s10, s10, 0x10000
	s_addc_u32 s11, s11, 0
	global_load_dword v47, v34, s[10:11] nt
	s_mul_i32 s12, s21, 5
	s_add_u32 s12, s12, s8
	s_cmp_ge_u32 s12, 0xb00
	s_cbranch_scc1 .Lcv_wf2_l1_p1_pf_done
	s_mul_i32 s12, s21, 5
	s_add_u32 s12, s12, s8
	s_lshr_b32 s13, s12, 5
	s_and_b32 s14, s12, 31
	s_mul_i32 s15, s13, 0x80000
	s_lshl_b32 s16, s14, 8
	s_add_u32 s15, s15, s16
	s_add_u32 s10, s4, s15
	s_addc_u32 s11, s5, 0
	global_load_dword v48, v34, s[10:11] nt
	s_add_u32 s10, s10, 0x10000
	s_addc_u32 s11, s11, 0
	global_load_dword v49, v34, s[10:11] nt
	s_add_u32 s10, s10, 0x10000
	s_addc_u32 s11, s11, 0
	global_load_dword v50, v34, s[10:11] nt
	s_add_u32 s10, s10, 0x10000
	s_addc_u32 s11, s11, 0
	global_load_dword v51, v34, s[10:11] nt
	s_add_u32 s10, s10, 0x10000
	s_addc_u32 s11, s11, 0
	global_load_dword v52, v34, s[10:11] nt
	s_add_u32 s10, s10, 0x10000
	s_addc_u32 s11, s11, 0
	global_load_dword v53, v34, s[10:11] nt
	s_add_u32 s10, s10, 0x10000
	s_addc_u32 s11, s11, 0
	global_load_dword v54, v34, s[10:11] nt
	s_add_u32 s10, s10, 0x10000
	s_addc_u32 s11, s11, 0
	global_load_dword v55, v34, s[10:11] nt
	s_mul_i32 s12, s21, 6
	s_add_u32 s12, s12, s8
	s_cmp_ge_u32 s12, 0xb00
	s_cbranch_scc1 .Lcv_wf2_l1_p1_pf_done
	s_mul_i32 s12, s21, 6
	s_add_u32 s12, s12, s8
	s_lshr_b32 s13, s12, 5
	s_and_b32 s14, s12, 31
	s_mul_i32 s15, s13, 0x80000
	s_lshl_b32 s16, s14, 8
	s_add_u32 s15, s15, s16
	s_add_u32 s10, s4, s15
	s_addc_u32 s11, s5, 0
	global_load_dword v56, v34, s[10:11] nt
	s_add_u32 s10, s10, 0x10000
	s_addc_u32 s11, s11, 0
	global_load_dword v57, v34, s[10:11] nt
	s_add_u32 s10, s10, 0x10000
	s_addc_u32 s11, s11, 0
	global_load_dword v58, v34, s[10:11] nt
	s_add_u32 s10, s10, 0x10000
	s_addc_u32 s11, s11, 0
	global_load_dword v59, v34, s[10:11] nt
	s_add_u32 s10, s10, 0x10000
	s_addc_u32 s11, s11, 0
	global_load_dword v60, v34, s[10:11] nt
	s_add_u32 s10, s10, 0x10000
	s_addc_u32 s11, s11, 0
	global_load_dword v61, v34, s[10:11] nt
	s_add_u32 s10, s10, 0x10000
	s_addc_u32 s11, s11, 0
	global_load_dword v62, v34, s[10:11] nt
	s_add_u32 s10, s10, 0x10000
	s_addc_u32 s11, s11, 0
	global_load_dword v63, v34, s[10:11] nt
	s_mul_i32 s12, s21, 7
	s_add_u32 s12, s12, s8
	s_cmp_ge_u32 s12, 0xb00
	s_cbranch_scc1 .Lcv_wf2_l1_p1_pf_done
	s_mul_i32 s12, s21, 7
	s_add_u32 s12, s12, s8
	s_lshr_b32 s13, s12, 5
	s_and_b32 s14, s12, 31
	s_mul_i32 s15, s13, 0x80000
	s_lshl_b32 s16, s14, 8
	s_add_u32 s15, s15, s16
	s_add_u32 s10, s4, s15
	s_addc_u32 s11, s5, 0
	global_load_dword v64, v34, s[10:11] nt
	s_add_u32 s10, s10, 0x10000
	s_addc_u32 s11, s11, 0
	global_load_dword v65, v34, s[10:11] nt
	s_add_u32 s10, s10, 0x10000
	s_addc_u32 s11, s11, 0
	global_load_dword v66, v34, s[10:11] nt
	s_add_u32 s10, s10, 0x10000
	s_addc_u32 s11, s11, 0
	global_load_dword v67, v34, s[10:11] nt
	s_add_u32 s10, s10, 0x10000
	s_addc_u32 s11, s11, 0
	global_load_dword v68, v34, s[10:11] nt
	s_add_u32 s10, s10, 0x10000
	s_addc_u32 s11, s11, 0
	global_load_dword v69, v34, s[10:11] nt
	s_add_u32 s10, s10, 0x10000
	s_addc_u32 s11, s11, 0
	global_load_dword v70, v34, s[10:11] nt
	s_add_u32 s10, s10, 0x10000
	s_addc_u32 s11, s11, 0
	global_load_dword v71, v34, s[10:11] nt
; DI unsigned cvtpk(float lo, float hi) { unsigned r; asm volatile("v_cvt_pk_bf16_f32 %0, %1, %2" : "=v"(r) : "v"(lo), "v"(hi)); return r; }
; template <class Map>
; DI void conv_T(bf16_t* __restrict__ dst, const float* __restrict__ src, int K, int ldsrc, int nphys, Map map, const float* __restrict__ kscale, float* tile) {
;     ...
;     __syncthreads();
;     const int np = tid >> 3, ks = tid & 7;
;     float v[8];
; #pragma unroll
;     for (int j = 0; j < 8; ++j) v[j] = tile[(ks * 8 + j) * 65 + np];
;     u32x4 w = {cvtpk(v[0], v[1]), cvtpk(v[2], v[3]), cvtpk(v[4], v[5]), cvtpk(v[6], v[7])};
;     *(u32x4*)(dst + (size_t)(n0 + np) * K + k0 + ks * 8) = w;
;     __syncthreads();
.Lcv_wf2_l1_p1_pf_done:
	s_waitcnt lgkmcnt(0)
	s_barrier
	ds_read_b32 v88, v33
	ds_read_b32 v89, v33 offset:260
	ds_read_b32 v90, v33 offset:520
	ds_read_b32 v91, v33 offset:780
	ds_read_b32 v92, v33 offset:1040
	ds_read_b32 v93, v33 offset:1300
	ds_read_b32 v94, v33 offset:1560
	ds_read_b32 v95, v33 offset:1820
	s_mul_i32 s12, s21, 1
	s_add_u32 s12, s12, s8
	s_cmp_ge_u32 s12, 0xb00
	s_cbranch_scc1 .Lcv_wf2_l1_p1_rd_done
	ds_read_b32 v96, v33 offset:16640
	ds_read_b32 v97, v33 offset:16900
	ds_read_b32 v98, v33 offset:17160
	ds_read_b32 v99, v33 offset:17420
	ds_read_b32 v100, v33 offset:17680
	ds_read_b32 v101, v33 offset:17940
	ds_read_b32 v102, v33 offset:18200
	ds_read_b32 v103, v33 offset:18460
	s_mul_i32 s12, s21, 2
	s_add_u32 s12, s12, s8
	s_cmp_ge_u32 s12, 0xb00
	s_cbranch_scc1 .Lcv_wf2_l1_p1_rd_done
	ds_read_b32 v104, v33 offset:33280
	ds_read_b32 v105, v33 offset:33540
	ds_read_b32 v106, v33 offset:33800
	ds_read_b32 v107, v33 offset:34060
	ds_read_b32 v108, v33 offset:34320
	ds_read_b32 v109, v33 offset:34580
	ds_read_b32 v110, v33 offset:34840
	ds_read_b32 v111, v33 offset:35100
	s_mul_i32 s12, s21, 3
	s_add_u32 s12, s12, s8
	s_cmp_ge_u32 s12, 0xb00
	s_cbranch_scc1 .Lcv_wf2_l1_p1_rd_done
	ds_read_b32 v112, v33 offset:49920
	ds_read_b32 v113, v33 offset:50180
	ds_read_b32 v114, v33 offset:50440
	ds_read_b32 v115, v33 offset:50700
	ds_read_b32 v116, v33 offset:50960
	ds_read_b32 v117, v33 offset:51220
	ds_read_b32 v118, v33 offset:51480
	ds_read_b32 v119, v33 offset:51740
.Lcv_wf2_l1_p1_rd_done:
	s_waitcnt lgkmcnt(0)
	s_mov_b32 s12, s8
	s_lshr_b32 s13, s12, 5
	s_and_b32 s14, s12, 31
	s_mul_i32 s15, s14, 0xb0000
	s_lshl_b32 s16, s13, 7
	s_add_u32 s15, s15, s16
	s_add_u32 s10, s6, s15
	s_addc_u32 s11, s7, 0
	v_cvt_pk_bf16_f32 v72, v88, v89
	v_cvt_pk_bf16_f32 v73, v90, v91
	v_cvt_pk_bf16_f32 v74, v92, v93
	v_cvt_pk_bf16_f32 v75, v94, v95
	global_store_dwordx4 v35, v[72:75], s[10:11]
	s_mul_i32 s12, s21, 1
	s_add_u32 s12, s12, s8
	s_cmp_ge_u32 s12, 0xb00
	s_cbranch_scc1 .Lcv_wf2_l1_p1_st_done
	s_mul_i32 s12, s21, 1
	s_add_u32 s12, s12, s8
	s_lshr_b32 s13, s12, 5
	s_and_b32 s14, s12, 31
	s_mul_i32 s15, s14, 0xb0000
	s_lshl_b32 s16, s13, 7
	s_add_u32 s15, s15, s16
	s_add_u32 s10, s6, s15
	s_addc_u32 s11, s7, 0
	v_cvt_pk_bf16_f32 v76, v96, v97
	v_cvt_pk_bf16_f32 v77, v98, v99
	v_cvt_pk_bf16_f32 v78, v100, v101
	v_cvt_pk_bf16_f32 v79, v102, v103
	global_store_dwordx4 v35, v[76:79], s[10:11]
	s_mul_i32 s12, s21, 2
	s_add_u32 s12, s12, s8
	s_cmp_ge_u32 s12, 0xb00
	s_cbranch_scc1 .Lcv_wf2_l1_p1_st_done
	s_mul_i32 s12, s21, 2
	s_add_u32 s12, s12, s8
	s_lshr_b32 s13, s12, 5
	s_and_b32 s14, s12, 31
	s_mul_i32 s15, s14, 0xb0000
	s_lshl_b32 s16, s13, 7
	s_add_u32 s15, s15, s16
	s_add_u32 s10, s6, s15
	s_addc_u32 s11, s7, 0
	v_cvt_pk_bf16_f32 v80, v104, v105
	v_cvt_pk_bf16_f32 v81, v106, v107
	v_cvt_pk_bf16_f32 v82, v108, v109
	v_cvt_pk_bf16_f32 v83, v110, v111
	global_store_dwordx4 v35, v[80:83], s[10:11]
	s_mul_i32 s12, s21, 3
	s_add_u32 s12, s12, s8
	s_cmp_ge_u32 s12, 0xb00
	s_cbranch_scc1 .Lcv_wf2_l1_p1_st_done
	s_mul_i32 s12, s21, 3
	s_add_u32 s12, s12, s8
	s_lshr_b32 s13, s12, 5
	s_and_b32 s14, s12, 31
	s_mul_i32 s15, s14, 0xb0000
	s_lshl_b32 s16, s13, 7
	s_add_u32 s15, s15, s16
	s_add_u32 s10, s6, s15
	s_addc_u32 s11, s7, 0
	v_cvt_pk_bf16_f32 v84, v112, v113
	v_cvt_pk_bf16_f32 v85, v114, v115
	v_cvt_pk_bf16_f32 v86, v116, v117
	v_cvt_pk_bf16_f32 v87, v118, v119
	global_store_dwordx4 v35, v[84:87], s[10:11]
.Lcv_wf2_l1_p1_st_done:
	s_lshl_b32 s12, s21, 2
	s_add_u32 s8, s8, s12
	s_cmp_ge_u32 s8, 0xb00
	s_cbranch_scc0 .Lcv_wf2_l1_loop
.Lcv_wf2_l1_end:
	s_barrier
.LBB0_2136:
	v_mov_b32_e32 v0, v248
	s_mov_b32 s4, s85
	s_cmpk_gt_i32 s4, 0x7f
	s_cbranch_scc1 .LBB0_2143
	v_and_b32_e32 v4, 63, v0
	v_ashrrev_i32_e32 v5, 6, v0
	v_ashrrev_i32_e32 v6, 3, v0
	v_lshlrev_b32_e32 v0, 3, v0
	v_and_b32_e32 v0, 56, v0
	v_lshl_add_u32 v2, v4, 2, 0
	v_lshl_add_u32 v3, v6, 2, 0
	v_mul_u32_u24_e32 v7, 0x104, v0
	v_mul_lo_u32 v8, v5, s28
	v_readlane_b32 s0, v251, 63
	s_lshl_b32 s5, s4, 6
	s_lshl_b32 s6, s0, 6
	v_add_u32_e32 v7, v3, v7
	v_lshlrev_b32_e32 v0, 1, v0
	v_add_u32_e32 v8, v2, v8
	v_readlane_b32 s1, v252, 0
	s_branch .LBB0_2139
